# SGU: LN gain/bias staged in LDS (ds_read_b128 broadcast) + phase-2 stores widened to 16B via permlane32_swap (on v18)
# speedup vs baseline: 1.0081x; 1.0073x over previous
.LBB0_402:
	s_or_b64 exec, exec, s[8:9]
	v_mov_b32_e32 v108, v224
	s_load_dwordx4 s[8:11], s[36:37], 0x40
	s_and_b32 s12, s64, 3
	s_lshl_b32 s12, s12, 9
	v_lshlrev_b32_e32 v0, 3, v224
	v_add_u32_e32 v0, s12, v0
	v_lshlrev_b32_e32 v1, 4, v224
	v_add_u32_e32 v1, 0x22800, v1
	v_cmp_gt_u32_e32 vcc, 64, v224
	s_and_saveexec_b64 s[14:15], vcc
	s_waitcnt lgkmcnt(0)
	global_load_dwordx2 v[2:3], v0, s[8:9]
	global_load_dwordx2 v[4:5], v0, s[10:11]
	s_waitcnt vmcnt(0)
	ds_write_b128 v1, v[2:5]
	s_waitcnt lgkmcnt(0)
	s_or_b64 exec, exec, s[14:15]
	s_waitcnt vmcnt(0)
	s_barrier
	s_load_dwordx8 s[8:15], s[36:37], 0x40
	v_mov_b32_e32 v255, 0x22800
	s_movk_i32 s16, 0x80
	v_readfirstlane_b32 s39, v108
	s_ashr_i32 s41, s39, 7
	s_cmp_eq_u32 s41, 2
	s_cselect_b32 s16, s16, 0x100
	s_cmp_lg_u32 s41, 1
	s_cselect_b32 s16, s16, 0
	s_cmpk_gt_u32 s39, 0x7f
	s_cselect_b32 s16, s16, 0xffffff80
	s_add_i32 s16, s16, s64
	s_mov_b32 s17, 0
	s_lshr_b32 s16, s16, 2
	v_and_b32_e32 v109, 0x7f, v108
	s_lshl_b64 s[18:19], s[16:17], 7
	v_or_b32_e32 v2, s18, v109
	s_movk_i32 s16, 0x1400
	v_mov_b64_e32 v[0:1], s[22:23]
	v_mad_u64_u32 v[0:1], s[26:27], v2, s16, v[0:1]
	s_lshl_b32 s16, s64, 7
	v_mov_b32_e32 v2, 0x1400
	s_and_b32 s37, s16, 0x180
	v_mad_u32_u24 v1, s19, v2, v1
	s_lshl_b32 s16, s37, 1
	v_lshl_add_u64 v[4:5], v[0:1], 0, s[16:17]
	s_movk_i32 s17, 0x1000
	v_add_co_u32_e32 v0, vcc, s17, v4
	s_mov_b32 s38, 0x3d372713
	s_nop 0
	v_addc_co_u32_e32 v1, vcc, 0, v5, vcc
	global_load_dwordx4 v[0:3], v[0:1], off
	s_mov_b32 s36, 0xc0135761
	s_mov_b64 s[26:27], 0x1000
	v_lshl_add_u64 v[4:5], v[4:5], 0, s[26:27]
	global_load_dwordx4 v[172:175], v[4:5], off offset:16
	global_load_dwordx4 v[176:179], v[4:5], off offset:32
	global_load_dwordx4 v[180:183], v[4:5], off offset:48
	global_load_dwordx4 v[184:187], v[4:5], off offset:64
	global_load_dwordx4 v[188:191], v[4:5], off offset:80
	global_load_dwordx4 v[192:195], v[4:5], off offset:96
	global_load_dwordx4 v[196:199], v[4:5], off offset:112
	global_load_dwordx4 v[200:203], v[4:5], off offset:128
	global_load_dwordx4 v[204:207], v[4:5], off offset:144
	global_load_dwordx4 v[208:211], v[4:5], off offset:160
	global_load_dwordx4 v[212:215], v[4:5], off offset:176
	global_load_dwordx4 v[216:219], v[4:5], off offset:192
	global_load_dwordx4 v[220:223], v[4:5], off offset:208
	global_load_dwordx4 v[228:231], v[4:5], off offset:224
	global_load_dwordx4 v[232:235], v[4:5], off offset:240
	s_lshl_b32 s17, s37, 2
	s_brev_b32 s40, 60
	s_waitcnt vmcnt(15)
	v_lshlrev_b32_e32 v6, 16, v0
	v_and_b32_e32 v7, 0xffff0000, v0
	v_lshlrev_b32_e32 v0, 16, v1
	v_and_b32_e32 v1, 0xffff0000, v1
	v_lshlrev_b32_e32 v8, 16, v2
	v_and_b32_e32 v9, 0xffff0000, v2
	v_lshlrev_b32_e32 v2, 16, v3
	v_and_b32_e32 v3, 0xffff0000, v3
	v_pk_mul_f32 v[10:11], v[6:7], v[6:7]
	v_pk_mul_f32 v[12:13], v[0:1], v[0:1]
	v_pk_mul_f32 v[14:15], v[8:9], v[8:9]
	v_pk_mul_f32 v[16:17], v[2:3], v[2:3]
	v_pk_fma_f32 v[10:11], v[10:11], s[38:39], 1.0 op_sel_hi:[1,0,0]
	v_pk_fma_f32 v[12:13], v[12:13], s[38:39], 1.0 op_sel_hi:[1,0,0]
	v_pk_fma_f32 v[14:15], v[14:15], s[38:39], 1.0 op_sel_hi:[1,0,0]
	v_pk_fma_f32 v[16:17], v[16:17], s[38:39], 1.0 op_sel_hi:[1,0,0]
	v_pk_mul_f32 v[10:11], v[10:11], v[6:7]
	v_pk_mul_f32 v[12:13], v[12:13], v[0:1]
	v_pk_mul_f32 v[14:15], v[14:15], v[8:9]
	v_pk_mul_f32 v[16:17], v[16:17], v[2:3]
	v_pk_mul_f32 v[10:11], v[10:11], s[36:37] op_sel_hi:[1,0]
	v_pk_mul_f32 v[12:13], v[12:13], s[36:37] op_sel_hi:[1,0]
	v_pk_mul_f32 v[14:15], v[14:15], s[36:37] op_sel_hi:[1,0]
	v_pk_mul_f32 v[16:17], v[16:17], s[36:37] op_sel_hi:[1,0]
	v_exp_f32_e32 v10, v10
	v_exp_f32_e32 v11, v11
	v_exp_f32_e32 v12, v12
	v_exp_f32_e32 v13, v13
	v_exp_f32_e32 v14, v14
	v_exp_f32_e32 v15, v15
	v_exp_f32_e32 v16, v16
	v_exp_f32_e32 v17, v17
	v_pk_add_f32 v[10:11], v[10:11], 1.0 op_sel_hi:[1,0]
	v_pk_add_f32 v[12:13], v[12:13], 1.0 op_sel_hi:[1,0]
	v_pk_add_f32 v[18:19], v[14:15], 1.0 op_sel_hi:[1,0]
	v_pk_add_f32 v[16:17], v[16:17], 1.0 op_sel_hi:[1,0]
	v_rcp_f32_e32 v14, v10
	v_rcp_f32_e32 v15, v11
	v_rcp_f32_e32 v10, v12
	v_rcp_f32_e32 v11, v13
	v_rcp_f32_e32 v12, v18
	v_rcp_f32_e32 v13, v19
	v_rcp_f32_e32 v18, v16
	v_rcp_f32_e32 v19, v17
	v_pk_mul_f32 v[16:17], v[14:15], v[6:7]
	v_pk_mul_f32 v[10:11], v[10:11], v[0:1]
	v_pk_mul_f32 v[8:9], v[12:13], v[8:9]
	v_pk_mul_f32 v[12:13], v[18:19], v[2:3]
	v_cvt_pk_bf16_f32 v114, v16, v17
	v_cvt_pk_bf16_f32 v112, v10, v11
	v_cvt_pk_bf16_f32 v111, v8, v9
	v_pk_fma_f32 v[6:7], v[14:15], v[6:7], v[16:17] op_sel_hi:[1,1,0]
	v_cvt_pk_bf16_f32 v110, v12, v13
	v_pk_mul_f32 v[14:15], v[16:17], v[16:17]
	v_pk_mul_f32 v[16:17], v[10:11], v[10:11]
	v_mov_b32_e32 v165, v10
	v_mov_b32_e32 v164, v14
	v_mov_b32_e32 v10, v15
	v_mov_b32_e32 v6, v16
	v_mov_b32_e32 v167, v8
	v_pk_add_f32 v[10:11], v[164:165], v[10:11]
	v_pk_mul_f32 v[162:163], v[12:13], v[12:13]
	v_mov_b32_e32 v169, v12
	v_mov_b32_e32 v168, v162
	v_mov_b32_e32 v12, v163
	v_pk_add_f32 v[12:13], v[168:169], v[12:13]
	s_waitcnt vmcnt(14)
	v_mov_b32_e32 v0, v172
	v_mov_b32_e32 v1, v173
	v_mov_b32_e32 v2, v174
	v_mov_b32_e32 v3, v175
	v_lshlrev_b32_e32 v18, 16, v0
	v_and_b32_e32 v19, 0xffff0000, v0
	v_lshlrev_b32_e32 v0, 16, v1
	v_and_b32_e32 v1, 0xffff0000, v1
	v_lshlrev_b32_e32 v24, 16, v2
	v_and_b32_e32 v25, 0xffff0000, v2
	v_lshlrev_b32_e32 v2, 16, v3
	v_and_b32_e32 v3, 0xffff0000, v3
	v_pk_mul_f32 v[20:21], v[18:19], v[18:19]
	v_pk_mul_f32 v[22:23], v[0:1], v[0:1]
	v_pk_mul_f32 v[26:27], v[24:25], v[24:25]
	v_pk_mul_f32 v[28:29], v[2:3], v[2:3]
	v_pk_fma_f32 v[20:21], v[20:21], s[38:39], 1.0 op_sel_hi:[1,0,0]
	v_pk_fma_f32 v[22:23], v[22:23], s[38:39], 1.0 op_sel_hi:[1,0,0]
	v_pk_fma_f32 v[26:27], v[26:27], s[38:39], 1.0 op_sel_hi:[1,0,0]
	v_pk_fma_f32 v[28:29], v[28:29], s[38:39], 1.0 op_sel_hi:[1,0,0]
	v_pk_mul_f32 v[20:21], v[20:21], v[18:19]
	v_pk_mul_f32 v[22:23], v[22:23], v[0:1]
	v_pk_mul_f32 v[26:27], v[26:27], v[24:25]
	v_pk_mul_f32 v[28:29], v[28:29], v[2:3]
	v_pk_mul_f32 v[20:21], v[20:21], s[36:37] op_sel_hi:[1,0]
	v_pk_mul_f32 v[22:23], v[22:23], s[36:37] op_sel_hi:[1,0]
	v_pk_mul_f32 v[26:27], v[26:27], s[36:37] op_sel_hi:[1,0]
	v_pk_mul_f32 v[28:29], v[28:29], s[36:37] op_sel_hi:[1,0]
	v_exp_f32_e32 v20, v20
	v_exp_f32_e32 v21, v21
	v_exp_f32_e32 v22, v22
	v_exp_f32_e32 v23, v23
	v_exp_f32_e32 v26, v26
	v_exp_f32_e32 v27, v27
	v_exp_f32_e32 v28, v28
	v_exp_f32_e32 v29, v29
	v_pk_add_f32 v[20:21], v[20:21], 1.0 op_sel_hi:[1,0]
	v_pk_add_f32 v[22:23], v[22:23], 1.0 op_sel_hi:[1,0]
	v_pk_add_f32 v[26:27], v[26:27], 1.0 op_sel_hi:[1,0]
	v_pk_add_f32 v[28:29], v[28:29], 1.0 op_sel_hi:[1,0]
	v_rcp_f32_e32 v20, v20
	v_rcp_f32_e32 v21, v21
	v_rcp_f32_e32 v30, v22
	v_rcp_f32_e32 v31, v23
	v_rcp_f32_e32 v26, v26
	v_rcp_f32_e32 v27, v27
	v_rcp_f32_e32 v28, v28
	v_rcp_f32_e32 v29, v29
	v_pk_mul_f32 v[22:23], v[20:21], v[18:19]
	v_pk_mul_f32 v[20:21], v[30:31], v[0:1]
	v_pk_mul_f32 v[18:19], v[26:27], v[24:25]
	v_pk_mul_f32 v[24:25], v[28:29], v[2:3]
	v_cvt_pk_bf16_f32 v117, v22, v23
	v_cvt_pk_bf16_f32 v116, v20, v21
	v_cvt_pk_bf16_f32 v115, v18, v19
	v_mov_b32_e32 v163, v18
	v_cvt_pk_bf16_f32 v113, v24, v25
	v_pk_mul_f32 v[14:15], v[24:25], v[24:25]
	v_mov_b32_e32 v165, v24
	v_mov_b32_e32 v164, v14
	v_mov_b32_e32 v24, v15
	v_pk_add_f32 v[14:15], v[164:165], v[24:25]
	s_waitcnt vmcnt(13)
	v_mov_b32_e32 v0, v176
	v_mov_b32_e32 v1, v177
	v_mov_b32_e32 v2, v178
	v_mov_b32_e32 v3, v179
	v_lshlrev_b32_e32 v26, 16, v0
	v_and_b32_e32 v27, 0xffff0000, v0
	v_lshlrev_b32_e32 v0, 16, v1
	v_and_b32_e32 v1, 0xffff0000, v1
	v_lshlrev_b32_e32 v32, 16, v2
	v_and_b32_e32 v33, 0xffff0000, v2
	v_lshlrev_b32_e32 v2, 16, v3
	v_and_b32_e32 v3, 0xffff0000, v3
	v_pk_mul_f32 v[28:29], v[26:27], v[26:27]
	v_pk_mul_f32 v[30:31], v[0:1], v[0:1]
	v_pk_mul_f32 v[34:35], v[32:33], v[32:33]
	v_pk_mul_f32 v[36:37], v[2:3], v[2:3]
	v_pk_fma_f32 v[28:29], v[28:29], s[38:39], 1.0 op_sel_hi:[1,0,0]
	v_pk_fma_f32 v[30:31], v[30:31], s[38:39], 1.0 op_sel_hi:[1,0,0]
	v_pk_fma_f32 v[34:35], v[34:35], s[38:39], 1.0 op_sel_hi:[1,0,0]
	v_pk_fma_f32 v[36:37], v[36:37], s[38:39], 1.0 op_sel_hi:[1,0,0]
	v_pk_mul_f32 v[28:29], v[28:29], v[26:27]
	v_pk_mul_f32 v[30:31], v[30:31], v[0:1]
	v_pk_mul_f32 v[34:35], v[34:35], v[32:33]
	v_pk_mul_f32 v[36:37], v[36:37], v[2:3]
	v_pk_mul_f32 v[28:29], v[28:29], s[36:37] op_sel_hi:[1,0]
	v_pk_mul_f32 v[30:31], v[30:31], s[36:37] op_sel_hi:[1,0]
	v_pk_mul_f32 v[34:35], v[34:35], s[36:37] op_sel_hi:[1,0]
	v_pk_mul_f32 v[36:37], v[36:37], s[36:37] op_sel_hi:[1,0]
	v_exp_f32_e32 v28, v28
	v_exp_f32_e32 v29, v29
	v_exp_f32_e32 v30, v30
	v_exp_f32_e32 v31, v31
	v_exp_f32_e32 v34, v34
	v_exp_f32_e32 v35, v35
	v_exp_f32_e32 v36, v36
	v_exp_f32_e32 v37, v37
	v_pk_add_f32 v[28:29], v[28:29], 1.0 op_sel_hi:[1,0]
	v_pk_add_f32 v[30:31], v[30:31], 1.0 op_sel_hi:[1,0]
	v_pk_add_f32 v[34:35], v[34:35], 1.0 op_sel_hi:[1,0]
	v_pk_add_f32 v[36:37], v[36:37], 1.0 op_sel_hi:[1,0]
	v_rcp_f32_e32 v28, v28
	v_rcp_f32_e32 v29, v29
	v_rcp_f32_e32 v38, v30
	v_rcp_f32_e32 v39, v31
	v_rcp_f32_e32 v34, v34
	v_rcp_f32_e32 v35, v35
	v_rcp_f32_e32 v36, v36
	v_rcp_f32_e32 v37, v37
	v_pk_mul_f32 v[30:31], v[28:29], v[26:27]
	v_pk_mul_f32 v[28:29], v[38:39], v[0:1]
	v_pk_mul_f32 v[26:27], v[34:35], v[32:33]
	v_pk_mul_f32 v[32:33], v[36:37], v[2:3]
	v_cvt_pk_bf16_f32 v122, v30, v31
	v_cvt_pk_bf16_f32 v120, v28, v29
	v_cvt_pk_bf16_f32 v119, v26, v27
	s_nop 0
	v_cvt_pk_bf16_f32 v118, v32, v33
	s_waitcnt vmcnt(12)
	v_mov_b32_e32 v0, v180
	v_mov_b32_e32 v1, v181
	v_mov_b32_e32 v2, v182
	v_mov_b32_e32 v3, v183
	v_lshlrev_b32_e32 v34, 16, v0
	v_and_b32_e32 v35, 0xffff0000, v0
	v_lshlrev_b32_e32 v0, 16, v1
	v_and_b32_e32 v1, 0xffff0000, v1
	v_lshlrev_b32_e32 v40, 16, v2
	v_and_b32_e32 v41, 0xffff0000, v2
	v_lshlrev_b32_e32 v2, 16, v3
	v_and_b32_e32 v3, 0xffff0000, v3
	v_pk_mul_f32 v[36:37], v[34:35], v[34:35]
	v_pk_mul_f32 v[38:39], v[0:1], v[0:1]
	v_pk_mul_f32 v[42:43], v[40:41], v[40:41]
	v_pk_mul_f32 v[44:45], v[2:3], v[2:3]
	v_pk_fma_f32 v[36:37], v[36:37], s[38:39], 1.0 op_sel_hi:[1,0,0]
	v_pk_fma_f32 v[38:39], v[38:39], s[38:39], 1.0 op_sel_hi:[1,0,0]
	v_pk_fma_f32 v[42:43], v[42:43], s[38:39], 1.0 op_sel_hi:[1,0,0]
	v_pk_fma_f32 v[44:45], v[44:45], s[38:39], 1.0 op_sel_hi:[1,0,0]
	v_pk_mul_f32 v[36:37], v[36:37], v[34:35]
	v_pk_mul_f32 v[38:39], v[38:39], v[0:1]
	v_pk_mul_f32 v[42:43], v[42:43], v[40:41]
	v_pk_mul_f32 v[44:45], v[44:45], v[2:3]
	v_pk_mul_f32 v[36:37], v[36:37], s[36:37] op_sel_hi:[1,0]
	v_pk_mul_f32 v[38:39], v[38:39], s[36:37] op_sel_hi:[1,0]
	v_pk_mul_f32 v[42:43], v[42:43], s[36:37] op_sel_hi:[1,0]
	v_pk_mul_f32 v[44:45], v[44:45], s[36:37] op_sel_hi:[1,0]
	v_exp_f32_e32 v36, v36
	v_exp_f32_e32 v37, v37
	v_exp_f32_e32 v38, v38
	v_exp_f32_e32 v39, v39
	v_exp_f32_e32 v42, v42
	v_exp_f32_e32 v43, v43
	v_exp_f32_e32 v44, v44
	v_exp_f32_e32 v45, v45
	v_pk_add_f32 v[36:37], v[36:37], 1.0 op_sel_hi:[1,0]
	v_pk_add_f32 v[38:39], v[38:39], 1.0 op_sel_hi:[1,0]
	v_pk_add_f32 v[42:43], v[42:43], 1.0 op_sel_hi:[1,0]
	v_pk_add_f32 v[44:45], v[44:45], 1.0 op_sel_hi:[1,0]
	v_rcp_f32_e32 v36, v36
	v_rcp_f32_e32 v37, v37
	v_rcp_f32_e32 v46, v38
	v_rcp_f32_e32 v47, v39
	v_rcp_f32_e32 v42, v42
	v_rcp_f32_e32 v43, v43
	v_rcp_f32_e32 v44, v44
	v_rcp_f32_e32 v45, v45
	v_pk_mul_f32 v[38:39], v[36:37], v[34:35]
	v_pk_mul_f32 v[36:37], v[46:47], v[0:1]
	v_pk_mul_f32 v[34:35], v[42:43], v[40:41]
	v_pk_mul_f32 v[40:41], v[44:45], v[2:3]
	v_cvt_pk_bf16_f32 v126, v38, v39
	v_cvt_pk_bf16_f32 v124, v36, v37
	v_cvt_pk_bf16_f32 v123, v34, v35
	v_pk_mul_f32 v[24:25], v[36:37], v[36:37]
	v_cvt_pk_bf16_f32 v121, v40, v41
	s_waitcnt vmcnt(11)
	v_mov_b32_e32 v0, v184
	v_mov_b32_e32 v1, v185
	v_mov_b32_e32 v2, v186
	v_mov_b32_e32 v3, v187
	v_lshlrev_b32_e32 v42, 16, v0
	v_and_b32_e32 v43, 0xffff0000, v0
	v_lshlrev_b32_e32 v0, 16, v1
	v_and_b32_e32 v1, 0xffff0000, v1
	v_lshlrev_b32_e32 v48, 16, v2
	v_and_b32_e32 v49, 0xffff0000, v2
	v_lshlrev_b32_e32 v2, 16, v3
	v_and_b32_e32 v3, 0xffff0000, v3
	v_pk_mul_f32 v[44:45], v[42:43], v[42:43]
	v_pk_mul_f32 v[46:47], v[0:1], v[0:1]
	v_pk_mul_f32 v[50:51], v[48:49], v[48:49]
	v_pk_mul_f32 v[52:53], v[2:3], v[2:3]
	v_pk_fma_f32 v[44:45], v[44:45], s[38:39], 1.0 op_sel_hi:[1,0,0]
	v_pk_fma_f32 v[46:47], v[46:47], s[38:39], 1.0 op_sel_hi:[1,0,0]
	v_pk_fma_f32 v[50:51], v[50:51], s[38:39], 1.0 op_sel_hi:[1,0,0]
	v_pk_fma_f32 v[52:53], v[52:53], s[38:39], 1.0 op_sel_hi:[1,0,0]
	v_pk_mul_f32 v[44:45], v[44:45], v[42:43]
	v_pk_mul_f32 v[46:47], v[46:47], v[0:1]
	v_pk_mul_f32 v[50:51], v[50:51], v[48:49]
	v_pk_mul_f32 v[52:53], v[52:53], v[2:3]
	v_pk_mul_f32 v[44:45], v[44:45], s[36:37] op_sel_hi:[1,0]
	v_pk_mul_f32 v[46:47], v[46:47], s[36:37] op_sel_hi:[1,0]
	v_pk_mul_f32 v[50:51], v[50:51], s[36:37] op_sel_hi:[1,0]
	v_pk_mul_f32 v[52:53], v[52:53], s[36:37] op_sel_hi:[1,0]
	v_exp_f32_e32 v44, v44
	v_exp_f32_e32 v45, v45
	v_exp_f32_e32 v46, v46
	v_exp_f32_e32 v47, v47
	v_exp_f32_e32 v50, v50
	v_exp_f32_e32 v51, v51
	v_exp_f32_e32 v52, v52
	v_exp_f32_e32 v53, v53
	v_pk_add_f32 v[44:45], v[44:45], 1.0 op_sel_hi:[1,0]
	v_pk_add_f32 v[46:47], v[46:47], 1.0 op_sel_hi:[1,0]
	v_pk_add_f32 v[50:51], v[50:51], 1.0 op_sel_hi:[1,0]
	v_pk_add_f32 v[52:53], v[52:53], 1.0 op_sel_hi:[1,0]
	v_rcp_f32_e32 v44, v44
	v_rcp_f32_e32 v45, v45
	v_rcp_f32_e32 v54, v46
	v_rcp_f32_e32 v55, v47
	v_rcp_f32_e32 v50, v50
	v_rcp_f32_e32 v51, v51
	v_rcp_f32_e32 v52, v52
	v_rcp_f32_e32 v53, v53
	v_pk_mul_f32 v[46:47], v[44:45], v[42:43]
	v_pk_mul_f32 v[44:45], v[54:55], v[0:1]
	v_pk_mul_f32 v[42:43], v[50:51], v[48:49]
	v_pk_mul_f32 v[48:49], v[52:53], v[2:3]
	v_cvt_pk_bf16_f32 v129, v46, v47
	v_cvt_pk_bf16_f32 v128, v44, v45
	v_cvt_pk_bf16_f32 v127, v42, v43
	s_nop 0
	v_cvt_pk_bf16_f32 v125, v48, v49
	s_waitcnt vmcnt(10)
	v_mov_b32_e32 v0, v188
	v_mov_b32_e32 v1, v189
	v_mov_b32_e32 v2, v190
	v_mov_b32_e32 v3, v191
	v_lshlrev_b32_e32 v50, 16, v0
	v_and_b32_e32 v51, 0xffff0000, v0
	v_lshlrev_b32_e32 v0, 16, v1
	v_and_b32_e32 v1, 0xffff0000, v1
	v_lshlrev_b32_e32 v56, 16, v2
	v_and_b32_e32 v57, 0xffff0000, v2
	v_lshlrev_b32_e32 v2, 16, v3
	v_and_b32_e32 v3, 0xffff0000, v3
	v_pk_mul_f32 v[52:53], v[50:51], v[50:51]
	v_pk_mul_f32 v[54:55], v[0:1], v[0:1]
	v_pk_mul_f32 v[58:59], v[56:57], v[56:57]
	v_pk_mul_f32 v[60:61], v[2:3], v[2:3]
	v_pk_fma_f32 v[52:53], v[52:53], s[38:39], 1.0 op_sel_hi:[1,0,0]
	v_pk_fma_f32 v[54:55], v[54:55], s[38:39], 1.0 op_sel_hi:[1,0,0]
	v_pk_fma_f32 v[58:59], v[58:59], s[38:39], 1.0 op_sel_hi:[1,0,0]
	v_pk_fma_f32 v[60:61], v[60:61], s[38:39], 1.0 op_sel_hi:[1,0,0]
	v_pk_mul_f32 v[52:53], v[52:53], v[50:51]
	v_pk_mul_f32 v[54:55], v[54:55], v[0:1]
	v_pk_mul_f32 v[58:59], v[58:59], v[56:57]
	v_pk_mul_f32 v[60:61], v[60:61], v[2:3]
	v_pk_mul_f32 v[52:53], v[52:53], s[36:37] op_sel_hi:[1,0]
	v_pk_mul_f32 v[54:55], v[54:55], s[36:37] op_sel_hi:[1,0]
	v_pk_mul_f32 v[58:59], v[58:59], s[36:37] op_sel_hi:[1,0]
	v_pk_mul_f32 v[60:61], v[60:61], s[36:37] op_sel_hi:[1,0]
	v_exp_f32_e32 v52, v52
	v_exp_f32_e32 v53, v53
	v_exp_f32_e32 v54, v54
	v_exp_f32_e32 v55, v55
	v_exp_f32_e32 v58, v58
	v_exp_f32_e32 v59, v59
	v_exp_f32_e32 v60, v60
	v_exp_f32_e32 v61, v61
	v_pk_add_f32 v[52:53], v[52:53], 1.0 op_sel_hi:[1,0]
	v_pk_add_f32 v[54:55], v[54:55], 1.0 op_sel_hi:[1,0]
	v_pk_add_f32 v[58:59], v[58:59], 1.0 op_sel_hi:[1,0]
	v_pk_add_f32 v[60:61], v[60:61], 1.0 op_sel_hi:[1,0]
	v_rcp_f32_e32 v52, v52
	v_rcp_f32_e32 v53, v53
	v_rcp_f32_e32 v62, v54
	v_rcp_f32_e32 v63, v55
	v_rcp_f32_e32 v58, v58
	v_rcp_f32_e32 v59, v59
	v_rcp_f32_e32 v60, v60
	v_rcp_f32_e32 v61, v61
	v_pk_mul_f32 v[54:55], v[52:53], v[50:51]
	v_pk_mul_f32 v[52:53], v[62:63], v[0:1]
	v_pk_mul_f32 v[50:51], v[58:59], v[56:57]
	v_pk_mul_f32 v[56:57], v[60:61], v[2:3]
	v_cvt_pk_bf16_f32 v134, v54, v55
	v_cvt_pk_bf16_f32 v132, v52, v53
	v_cvt_pk_bf16_f32 v131, v50, v51
	s_nop 0
	v_cvt_pk_bf16_f32 v130, v56, v57
	s_waitcnt vmcnt(9)
	v_mov_b32_e32 v0, v192
	v_mov_b32_e32 v1, v193
	v_mov_b32_e32 v2, v194
	v_mov_b32_e32 v3, v195
	v_lshlrev_b32_e32 v58, 16, v0
	v_and_b32_e32 v59, 0xffff0000, v0
	v_lshlrev_b32_e32 v0, 16, v1
	v_and_b32_e32 v1, 0xffff0000, v1
	v_lshlrev_b32_e32 v64, 16, v2
	v_and_b32_e32 v65, 0xffff0000, v2
	v_lshlrev_b32_e32 v2, 16, v3
	v_and_b32_e32 v3, 0xffff0000, v3
	v_pk_mul_f32 v[60:61], v[58:59], v[58:59]
	v_pk_mul_f32 v[62:63], v[0:1], v[0:1]
	v_pk_mul_f32 v[66:67], v[64:65], v[64:65]
	v_pk_mul_f32 v[68:69], v[2:3], v[2:3]
	v_pk_fma_f32 v[60:61], v[60:61], s[38:39], 1.0 op_sel_hi:[1,0,0]
	v_pk_fma_f32 v[62:63], v[62:63], s[38:39], 1.0 op_sel_hi:[1,0,0]
	v_pk_fma_f32 v[66:67], v[66:67], s[38:39], 1.0 op_sel_hi:[1,0,0]
	v_pk_fma_f32 v[68:69], v[68:69], s[38:39], 1.0 op_sel_hi:[1,0,0]
	v_pk_mul_f32 v[60:61], v[60:61], v[58:59]
	v_pk_mul_f32 v[62:63], v[62:63], v[0:1]
	v_pk_mul_f32 v[66:67], v[66:67], v[64:65]
	v_pk_mul_f32 v[68:69], v[68:69], v[2:3]
	v_pk_mul_f32 v[60:61], v[60:61], s[36:37] op_sel_hi:[1,0]
	v_pk_mul_f32 v[62:63], v[62:63], s[36:37] op_sel_hi:[1,0]
	v_pk_mul_f32 v[66:67], v[66:67], s[36:37] op_sel_hi:[1,0]
	v_pk_mul_f32 v[68:69], v[68:69], s[36:37] op_sel_hi:[1,0]
	v_exp_f32_e32 v60, v60
	v_exp_f32_e32 v61, v61
	v_exp_f32_e32 v62, v62
	v_exp_f32_e32 v63, v63
	v_exp_f32_e32 v66, v66
	v_exp_f32_e32 v67, v67
	v_exp_f32_e32 v68, v68
	v_exp_f32_e32 v69, v69
	v_pk_add_f32 v[60:61], v[60:61], 1.0 op_sel_hi:[1,0]
	v_pk_add_f32 v[62:63], v[62:63], 1.0 op_sel_hi:[1,0]
	v_pk_add_f32 v[66:67], v[66:67], 1.0 op_sel_hi:[1,0]
	v_pk_add_f32 v[68:69], v[68:69], 1.0 op_sel_hi:[1,0]
	v_rcp_f32_e32 v60, v60
	v_rcp_f32_e32 v61, v61
	v_rcp_f32_e32 v70, v62
	v_rcp_f32_e32 v71, v63
	v_rcp_f32_e32 v66, v66
	v_rcp_f32_e32 v67, v67
	v_rcp_f32_e32 v68, v68
	v_rcp_f32_e32 v69, v69
	v_pk_mul_f32 v[62:63], v[60:61], v[58:59]
	v_pk_mul_f32 v[60:61], v[70:71], v[0:1]
	v_pk_mul_f32 v[58:59], v[66:67], v[64:65]
	v_pk_mul_f32 v[64:65], v[68:69], v[2:3]
	v_cvt_pk_bf16_f32 v137, v62, v63
	v_cvt_pk_bf16_f32 v136, v60, v61
	v_cvt_pk_bf16_f32 v135, v58, v59
	s_nop 0
	v_cvt_pk_bf16_f32 v133, v64, v65
	s_waitcnt vmcnt(8)
	v_mov_b32_e32 v0, v196
	v_mov_b32_e32 v1, v197
	v_mov_b32_e32 v2, v198
	v_mov_b32_e32 v3, v199
	v_lshlrev_b32_e32 v66, 16, v0
	v_and_b32_e32 v67, 0xffff0000, v0
	v_lshlrev_b32_e32 v0, 16, v1
	v_and_b32_e32 v1, 0xffff0000, v1
	v_lshlrev_b32_e32 v72, 16, v2
	v_and_b32_e32 v73, 0xffff0000, v2
	v_lshlrev_b32_e32 v2, 16, v3
	v_and_b32_e32 v3, 0xffff0000, v3
	v_pk_mul_f32 v[68:69], v[66:67], v[66:67]
	v_pk_mul_f32 v[70:71], v[0:1], v[0:1]
	v_pk_mul_f32 v[74:75], v[72:73], v[72:73]
	v_pk_mul_f32 v[76:77], v[2:3], v[2:3]
	v_pk_fma_f32 v[68:69], v[68:69], s[38:39], 1.0 op_sel_hi:[1,0,0]
	v_pk_fma_f32 v[70:71], v[70:71], s[38:39], 1.0 op_sel_hi:[1,0,0]
	v_pk_fma_f32 v[74:75], v[74:75], s[38:39], 1.0 op_sel_hi:[1,0,0]
	v_pk_fma_f32 v[76:77], v[76:77], s[38:39], 1.0 op_sel_hi:[1,0,0]
	v_pk_mul_f32 v[68:69], v[68:69], v[66:67]
	v_pk_mul_f32 v[70:71], v[70:71], v[0:1]
	v_pk_mul_f32 v[74:75], v[74:75], v[72:73]
	v_pk_mul_f32 v[76:77], v[76:77], v[2:3]
	v_pk_mul_f32 v[68:69], v[68:69], s[36:37] op_sel_hi:[1,0]
	v_pk_mul_f32 v[70:71], v[70:71], s[36:37] op_sel_hi:[1,0]
	v_pk_mul_f32 v[74:75], v[74:75], s[36:37] op_sel_hi:[1,0]
	v_pk_mul_f32 v[76:77], v[76:77], s[36:37] op_sel_hi:[1,0]
	v_exp_f32_e32 v68, v68
	v_exp_f32_e32 v69, v69
	v_exp_f32_e32 v70, v70
	v_exp_f32_e32 v71, v71
	v_exp_f32_e32 v74, v74
	v_exp_f32_e32 v75, v75
	v_exp_f32_e32 v76, v76
	v_exp_f32_e32 v77, v77
	v_pk_add_f32 v[68:69], v[68:69], 1.0 op_sel_hi:[1,0]
	v_pk_add_f32 v[70:71], v[70:71], 1.0 op_sel_hi:[1,0]
	v_pk_add_f32 v[74:75], v[74:75], 1.0 op_sel_hi:[1,0]
	v_pk_add_f32 v[76:77], v[76:77], 1.0 op_sel_hi:[1,0]
	v_rcp_f32_e32 v68, v68
	v_rcp_f32_e32 v69, v69
	v_rcp_f32_e32 v78, v70
	v_rcp_f32_e32 v79, v71
	v_rcp_f32_e32 v74, v74
	v_rcp_f32_e32 v75, v75
	v_rcp_f32_e32 v76, v76
	v_rcp_f32_e32 v77, v77
	v_pk_mul_f32 v[70:71], v[68:69], v[66:67]
	v_pk_mul_f32 v[68:69], v[78:79], v[0:1]
	v_pk_mul_f32 v[66:67], v[74:75], v[72:73]
	v_pk_mul_f32 v[72:73], v[76:77], v[2:3]
	v_cvt_pk_bf16_f32 v142, v70, v71
	v_cvt_pk_bf16_f32 v140, v68, v69
	v_cvt_pk_bf16_f32 v139, v66, v67
	s_nop 0
	v_cvt_pk_bf16_f32 v138, v72, v73
	s_waitcnt vmcnt(7)
	v_mov_b32_e32 v0, v200
	v_mov_b32_e32 v1, v201
	v_mov_b32_e32 v2, v202
	v_mov_b32_e32 v3, v203
	v_lshlrev_b32_e32 v74, 16, v0
	v_and_b32_e32 v75, 0xffff0000, v0
	v_lshlrev_b32_e32 v0, 16, v1
	v_and_b32_e32 v1, 0xffff0000, v1
	v_lshlrev_b32_e32 v80, 16, v2
	v_and_b32_e32 v81, 0xffff0000, v2
	v_lshlrev_b32_e32 v2, 16, v3
	v_and_b32_e32 v3, 0xffff0000, v3
	v_pk_mul_f32 v[76:77], v[74:75], v[74:75]
	v_pk_mul_f32 v[78:79], v[0:1], v[0:1]
	v_pk_mul_f32 v[82:83], v[80:81], v[80:81]
	v_pk_mul_f32 v[84:85], v[2:3], v[2:3]
	v_pk_fma_f32 v[76:77], v[76:77], s[38:39], 1.0 op_sel_hi:[1,0,0]
	v_pk_fma_f32 v[78:79], v[78:79], s[38:39], 1.0 op_sel_hi:[1,0,0]
	v_pk_fma_f32 v[82:83], v[82:83], s[38:39], 1.0 op_sel_hi:[1,0,0]
	v_pk_fma_f32 v[84:85], v[84:85], s[38:39], 1.0 op_sel_hi:[1,0,0]
	v_pk_mul_f32 v[76:77], v[76:77], v[74:75]
	v_pk_mul_f32 v[78:79], v[78:79], v[0:1]
	v_pk_mul_f32 v[82:83], v[82:83], v[80:81]
	v_pk_mul_f32 v[84:85], v[84:85], v[2:3]
	v_pk_mul_f32 v[76:77], v[76:77], s[36:37] op_sel_hi:[1,0]
	v_pk_mul_f32 v[78:79], v[78:79], s[36:37] op_sel_hi:[1,0]
	v_pk_mul_f32 v[82:83], v[82:83], s[36:37] op_sel_hi:[1,0]
	v_pk_mul_f32 v[84:85], v[84:85], s[36:37] op_sel_hi:[1,0]
	v_exp_f32_e32 v76, v76
	v_exp_f32_e32 v77, v77
	v_exp_f32_e32 v78, v78
	v_exp_f32_e32 v79, v79
	v_exp_f32_e32 v82, v82
	v_exp_f32_e32 v83, v83
	v_exp_f32_e32 v84, v84
	v_exp_f32_e32 v85, v85
	v_pk_add_f32 v[76:77], v[76:77], 1.0 op_sel_hi:[1,0]
	v_pk_add_f32 v[78:79], v[78:79], 1.0 op_sel_hi:[1,0]
	v_pk_add_f32 v[82:83], v[82:83], 1.0 op_sel_hi:[1,0]
	v_pk_add_f32 v[84:85], v[84:85], 1.0 op_sel_hi:[1,0]
	v_rcp_f32_e32 v76, v76
	v_rcp_f32_e32 v77, v77
	v_rcp_f32_e32 v86, v78
	v_rcp_f32_e32 v87, v79
	v_rcp_f32_e32 v82, v82
	v_rcp_f32_e32 v83, v83
	v_rcp_f32_e32 v84, v84
	v_rcp_f32_e32 v85, v85
	v_pk_mul_f32 v[78:79], v[76:77], v[74:75]
	v_pk_mul_f32 v[76:77], v[86:87], v[0:1]
	v_pk_mul_f32 v[74:75], v[82:83], v[80:81]
	v_pk_mul_f32 v[80:81], v[84:85], v[2:3]
	v_cvt_pk_bf16_f32 v146, v78, v79
	v_cvt_pk_bf16_f32 v144, v76, v77
	v_cvt_pk_bf16_f32 v143, v74, v75
	s_nop 0
	v_cvt_pk_bf16_f32 v141, v80, v81
	s_waitcnt vmcnt(6)
	v_mov_b32_e32 v0, v204
	v_mov_b32_e32 v1, v205
	v_mov_b32_e32 v2, v206
	v_mov_b32_e32 v3, v207
	v_lshlrev_b32_e32 v82, 16, v0
	v_and_b32_e32 v83, 0xffff0000, v0
	v_lshlrev_b32_e32 v0, 16, v1
	v_and_b32_e32 v1, 0xffff0000, v1
	v_lshlrev_b32_e32 v84, 16, v2
	v_and_b32_e32 v85, 0xffff0000, v2
	v_lshlrev_b32_e32 v2, 16, v3
	v_and_b32_e32 v3, 0xffff0000, v3
	v_pk_mul_f32 v[86:87], v[82:83], v[82:83]
	v_pk_mul_f32 v[88:89], v[0:1], v[0:1]
	v_pk_mul_f32 v[90:91], v[84:85], v[84:85]
	v_pk_mul_f32 v[92:93], v[2:3], v[2:3]
	v_pk_fma_f32 v[86:87], v[86:87], s[38:39], 1.0 op_sel_hi:[1,0,0]
	v_pk_fma_f32 v[88:89], v[88:89], s[38:39], 1.0 op_sel_hi:[1,0,0]
	v_pk_fma_f32 v[90:91], v[90:91], s[38:39], 1.0 op_sel_hi:[1,0,0]
	v_pk_fma_f32 v[92:93], v[92:93], s[38:39], 1.0 op_sel_hi:[1,0,0]
	v_pk_mul_f32 v[86:87], v[86:87], v[82:83]
	v_pk_mul_f32 v[88:89], v[88:89], v[0:1]
	v_pk_mul_f32 v[90:91], v[90:91], v[84:85]
	v_pk_mul_f32 v[92:93], v[92:93], v[2:3]
	v_pk_mul_f32 v[86:87], v[86:87], s[36:37] op_sel_hi:[1,0]
	v_pk_mul_f32 v[88:89], v[88:89], s[36:37] op_sel_hi:[1,0]
	v_pk_mul_f32 v[90:91], v[90:91], s[36:37] op_sel_hi:[1,0]
	v_pk_mul_f32 v[92:93], v[92:93], s[36:37] op_sel_hi:[1,0]
	v_exp_f32_e32 v86, v86
	v_exp_f32_e32 v87, v87
	v_exp_f32_e32 v88, v88
	v_exp_f32_e32 v89, v89
	v_exp_f32_e32 v90, v90
	v_exp_f32_e32 v91, v91
	v_exp_f32_e32 v92, v92
	v_exp_f32_e32 v93, v93
	v_pk_add_f32 v[86:87], v[86:87], 1.0 op_sel_hi:[1,0]
	v_pk_add_f32 v[88:89], v[88:89], 1.0 op_sel_hi:[1,0]
	v_pk_add_f32 v[90:91], v[90:91], 1.0 op_sel_hi:[1,0]
	v_pk_add_f32 v[92:93], v[92:93], 1.0 op_sel_hi:[1,0]
	v_rcp_f32_e32 v86, v86
	v_rcp_f32_e32 v87, v87
	v_rcp_f32_e32 v88, v88
	v_rcp_f32_e32 v89, v89
	v_rcp_f32_e32 v94, v90
	v_rcp_f32_e32 v95, v91
	v_rcp_f32_e32 v92, v92
	v_rcp_f32_e32 v93, v93
	v_pk_mul_f32 v[90:91], v[86:87], v[82:83]
	v_pk_mul_f32 v[86:87], v[88:89], v[0:1]
	v_pk_mul_f32 v[84:85], v[94:95], v[84:85]
	v_pk_mul_f32 v[82:83], v[92:93], v[2:3]
	v_cvt_pk_bf16_f32 v149, v90, v91
	v_cvt_pk_bf16_f32 v148, v86, v87
	v_cvt_pk_bf16_f32 v147, v84, v85
	s_nop 0
	v_cvt_pk_bf16_f32 v145, v82, v83
	s_waitcnt vmcnt(5)
	v_mov_b32_e32 v0, v208
	v_mov_b32_e32 v1, v209
	v_mov_b32_e32 v2, v210
	v_mov_b32_e32 v3, v211
	v_lshlrev_b32_e32 v88, 16, v0
	v_and_b32_e32 v89, 0xffff0000, v0
	v_lshlrev_b32_e32 v0, 16, v1
	v_and_b32_e32 v1, 0xffff0000, v1
	v_lshlrev_b32_e32 v92, 16, v2
	v_and_b32_e32 v93, 0xffff0000, v2
	v_lshlrev_b32_e32 v2, 16, v3
	v_and_b32_e32 v3, 0xffff0000, v3
	v_pk_mul_f32 v[94:95], v[88:89], v[88:89]
	v_pk_mul_f32 v[96:97], v[0:1], v[0:1]
	v_pk_mul_f32 v[98:99], v[92:93], v[92:93]
	v_pk_mul_f32 v[100:101], v[2:3], v[2:3]
	v_pk_fma_f32 v[94:95], v[94:95], s[38:39], 1.0 op_sel_hi:[1,0,0]
	v_pk_fma_f32 v[96:97], v[96:97], s[38:39], 1.0 op_sel_hi:[1,0,0]
	v_pk_fma_f32 v[98:99], v[98:99], s[38:39], 1.0 op_sel_hi:[1,0,0]
	v_pk_fma_f32 v[100:101], v[100:101], s[38:39], 1.0 op_sel_hi:[1,0,0]
	v_pk_mul_f32 v[94:95], v[94:95], v[88:89]
	v_pk_mul_f32 v[96:97], v[96:97], v[0:1]
	v_pk_mul_f32 v[98:99], v[98:99], v[92:93]
	v_pk_mul_f32 v[100:101], v[100:101], v[2:3]
	v_pk_mul_f32 v[94:95], v[94:95], s[36:37] op_sel_hi:[1,0]
	v_pk_mul_f32 v[96:97], v[96:97], s[36:37] op_sel_hi:[1,0]
	v_pk_mul_f32 v[98:99], v[98:99], s[36:37] op_sel_hi:[1,0]
	v_pk_mul_f32 v[100:101], v[100:101], s[36:37] op_sel_hi:[1,0]
	v_exp_f32_e32 v94, v94
	v_exp_f32_e32 v95, v95
	v_exp_f32_e32 v96, v96
	v_exp_f32_e32 v97, v97
	v_exp_f32_e32 v98, v98
	v_exp_f32_e32 v99, v99
	v_exp_f32_e32 v100, v100
	v_exp_f32_e32 v101, v101
	v_pk_add_f32 v[94:95], v[94:95], 1.0 op_sel_hi:[1,0]
	v_pk_add_f32 v[96:97], v[96:97], 1.0 op_sel_hi:[1,0]
	v_pk_add_f32 v[98:99], v[98:99], 1.0 op_sel_hi:[1,0]
	v_pk_add_f32 v[100:101], v[100:101], 1.0 op_sel_hi:[1,0]
	v_rcp_f32_e32 v94, v94
	v_rcp_f32_e32 v95, v95
	v_rcp_f32_e32 v102, v96
	v_rcp_f32_e32 v103, v97
	v_rcp_f32_e32 v98, v98
	v_rcp_f32_e32 v99, v99
	v_rcp_f32_e32 v100, v100
	v_rcp_f32_e32 v101, v101
	v_pk_mul_f32 v[96:97], v[94:95], v[88:89]
	v_pk_mul_f32 v[94:95], v[102:103], v[0:1]
	v_pk_mul_f32 v[92:93], v[98:99], v[92:93]
	v_pk_mul_f32 v[98:99], v[100:101], v[2:3]
	v_cvt_pk_bf16_f32 v154, v96, v97
	v_cvt_pk_bf16_f32 v152, v94, v95
	v_cvt_pk_bf16_f32 v151, v92, v93
	v_mov_b32_e32 v89, 0
	v_cvt_pk_bf16_f32 v150, v98, v99
	v_mov_b32_e32 v88, v17
	v_pk_add_f32 v[6:7], v[6:7], v[88:89]
	v_mov_b32_e32 v17, v22
	v_pk_add_f32 v[6:7], v[10:11], v[6:7]
	v_pk_mul_f32 v[10:11], v[20:21], v[20:21]
	s_waitcnt vmcnt(4)
	v_mov_b32_e32 v0, v212
	v_mov_b32_e32 v1, v213
	v_mov_b32_e32 v2, v214
	v_mov_b32_e32 v3, v215
	v_lshlrev_b32_e32 v100, 16, v0
	v_and_b32_e32 v101, 0xffff0000, v0
	v_lshlrev_b32_e32 v0, 16, v1
	v_and_b32_e32 v1, 0xffff0000, v1
	v_lshlrev_b32_e32 v106, 16, v2
	v_and_b32_e32 v107, 0xffff0000, v2
	v_lshlrev_b32_e32 v2, 16, v3
	v_and_b32_e32 v3, 0xffff0000, v3
	v_pk_mul_f32 v[102:103], v[100:101], v[100:101]
	v_pk_mul_f32 v[104:105], v[0:1], v[0:1]
	v_pk_mul_f32 v[156:157], v[106:107], v[106:107]
	v_pk_mul_f32 v[158:159], v[2:3], v[2:3]
	v_pk_fma_f32 v[102:103], v[102:103], s[38:39], 1.0 op_sel_hi:[1,0,0]
	v_pk_fma_f32 v[104:105], v[104:105], s[38:39], 1.0 op_sel_hi:[1,0,0]
	v_pk_fma_f32 v[156:157], v[156:157], s[38:39], 1.0 op_sel_hi:[1,0,0]
	v_pk_fma_f32 v[158:159], v[158:159], s[38:39], 1.0 op_sel_hi:[1,0,0]
	v_pk_mul_f32 v[102:103], v[102:103], v[100:101]
	v_pk_mul_f32 v[104:105], v[104:105], v[0:1]
	v_pk_mul_f32 v[156:157], v[156:157], v[106:107]
	v_pk_mul_f32 v[158:159], v[158:159], v[2:3]
	v_pk_mul_f32 v[102:103], v[102:103], s[36:37] op_sel_hi:[1,0]
	v_pk_mul_f32 v[104:105], v[104:105], s[36:37] op_sel_hi:[1,0]
	v_pk_mul_f32 v[156:157], v[156:157], s[36:37] op_sel_hi:[1,0]
	v_pk_mul_f32 v[158:159], v[158:159], s[36:37] op_sel_hi:[1,0]
	v_exp_f32_e32 v102, v102
	v_exp_f32_e32 v103, v103
	v_exp_f32_e32 v104, v104
	v_exp_f32_e32 v105, v105
	v_exp_f32_e32 v156, v156
	v_exp_f32_e32 v157, v157
	v_exp_f32_e32 v158, v158
	v_exp_f32_e32 v159, v159
	v_pk_add_f32 v[102:103], v[102:103], 1.0 op_sel_hi:[1,0]
	v_pk_add_f32 v[104:105], v[104:105], 1.0 op_sel_hi:[1,0]
	v_pk_add_f32 v[156:157], v[156:157], 1.0 op_sel_hi:[1,0]
	v_pk_add_f32 v[158:159], v[158:159], 1.0 op_sel_hi:[1,0]
	v_rcp_f32_e32 v102, v102
	v_rcp_f32_e32 v103, v103
	v_rcp_f32_e32 v160, v104
	v_rcp_f32_e32 v161, v105
	v_rcp_f32_e32 v156, v156
	v_rcp_f32_e32 v157, v157
	v_rcp_f32_e32 v158, v158
	v_rcp_f32_e32 v159, v159
	v_pk_mul_f32 v[104:105], v[102:103], v[100:101]
	v_pk_mul_f32 v[102:103], v[160:161], v[0:1]
	v_pk_mul_f32 v[100:101], v[156:157], v[106:107]
	v_pk_mul_f32 v[106:107], v[158:159], v[2:3]
	v_cvt_pk_bf16_f32 v157, v104, v105
	v_cvt_pk_bf16_f32 v156, v102, v103
	v_cvt_pk_bf16_f32 v155, v100, v101
	v_pk_mul_f32 v[160:161], v[8:9], v[8:9]
	v_cvt_pk_bf16_f32 v153, v106, v107
	v_mov_b32_e32 v166, v160
	v_mov_b32_e32 v8, v161
	v_pk_add_f32 v[8:9], v[166:167], v[8:9]
	v_mov_b32_e32 v161, v20
	v_pk_add_f32 v[6:7], v[8:9], v[6:7]
	v_pk_mul_f32 v[8:9], v[22:23], v[22:23]
	v_pk_add_f32 v[6:7], v[12:13], v[6:7]
	v_mov_b32_e32 v16, v8
	v_mov_b32_e32 v22, v9
	v_pk_mul_f32 v[12:13], v[18:19], v[18:19]
	v_mov_b32_e32 v160, v10
	v_mov_b32_e32 v20, v11
	v_pk_add_f32 v[8:9], v[16:17], v[22:23]
	v_mov_b32_e32 v162, v12
	v_mov_b32_e32 v18, v13
	v_pk_add_f32 v[10:11], v[160:161], v[20:21]
	v_pk_add_f32 v[6:7], v[6:7], v[8:9]
	v_pk_add_f32 v[12:13], v[162:163], v[18:19]
	v_pk_add_f32 v[6:7], v[10:11], v[6:7]
	v_pk_mul_f32 v[8:9], v[30:31], v[30:31]
	v_pk_add_f32 v[6:7], v[12:13], v[6:7]
	v_mov_b32_e32 v11, v30
	v_pk_mul_f32 v[12:13], v[28:29], v[28:29]
	v_mov_b32_e32 v10, v8
	v_mov_b32_e32 v30, v9
	v_pk_add_f32 v[6:7], v[14:15], v[6:7]
	v_mov_b32_e32 v15, v28
	v_pk_mul_f32 v[16:17], v[26:27], v[26:27]
	v_mov_b32_e32 v14, v12
	v_mov_b32_e32 v28, v13
	v_pk_add_f32 v[8:9], v[10:11], v[30:31]
	v_pk_mul_f32 v[18:19], v[32:33], v[32:33]
	v_mov_b32_e32 v21, v26
	v_mov_b32_e32 v20, v16
	v_mov_b32_e32 v26, v17
	v_pk_add_f32 v[10:11], v[14:15], v[28:29]
	v_pk_add_f32 v[6:7], v[6:7], v[8:9]
	v_mov_b32_e32 v23, v32
	v_mov_b32_e32 v22, v18
	v_mov_b32_e32 v32, v19
	v_pk_add_f32 v[12:13], v[20:21], v[26:27]
	v_pk_add_f32 v[6:7], v[10:11], v[6:7]
	v_pk_add_f32 v[14:15], v[22:23], v[32:33]
	v_pk_add_f32 v[6:7], v[12:13], v[6:7]
	v_pk_mul_f32 v[16:17], v[38:39], v[38:39]
	v_pk_add_f32 v[14:15], v[14:15], v[6:7]
	v_mov_b32_e32 v31, v38
	v_mov_b32_e32 v30, v16
	v_mov_b32_e32 v38, v17
	v_pk_mul_f32 v[26:27], v[34:35], v[34:35]
	v_mov_b32_e32 v33, v36
	v_mov_b32_e32 v32, v24
	v_mov_b32_e32 v36, v25
	v_pk_add_f32 v[16:17], v[30:31], v[38:39]
	v_pk_mul_f32 v[28:29], v[40:41], v[40:41]
	v_mov_b32_e32 v161, v34
	v_mov_b32_e32 v160, v26
	v_mov_b32_e32 v34, v27
	v_pk_add_f32 v[24:25], v[32:33], v[36:37]
	v_pk_add_f32 v[14:15], v[14:15], v[16:17]
	v_mov_b32_e32 v163, v40
	v_mov_b32_e32 v162, v28
	v_mov_b32_e32 v40, v29
	v_pk_add_f32 v[26:27], v[160:161], v[34:35]
	v_pk_add_f32 v[14:15], v[24:25], v[14:15]
	v_pk_mul_f32 v[16:17], v[46:47], v[46:47]
	v_pk_add_f32 v[28:29], v[162:163], v[40:41]
	v_pk_add_f32 v[14:15], v[26:27], v[14:15]
	v_pk_mul_f32 v[24:25], v[44:45], v[44:45]
	v_mov_b32_e32 v31, v46
	v_mov_b32_e32 v30, v16
	v_mov_b32_e32 v46, v17
	v_pk_add_f32 v[14:15], v[28:29], v[14:15]
	v_pk_mul_f32 v[26:27], v[42:43], v[42:43]
	v_mov_b32_e32 v33, v44
	v_mov_b32_e32 v32, v24
	v_mov_b32_e32 v44, v25
	v_pk_add_f32 v[16:17], v[30:31], v[46:47]
	v_pk_mul_f32 v[28:29], v[48:49], v[48:49]
	s_waitcnt vmcnt(3)
	v_mov_b32_e32 v0, v216
	v_mov_b32_e32 v1, v217
	v_mov_b32_e32 v2, v218
	v_mov_b32_e32 v3, v219
	v_lshlrev_b32_e32 v6, 16, v0
	v_and_b32_e32 v7, 0xffff0000, v0
	v_lshlrev_b32_e32 v0, 16, v1
	v_and_b32_e32 v1, 0xffff0000, v1
	v_lshlrev_b32_e32 v10, 16, v2
	v_and_b32_e32 v11, 0xffff0000, v2
	v_lshlrev_b32_e32 v12, 16, v3
	v_and_b32_e32 v13, 0xffff0000, v3
	v_pk_mul_f32 v[2:3], v[6:7], v[6:7]
	v_pk_mul_f32 v[8:9], v[0:1], v[0:1]
	v_pk_mul_f32 v[18:19], v[10:11], v[10:11]
	v_pk_mul_f32 v[20:21], v[12:13], v[12:13]
	v_pk_fma_f32 v[2:3], v[2:3], s[38:39], 1.0 op_sel_hi:[1,0,0]
	v_pk_fma_f32 v[8:9], v[8:9], s[38:39], 1.0 op_sel_hi:[1,0,0]
	v_pk_fma_f32 v[18:19], v[18:19], s[38:39], 1.0 op_sel_hi:[1,0,0]
	v_pk_fma_f32 v[20:21], v[20:21], s[38:39], 1.0 op_sel_hi:[1,0,0]
	v_pk_mul_f32 v[2:3], v[2:3], v[6:7]
	v_pk_mul_f32 v[8:9], v[8:9], v[0:1]
	v_pk_mul_f32 v[18:19], v[18:19], v[10:11]
	v_pk_mul_f32 v[20:21], v[20:21], v[12:13]
	v_pk_mul_f32 v[2:3], v[2:3], s[36:37] op_sel_hi:[1,0]
	v_pk_mul_f32 v[8:9], v[8:9], s[36:37] op_sel_hi:[1,0]
	v_pk_mul_f32 v[18:19], v[18:19], s[36:37] op_sel_hi:[1,0]
	v_pk_mul_f32 v[20:21], v[20:21], s[36:37] op_sel_hi:[1,0]
	v_exp_f32_e32 v2, v2
	v_exp_f32_e32 v3, v3
	v_exp_f32_e32 v8, v8
	v_exp_f32_e32 v9, v9
	v_exp_f32_e32 v18, v18
	v_exp_f32_e32 v19, v19
	v_exp_f32_e32 v20, v20
	v_exp_f32_e32 v21, v21
	v_pk_add_f32 v[2:3], v[2:3], 1.0 op_sel_hi:[1,0]
	v_pk_add_f32 v[8:9], v[8:9], 1.0 op_sel_hi:[1,0]
	v_pk_add_f32 v[18:19], v[18:19], 1.0 op_sel_hi:[1,0]
	v_pk_add_f32 v[20:21], v[20:21], 1.0 op_sel_hi:[1,0]
	v_rcp_f32_e32 v2, v2
	v_rcp_f32_e32 v3, v3
	v_rcp_f32_e32 v22, v8
	v_rcp_f32_e32 v23, v9
	v_rcp_f32_e32 v18, v18
	v_rcp_f32_e32 v19, v19
	v_rcp_f32_e32 v20, v20
	v_rcp_f32_e32 v21, v21
	v_pk_mul_f32 v[8:9], v[2:3], v[6:7]
	v_pk_mul_f32 v[6:7], v[22:23], v[0:1]
	v_pk_mul_f32 v[2:3], v[18:19], v[10:11]
	v_pk_mul_f32 v[0:1], v[20:21], v[12:13]
	v_cvt_pk_bf16_f32 v22, v8, v9
	v_cvt_pk_bf16_f32 v20, v6, v7
	v_cvt_pk_bf16_f32 v19, v2, v3
	v_mov_b32_e32 v35, v42
	v_cvt_pk_bf16_f32 v18, v0, v1
	v_mov_b32_e32 v34, v26
	v_mov_b32_e32 v42, v27
	v_pk_add_f32 v[24:25], v[32:33], v[44:45]
	v_pk_add_f32 v[14:15], v[14:15], v[16:17]
	v_mov_b32_e32 v37, v48
	v_mov_b32_e32 v36, v28
	v_mov_b32_e32 v48, v29
	v_pk_add_f32 v[26:27], v[34:35], v[42:43]
	v_pk_add_f32 v[14:15], v[24:25], v[14:15]
	v_pk_mul_f32 v[16:17], v[54:55], v[54:55]
	v_pk_add_f32 v[28:29], v[36:37], v[48:49]
	v_pk_add_f32 v[14:15], v[26:27], v[14:15]
	v_mov_b32_e32 v25, v54
	v_pk_mul_f32 v[26:27], v[52:53], v[52:53]
	v_mov_b32_e32 v24, v16
	v_mov_b32_e32 v54, v17
	v_pk_add_f32 v[14:15], v[28:29], v[14:15]
	v_pk_mul_f32 v[28:29], v[50:51], v[50:51]
	v_mov_b32_e32 v33, v52
	v_mov_b32_e32 v32, v26
	v_mov_b32_e32 v52, v27
	v_pk_add_f32 v[16:17], v[24:25], v[54:55]
	v_pk_mul_f32 v[30:31], v[56:57], v[56:57]
	v_mov_b32_e32 v35, v50
	v_mov_b32_e32 v34, v28
	v_mov_b32_e32 v50, v29
	v_pk_add_f32 v[24:25], v[32:33], v[52:53]
	v_pk_add_f32 v[14:15], v[14:15], v[16:17]
	v_mov_b32_e32 v37, v56
	v_mov_b32_e32 v36, v30
	v_mov_b32_e32 v56, v31
	v_pk_add_f32 v[26:27], v[34:35], v[50:51]
	v_pk_add_f32 v[14:15], v[24:25], v[14:15]
	v_pk_add_f32 v[28:29], v[36:37], v[56:57]
	v_pk_add_f32 v[14:15], v[26:27], v[14:15]
	v_pk_mul_f32 v[16:17], v[60:61], v[60:61]
	v_pk_add_f32 v[32:33], v[28:29], v[14:15]
	v_pk_mul_f32 v[14:15], v[62:63], v[62:63]
	v_mov_b32_e32 v39, v62
	v_mov_b32_e32 v38, v14
	v_mov_b32_e32 v62, v15
	v_mov_b32_e32 v41, v60
	v_mov_b32_e32 v40, v16
	v_mov_b32_e32 v60, v17
	v_pk_mul_f32 v[34:35], v[58:59], v[58:59]
	v_pk_mul_f32 v[36:37], v[64:65], v[64:65]
	v_mov_b32_e32 v43, v58
	v_mov_b32_e32 v42, v34
	v_mov_b32_e32 v58, v35
	v_pk_add_f32 v[34:35], v[38:39], v[62:63]
	v_mov_b32_e32 v45, v64
	v_mov_b32_e32 v44, v36
	v_mov_b32_e32 v64, v37
	v_pk_add_f32 v[36:37], v[40:41], v[60:61]
	v_pk_add_f32 v[32:33], v[32:33], v[34:35]
	v_pk_add_f32 v[38:39], v[42:43], v[58:59]
	v_pk_add_f32 v[32:33], v[36:37], v[32:33]
	v_pk_add_f32 v[40:41], v[44:45], v[64:65]
	v_pk_add_f32 v[32:33], v[38:39], v[32:33]
	v_pk_mul_f32 v[34:35], v[70:71], v[70:71]
	v_pk_add_f32 v[32:33], v[40:41], v[32:33]
	v_pk_mul_f32 v[36:37], v[68:69], v[68:69]
	v_mov_b32_e32 v41, v70
	v_mov_b32_e32 v40, v34
	v_mov_b32_e32 v70, v35
	v_pk_mul_f32 v[38:39], v[66:67], v[66:67]
	v_mov_b32_e32 v43, v68
	v_mov_b32_e32 v42, v36
	v_mov_b32_e32 v68, v37
	v_pk_add_f32 v[34:35], v[40:41], v[70:71]
	v_mov_b32_e32 v45, v66
	v_mov_b32_e32 v44, v38
	v_mov_b32_e32 v66, v39
	v_pk_add_f32 v[36:37], v[42:43], v[68:69]
	v_pk_add_f32 v[32:33], v[32:33], v[34:35]
	v_mov_b32_e32 v49, v72
	v_pk_add_f32 v[38:39], v[44:45], v[66:67]
	v_pk_add_f32 v[32:33], v[36:37], v[32:33]
	v_pk_mul_f32 v[34:35], v[78:79], v[78:79]
	s_waitcnt vmcnt(2)
	v_mov_b32_e32 v10, v220
	v_mov_b32_e32 v11, v221
	v_mov_b32_e32 v12, v222
	v_mov_b32_e32 v13, v223
	v_lshlrev_b32_e32 v14, 16, v10
	v_and_b32_e32 v15, 0xffff0000, v10
	v_lshlrev_b32_e32 v10, 16, v11
	v_and_b32_e32 v11, 0xffff0000, v11
	v_lshlrev_b32_e32 v24, 16, v12
	v_and_b32_e32 v25, 0xffff0000, v12
	v_lshlrev_b32_e32 v26, 16, v13
	v_and_b32_e32 v27, 0xffff0000, v13
	v_pk_mul_f32 v[12:13], v[14:15], v[14:15]
	v_pk_mul_f32 v[16:17], v[10:11], v[10:11]
	v_pk_mul_f32 v[28:29], v[24:25], v[24:25]
	v_pk_mul_f32 v[30:31], v[26:27], v[26:27]
	v_pk_fma_f32 v[12:13], v[12:13], s[38:39], 1.0 op_sel_hi:[1,0,0]
	v_pk_fma_f32 v[16:17], v[16:17], s[38:39], 1.0 op_sel_hi:[1,0,0]
	v_pk_fma_f32 v[28:29], v[28:29], s[38:39], 1.0 op_sel_hi:[1,0,0]
	v_pk_fma_f32 v[30:31], v[30:31], s[38:39], 1.0 op_sel_hi:[1,0,0]
	v_pk_mul_f32 v[12:13], v[12:13], v[14:15]
	v_pk_mul_f32 v[16:17], v[16:17], v[10:11]
	v_pk_mul_f32 v[28:29], v[28:29], v[24:25]
	v_pk_mul_f32 v[30:31], v[30:31], v[26:27]
	v_pk_mul_f32 v[12:13], v[12:13], s[36:37] op_sel_hi:[1,0]
	v_pk_mul_f32 v[16:17], v[16:17], s[36:37] op_sel_hi:[1,0]
	v_pk_mul_f32 v[28:29], v[28:29], s[36:37] op_sel_hi:[1,0]
	v_pk_mul_f32 v[30:31], v[30:31], s[36:37] op_sel_hi:[1,0]
	v_exp_f32_e32 v12, v12
	v_exp_f32_e32 v13, v13
	v_exp_f32_e32 v16, v16
	v_exp_f32_e32 v17, v17
	v_exp_f32_e32 v28, v28
	v_exp_f32_e32 v29, v29
	v_exp_f32_e32 v30, v30
	v_exp_f32_e32 v31, v31
	v_pk_add_f32 v[12:13], v[12:13], 1.0 op_sel_hi:[1,0]
	v_pk_add_f32 v[16:17], v[16:17], 1.0 op_sel_hi:[1,0]
	v_pk_add_f32 v[28:29], v[28:29], 1.0 op_sel_hi:[1,0]
	v_pk_add_f32 v[30:31], v[30:31], 1.0 op_sel_hi:[1,0]
	v_rcp_f32_e32 v12, v12
	v_rcp_f32_e32 v13, v13
	v_rcp_f32_e32 v46, v16
	v_rcp_f32_e32 v47, v17
	v_rcp_f32_e32 v28, v28
	v_rcp_f32_e32 v29, v29
	v_rcp_f32_e32 v30, v30
	v_rcp_f32_e32 v31, v31
	v_pk_mul_f32 v[16:17], v[12:13], v[14:15]
	v_pk_mul_f32 v[14:15], v[46:47], v[10:11]
	v_pk_mul_f32 v[12:13], v[28:29], v[24:25]
	v_pk_mul_f32 v[10:11], v[30:31], v[26:27]
	v_cvt_pk_bf16_f32 v26, v16, v17
	v_cvt_pk_bf16_f32 v24, v14, v15
	v_cvt_pk_bf16_f32 v23, v12, v13
	v_pk_mul_f32 v[46:47], v[72:73], v[72:73]
	v_cvt_pk_bf16_f32 v21, v10, v11
	v_mov_b32_e32 v48, v46
	v_mov_b32_e32 v72, v47
	v_pk_add_f32 v[40:41], v[48:49], v[72:73]
	v_pk_add_f32 v[32:33], v[38:39], v[32:33]
	v_pk_mul_f32 v[36:37], v[76:77], v[76:77]
	v_mov_b32_e32 v43, v78
	v_mov_b32_e32 v42, v34
	v_mov_b32_e32 v78, v35
	v_pk_add_f32 v[32:33], v[40:41], v[32:33]
	v_pk_mul_f32 v[38:39], v[74:75], v[74:75]
	v_mov_b32_e32 v45, v76
	v_mov_b32_e32 v44, v36
	v_mov_b32_e32 v76, v37
	v_pk_add_f32 v[34:35], v[42:43], v[78:79]
	v_pk_mul_f32 v[40:41], v[80:81], v[80:81]
	v_mov_b32_e32 v47, v74
	v_mov_b32_e32 v46, v38
	v_mov_b32_e32 v74, v39
	v_pk_add_f32 v[36:37], v[44:45], v[76:77]
	v_pk_add_f32 v[32:33], v[32:33], v[34:35]
	v_mov_b32_e32 v49, v80
	v_mov_b32_e32 v48, v40
	v_mov_b32_e32 v80, v41
	v_pk_add_f32 v[38:39], v[46:47], v[74:75]
	v_pk_add_f32 v[32:33], v[36:37], v[32:33]
	v_pk_add_f32 v[40:41], v[48:49], v[80:81]
	v_pk_add_f32 v[32:33], v[38:39], v[32:33]
	v_pk_mul_f32 v[36:37], v[86:87], v[86:87]
	v_pk_add_f32 v[34:35], v[40:41], v[32:33]
	v_pk_mul_f32 v[32:33], v[90:91], v[90:91]
	v_pk_mul_f32 v[38:39], v[84:85], v[84:85]
	v_mov_b32_e32 v43, v90
	v_mov_b32_e32 v42, v32
	v_mov_b32_e32 v90, v33
	v_pk_mul_f32 v[40:41], v[82:83], v[82:83]
	v_mov_b32_e32 v45, v86
	v_mov_b32_e32 v47, v84
	v_mov_b32_e32 v44, v36
	v_mov_b32_e32 v86, v37
	v_mov_b32_e32 v46, v38
	v_mov_b32_e32 v84, v39
	v_pk_add_f32 v[36:37], v[42:43], v[90:91]
	v_mov_b32_e32 v49, v82
	v_mov_b32_e32 v48, v40
	v_mov_b32_e32 v82, v41
	v_pk_add_f32 v[38:39], v[44:45], v[86:87]
	v_pk_add_f32 v[40:41], v[46:47], v[84:85]
	v_pk_add_f32 v[34:35], v[34:35], v[36:37]
	v_pk_mul_f32 v[36:37], v[94:95], v[94:95]
	v_pk_add_f32 v[34:35], v[38:39], v[34:35]
	v_mov_b32_e32 v39, v96
	v_pk_add_f32 v[34:35], v[40:41], v[34:35]
	v_mov_b32_e32 v41, v94
	v_mov_b32_e32 v40, v36
	v_mov_b32_e32 v94, v37
	v_pk_mul_f32 v[54:55], v[98:99], v[98:99]
	v_pk_add_f32 v[36:37], v[40:41], v[94:95]
	v_mov_b32_e32 v57, v98
	v_mov_b32_e32 v56, v54
	v_mov_b32_e32 v98, v55
	v_pk_add_f32 v[40:41], v[56:57], v[98:99]
	v_mov_b32_e32 v55, v100
	v_mov_b32_e32 v57, v106
	v_mov_b32_e32 v158, s17
	v_pk_mul_f32 v[58:59], v[10:11], v[10:11]
	v_mov_b32_e32 v61, v12
	v_mov_b32_e32 v63, v10
	v_mov_b32_e32 v62, v58
	v_mov_b32_e32 v10, v59
	v_pk_add_f32 v[10:11], v[62:63], v[10:11]
	v_mov_b32_e32 v76, 0
	v_mov_b32_e32 v77, 0
	v_mov_b32_e32 v78, 0
	v_mov_b32_e32 v79, 0
	v_mov_b32_e32 v72, 0
	v_mov_b32_e32 v73, 0
	v_mov_b32_e32 v74, 0
	v_mov_b32_e32 v75, 0
	s_waitcnt vmcnt(1)
	v_mov_b32_e32 v28, v228
	v_mov_b32_e32 v29, v229
	v_mov_b32_e32 v30, v230
	v_mov_b32_e32 v31, v231
	v_lshlrev_b32_e32 v32, 16, v28
	v_and_b32_e32 v33, 0xffff0000, v28
	v_lshlrev_b32_e32 v28, 16, v29
	v_and_b32_e32 v29, 0xffff0000, v29
	v_lshlrev_b32_e32 v42, 16, v30
	v_and_b32_e32 v43, 0xffff0000, v30
	v_lshlrev_b32_e32 v30, 16, v31
	v_and_b32_e32 v31, 0xffff0000, v31
	v_pk_mul_f32 v[44:45], v[32:33], v[32:33]
	v_pk_mul_f32 v[46:47], v[28:29], v[28:29]
	v_pk_mul_f32 v[50:51], v[42:43], v[42:43]
	v_pk_mul_f32 v[52:53], v[30:31], v[30:31]
	v_pk_fma_f32 v[44:45], v[44:45], s[38:39], 1.0 op_sel_hi:[1,0,0]
	v_pk_fma_f32 v[46:47], v[46:47], s[38:39], 1.0 op_sel_hi:[1,0,0]
	v_pk_fma_f32 v[50:51], v[50:51], s[38:39], 1.0 op_sel_hi:[1,0,0]
	v_pk_fma_f32 v[52:53], v[52:53], s[38:39], 1.0 op_sel_hi:[1,0,0]
	v_pk_mul_f32 v[44:45], v[44:45], v[32:33]
	v_pk_mul_f32 v[46:47], v[46:47], v[28:29]
	v_pk_mul_f32 v[50:51], v[50:51], v[42:43]
	v_pk_mul_f32 v[52:53], v[52:53], v[30:31]
	v_pk_mul_f32 v[44:45], v[44:45], s[36:37] op_sel_hi:[1,0]
	v_pk_mul_f32 v[46:47], v[46:47], s[36:37] op_sel_hi:[1,0]
	v_pk_mul_f32 v[50:51], v[50:51], s[36:37] op_sel_hi:[1,0]
	v_pk_mul_f32 v[52:53], v[52:53], s[36:37] op_sel_hi:[1,0]
	v_exp_f32_e32 v44, v44
	v_exp_f32_e32 v45, v45
	v_exp_f32_e32 v46, v46
	v_exp_f32_e32 v47, v47
	v_exp_f32_e32 v50, v50
	v_exp_f32_e32 v51, v51
	v_exp_f32_e32 v52, v52
	v_exp_f32_e32 v53, v53
	v_pk_add_f32 v[44:45], v[44:45], 1.0 op_sel_hi:[1,0]
	v_pk_add_f32 v[46:47], v[46:47], 1.0 op_sel_hi:[1,0]
	v_pk_add_f32 v[50:51], v[50:51], 1.0 op_sel_hi:[1,0]
	v_pk_add_f32 v[52:53], v[52:53], 1.0 op_sel_hi:[1,0]
	v_rcp_f32_e32 v44, v44
	v_rcp_f32_e32 v45, v45
	v_rcp_f32_e32 v46, v46
	v_rcp_f32_e32 v47, v47
	v_rcp_f32_e32 v50, v50
	v_rcp_f32_e32 v51, v51
	v_rcp_f32_e32 v52, v52
	v_rcp_f32_e32 v53, v53
	v_pk_mul_f32 v[44:45], v[44:45], v[32:33]
	v_pk_mul_f32 v[46:47], v[46:47], v[28:29]
	v_pk_mul_f32 v[42:43], v[50:51], v[42:43]
	v_pk_mul_f32 v[50:51], v[52:53], v[30:31]
	v_cvt_pk_bf16_f32 v29, v44, v45
	v_cvt_pk_bf16_f32 v28, v46, v47
	v_cvt_pk_bf16_f32 v27, v42, v43
	v_mov_b32_e32 v53, v92
	v_cvt_pk_bf16_f32 v25, v50, v51
	v_pk_add_f32 v[4:5], v[48:49], v[82:83]
	v_pk_mul_f32 v[48:49], v[92:93], v[92:93]
	v_pk_add_f32 v[4:5], v[4:5], v[34:35]
	v_pk_mul_f32 v[34:35], v[96:97], v[96:97]
	v_mov_b32_e32 v52, v48
	v_mov_b32_e32 v38, v34
	v_mov_b32_e32 v96, v35
	v_pk_add_f32 v[34:35], v[38:39], v[96:97]
	v_mov_b32_e32 v92, v49
	v_pk_add_f32 v[4:5], v[4:5], v[34:35]
	v_pk_add_f32 v[38:39], v[52:53], v[92:93]
	v_pk_add_f32 v[4:5], v[36:37], v[4:5]
	v_pk_mul_f32 v[34:35], v[104:105], v[104:105]
	v_pk_add_f32 v[4:5], v[38:39], v[4:5]
	v_pk_mul_f32 v[36:37], v[102:103], v[102:103]
	v_mov_b32_e32 v49, v104
	v_mov_b32_e32 v48, v34
	v_mov_b32_e32 v104, v35
	v_pk_add_f32 v[4:5], v[40:41], v[4:5]
	v_pk_mul_f32 v[38:39], v[100:101], v[100:101]
	v_mov_b32_e32 v53, v102
	v_mov_b32_e32 v52, v36
	v_mov_b32_e32 v102, v37
	v_pk_add_f32 v[34:35], v[48:49], v[104:105]
	v_pk_mul_f32 v[40:41], v[106:107], v[106:107]
	v_mov_b32_e32 v54, v38
	v_mov_b32_e32 v100, v39
	v_pk_add_f32 v[36:37], v[52:53], v[102:103]
	v_pk_add_f32 v[4:5], v[4:5], v[34:35]
	v_mov_b32_e32 v56, v40
	v_mov_b32_e32 v106, v41
	v_pk_add_f32 v[38:39], v[54:55], v[100:101]
	v_pk_add_f32 v[4:5], v[36:37], v[4:5]
	v_pk_mul_f32 v[34:35], v[8:9], v[8:9]
	v_pk_add_f32 v[40:41], v[56:57], v[106:107]
	v_pk_add_f32 v[4:5], v[38:39], v[4:5]
	v_pk_mul_f32 v[36:37], v[6:7], v[6:7]
	v_mov_b32_e32 v49, v8
	v_mov_b32_e32 v48, v34
	v_mov_b32_e32 v8, v35
	v_pk_add_f32 v[4:5], v[40:41], v[4:5]
	v_pk_mul_f32 v[38:39], v[2:3], v[2:3]
	v_mov_b32_e32 v53, v6
	v_mov_b32_e32 v52, v36
	v_mov_b32_e32 v6, v37
	v_pk_add_f32 v[8:9], v[48:49], v[8:9]
	v_pk_mul_f32 v[40:41], v[0:1], v[0:1]
	v_mov_b32_e32 v55, v2
	v_mov_b32_e32 v54, v38
	v_mov_b32_e32 v2, v39
	v_pk_add_f32 v[6:7], v[52:53], v[6:7]
	v_pk_add_f32 v[4:5], v[4:5], v[8:9]
	v_mov_b32_e32 v57, v0
	v_mov_b32_e32 v56, v40
	v_mov_b32_e32 v0, v41
	v_pk_add_f32 v[2:3], v[54:55], v[2:3]
	v_pk_add_f32 v[4:5], v[6:7], v[4:5]
	v_pk_add_f32 v[0:1], v[56:57], v[0:1]
	v_pk_add_f32 v[2:3], v[2:3], v[4:5]
	v_pk_mul_f32 v[8:9], v[16:17], v[16:17]
	v_pk_add_f32 v[0:1], v[0:1], v[2:3]
	v_mov_b32_e32 v35, v16
	v_pk_mul_f32 v[52:53], v[14:15], v[14:15]
	v_mov_b32_e32 v34, v8
	v_mov_b32_e32 v16, v9
	v_mov_b32_e32 v55, v14
	v_pk_mul_f32 v[56:57], v[12:13], v[12:13]
	v_mov_b32_e32 v54, v52
	v_mov_b32_e32 v14, v53
	v_pk_add_f32 v[8:9], v[34:35], v[16:17]
	v_mov_b32_e32 v60, v56
	v_mov_b32_e32 v12, v57
	v_pk_add_f32 v[14:15], v[54:55], v[14:15]
	v_pk_add_f32 v[0:1], v[0:1], v[8:9]
	v_pk_add_f32 v[12:13], v[60:61], v[12:13]
	v_pk_add_f32 v[0:1], v[14:15], v[0:1]
	v_pk_mul_f32 v[8:9], v[44:45], v[44:45]
	v_pk_add_f32 v[0:1], v[12:13], v[0:1]
	v_mov_b32_e32 v17, v44
	s_waitcnt vmcnt(0)
	v_mov_b32_e32 v30, v232
	v_mov_b32_e32 v31, v233
	v_mov_b32_e32 v32, v234
	v_mov_b32_e32 v33, v235
	v_lshlrev_b32_e32 v2, 16, v30
	v_and_b32_e32 v3, 0xffff0000, v30
	v_lshlrev_b32_e32 v4, 16, v31
	v_and_b32_e32 v5, 0xffff0000, v31
	v_lshlrev_b32_e32 v6, 16, v32
	v_and_b32_e32 v7, 0xffff0000, v32
	v_lshlrev_b32_e32 v30, 16, v33
	v_and_b32_e32 v31, 0xffff0000, v33
	v_pk_mul_f32 v[32:33], v[2:3], v[2:3]
	v_pk_mul_f32 v[36:37], v[4:5], v[4:5]
	v_pk_mul_f32 v[38:39], v[6:7], v[6:7]
	v_pk_mul_f32 v[40:41], v[30:31], v[30:31]
	v_pk_fma_f32 v[32:33], v[32:33], s[38:39], 1.0 op_sel_hi:[1,0,0]
	v_pk_fma_f32 v[36:37], v[36:37], s[38:39], 1.0 op_sel_hi:[1,0,0]
	v_pk_fma_f32 v[38:39], v[38:39], s[38:39], 1.0 op_sel_hi:[1,0,0]
	v_pk_fma_f32 v[40:41], v[40:41], s[38:39], 1.0 op_sel_hi:[1,0,0]
	v_pk_mul_f32 v[32:33], v[32:33], v[2:3]
	v_pk_mul_f32 v[36:37], v[36:37], v[4:5]
	v_pk_mul_f32 v[38:39], v[38:39], v[6:7]
	v_pk_mul_f32 v[40:41], v[40:41], v[30:31]
	v_pk_mul_f32 v[32:33], v[32:33], s[36:37] op_sel_hi:[1,0]
	v_pk_mul_f32 v[36:37], v[36:37], s[36:37] op_sel_hi:[1,0]
	v_pk_mul_f32 v[38:39], v[38:39], s[36:37] op_sel_hi:[1,0]
	v_pk_mul_f32 v[40:41], v[40:41], s[36:37] op_sel_hi:[1,0]
	v_exp_f32_e32 v32, v32
	v_exp_f32_e32 v33, v33
	v_exp_f32_e32 v36, v36
	v_exp_f32_e32 v37, v37
	v_exp_f32_e32 v38, v38
	v_exp_f32_e32 v39, v39
	v_exp_f32_e32 v40, v40
	v_exp_f32_e32 v41, v41
	v_pk_add_f32 v[32:33], v[32:33], 1.0 op_sel_hi:[1,0]
	v_pk_add_f32 v[36:37], v[36:37], 1.0 op_sel_hi:[1,0]
	v_pk_add_f32 v[38:39], v[38:39], 1.0 op_sel_hi:[1,0]
	v_pk_add_f32 v[40:41], v[40:41], 1.0 op_sel_hi:[1,0]
	v_rcp_f32_e32 v32, v32
	v_rcp_f32_e32 v33, v33
	v_rcp_f32_e32 v36, v36
	v_rcp_f32_e32 v37, v37
	v_rcp_f32_e32 v38, v38
	v_rcp_f32_e32 v39, v39
	v_rcp_f32_e32 v40, v40
	v_rcp_f32_e32 v41, v41
	v_pk_mul_f32 v[32:33], v[32:33], v[2:3]
	v_pk_mul_f32 v[36:37], v[36:37], v[4:5]
	v_pk_mul_f32 v[38:39], v[38:39], v[6:7]
	v_pk_mul_f32 v[30:31], v[40:41], v[30:31]
	v_cvt_pk_bf16_f32 v6, v32, v33
	v_cvt_pk_bf16_f32 v5, v36, v37
	v_cvt_pk_bf16_f32 v4, v38, v39
	v_pk_add_f32 v[0:1], v[10:11], v[0:1]
	v_cvt_pk_bf16_f32 v3, v30, v31
	s_waitcnt lgkmcnt(0)
	ds_read_b128 v[172:175], v255 offset:0
	ds_read_b128 v[176:179], v255 offset:16
	ds_read_b128 v[180:183], v255 offset:32
	ds_read_b128 v[184:187], v255 offset:48
	ds_read_b128 v[188:191], v255 offset:64
	ds_read_b128 v[192:195], v255 offset:80
	ds_read_b128 v[196:199], v255 offset:96
	ds_read_b128 v[200:203], v255 offset:112
	ds_read_b128 v[204:207], v255 offset:128
	ds_read_b128 v[208:211], v255 offset:144
	ds_read_b128 v[212:215], v255 offset:160
	ds_read_b128 v[216:219], v255 offset:176
	ds_read_b128 v[220:223], v255 offset:192
	ds_read_b128 v[228:231], v255 offset:208
	ds_read_b128 v[232:235], v255 offset:224
	ds_read_b128 v[236:239], v255 offset:240
	v_pk_mul_f32 v[10:11], v[46:47], v[46:47]
	v_mov_b32_e32 v16, v8
	v_mov_b32_e32 v44, v9
	v_pk_mul_f32 v[12:13], v[42:43], v[42:43]
	v_mov_b32_e32 v35, v46
	v_mov_b32_e32 v34, v10
	v_mov_b32_e32 v46, v11
	v_pk_add_f32 v[8:9], v[16:17], v[44:45]
	v_pk_mul_f32 v[14:15], v[50:51], v[50:51]
	v_mov_b32_e32 v53, v42
	v_mov_b32_e32 v52, v12
	v_mov_b32_e32 v42, v13
	v_pk_add_f32 v[10:11], v[34:35], v[46:47]
	v_pk_add_f32 v[0:1], v[0:1], v[8:9]
	v_mov_b32_e32 v55, v50
	v_mov_b32_e32 v54, v14
	v_mov_b32_e32 v50, v15
	v_pk_add_f32 v[12:13], v[52:53], v[42:43]
	v_pk_add_f32 v[0:1], v[10:11], v[0:1]
	v_pk_mul_f32 v[8:9], v[32:33], v[32:33]
	v_pk_add_f32 v[14:15], v[54:55], v[50:51]
	v_pk_add_f32 v[0:1], v[12:13], v[0:1]
	v_pk_mul_f32 v[10:11], v[36:37], v[36:37]
	v_mov_b32_e32 v17, v32
	v_mov_b32_e32 v16, v8
	v_mov_b32_e32 v32, v9
	v_pk_add_f32 v[0:1], v[14:15], v[0:1]
	v_pk_mul_f32 v[12:13], v[38:39], v[38:39]
	v_mov_b32_e32 v35, v36
	v_mov_b32_e32 v34, v10
	v_mov_b32_e32 v36, v11
	v_pk_add_f32 v[8:9], v[16:17], v[32:33]
	v_pk_mul_f32 v[14:15], v[30:31], v[30:31]
	v_mov_b32_e32 v43, v38
	v_mov_b32_e32 v42, v12
	v_mov_b32_e32 v38, v13
	v_pk_add_f32 v[10:11], v[34:35], v[36:37]
	v_pk_add_f32 v[0:1], v[0:1], v[8:9]
	v_mov_b32_e32 v45, v30
	v_mov_b32_e32 v44, v14
	v_mov_b32_e32 v30, v15
	v_pk_add_f32 v[12:13], v[42:43], v[38:39]
	v_pk_add_f32 v[0:1], v[10:11], v[0:1]
	v_pk_add_f32 v[14:15], v[44:45], v[30:31]
	v_pk_add_f32 v[0:1], v[12:13], v[0:1]
	v_lshlrev_b32_e32 v8, 16, v114
	v_pk_add_f32 v[0:1], v[14:15], v[0:1]
	v_and_b32_e32 v9, 0xffff0000, v114
	v_pk_mul_f32 v[0:1], v[0:1], s[40:41] op_sel_hi:[1,0]
	v_lshlrev_b32_e32 v12, 16, v112
	v_fma_f32 v2, -v1, v1, v0
	v_max_f32_e32 v2, 0, v2
	v_add_f32_e32 v2, 0x3727c5ac, v2
	v_rsq_f32_e32 v2, v2
	v_pk_add_f32 v[8:9], v[8:9], v[0:1] op_sel:[0,1] neg_lo:[0,1] neg_hi:[0,1]
	v_and_b32_e32 v13, 0xffff0000, v112
	s_mul_i32 s41, s41, 0x8a00
	v_pk_mul_f32 v[8:9], v[8:9], v[2:3] op_sel_hi:[1,0]
	v_pk_add_f32 v[12:13], v[12:13], v[0:1] op_sel:[0,1] neg_lo:[0,1] neg_hi:[0,1]
	s_add_i32 s17, s41, 0
	v_pk_mul_f32 v[12:13], v[12:13], v[2:3] op_sel_hi:[1,0]
	v_lshl_add_u32 v7, v109, 1, s17
	v_and_b32_e32 v15, 0xffff0000, v3
	s_waitcnt lgkmcnt(15)
	v_pk_fma_f32 v[8:9], v[172:173], v[8:9], v[174:175]
	s_nop 0
	v_cvt_pk_bf16_f32 v14, v8, v9
	ds_write_b16 v7, v14
	ds_write_b16_d16_hi v7, v14 offset:272
	s_waitcnt lgkmcnt(15)
	v_pk_fma_f32 v[8:9], v[176:177], v[12:13], v[178:179]
	s_nop 0
	v_cvt_pk_bf16_f32 v14, v8, v9
	v_lshlrev_b32_e32 v12, 16, v111
	v_and_b32_e32 v13, 0xffff0000, v111
	v_pk_add_f32 v[12:13], v[12:13], v[0:1] op_sel:[0,1] neg_lo:[0,1] neg_hi:[0,1]
	ds_write_b16 v7, v14 offset:544
	ds_write_b16_d16_hi v7, v14 offset:816
	v_pk_mul_f32 v[12:13], v[12:13], v[2:3] op_sel_hi:[1,0]
	s_waitcnt lgkmcnt(15)
	v_pk_fma_f32 v[8:9], v[180:181], v[12:13], v[182:183]
	s_nop 0
	v_cvt_pk_bf16_f32 v14, v8, v9
	v_lshlrev_b32_e32 v12, 16, v110
	v_and_b32_e32 v13, 0xffff0000, v110
	v_pk_add_f32 v[12:13], v[12:13], v[0:1] op_sel:[0,1] neg_lo:[0,1] neg_hi:[0,1]
	ds_write_b16 v7, v14 offset:1088
	ds_write_b16_d16_hi v7, v14 offset:1360
	v_pk_mul_f32 v[12:13], v[12:13], v[2:3] op_sel_hi:[1,0]
	s_waitcnt lgkmcnt(15)
	v_pk_fma_f32 v[8:9], v[184:185], v[12:13], v[186:187]
	s_nop 0
	v_cvt_pk_bf16_f32 v14, v8, v9
	v_lshlrev_b32_e32 v12, 16, v117
	v_and_b32_e32 v13, 0xffff0000, v117
	v_pk_add_f32 v[12:13], v[12:13], v[0:1] op_sel:[0,1] neg_lo:[0,1] neg_hi:[0,1]
	ds_write_b16 v7, v14 offset:1632
	ds_write_b16_d16_hi v7, v14 offset:1904
	v_pk_mul_f32 v[12:13], v[12:13], v[2:3] op_sel_hi:[1,0]
	s_waitcnt lgkmcnt(15)
	v_pk_fma_f32 v[8:9], v[188:189], v[12:13], v[190:191]
	s_nop 0
	v_cvt_pk_bf16_f32 v14, v8, v9
	v_lshlrev_b32_e32 v12, 16, v116
	v_and_b32_e32 v13, 0xffff0000, v116
	v_pk_add_f32 v[12:13], v[12:13], v[0:1] op_sel:[0,1] neg_lo:[0,1] neg_hi:[0,1]
	ds_write_b16 v7, v14 offset:2176
	ds_write_b16_d16_hi v7, v14 offset:2448
	v_pk_mul_f32 v[12:13], v[12:13], v[2:3] op_sel_hi:[1,0]
	s_waitcnt lgkmcnt(15)
	v_pk_fma_f32 v[8:9], v[12:13], v[192:193], v[194:195]
	s_nop 0
	v_cvt_pk_bf16_f32 v14, v8, v9
	v_lshlrev_b32_e32 v12, 16, v115
	v_and_b32_e32 v13, 0xffff0000, v115
	v_pk_add_f32 v[12:13], v[12:13], v[0:1] op_sel:[0,1] neg_lo:[0,1] neg_hi:[0,1]
	ds_write_b16 v7, v14 offset:2720
	ds_write_b16_d16_hi v7, v14 offset:2992
	v_pk_mul_f32 v[12:13], v[12:13], v[2:3] op_sel_hi:[1,0]
	v_bfe_u32 v115, v108, 5, 1
	v_lshlrev_b32_e32 v88, 5, v115
	v_lshl_add_u64 v[90:91], s[12:13], 0, v[88:89]
	s_waitcnt lgkmcnt(15)
	v_pk_fma_f32 v[8:9], v[12:13], v[196:197], v[198:199]
	s_nop 0
	v_cvt_pk_bf16_f32 v14, v8, v9
	v_lshlrev_b32_e32 v12, 16, v113
	v_and_b32_e32 v13, 0xffff0000, v113
	v_pk_add_f32 v[12:13], v[12:13], v[0:1] op_sel:[0,1] neg_lo:[0,1] neg_hi:[0,1]
	ds_write_b16 v7, v14 offset:3264
	ds_write_b16_d16_hi v7, v14 offset:3536
	v_pk_mul_f32 v[12:13], v[12:13], v[2:3] op_sel_hi:[1,0]
	s_waitcnt lgkmcnt(15)
	v_pk_fma_f32 v[8:9], v[12:13], v[200:201], v[202:203]
	s_nop 0
	v_cvt_pk_bf16_f32 v14, v8, v9
	ds_read_b128 v[172:175], v255 offset:256
	ds_read_b128 v[176:179], v255 offset:272
	ds_read_b128 v[180:183], v255 offset:288
	ds_read_b128 v[184:187], v255 offset:304
	ds_read_b128 v[188:191], v255 offset:320
	ds_read_b128 v[192:195], v255 offset:336
	ds_read_b128 v[196:199], v255 offset:352
	ds_read_b128 v[200:203], v255 offset:368
	v_lshlrev_b32_e32 v12, 16, v122
	v_and_b32_e32 v13, 0xffff0000, v122
	v_pk_add_f32 v[12:13], v[12:13], v[0:1] op_sel:[0,1] neg_lo:[0,1] neg_hi:[0,1]
	ds_write_b16 v7, v14 offset:3808
	ds_write_b16_d16_hi v7, v14 offset:4080
	v_pk_mul_f32 v[12:13], v[12:13], v[2:3] op_sel_hi:[1,0]
	s_waitcnt lgkmcnt(15)
	v_pk_fma_f32 v[8:9], v[12:13], v[204:205], v[206:207]
	s_nop 0
	v_cvt_pk_bf16_f32 v14, v8, v9
	v_lshlrev_b32_e32 v12, 16, v120
	v_and_b32_e32 v13, 0xffff0000, v120
	v_pk_add_f32 v[12:13], v[12:13], v[0:1] op_sel:[0,1] neg_lo:[0,1] neg_hi:[0,1]
	ds_write_b16 v7, v14 offset:4352
	ds_write_b16_d16_hi v7, v14 offset:4624
	v_pk_mul_f32 v[12:13], v[12:13], v[2:3] op_sel_hi:[1,0]
	s_waitcnt lgkmcnt(15)
	v_pk_fma_f32 v[8:9], v[12:13], v[208:209], v[210:211]
	s_nop 0
	v_cvt_pk_bf16_f32 v14, v8, v9
	v_lshlrev_b32_e32 v12, 16, v119
	v_and_b32_e32 v13, 0xffff0000, v119
	v_pk_add_f32 v[12:13], v[12:13], v[0:1] op_sel:[0,1] neg_lo:[0,1] neg_hi:[0,1]
	ds_write_b16 v7, v14 offset:4896
	ds_write_b16_d16_hi v7, v14 offset:5168
	v_pk_mul_f32 v[12:13], v[12:13], v[2:3] op_sel_hi:[1,0]
	s_waitcnt lgkmcnt(15)
	v_pk_fma_f32 v[8:9], v[12:13], v[212:213], v[214:215]
	s_nop 0
	v_cvt_pk_bf16_f32 v14, v8, v9
	v_lshlrev_b32_e32 v12, 16, v118
	v_and_b32_e32 v13, 0xffff0000, v118
	v_pk_add_f32 v[12:13], v[12:13], v[0:1] op_sel:[0,1] neg_lo:[0,1] neg_hi:[0,1]
	ds_write_b16 v7, v14 offset:5440
	ds_write_b16_d16_hi v7, v14 offset:5712
	v_pk_mul_f32 v[12:13], v[12:13], v[2:3] op_sel_hi:[1,0]
	v_and_b32_e32 v118, 31, v108
	s_waitcnt lgkmcnt(15)
	v_pk_fma_f32 v[8:9], v[12:13], v[216:217], v[218:219]
	s_nop 0
	v_cvt_pk_bf16_f32 v14, v8, v9
	v_lshlrev_b32_e32 v12, 16, v126
	v_and_b32_e32 v13, 0xffff0000, v126
	v_pk_add_f32 v[12:13], v[12:13], v[0:1] op_sel:[0,1] neg_lo:[0,1] neg_hi:[0,1]
	ds_write_b16 v7, v14 offset:5984
	ds_write_b16_d16_hi v7, v14 offset:6256
	v_pk_mul_f32 v[12:13], v[12:13], v[2:3] op_sel_hi:[1,0]
	s_waitcnt lgkmcnt(15)
	v_pk_fma_f32 v[8:9], v[12:13], v[220:221], v[222:223]
	s_nop 0
	v_cvt_pk_bf16_f32 v14, v8, v9
	v_lshlrev_b32_e32 v12, 16, v124
	v_and_b32_e32 v13, 0xffff0000, v124
	v_pk_add_f32 v[12:13], v[12:13], v[0:1] op_sel:[0,1] neg_lo:[0,1] neg_hi:[0,1]
	ds_write_b16 v7, v14 offset:6528
	ds_write_b16_d16_hi v7, v14 offset:6800
	v_pk_mul_f32 v[12:13], v[12:13], v[2:3] op_sel_hi:[1,0]
	s_waitcnt lgkmcnt(15)
	v_pk_fma_f32 v[8:9], v[12:13], v[228:229], v[230:231]
	s_nop 0
	v_cvt_pk_bf16_f32 v14, v8, v9
	v_lshlrev_b32_e32 v12, 16, v123
	v_and_b32_e32 v13, 0xffff0000, v123
	v_pk_add_f32 v[12:13], v[12:13], v[0:1] op_sel:[0,1] neg_lo:[0,1] neg_hi:[0,1]
	ds_write_b16 v7, v14 offset:7072
	ds_write_b16_d16_hi v7, v14 offset:7344
	v_pk_mul_f32 v[12:13], v[12:13], v[2:3] op_sel_hi:[1,0]
	s_waitcnt lgkmcnt(15)
	v_pk_fma_f32 v[8:9], v[12:13], v[232:233], v[234:235]
	s_nop 0
	v_cvt_pk_bf16_f32 v14, v8, v9
	v_lshlrev_b32_e32 v12, 16, v121
	v_and_b32_e32 v13, 0xffff0000, v121
	v_pk_add_f32 v[12:13], v[12:13], v[0:1] op_sel:[0,1] neg_lo:[0,1] neg_hi:[0,1]
	ds_write_b16 v7, v14 offset:7616
	ds_write_b16_d16_hi v7, v14 offset:7888
	v_pk_mul_f32 v[12:13], v[12:13], v[2:3] op_sel_hi:[1,0]
	s_waitcnt lgkmcnt(15)
	v_pk_fma_f32 v[8:9], v[12:13], v[236:237], v[238:239]
	s_nop 0
	v_cvt_pk_bf16_f32 v14, v8, v9
	ds_read_b128 v[204:207], v255 offset:384
	ds_read_b128 v[208:211], v255 offset:400
	ds_read_b128 v[212:215], v255 offset:416
	ds_read_b128 v[216:219], v255 offset:432
	ds_read_b128 v[220:223], v255 offset:448
	ds_read_b128 v[228:231], v255 offset:464
	ds_read_b128 v[232:235], v255 offset:480
	ds_read_b128 v[236:239], v255 offset:496
	v_lshlrev_b32_e32 v12, 16, v129
	v_and_b32_e32 v13, 0xffff0000, v129
	v_pk_add_f32 v[12:13], v[12:13], v[0:1] op_sel:[0,1] neg_lo:[0,1] neg_hi:[0,1]
	ds_write_b16 v7, v14 offset:8160
	ds_write_b16_d16_hi v7, v14 offset:8432
	v_pk_mul_f32 v[12:13], v[12:13], v[2:3] op_sel_hi:[1,0]
	s_waitcnt lgkmcnt(15)
	v_pk_fma_f32 v[8:9], v[12:13], v[172:173], v[174:175]
	s_nop 0
	v_cvt_pk_bf16_f32 v14, v8, v9
	v_lshlrev_b32_e32 v12, 16, v128
	v_and_b32_e32 v13, 0xffff0000, v128
	v_pk_add_f32 v[12:13], v[12:13], v[0:1] op_sel:[0,1] neg_lo:[0,1] neg_hi:[0,1]
	ds_write_b16 v7, v14 offset:8704
	ds_write_b16_d16_hi v7, v14 offset:8976
	v_pk_mul_f32 v[12:13], v[12:13], v[2:3] op_sel_hi:[1,0]
	s_waitcnt lgkmcnt(15)
	v_pk_fma_f32 v[8:9], v[12:13], v[176:177], v[178:179]
	s_nop 0
	v_cvt_pk_bf16_f32 v14, v8, v9
	v_lshlrev_b32_e32 v12, 16, v127
	v_and_b32_e32 v13, 0xffff0000, v127
	v_pk_add_f32 v[12:13], v[12:13], v[0:1] op_sel:[0,1] neg_lo:[0,1] neg_hi:[0,1]
	ds_write_b16 v7, v14 offset:9248
	ds_write_b16_d16_hi v7, v14 offset:9520
	v_pk_mul_f32 v[12:13], v[12:13], v[2:3] op_sel_hi:[1,0]
	s_waitcnt lgkmcnt(15)
	v_pk_fma_f32 v[8:9], v[12:13], v[180:181], v[182:183]
	s_nop 0
	v_cvt_pk_bf16_f32 v14, v8, v9
	v_lshlrev_b32_e32 v12, 16, v125
	v_and_b32_e32 v13, 0xffff0000, v125
	v_pk_add_f32 v[12:13], v[12:13], v[0:1] op_sel:[0,1] neg_lo:[0,1] neg_hi:[0,1]
	ds_write_b16 v7, v14 offset:9792
	ds_write_b16_d16_hi v7, v14 offset:10064
	v_pk_mul_f32 v[12:13], v[12:13], v[2:3] op_sel_hi:[1,0]
	s_waitcnt lgkmcnt(15)
	v_pk_fma_f32 v[8:9], v[12:13], v[184:185], v[186:187]
	s_nop 0
	v_cvt_pk_bf16_f32 v14, v8, v9
	v_lshlrev_b32_e32 v12, 16, v134
	v_and_b32_e32 v13, 0xffff0000, v134
	v_pk_add_f32 v[12:13], v[12:13], v[0:1] op_sel:[0,1] neg_lo:[0,1] neg_hi:[0,1]
	ds_write_b16 v7, v14 offset:10336
	ds_write_b16_d16_hi v7, v14 offset:10608
	v_pk_mul_f32 v[12:13], v[12:13], v[2:3] op_sel_hi:[1,0]
	s_waitcnt lgkmcnt(15)
	v_pk_fma_f32 v[8:9], v[12:13], v[188:189], v[190:191]
	s_nop 0
	v_cvt_pk_bf16_f32 v14, v8, v9
	v_lshlrev_b32_e32 v12, 16, v132
	v_and_b32_e32 v13, 0xffff0000, v132
	v_pk_add_f32 v[12:13], v[12:13], v[0:1] op_sel:[0,1] neg_lo:[0,1] neg_hi:[0,1]
	ds_write_b16 v7, v14 offset:10880
	ds_write_b16_d16_hi v7, v14 offset:11152
	v_pk_mul_f32 v[12:13], v[12:13], v[2:3] op_sel_hi:[1,0]
	s_waitcnt lgkmcnt(15)
	v_pk_fma_f32 v[8:9], v[12:13], v[192:193], v[194:195]
	s_nop 0
	v_cvt_pk_bf16_f32 v14, v8, v9
	v_lshlrev_b32_e32 v12, 16, v131
	v_and_b32_e32 v13, 0xffff0000, v131
	v_pk_add_f32 v[12:13], v[12:13], v[0:1] op_sel:[0,1] neg_lo:[0,1] neg_hi:[0,1]
	ds_write_b16 v7, v14 offset:11424
	ds_write_b16_d16_hi v7, v14 offset:11696
	v_pk_mul_f32 v[12:13], v[12:13], v[2:3] op_sel_hi:[1,0]
	s_waitcnt lgkmcnt(15)
	v_pk_fma_f32 v[8:9], v[12:13], v[196:197], v[198:199]
	s_nop 0
	v_cvt_pk_bf16_f32 v14, v8, v9
	v_lshlrev_b32_e32 v12, 16, v130
	v_and_b32_e32 v13, 0xffff0000, v130
	v_pk_add_f32 v[12:13], v[12:13], v[0:1] op_sel:[0,1] neg_lo:[0,1] neg_hi:[0,1]
	ds_write_b16 v7, v14 offset:11968
	ds_write_b16_d16_hi v7, v14 offset:12240
	v_pk_mul_f32 v[12:13], v[12:13], v[2:3] op_sel_hi:[1,0]
	s_waitcnt lgkmcnt(15)
	v_pk_fma_f32 v[8:9], v[12:13], v[200:201], v[202:203]
	s_nop 0
	v_cvt_pk_bf16_f32 v14, v8, v9
	ds_read_b128 v[172:175], v255 offset:512
	ds_read_b128 v[176:179], v255 offset:528
	ds_read_b128 v[180:183], v255 offset:544
	ds_read_b128 v[184:187], v255 offset:560
	ds_read_b128 v[188:191], v255 offset:576
	ds_read_b128 v[192:195], v255 offset:592
	ds_read_b128 v[196:199], v255 offset:608
	ds_read_b128 v[200:203], v255 offset:624
	v_lshlrev_b32_e32 v12, 16, v137
	v_and_b32_e32 v13, 0xffff0000, v137
	v_pk_add_f32 v[12:13], v[12:13], v[0:1] op_sel:[0,1] neg_lo:[0,1] neg_hi:[0,1]
	ds_write_b16 v7, v14 offset:12512
	ds_write_b16_d16_hi v7, v14 offset:12784
	v_pk_mul_f32 v[12:13], v[12:13], v[2:3] op_sel_hi:[1,0]
	s_waitcnt lgkmcnt(15)
	v_pk_fma_f32 v[8:9], v[12:13], v[204:205], v[206:207]
	s_nop 0
	v_cvt_pk_bf16_f32 v14, v8, v9
	v_lshlrev_b32_e32 v12, 16, v136
	v_and_b32_e32 v13, 0xffff0000, v136
	v_pk_add_f32 v[12:13], v[12:13], v[0:1] op_sel:[0,1] neg_lo:[0,1] neg_hi:[0,1]
	ds_write_b16 v7, v14 offset:13056
	ds_write_b16_d16_hi v7, v14 offset:13328
	v_pk_mul_f32 v[12:13], v[12:13], v[2:3] op_sel_hi:[1,0]
	s_waitcnt lgkmcnt(15)
	v_pk_fma_f32 v[8:9], v[12:13], v[208:209], v[210:211]
	s_nop 0
	v_cvt_pk_bf16_f32 v14, v8, v9
	v_lshlrev_b32_e32 v12, 16, v135
	v_and_b32_e32 v13, 0xffff0000, v135
	v_pk_add_f32 v[12:13], v[12:13], v[0:1] op_sel:[0,1] neg_lo:[0,1] neg_hi:[0,1]
	ds_write_b16 v7, v14 offset:13600
	ds_write_b16_d16_hi v7, v14 offset:13872
	v_pk_mul_f32 v[12:13], v[12:13], v[2:3] op_sel_hi:[1,0]
	s_waitcnt lgkmcnt(15)
	v_pk_fma_f32 v[8:9], v[12:13], v[212:213], v[214:215]
	s_nop 0
	v_cvt_pk_bf16_f32 v14, v8, v9
	v_lshlrev_b32_e32 v12, 16, v133
	v_and_b32_e32 v13, 0xffff0000, v133
	v_pk_add_f32 v[12:13], v[12:13], v[0:1] op_sel:[0,1] neg_lo:[0,1] neg_hi:[0,1]
	ds_write_b16 v7, v14 offset:14144
	ds_write_b16_d16_hi v7, v14 offset:14416
	v_pk_mul_f32 v[12:13], v[12:13], v[2:3] op_sel_hi:[1,0]
	s_waitcnt lgkmcnt(15)
	v_pk_fma_f32 v[8:9], v[12:13], v[216:217], v[218:219]
	s_nop 0
	v_cvt_pk_bf16_f32 v14, v8, v9
	v_lshlrev_b32_e32 v12, 16, v142
	v_and_b32_e32 v13, 0xffff0000, v142
	v_pk_add_f32 v[12:13], v[12:13], v[0:1] op_sel:[0,1] neg_lo:[0,1] neg_hi:[0,1]
	ds_write_b16 v7, v14 offset:14688
	ds_write_b16_d16_hi v7, v14 offset:14960
	v_pk_mul_f32 v[12:13], v[12:13], v[2:3] op_sel_hi:[1,0]
	s_waitcnt lgkmcnt(15)
	v_pk_fma_f32 v[8:9], v[12:13], v[220:221], v[222:223]
	s_nop 0
	v_cvt_pk_bf16_f32 v14, v8, v9
	v_lshlrev_b32_e32 v12, 16, v140
	v_and_b32_e32 v13, 0xffff0000, v140
	v_pk_add_f32 v[12:13], v[12:13], v[0:1] op_sel:[0,1] neg_lo:[0,1] neg_hi:[0,1]
	ds_write_b16 v7, v14 offset:15232
	ds_write_b16_d16_hi v7, v14 offset:15504
	v_pk_mul_f32 v[12:13], v[12:13], v[2:3] op_sel_hi:[1,0]
	s_waitcnt lgkmcnt(15)
	v_pk_fma_f32 v[8:9], v[12:13], v[228:229], v[230:231]
	s_nop 0
	v_cvt_pk_bf16_f32 v14, v8, v9
	v_lshlrev_b32_e32 v12, 16, v139
	v_and_b32_e32 v13, 0xffff0000, v139
	v_pk_add_f32 v[12:13], v[12:13], v[0:1] op_sel:[0,1] neg_lo:[0,1] neg_hi:[0,1]
	ds_write_b16 v7, v14 offset:15776
	ds_write_b16_d16_hi v7, v14 offset:16048
	v_pk_mul_f32 v[12:13], v[12:13], v[2:3] op_sel_hi:[1,0]
	s_waitcnt lgkmcnt(15)
	v_pk_fma_f32 v[8:9], v[12:13], v[232:233], v[234:235]
	s_nop 0
	v_cvt_pk_bf16_f32 v14, v8, v9
	v_lshlrev_b32_e32 v12, 16, v138
	v_and_b32_e32 v13, 0xffff0000, v138
	v_pk_add_f32 v[12:13], v[12:13], v[0:1] op_sel:[0,1] neg_lo:[0,1] neg_hi:[0,1]
	ds_write_b16 v7, v14 offset:16320
	ds_write_b16_d16_hi v7, v14 offset:16592
	v_pk_mul_f32 v[12:13], v[12:13], v[2:3] op_sel_hi:[1,0]
	s_waitcnt lgkmcnt(15)
	v_pk_fma_f32 v[8:9], v[12:13], v[236:237], v[238:239]
	s_nop 0
	v_cvt_pk_bf16_f32 v14, v8, v9
	ds_read_b128 v[204:207], v255 offset:640
	ds_read_b128 v[208:211], v255 offset:656
	ds_read_b128 v[212:215], v255 offset:672
	ds_read_b128 v[216:219], v255 offset:688
	ds_read_b128 v[220:223], v255 offset:704
	ds_read_b128 v[228:231], v255 offset:720
	ds_read_b128 v[232:235], v255 offset:736
	ds_read_b128 v[236:239], v255 offset:752
	v_lshlrev_b32_e32 v12, 16, v146
	v_and_b32_e32 v13, 0xffff0000, v146
	v_pk_add_f32 v[12:13], v[12:13], v[0:1] op_sel:[0,1] neg_lo:[0,1] neg_hi:[0,1]
	ds_write_b16 v7, v14 offset:16864
	ds_write_b16_d16_hi v7, v14 offset:17136
	v_pk_mul_f32 v[12:13], v[12:13], v[2:3] op_sel_hi:[1,0]
	s_waitcnt lgkmcnt(15)
	v_pk_fma_f32 v[8:9], v[12:13], v[172:173], v[174:175]
	s_nop 0
	v_cvt_pk_bf16_f32 v14, v8, v9
	v_lshlrev_b32_e32 v12, 16, v144
	v_and_b32_e32 v13, 0xffff0000, v144
	v_pk_add_f32 v[12:13], v[12:13], v[0:1] op_sel:[0,1] neg_lo:[0,1] neg_hi:[0,1]
	ds_write_b16 v7, v14 offset:17408
	ds_write_b16_d16_hi v7, v14 offset:17680
	v_pk_mul_f32 v[12:13], v[12:13], v[2:3] op_sel_hi:[1,0]
	s_waitcnt lgkmcnt(15)
	v_pk_fma_f32 v[8:9], v[12:13], v[176:177], v[178:179]
	s_nop 0
	v_cvt_pk_bf16_f32 v14, v8, v9
	v_lshlrev_b32_e32 v12, 16, v143
	v_and_b32_e32 v13, 0xffff0000, v143
	v_pk_add_f32 v[12:13], v[12:13], v[0:1] op_sel:[0,1] neg_lo:[0,1] neg_hi:[0,1]
	ds_write_b16 v7, v14 offset:17952
	ds_write_b16_d16_hi v7, v14 offset:18224
	v_pk_mul_f32 v[12:13], v[12:13], v[2:3] op_sel_hi:[1,0]
	s_waitcnt lgkmcnt(15)
	v_pk_fma_f32 v[8:9], v[12:13], v[180:181], v[182:183]
	s_nop 0
	v_cvt_pk_bf16_f32 v14, v8, v9
	v_lshlrev_b32_e32 v12, 16, v141
	v_and_b32_e32 v13, 0xffff0000, v141
	v_pk_add_f32 v[12:13], v[12:13], v[0:1] op_sel:[0,1] neg_lo:[0,1] neg_hi:[0,1]
	ds_write_b16 v7, v14 offset:18496
	ds_write_b16_d16_hi v7, v14 offset:18768
	v_pk_mul_f32 v[12:13], v[12:13], v[2:3] op_sel_hi:[1,0]
	s_waitcnt lgkmcnt(15)
	v_pk_fma_f32 v[8:9], v[12:13], v[184:185], v[186:187]
	s_nop 0
	v_cvt_pk_bf16_f32 v14, v8, v9
	v_lshlrev_b32_e32 v12, 16, v149
	v_and_b32_e32 v13, 0xffff0000, v149
	v_pk_add_f32 v[12:13], v[12:13], v[0:1] op_sel:[0,1] neg_lo:[0,1] neg_hi:[0,1]
	ds_write_b16 v7, v14 offset:19040
	ds_write_b16_d16_hi v7, v14 offset:19312
	v_pk_mul_f32 v[12:13], v[12:13], v[2:3] op_sel_hi:[1,0]
	s_waitcnt lgkmcnt(15)
	v_pk_fma_f32 v[8:9], v[12:13], v[188:189], v[190:191]
	s_nop 0
	v_cvt_pk_bf16_f32 v14, v8, v9
	v_lshlrev_b32_e32 v12, 16, v148
	v_and_b32_e32 v13, 0xffff0000, v148
	v_pk_add_f32 v[12:13], v[12:13], v[0:1] op_sel:[0,1] neg_lo:[0,1] neg_hi:[0,1]
	ds_write_b16 v7, v14 offset:19584
	ds_write_b16_d16_hi v7, v14 offset:19856
	v_pk_mul_f32 v[12:13], v[12:13], v[2:3] op_sel_hi:[1,0]
	s_waitcnt lgkmcnt(15)
	v_pk_fma_f32 v[8:9], v[12:13], v[192:193], v[194:195]
	s_nop 0
	v_cvt_pk_bf16_f32 v14, v8, v9
	v_lshlrev_b32_e32 v12, 16, v147
	v_and_b32_e32 v13, 0xffff0000, v147
	v_pk_add_f32 v[12:13], v[12:13], v[0:1] op_sel:[0,1] neg_lo:[0,1] neg_hi:[0,1]
	ds_write_b16 v7, v14 offset:20128
	ds_write_b16_d16_hi v7, v14 offset:20400
	v_pk_mul_f32 v[12:13], v[12:13], v[2:3] op_sel_hi:[1,0]
	s_waitcnt lgkmcnt(15)
	v_pk_fma_f32 v[8:9], v[12:13], v[196:197], v[198:199]
	s_nop 0
	v_cvt_pk_bf16_f32 v14, v8, v9
	v_lshlrev_b32_e32 v12, 16, v145
	v_and_b32_e32 v13, 0xffff0000, v145
	v_pk_add_f32 v[12:13], v[12:13], v[0:1] op_sel:[0,1] neg_lo:[0,1] neg_hi:[0,1]
	ds_write_b16 v7, v14 offset:20672
	ds_write_b16_d16_hi v7, v14 offset:20944
	v_pk_mul_f32 v[12:13], v[12:13], v[2:3] op_sel_hi:[1,0]
	s_waitcnt lgkmcnt(15)
	v_pk_fma_f32 v[8:9], v[12:13], v[200:201], v[202:203]
	s_nop 0
	v_cvt_pk_bf16_f32 v14, v8, v9
	ds_read_b128 v[172:175], v255 offset:768
	ds_read_b128 v[176:179], v255 offset:784
	ds_read_b128 v[180:183], v255 offset:800
	ds_read_b128 v[184:187], v255 offset:816
	ds_read_b128 v[188:191], v255 offset:832
	ds_read_b128 v[192:195], v255 offset:848
	ds_read_b128 v[196:199], v255 offset:864
	ds_read_b128 v[200:203], v255 offset:880
	v_lshlrev_b32_e32 v12, 16, v154
	v_and_b32_e32 v13, 0xffff0000, v154
	v_pk_add_f32 v[12:13], v[12:13], v[0:1] op_sel:[0,1] neg_lo:[0,1] neg_hi:[0,1]
	ds_write_b16 v7, v14 offset:21216
	ds_write_b16_d16_hi v7, v14 offset:21488
	v_pk_mul_f32 v[12:13], v[12:13], v[2:3] op_sel_hi:[1,0]
	s_waitcnt lgkmcnt(15)
	v_pk_fma_f32 v[8:9], v[12:13], v[204:205], v[206:207]
	s_nop 0
	v_cvt_pk_bf16_f32 v14, v8, v9
	v_lshlrev_b32_e32 v12, 16, v152
	v_and_b32_e32 v13, 0xffff0000, v152
	v_pk_add_f32 v[12:13], v[12:13], v[0:1] op_sel:[0,1] neg_lo:[0,1] neg_hi:[0,1]
	ds_write_b16 v7, v14 offset:21760
	ds_write_b16_d16_hi v7, v14 offset:22032
	v_pk_mul_f32 v[12:13], v[12:13], v[2:3] op_sel_hi:[1,0]
	s_waitcnt lgkmcnt(15)
	v_pk_fma_f32 v[8:9], v[12:13], v[208:209], v[210:211]
	s_nop 0
	v_cvt_pk_bf16_f32 v14, v8, v9
	v_lshlrev_b32_e32 v12, 16, v151
	v_and_b32_e32 v13, 0xffff0000, v151
	v_pk_add_f32 v[12:13], v[12:13], v[0:1] op_sel:[0,1] neg_lo:[0,1] neg_hi:[0,1]
	ds_write_b16 v7, v14 offset:22304
	ds_write_b16_d16_hi v7, v14 offset:22576
	v_pk_mul_f32 v[12:13], v[12:13], v[2:3] op_sel_hi:[1,0]
	s_waitcnt lgkmcnt(15)
	v_pk_fma_f32 v[8:9], v[12:13], v[212:213], v[214:215]
	s_nop 0
	v_cvt_pk_bf16_f32 v14, v8, v9
	v_lshlrev_b32_e32 v12, 16, v150
	v_and_b32_e32 v13, 0xffff0000, v150
	v_pk_add_f32 v[12:13], v[12:13], v[0:1] op_sel:[0,1] neg_lo:[0,1] neg_hi:[0,1]
	ds_write_b16 v7, v14 offset:22848
	ds_write_b16_d16_hi v7, v14 offset:23120
	v_pk_mul_f32 v[12:13], v[12:13], v[2:3] op_sel_hi:[1,0]
	s_waitcnt lgkmcnt(15)
	v_pk_fma_f32 v[8:9], v[12:13], v[216:217], v[218:219]
	s_nop 0
	v_cvt_pk_bf16_f32 v14, v8, v9
	v_lshlrev_b32_e32 v12, 16, v157
	v_and_b32_e32 v13, 0xffff0000, v157
	v_pk_add_f32 v[12:13], v[12:13], v[0:1] op_sel:[0,1] neg_lo:[0,1] neg_hi:[0,1]
	ds_write_b16 v7, v14 offset:23392
	ds_write_b16_d16_hi v7, v14 offset:23664
	v_pk_mul_f32 v[12:13], v[12:13], v[2:3] op_sel_hi:[1,0]
	s_waitcnt lgkmcnt(15)
	v_pk_fma_f32 v[8:9], v[12:13], v[220:221], v[222:223]
	s_nop 0
	v_cvt_pk_bf16_f32 v14, v8, v9
	v_lshlrev_b32_e32 v12, 16, v156
	v_and_b32_e32 v13, 0xffff0000, v156
	v_pk_add_f32 v[12:13], v[12:13], v[0:1] op_sel:[0,1] neg_lo:[0,1] neg_hi:[0,1]
	ds_write_b16 v7, v14 offset:23936
	ds_write_b16_d16_hi v7, v14 offset:24208
	v_pk_mul_f32 v[12:13], v[12:13], v[2:3] op_sel_hi:[1,0]
	s_waitcnt lgkmcnt(15)
	v_pk_fma_f32 v[8:9], v[12:13], v[228:229], v[230:231]
	s_nop 0
	v_cvt_pk_bf16_f32 v14, v8, v9
	v_lshlrev_b32_e32 v12, 16, v155
	v_and_b32_e32 v13, 0xffff0000, v155
	v_pk_add_f32 v[12:13], v[12:13], v[0:1] op_sel:[0,1] neg_lo:[0,1] neg_hi:[0,1]
	ds_write_b16 v7, v14 offset:24480
	ds_write_b16_d16_hi v7, v14 offset:24752
	v_pk_mul_f32 v[12:13], v[12:13], v[2:3] op_sel_hi:[1,0]
	s_waitcnt lgkmcnt(15)
	v_pk_fma_f32 v[8:9], v[12:13], v[232:233], v[234:235]
	s_nop 0
	v_cvt_pk_bf16_f32 v14, v8, v9
	v_lshlrev_b32_e32 v12, 16, v153
	v_and_b32_e32 v13, 0xffff0000, v153
	v_pk_add_f32 v[12:13], v[12:13], v[0:1] op_sel:[0,1] neg_lo:[0,1] neg_hi:[0,1]
	ds_write_b16 v7, v14 offset:25024
	ds_write_b16_d16_hi v7, v14 offset:25296
	v_pk_mul_f32 v[12:13], v[12:13], v[2:3] op_sel_hi:[1,0]
	s_waitcnt lgkmcnt(15)
	v_pk_fma_f32 v[8:9], v[12:13], v[236:237], v[238:239]
	s_nop 0
	v_cvt_pk_bf16_f32 v14, v8, v9
	ds_read_b128 v[204:207], v255 offset:896
	ds_read_b128 v[208:211], v255 offset:912
	ds_read_b128 v[212:215], v255 offset:928
	ds_read_b128 v[216:219], v255 offset:944
	ds_read_b128 v[220:223], v255 offset:960
	ds_read_b128 v[228:231], v255 offset:976
	ds_read_b128 v[232:235], v255 offset:992
	ds_read_b128 v[236:239], v255 offset:1008
	v_lshlrev_b32_e32 v12, 16, v22
	v_and_b32_e32 v13, 0xffff0000, v22
	v_pk_add_f32 v[12:13], v[12:13], v[0:1] op_sel:[0,1] neg_lo:[0,1] neg_hi:[0,1]
	ds_write_b16 v7, v14 offset:25568
	ds_write_b16_d16_hi v7, v14 offset:25840
	v_pk_mul_f32 v[12:13], v[12:13], v[2:3] op_sel_hi:[1,0]
	s_waitcnt lgkmcnt(15)
	v_pk_fma_f32 v[8:9], v[12:13], v[172:173], v[174:175]
	s_nop 0
	v_cvt_pk_bf16_f32 v14, v8, v9
	v_lshlrev_b32_e32 v12, 16, v20
	v_and_b32_e32 v13, 0xffff0000, v20
	v_pk_add_f32 v[12:13], v[12:13], v[0:1] op_sel:[0,1] neg_lo:[0,1] neg_hi:[0,1]
	ds_write_b16 v7, v14 offset:26112
	ds_write_b16_d16_hi v7, v14 offset:26384
	v_pk_mul_f32 v[12:13], v[12:13], v[2:3] op_sel_hi:[1,0]
	s_waitcnt lgkmcnt(15)
	v_pk_fma_f32 v[8:9], v[12:13], v[176:177], v[178:179]
	s_nop 0
	v_cvt_pk_bf16_f32 v14, v8, v9
	v_lshlrev_b32_e32 v12, 16, v19
	v_and_b32_e32 v13, 0xffff0000, v19
	v_pk_add_f32 v[12:13], v[12:13], v[0:1] op_sel:[0,1] neg_lo:[0,1] neg_hi:[0,1]
	ds_write_b16 v7, v14 offset:26656
	ds_write_b16_d16_hi v7, v14 offset:26928
	v_pk_mul_f32 v[12:13], v[12:13], v[2:3] op_sel_hi:[1,0]
	s_waitcnt lgkmcnt(15)
	v_pk_fma_f32 v[8:9], v[12:13], v[180:181], v[182:183]
	s_nop 0
	v_cvt_pk_bf16_f32 v14, v8, v9
	v_lshlrev_b32_e32 v12, 16, v18
	v_and_b32_e32 v13, 0xffff0000, v18
	v_pk_add_f32 v[12:13], v[12:13], v[0:1] op_sel:[0,1] neg_lo:[0,1] neg_hi:[0,1]
	ds_write_b16 v7, v14 offset:27200
	ds_write_b16_d16_hi v7, v14 offset:27472
	v_pk_mul_f32 v[12:13], v[12:13], v[2:3] op_sel_hi:[1,0]
	s_waitcnt lgkmcnt(15)
	v_pk_fma_f32 v[8:9], v[12:13], v[184:185], v[186:187]
	s_nop 0
	v_cvt_pk_bf16_f32 v14, v8, v9
	v_lshlrev_b32_e32 v12, 16, v26
	v_and_b32_e32 v13, 0xffff0000, v26
	v_pk_add_f32 v[12:13], v[12:13], v[0:1] op_sel:[0,1] neg_lo:[0,1] neg_hi:[0,1]
	ds_write_b16 v7, v14 offset:27744
	ds_write_b16_d16_hi v7, v14 offset:28016
	v_pk_mul_f32 v[12:13], v[12:13], v[2:3] op_sel_hi:[1,0]
	s_waitcnt lgkmcnt(15)
	v_pk_fma_f32 v[8:9], v[12:13], v[188:189], v[190:191]
	s_nop 0
	v_cvt_pk_bf16_f32 v14, v8, v9
	v_lshlrev_b32_e32 v12, 16, v24
	v_and_b32_e32 v13, 0xffff0000, v24
	v_pk_add_f32 v[12:13], v[12:13], v[0:1] op_sel:[0,1] neg_lo:[0,1] neg_hi:[0,1]
	ds_write_b16 v7, v14 offset:28288
	ds_write_b16_d16_hi v7, v14 offset:28560
	v_pk_mul_f32 v[12:13], v[12:13], v[2:3] op_sel_hi:[1,0]
	s_waitcnt lgkmcnt(15)
	v_pk_fma_f32 v[8:9], v[12:13], v[192:193], v[194:195]
	s_nop 0
	v_cvt_pk_bf16_f32 v14, v8, v9
	v_lshlrev_b32_e32 v12, 16, v23
	v_and_b32_e32 v13, 0xffff0000, v23
	v_pk_add_f32 v[12:13], v[12:13], v[0:1] op_sel:[0,1] neg_lo:[0,1] neg_hi:[0,1]
	ds_write_b16 v7, v14 offset:28832
	ds_write_b16_d16_hi v7, v14 offset:29104
	v_pk_mul_f32 v[12:13], v[12:13], v[2:3] op_sel_hi:[1,0]
	s_waitcnt lgkmcnt(15)
	v_pk_fma_f32 v[8:9], v[12:13], v[196:197], v[198:199]
	s_nop 0
	v_cvt_pk_bf16_f32 v14, v8, v9
	v_lshlrev_b32_e32 v12, 16, v21
	v_and_b32_e32 v13, 0xffff0000, v21
	v_pk_add_f32 v[12:13], v[12:13], v[0:1] op_sel:[0,1] neg_lo:[0,1] neg_hi:[0,1]
	ds_write_b16 v7, v14 offset:29376
	ds_write_b16_d16_hi v7, v14 offset:29648
	v_pk_mul_f32 v[12:13], v[12:13], v[2:3] op_sel_hi:[1,0]
	s_waitcnt lgkmcnt(15)
	v_pk_fma_f32 v[8:9], v[12:13], v[200:201], v[202:203]
	s_nop 0
	v_cvt_pk_bf16_f32 v14, v8, v9
	v_lshlrev_b32_e32 v12, 16, v29
	v_and_b32_e32 v13, 0xffff0000, v29
	v_pk_add_f32 v[12:13], v[12:13], v[0:1] op_sel:[0,1] neg_lo:[0,1] neg_hi:[0,1]
	ds_write_b16 v7, v14 offset:29920
	ds_write_b16_d16_hi v7, v14 offset:30192
	v_pk_mul_f32 v[12:13], v[12:13], v[2:3] op_sel_hi:[1,0]
	s_waitcnt lgkmcnt(15)
	v_pk_fma_f32 v[8:9], v[12:13], v[204:205], v[206:207]
	s_nop 0
	v_cvt_pk_bf16_f32 v14, v8, v9
	v_lshlrev_b32_e32 v12, 16, v28
	v_and_b32_e32 v13, 0xffff0000, v28
	v_pk_add_f32 v[12:13], v[12:13], v[0:1] op_sel:[0,1] neg_lo:[0,1] neg_hi:[0,1]
	ds_write_b16 v7, v14 offset:30464
	ds_write_b16_d16_hi v7, v14 offset:30736
	v_pk_mul_f32 v[12:13], v[12:13], v[2:3] op_sel_hi:[1,0]
	s_waitcnt lgkmcnt(15)
	v_pk_fma_f32 v[8:9], v[12:13], v[208:209], v[210:211]
	s_nop 0
	v_cvt_pk_bf16_f32 v14, v8, v9
	v_lshlrev_b32_e32 v12, 16, v27
	v_and_b32_e32 v13, 0xffff0000, v27
	v_pk_add_f32 v[12:13], v[12:13], v[0:1] op_sel:[0,1] neg_lo:[0,1] neg_hi:[0,1]
	ds_write_b16 v7, v14 offset:31008
	ds_write_b16_d16_hi v7, v14 offset:31280
	v_pk_mul_f32 v[12:13], v[12:13], v[2:3] op_sel_hi:[1,0]
	s_waitcnt lgkmcnt(15)
	v_pk_fma_f32 v[8:9], v[12:13], v[212:213], v[214:215]
	s_nop 0
	v_cvt_pk_bf16_f32 v14, v8, v9
	v_lshlrev_b32_e32 v12, 16, v25
	v_and_b32_e32 v13, 0xffff0000, v25
	v_pk_add_f32 v[12:13], v[12:13], v[0:1] op_sel:[0,1] neg_lo:[0,1] neg_hi:[0,1]
	ds_write_b16 v7, v14 offset:31552
	ds_write_b16_d16_hi v7, v14 offset:31824
	v_pk_mul_f32 v[12:13], v[12:13], v[2:3] op_sel_hi:[1,0]
	s_waitcnt lgkmcnt(15)
	v_pk_fma_f32 v[8:9], v[12:13], v[216:217], v[218:219]
	s_nop 0
	v_cvt_pk_bf16_f32 v14, v8, v9
	v_lshlrev_b32_e32 v12, 16, v6
	v_and_b32_e32 v13, 0xffff0000, v6
	v_pk_add_f32 v[12:13], v[12:13], v[0:1] op_sel:[0,1] neg_lo:[0,1] neg_hi:[0,1]
	ds_write_b16 v7, v14 offset:32096
	ds_write_b16_d16_hi v7, v14 offset:32368
	v_pk_mul_f32 v[12:13], v[12:13], v[2:3] op_sel_hi:[1,0]
	v_lshlrev_b32_e32 v14, 16, v3
	s_waitcnt lgkmcnt(15)
	v_pk_fma_f32 v[8:9], v[12:13], v[220:221], v[222:223]
	s_nop 0
	v_cvt_pk_bf16_f32 v6, v8, v9
	v_lshlrev_b32_e32 v12, 16, v5
	v_and_b32_e32 v13, 0xffff0000, v5
	v_pk_add_f32 v[12:13], v[12:13], v[0:1] op_sel:[0,1] neg_lo:[0,1] neg_hi:[0,1]
	ds_write_b16 v7, v6 offset:32640
	ds_write_b16_d16_hi v7, v6 offset:32912
	v_pk_mul_f32 v[12:13], v[12:13], v[2:3] op_sel_hi:[1,0]
	s_waitcnt lgkmcnt(15)
	v_pk_fma_f32 v[8:9], v[12:13], v[228:229], v[230:231]
	s_nop 0
	v_cvt_pk_bf16_f32 v6, v8, v9
	v_lshlrev_b32_e32 v12, 16, v4
	v_and_b32_e32 v13, 0xffff0000, v4
	v_pk_add_f32 v[4:5], v[12:13], v[0:1] op_sel:[0,1] neg_lo:[0,1] neg_hi:[0,1]
	ds_write_b16 v7, v6 offset:33184
	ds_write_b16_d16_hi v7, v6 offset:33456
	v_pk_mul_f32 v[4:5], v[4:5], v[2:3] op_sel_hi:[1,0]
	v_pk_add_f32 v[0:1], v[14:15], v[0:1] op_sel:[0,1] neg_lo:[0,1] neg_hi:[0,1]
	s_waitcnt lgkmcnt(15)
	v_pk_fma_f32 v[4:5], v[4:5], v[232:233], v[234:235]
	s_nop 0
	v_cvt_pk_bf16_f32 v6, v4, v5
	s_bfe_u32 s8, s39, 0x10006
	v_lshl_or_b32 v124, s8, 5, v118
	v_or_b32_e32 v10, s37, v124
	v_pk_mul_f32 v[0:1], v[0:1], v[2:3] op_sel_hi:[1,0]
	v_lshlrev_b32_e32 v88, 9, v10
	v_lshl_add_u64 v[8:9], v[90:91], 0, v[88:89]
	ds_write_b16 v7, v6 offset:33728
	ds_write_b16_d16_hi v7, v6 offset:34000
	s_and_b32 s9, 64, s39
	s_cmp_eq_u32 s8, 0
	s_cselect_b64 s[12:13], -1, 0
	s_cmp_lg_u32 s9, 0
	s_cselect_b64 s[10:11], -1, 0
	s_and_b64 vcc, exec, s[12:13]
	s_waitcnt lgkmcnt(15)
	v_pk_fma_f32 v[0:1], v[0:1], v[236:237], v[238:239]
	s_nop 0
	v_cvt_pk_bf16_f32 v0, v0, v1
	ds_write_b16 v7, v0 offset:34272
	ds_write_b16_d16_hi v7, v0 offset:34544
	s_waitcnt lgkmcnt(0)
	s_barrier
	global_load_dwordx4 v[0:3], v[8:9], off offset:16
	global_load_dwordx4 v[4:7], v[8:9], off
	global_load_dwordx4 v[80:83], v[8:9], off offset:80
	global_load_dwordx4 v[84:87], v[8:9], off offset:64
	s_cbranch_vccnz .LBB0_404
	global_load_dwordx4 v[76:79], v[8:9], off offset:128
	global_load_dwordx4 v[72:75], v[8:9], off offset:144

.LBB0_410:
	s_waitcnt vmcnt(15)
	v_lshlrev_b32_e32 v66, 16, v116
	v_and_b32_e32 v67, 0xffff0000, v116
	v_pk_mul_f32 v[70:71], v[66:67], v[66:67]
	s_mov_b32 s8, 0x3d372713
	v_lshlrev_b32_e32 v72, 16, v117
	v_and_b32_e32 v73, 0xffff0000, v117
	v_pk_fma_f32 v[70:71], v[70:71], s[8:9], 1.0 op_sel_hi:[1,0,0]
	v_pk_mul_f32 v[74:75], v[72:73], v[72:73]
	s_add_u32 s10, s34, 0xa000000
	v_pk_mul_f32 v[70:71], v[70:71], v[66:67]
	s_mov_b32 s34, 0xc0135761
	v_pk_fma_f32 v[74:75], v[74:75], s[8:9], 1.0 op_sel_hi:[1,0,0]
	v_pk_mul_f32 v[70:71], v[70:71], s[34:35] op_sel_hi:[1,0]
	v_pk_mul_f32 v[74:75], v[74:75], v[72:73]
	v_exp_f32_e32 v70, v70
	v_exp_f32_e32 v71, v71
	v_pk_mul_f32 v[74:75], v[74:75], s[34:35] op_sel_hi:[1,0]
	s_addc_u32 s11, s35, 0
	v_exp_f32_e32 v74, v74
	v_exp_f32_e32 v75, v75
	v_pk_add_f32 v[70:71], v[70:71], 1.0 op_sel_hi:[1,0]
	v_lshlrev_b64 v[64:65], 11, v[114:115]
	v_rcp_f32_e32 v70, v70
	v_rcp_f32_e32 v71, v71
	v_pk_add_f32 v[74:75], v[74:75], 1.0 op_sel_hi:[1,0]
	v_lshl_add_u64 v[64:65], s[10:11], 0, v[64:65]
	v_rcp_f32_e32 v74, v74
	v_rcp_f32_e32 v75, v75
	v_pk_mul_f32 v[66:67], v[70:71], v[66:67]
	v_pk_add_f32 v[48:49], v[68:69], v[48:49] op_sel_hi:[0,1]
	v_lshl_add_u64 v[64:65], v[64:65], 0, s[16:17]
	v_lshlrev_b32_e32 v122, 1, v88
	v_mov_b32_e32 v123, 0
	v_pk_mul_f32 v[48:49], v[66:67], v[48:49]
	v_pk_mul_f32 v[66:67], v[74:75], v[72:73]
	v_pk_add_f32 v[50:51], v[68:69], v[50:51] op_sel_hi:[0,1]
	v_lshl_add_u64 v[64:65], v[64:65], 0, v[122:123]
	v_bfe_u32 v138, v224, 5, 1
	v_lshlrev_b32_e32 v138, 3, v138
	v_mov_b32_e32 v139, 0
	v_lshl_add_u64 v[136:137], v[64:65], 0, v[138:139]
	v_pk_mul_f32 v[50:51], v[66:67], v[50:51]
	v_cvt_pk_bf16_f32 v128, v48, v49
	s_waitcnt vmcnt(14)
	v_lshlrev_b32_e32 v66, 16, v113
	v_cvt_pk_bf16_f32 v129, v50, v51
	v_lshlrev_b32_e32 v48, 16, v112
	v_and_b32_e32 v49, 0xffff0000, v112
	v_pk_mul_f32 v[50:51], v[48:49], v[48:49]
	v_and_b32_e32 v67, 0xffff0000, v113
	v_pk_fma_f32 v[50:51], v[50:51], s[8:9], 1.0 op_sel_hi:[1,0,0]
	v_pk_mul_f32 v[70:71], v[66:67], v[66:67]
	v_pk_mul_f32 v[50:51], v[50:51], v[48:49]
	v_pk_fma_f32 v[70:71], v[70:71], s[8:9], 1.0 op_sel_hi:[1,0,0]
	v_pk_mul_f32 v[50:51], v[50:51], s[34:35] op_sel_hi:[1,0]
	v_pk_mul_f32 v[70:71], v[70:71], v[66:67]
	v_exp_f32_e32 v50, v50
	v_exp_f32_e32 v51, v51
	v_pk_mul_f32 v[70:71], v[70:71], s[34:35] op_sel_hi:[1,0]
	v_pk_add_f32 v[32:33], v[68:69], v[32:33] op_sel_hi:[0,1]
	v_exp_f32_e32 v70, v70
	v_exp_f32_e32 v71, v71
	v_pk_add_f32 v[50:51], v[50:51], 1.0 op_sel_hi:[1,0]
	v_pk_add_f32 v[34:35], v[68:69], v[34:35] op_sel_hi:[0,1]
	v_rcp_f32_e32 v50, v50
	v_rcp_f32_e32 v51, v51
	v_pk_add_f32 v[70:71], v[70:71], 1.0 op_sel_hi:[1,0]
	v_pk_add_f32 v[16:17], v[68:69], v[16:17] op_sel_hi:[0,1]
	v_rcp_f32_e32 v70, v70
	v_rcp_f32_e32 v71, v71
	v_pk_mul_f32 v[48:49], v[50:51], v[48:49]
	v_pk_add_f32 v[50:51], v[68:69], v[52:53] op_sel_hi:[0,1]
	v_pk_mul_f32 v[48:49], v[48:49], v[50:51]
	v_pk_mul_f32 v[50:51], v[70:71], v[66:67]
	v_pk_add_f32 v[52:53], v[68:69], v[54:55] op_sel_hi:[0,1]
	v_pk_mul_f32 v[50:51], v[50:51], v[52:53]
	v_cvt_pk_bf16_f32 v130, v48, v49
	s_waitcnt vmcnt(13)
	v_lshlrev_b32_e32 v52, 16, v111
	v_cvt_pk_bf16_f32 v131, v50, v51
	s_nop 1
	v_permlane32_swap_b32_e32 v128, v130
	v_permlane32_swap_b32_e32 v129, v131
	global_store_dwordx4 v[136:137], v[128:131], off offset:1024
	v_lshlrev_b32_e32 v48, 16, v110
	v_and_b32_e32 v49, 0xffff0000, v110
	v_pk_mul_f32 v[50:51], v[48:49], v[48:49]
	v_and_b32_e32 v53, 0xffff0000, v111
	v_pk_fma_f32 v[50:51], v[50:51], s[8:9], 1.0 op_sel_hi:[1,0,0]
	v_pk_mul_f32 v[54:55], v[52:53], v[52:53]
	v_pk_mul_f32 v[50:51], v[50:51], v[48:49]
	v_pk_fma_f32 v[54:55], v[54:55], s[8:9], 1.0 op_sel_hi:[1,0,0]
	v_pk_mul_f32 v[50:51], v[50:51], s[34:35] op_sel_hi:[1,0]
	v_pk_mul_f32 v[54:55], v[54:55], v[52:53]
	v_exp_f32_e32 v50, v50
	v_exp_f32_e32 v51, v51
	v_pk_mul_f32 v[54:55], v[54:55], s[34:35] op_sel_hi:[1,0]
	v_pk_add_f32 v[18:19], v[68:69], v[18:19] op_sel_hi:[0,1]
	v_exp_f32_e32 v54, v54
	v_exp_f32_e32 v55, v55
	v_pk_add_f32 v[50:51], v[50:51], 1.0 op_sel_hi:[1,0]
	v_pk_add_f32 v[0:1], v[68:69], v[0:1] op_sel_hi:[0,1]
	v_rcp_f32_e32 v50, v50
	v_rcp_f32_e32 v51, v51
	v_pk_add_f32 v[54:55], v[54:55], 1.0 op_sel_hi:[1,0]
	v_pk_add_f32 v[2:3], v[68:69], v[2:3] op_sel_hi:[0,1]
	v_rcp_f32_e32 v54, v54
	v_rcp_f32_e32 v55, v55
	v_pk_mul_f32 v[48:49], v[50:51], v[48:49]
	v_pk_add_f32 v[50:51], v[68:69], v[56:57] op_sel_hi:[0,1]
	v_pk_mul_f32 v[48:49], v[48:49], v[50:51]
	v_pk_mul_f32 v[50:51], v[54:55], v[52:53]
	v_pk_add_f32 v[52:53], v[68:69], v[58:59] op_sel_hi:[0,1]
	v_pk_mul_f32 v[50:51], v[50:51], v[52:53]
	v_cvt_pk_bf16_f32 v132, v48, v49
	s_waitcnt vmcnt(13)
	v_lshlrev_b32_e32 v52, 16, v109
	v_cvt_pk_bf16_f32 v133, v50, v51
	v_lshlrev_b32_e32 v48, 16, v108
	v_and_b32_e32 v49, 0xffff0000, v108
	v_pk_mul_f32 v[50:51], v[48:49], v[48:49]
	v_and_b32_e32 v53, 0xffff0000, v109
	v_pk_fma_f32 v[50:51], v[50:51], s[8:9], 1.0 op_sel_hi:[1,0,0]
	v_pk_mul_f32 v[54:55], v[52:53], v[52:53]
	v_pk_mul_f32 v[50:51], v[50:51], v[48:49]
	v_pk_fma_f32 v[54:55], v[54:55], s[8:9], 1.0 op_sel_hi:[1,0,0]
	v_pk_mul_f32 v[50:51], v[50:51], s[34:35] op_sel_hi:[1,0]
	v_pk_mul_f32 v[54:55], v[54:55], v[52:53]
	v_exp_f32_e32 v50, v50
	v_exp_f32_e32 v51, v51
	v_pk_mul_f32 v[54:55], v[54:55], s[34:35] op_sel_hi:[1,0]
	s_andn2_b64 vcc, exec, s[12:13]
	v_exp_f32_e32 v54, v54
	v_exp_f32_e32 v55, v55
	v_pk_add_f32 v[50:51], v[50:51], 1.0 op_sel_hi:[1,0]
	v_mov_b32_e32 v76, 0
	v_rcp_f32_e32 v50, v50
	v_rcp_f32_e32 v51, v51
	v_pk_add_f32 v[54:55], v[54:55], 1.0 op_sel_hi:[1,0]
	v_mov_b32_e32 v77, 0
	v_rcp_f32_e32 v54, v54
	v_rcp_f32_e32 v55, v55
	v_pk_mul_f32 v[48:49], v[50:51], v[48:49]
	v_pk_add_f32 v[50:51], v[68:69], v[60:61] op_sel_hi:[0,1]
	v_pk_mul_f32 v[48:49], v[48:49], v[50:51]
	v_pk_mul_f32 v[50:51], v[54:55], v[52:53]
	v_pk_add_f32 v[52:53], v[68:69], v[62:63] op_sel_hi:[0,1]
	v_pk_mul_f32 v[50:51], v[50:51], v[52:53]
	v_cvt_pk_bf16_f32 v134, v48, v49
	s_waitcnt vmcnt(12)
	v_lshlrev_b32_e32 v52, 16, v107
	v_cvt_pk_bf16_f32 v135, v50, v51
	s_nop 1
	v_permlane32_swap_b32_e32 v132, v134
	v_permlane32_swap_b32_e32 v133, v135
	global_store_dwordx4 v[136:137], v[132:135], off offset:1056
	v_lshlrev_b32_e32 v48, 16, v106
	v_and_b32_e32 v49, 0xffff0000, v106
	v_pk_mul_f32 v[50:51], v[48:49], v[48:49]
	v_and_b32_e32 v53, 0xffff0000, v107
	v_pk_fma_f32 v[50:51], v[50:51], s[8:9], 1.0 op_sel_hi:[1,0,0]
	v_pk_mul_f32 v[54:55], v[52:53], v[52:53]
	v_pk_mul_f32 v[50:51], v[50:51], v[48:49]
	v_pk_fma_f32 v[54:55], v[54:55], s[8:9], 1.0 op_sel_hi:[1,0,0]
	v_pk_mul_f32 v[50:51], v[50:51], s[34:35] op_sel_hi:[1,0]
	v_pk_mul_f32 v[54:55], v[54:55], v[52:53]
	v_exp_f32_e32 v50, v50
	v_exp_f32_e32 v51, v51
	v_pk_mul_f32 v[54:55], v[54:55], s[34:35] op_sel_hi:[1,0]
	v_mov_b32_e32 v78, 0
	v_exp_f32_e32 v54, v54
	v_exp_f32_e32 v55, v55
	v_pk_add_f32 v[50:51], v[50:51], 1.0 op_sel_hi:[1,0]
	v_mov_b32_e32 v79, 0
	v_rcp_f32_e32 v50, v50
	v_rcp_f32_e32 v51, v51
	v_pk_add_f32 v[54:55], v[54:55], 1.0 op_sel_hi:[1,0]
	v_mov_b32_e32 v72, 0
	v_rcp_f32_e32 v54, v54
	v_rcp_f32_e32 v55, v55
	v_pk_mul_f32 v[48:49], v[50:51], v[48:49]
	v_mov_b32_e32 v73, 0
	v_pk_mul_f32 v[32:33], v[48:49], v[32:33]
	v_pk_mul_f32 v[48:49], v[54:55], v[52:53]
	v_cvt_pk_bf16_f32 v128, v32, v33
	v_mov_b32_e32 v74, 0
	v_pk_mul_f32 v[34:35], v[48:49], v[34:35]
	s_waitcnt vmcnt(12)
	v_lshlrev_b32_e32 v48, 16, v105
	v_cvt_pk_bf16_f32 v129, v34, v35
	v_lshlrev_b32_e32 v32, 16, v104
	v_and_b32_e32 v33, 0xffff0000, v104
	v_pk_mul_f32 v[34:35], v[32:33], v[32:33]
	v_and_b32_e32 v49, 0xffff0000, v105
	v_pk_fma_f32 v[34:35], v[34:35], s[8:9], 1.0 op_sel_hi:[1,0,0]
	v_pk_mul_f32 v[50:51], v[48:49], v[48:49]
	v_pk_mul_f32 v[34:35], v[34:35], v[32:33]
	v_pk_fma_f32 v[50:51], v[50:51], s[8:9], 1.0 op_sel_hi:[1,0,0]
	v_pk_mul_f32 v[34:35], v[34:35], s[34:35] op_sel_hi:[1,0]
	v_pk_mul_f32 v[50:51], v[50:51], v[48:49]
	v_exp_f32_e32 v34, v34
	v_exp_f32_e32 v35, v35
	v_pk_mul_f32 v[50:51], v[50:51], s[34:35] op_sel_hi:[1,0]
	v_mov_b32_e32 v75, 0
	v_exp_f32_e32 v50, v50
	v_exp_f32_e32 v51, v51
	v_pk_add_f32 v[34:35], v[34:35], 1.0 op_sel_hi:[1,0]
	v_pk_add_f32 v[50:51], v[50:51], 1.0 op_sel_hi:[1,0]
	v_rcp_f32_e32 v34, v34
	v_rcp_f32_e32 v35, v35
	v_rcp_f32_e32 v50, v50
	v_rcp_f32_e32 v51, v51
	v_pk_mul_f32 v[32:33], v[34:35], v[32:33]
	v_pk_add_f32 v[34:35], v[68:69], v[36:37] op_sel_hi:[0,1]
	v_pk_mul_f32 v[32:33], v[32:33], v[34:35]
	v_pk_mul_f32 v[34:35], v[50:51], v[48:49]
	v_pk_add_f32 v[36:37], v[68:69], v[38:39] op_sel_hi:[0,1]
	v_pk_mul_f32 v[34:35], v[34:35], v[36:37]
	v_cvt_pk_bf16_f32 v130, v32, v33
	s_waitcnt vmcnt(11)
	v_lshlrev_b32_e32 v36, 16, v103
	v_cvt_pk_bf16_f32 v131, v34, v35
	s_nop 1
	v_permlane32_swap_b32_e32 v128, v130
	v_permlane32_swap_b32_e32 v129, v131
	global_store_dwordx4 v[136:137], v[128:131], off offset:1088
	v_lshlrev_b32_e32 v32, 16, v102
	v_and_b32_e32 v33, 0xffff0000, v102
	v_pk_mul_f32 v[34:35], v[32:33], v[32:33]
	v_and_b32_e32 v37, 0xffff0000, v103
	v_pk_fma_f32 v[34:35], v[34:35], s[8:9], 1.0 op_sel_hi:[1,0,0]
	v_pk_mul_f32 v[38:39], v[36:37], v[36:37]
	v_pk_mul_f32 v[34:35], v[34:35], v[32:33]
	v_pk_fma_f32 v[38:39], v[38:39], s[8:9], 1.0 op_sel_hi:[1,0,0]
	v_pk_mul_f32 v[34:35], v[34:35], s[34:35] op_sel_hi:[1,0]
	v_pk_mul_f32 v[38:39], v[38:39], v[36:37]
	v_exp_f32_e32 v34, v34
	v_exp_f32_e32 v35, v35
	v_pk_mul_f32 v[38:39], v[38:39], s[34:35] op_sel_hi:[1,0]
	v_pk_add_f32 v[34:35], v[34:35], 1.0 op_sel_hi:[1,0]
	v_exp_f32_e32 v38, v38
	v_exp_f32_e32 v39, v39
	v_rcp_f32_e32 v34, v34
	v_rcp_f32_e32 v35, v35
	v_pk_add_f32 v[38:39], v[38:39], 1.0 op_sel_hi:[1,0]
	s_nop 0
	v_rcp_f32_e32 v38, v38
	v_rcp_f32_e32 v39, v39
	v_pk_mul_f32 v[32:33], v[34:35], v[32:33]
	v_pk_add_f32 v[34:35], v[68:69], v[40:41] op_sel_hi:[0,1]
	v_pk_mul_f32 v[32:33], v[32:33], v[34:35]
	v_pk_mul_f32 v[34:35], v[38:39], v[36:37]
	v_pk_add_f32 v[36:37], v[68:69], v[42:43] op_sel_hi:[0,1]
	v_pk_mul_f32 v[34:35], v[34:35], v[36:37]
	v_cvt_pk_bf16_f32 v132, v32, v33
	s_waitcnt vmcnt(11)
	v_lshlrev_b32_e32 v36, 16, v101
	v_cvt_pk_bf16_f32 v133, v34, v35
	v_lshlrev_b32_e32 v32, 16, v100
	v_and_b32_e32 v33, 0xffff0000, v100
	v_pk_mul_f32 v[34:35], v[32:33], v[32:33]
	v_and_b32_e32 v37, 0xffff0000, v101
	v_pk_fma_f32 v[34:35], v[34:35], s[8:9], 1.0 op_sel_hi:[1,0,0]
	v_pk_mul_f32 v[38:39], v[36:37], v[36:37]
	v_pk_mul_f32 v[34:35], v[34:35], v[32:33]
	v_pk_fma_f32 v[38:39], v[38:39], s[8:9], 1.0 op_sel_hi:[1,0,0]
	v_pk_mul_f32 v[34:35], v[34:35], s[34:35] op_sel_hi:[1,0]
	v_pk_mul_f32 v[38:39], v[38:39], v[36:37]
	v_exp_f32_e32 v34, v34
	v_exp_f32_e32 v35, v35
	v_pk_mul_f32 v[38:39], v[38:39], s[34:35] op_sel_hi:[1,0]
	v_pk_add_f32 v[34:35], v[34:35], 1.0 op_sel_hi:[1,0]
	v_exp_f32_e32 v38, v38
	v_exp_f32_e32 v39, v39
	v_rcp_f32_e32 v34, v34
	v_rcp_f32_e32 v35, v35
	v_pk_add_f32 v[38:39], v[38:39], 1.0 op_sel_hi:[1,0]
	s_nop 0
	v_rcp_f32_e32 v38, v38
	v_rcp_f32_e32 v39, v39
	v_pk_mul_f32 v[32:33], v[34:35], v[32:33]
	v_pk_add_f32 v[34:35], v[68:69], v[44:45] op_sel_hi:[0,1]
	v_pk_mul_f32 v[32:33], v[32:33], v[34:35]
	v_pk_mul_f32 v[34:35], v[38:39], v[36:37]
	v_pk_add_f32 v[36:37], v[68:69], v[46:47] op_sel_hi:[0,1]
	v_pk_mul_f32 v[34:35], v[34:35], v[36:37]
	v_cvt_pk_bf16_f32 v134, v32, v33
	s_waitcnt vmcnt(10)
	v_lshlrev_b32_e32 v36, 16, v99
	v_cvt_pk_bf16_f32 v135, v34, v35
	s_nop 1
	v_permlane32_swap_b32_e32 v132, v134
	v_permlane32_swap_b32_e32 v133, v135
	global_store_dwordx4 v[136:137], v[132:135], off offset:1120
	v_lshlrev_b32_e32 v32, 16, v98
	v_and_b32_e32 v33, 0xffff0000, v98
	v_pk_mul_f32 v[34:35], v[32:33], v[32:33]
	v_and_b32_e32 v37, 0xffff0000, v99
	v_pk_fma_f32 v[34:35], v[34:35], s[8:9], 1.0 op_sel_hi:[1,0,0]
	v_pk_mul_f32 v[38:39], v[36:37], v[36:37]
	v_pk_mul_f32 v[34:35], v[34:35], v[32:33]
	v_pk_fma_f32 v[38:39], v[38:39], s[8:9], 1.0 op_sel_hi:[1,0,0]
	v_pk_mul_f32 v[34:35], v[34:35], s[34:35] op_sel_hi:[1,0]
	v_pk_mul_f32 v[38:39], v[38:39], v[36:37]
	v_exp_f32_e32 v34, v34
	v_exp_f32_e32 v35, v35
	v_pk_mul_f32 v[38:39], v[38:39], s[34:35] op_sel_hi:[1,0]
	v_pk_add_f32 v[34:35], v[34:35], 1.0 op_sel_hi:[1,0]
	v_exp_f32_e32 v38, v38
	v_exp_f32_e32 v39, v39
	v_rcp_f32_e32 v34, v34
	v_rcp_f32_e32 v35, v35
	v_pk_add_f32 v[38:39], v[38:39], 1.0 op_sel_hi:[1,0]
	s_nop 0
	v_rcp_f32_e32 v38, v38
	v_rcp_f32_e32 v39, v39
	v_pk_mul_f32 v[32:33], v[34:35], v[32:33]
	s_nop 0
	v_pk_mul_f32 v[16:17], v[32:33], v[16:17]
	v_pk_mul_f32 v[32:33], v[38:39], v[36:37]
	v_cvt_pk_bf16_f32 v128, v16, v17
	s_nop 0
	v_pk_mul_f32 v[18:19], v[32:33], v[18:19]
	s_waitcnt vmcnt(10)
	v_lshlrev_b32_e32 v32, 16, v97
	v_cvt_pk_bf16_f32 v129, v18, v19
	v_lshlrev_b32_e32 v16, 16, v96
	v_and_b32_e32 v17, 0xffff0000, v96
	v_pk_mul_f32 v[18:19], v[16:17], v[16:17]
	v_and_b32_e32 v33, 0xffff0000, v97
	v_pk_fma_f32 v[18:19], v[18:19], s[8:9], 1.0 op_sel_hi:[1,0,0]
	v_pk_mul_f32 v[34:35], v[32:33], v[32:33]
	v_pk_mul_f32 v[18:19], v[18:19], v[16:17]
	v_pk_fma_f32 v[34:35], v[34:35], s[8:9], 1.0 op_sel_hi:[1,0,0]
	v_pk_mul_f32 v[18:19], v[18:19], s[34:35] op_sel_hi:[1,0]
	v_pk_mul_f32 v[34:35], v[34:35], v[32:33]
	v_exp_f32_e32 v18, v18
	v_exp_f32_e32 v19, v19
	v_pk_mul_f32 v[34:35], v[34:35], s[34:35] op_sel_hi:[1,0]
	v_pk_add_f32 v[18:19], v[18:19], 1.0 op_sel_hi:[1,0]
	v_exp_f32_e32 v34, v34
	v_exp_f32_e32 v35, v35
	v_rcp_f32_e32 v18, v18
	v_rcp_f32_e32 v19, v19
	v_pk_add_f32 v[34:35], v[34:35], 1.0 op_sel_hi:[1,0]
	s_nop 0
	v_rcp_f32_e32 v34, v34
	v_rcp_f32_e32 v35, v35
	v_pk_mul_f32 v[16:17], v[18:19], v[16:17]
	v_pk_add_f32 v[18:19], v[68:69], v[20:21] op_sel_hi:[0,1]
	v_pk_mul_f32 v[16:17], v[16:17], v[18:19]
	v_pk_mul_f32 v[18:19], v[34:35], v[32:33]
	v_pk_add_f32 v[20:21], v[68:69], v[22:23] op_sel_hi:[0,1]
	v_pk_mul_f32 v[18:19], v[18:19], v[20:21]
	v_cvt_pk_bf16_f32 v130, v16, v17
	s_waitcnt vmcnt(9)
	v_lshlrev_b32_e32 v20, 16, v95
	v_cvt_pk_bf16_f32 v131, v18, v19
	s_nop 1
	v_permlane32_swap_b32_e32 v128, v130
	v_permlane32_swap_b32_e32 v129, v131
	global_store_dwordx4 v[136:137], v[128:131], off offset:1152
	v_lshlrev_b32_e32 v16, 16, v94
	v_and_b32_e32 v17, 0xffff0000, v94
	v_pk_mul_f32 v[18:19], v[16:17], v[16:17]
	v_and_b32_e32 v21, 0xffff0000, v95
	v_pk_fma_f32 v[18:19], v[18:19], s[8:9], 1.0 op_sel_hi:[1,0,0]
	v_pk_mul_f32 v[22:23], v[20:21], v[20:21]
	v_pk_mul_f32 v[18:19], v[18:19], v[16:17]
	v_pk_fma_f32 v[22:23], v[22:23], s[8:9], 1.0 op_sel_hi:[1,0,0]
	v_pk_mul_f32 v[18:19], v[18:19], s[34:35] op_sel_hi:[1,0]
	v_pk_mul_f32 v[22:23], v[22:23], v[20:21]
	v_exp_f32_e32 v18, v18
	v_exp_f32_e32 v19, v19
	v_pk_mul_f32 v[22:23], v[22:23], s[34:35] op_sel_hi:[1,0]
	v_pk_add_f32 v[18:19], v[18:19], 1.0 op_sel_hi:[1,0]
	v_exp_f32_e32 v22, v22
	v_exp_f32_e32 v23, v23
	v_rcp_f32_e32 v18, v18
	v_rcp_f32_e32 v19, v19
	v_pk_add_f32 v[22:23], v[22:23], 1.0 op_sel_hi:[1,0]
	s_nop 0
	v_rcp_f32_e32 v22, v22
	v_rcp_f32_e32 v23, v23
	v_pk_mul_f32 v[16:17], v[18:19], v[16:17]
	v_pk_add_f32 v[18:19], v[68:69], v[24:25] op_sel_hi:[0,1]
	v_pk_mul_f32 v[16:17], v[16:17], v[18:19]
	v_pk_mul_f32 v[18:19], v[22:23], v[20:21]
	v_pk_add_f32 v[20:21], v[68:69], v[26:27] op_sel_hi:[0,1]
	v_pk_mul_f32 v[18:19], v[18:19], v[20:21]
	v_cvt_pk_bf16_f32 v132, v16, v17
	s_waitcnt vmcnt(9)
	v_lshlrev_b32_e32 v20, 16, v93
	v_cvt_pk_bf16_f32 v133, v18, v19
	v_lshlrev_b32_e32 v16, 16, v92
	v_and_b32_e32 v17, 0xffff0000, v92
	v_pk_mul_f32 v[18:19], v[16:17], v[16:17]
	v_and_b32_e32 v21, 0xffff0000, v93
	v_pk_fma_f32 v[18:19], v[18:19], s[8:9], 1.0 op_sel_hi:[1,0,0]
	v_pk_mul_f32 v[22:23], v[20:21], v[20:21]
	v_pk_mul_f32 v[18:19], v[18:19], v[16:17]
	v_pk_fma_f32 v[22:23], v[22:23], s[8:9], 1.0 op_sel_hi:[1,0,0]
	v_pk_mul_f32 v[18:19], v[18:19], s[34:35] op_sel_hi:[1,0]
	v_pk_mul_f32 v[22:23], v[22:23], v[20:21]
	v_exp_f32_e32 v18, v18
	v_exp_f32_e32 v19, v19
	v_pk_mul_f32 v[22:23], v[22:23], s[34:35] op_sel_hi:[1,0]
	v_pk_add_f32 v[18:19], v[18:19], 1.0 op_sel_hi:[1,0]
	v_exp_f32_e32 v22, v22
	v_exp_f32_e32 v23, v23
	v_rcp_f32_e32 v18, v18
	v_rcp_f32_e32 v19, v19
	v_pk_add_f32 v[22:23], v[22:23], 1.0 op_sel_hi:[1,0]
	s_nop 0
	v_rcp_f32_e32 v22, v22
	v_rcp_f32_e32 v23, v23
	v_pk_mul_f32 v[16:17], v[18:19], v[16:17]
	v_pk_add_f32 v[18:19], v[68:69], v[28:29] op_sel_hi:[0,1]
	v_pk_mul_f32 v[16:17], v[16:17], v[18:19]
	v_pk_mul_f32 v[18:19], v[22:23], v[20:21]
	v_pk_add_f32 v[20:21], v[68:69], v[30:31] op_sel_hi:[0,1]
	v_pk_mul_f32 v[18:19], v[18:19], v[20:21]
	v_cvt_pk_bf16_f32 v134, v16, v17
	s_waitcnt vmcnt(8)
	v_lshlrev_b32_e32 v20, 16, v87
	v_cvt_pk_bf16_f32 v135, v18, v19
	s_nop 1
	v_permlane32_swap_b32_e32 v132, v134
	v_permlane32_swap_b32_e32 v133, v135
	global_store_dwordx4 v[136:137], v[132:135], off offset:1184
	v_lshlrev_b32_e32 v16, 16, v86
	v_and_b32_e32 v17, 0xffff0000, v86
	v_pk_mul_f32 v[18:19], v[16:17], v[16:17]
	v_and_b32_e32 v21, 0xffff0000, v87
	v_pk_fma_f32 v[18:19], v[18:19], s[8:9], 1.0 op_sel_hi:[1,0,0]
	v_pk_mul_f32 v[22:23], v[20:21], v[20:21]
	v_pk_mul_f32 v[18:19], v[18:19], v[16:17]
	v_pk_fma_f32 v[22:23], v[22:23], s[8:9], 1.0 op_sel_hi:[1,0,0]
	v_pk_mul_f32 v[18:19], v[18:19], s[34:35] op_sel_hi:[1,0]
	v_pk_mul_f32 v[22:23], v[22:23], v[20:21]
	v_exp_f32_e32 v18, v18
	v_exp_f32_e32 v19, v19
	v_pk_mul_f32 v[22:23], v[22:23], s[34:35] op_sel_hi:[1,0]
	v_pk_add_f32 v[18:19], v[18:19], 1.0 op_sel_hi:[1,0]
	v_exp_f32_e32 v22, v22
	v_exp_f32_e32 v23, v23
	v_rcp_f32_e32 v18, v18
	v_rcp_f32_e32 v19, v19
	v_pk_add_f32 v[22:23], v[22:23], 1.0 op_sel_hi:[1,0]
	s_nop 0
	v_rcp_f32_e32 v22, v22
	v_rcp_f32_e32 v23, v23
	v_pk_mul_f32 v[16:17], v[18:19], v[16:17]
	s_nop 0
	v_pk_mul_f32 v[0:1], v[16:17], v[0:1]
	v_pk_mul_f32 v[16:17], v[22:23], v[20:21]
	v_cvt_pk_bf16_f32 v128, v0, v1
	s_nop 0
	v_pk_mul_f32 v[2:3], v[16:17], v[2:3]
	s_waitcnt vmcnt(8)
	v_lshlrev_b32_e32 v16, 16, v85
	v_cvt_pk_bf16_f32 v129, v2, v3
	v_lshlrev_b32_e32 v0, 16, v84
	v_and_b32_e32 v1, 0xffff0000, v84
	v_pk_mul_f32 v[2:3], v[0:1], v[0:1]
	v_and_b32_e32 v17, 0xffff0000, v85
	v_pk_fma_f32 v[2:3], v[2:3], s[8:9], 1.0 op_sel_hi:[1,0,0]
	v_pk_mul_f32 v[18:19], v[16:17], v[16:17]
	v_pk_mul_f32 v[2:3], v[2:3], v[0:1]
	v_pk_fma_f32 v[18:19], v[18:19], s[8:9], 1.0 op_sel_hi:[1,0,0]
	v_pk_mul_f32 v[2:3], v[2:3], s[34:35] op_sel_hi:[1,0]
	v_pk_mul_f32 v[18:19], v[18:19], v[16:17]
	v_exp_f32_e32 v2, v2
	v_exp_f32_e32 v3, v3
	v_pk_mul_f32 v[18:19], v[18:19], s[34:35] op_sel_hi:[1,0]
	v_pk_add_f32 v[2:3], v[2:3], 1.0 op_sel_hi:[1,0]
	v_exp_f32_e32 v18, v18
	v_exp_f32_e32 v19, v19
	v_rcp_f32_e32 v2, v2
	v_rcp_f32_e32 v3, v3
	v_pk_add_f32 v[18:19], v[18:19], 1.0 op_sel_hi:[1,0]
	s_nop 0
	v_rcp_f32_e32 v18, v18
	v_rcp_f32_e32 v19, v19
	v_pk_mul_f32 v[0:1], v[2:3], v[0:1]
	v_pk_add_f32 v[2:3], v[68:69], v[4:5] op_sel_hi:[0,1]
	v_pk_mul_f32 v[0:1], v[0:1], v[2:3]
	v_pk_mul_f32 v[2:3], v[18:19], v[16:17]
	v_pk_add_f32 v[4:5], v[68:69], v[6:7] op_sel_hi:[0,1]
	v_pk_mul_f32 v[2:3], v[2:3], v[4:5]
	v_cvt_pk_bf16_f32 v130, v0, v1
	s_waitcnt vmcnt(7)
	v_lshlrev_b32_e32 v4, 16, v83
	v_cvt_pk_bf16_f32 v131, v2, v3
	s_nop 1
	v_permlane32_swap_b32_e32 v128, v130
	v_permlane32_swap_b32_e32 v129, v131
	global_store_dwordx4 v[136:137], v[128:131], off offset:1216
	v_lshlrev_b32_e32 v0, 16, v82
	v_and_b32_e32 v1, 0xffff0000, v82
	v_pk_mul_f32 v[2:3], v[0:1], v[0:1]
	v_and_b32_e32 v5, 0xffff0000, v83
	v_pk_fma_f32 v[2:3], v[2:3], s[8:9], 1.0 op_sel_hi:[1,0,0]
	v_pk_mul_f32 v[6:7], v[4:5], v[4:5]
	v_pk_mul_f32 v[2:3], v[2:3], v[0:1]
	v_pk_fma_f32 v[6:7], v[6:7], s[8:9], 1.0 op_sel_hi:[1,0,0]
	v_pk_mul_f32 v[2:3], v[2:3], s[34:35] op_sel_hi:[1,0]
	v_pk_mul_f32 v[6:7], v[6:7], v[4:5]
	v_exp_f32_e32 v2, v2
	v_exp_f32_e32 v3, v3
	v_pk_mul_f32 v[6:7], v[6:7], s[34:35] op_sel_hi:[1,0]
	v_pk_add_f32 v[2:3], v[2:3], 1.0 op_sel_hi:[1,0]
	v_exp_f32_e32 v6, v6
	v_exp_f32_e32 v7, v7
	v_rcp_f32_e32 v2, v2
	v_rcp_f32_e32 v3, v3
	v_pk_add_f32 v[6:7], v[6:7], 1.0 op_sel_hi:[1,0]
	s_nop 0
	v_rcp_f32_e32 v6, v6
	v_rcp_f32_e32 v7, v7
	v_pk_mul_f32 v[0:1], v[2:3], v[0:1]
	v_pk_add_f32 v[2:3], v[68:69], v[8:9] op_sel_hi:[0,1]
	v_pk_mul_f32 v[0:1], v[0:1], v[2:3]
	v_pk_mul_f32 v[2:3], v[6:7], v[4:5]
	v_pk_add_f32 v[4:5], v[68:69], v[10:11] op_sel_hi:[0,1]
	v_pk_mul_f32 v[2:3], v[2:3], v[4:5]
	v_cvt_pk_bf16_f32 v132, v0, v1
	s_waitcnt vmcnt(7)
	v_lshlrev_b32_e32 v4, 16, v81
	v_cvt_pk_bf16_f32 v133, v2, v3
	v_lshlrev_b32_e32 v0, 16, v80
	v_and_b32_e32 v1, 0xffff0000, v80
	v_pk_mul_f32 v[2:3], v[0:1], v[0:1]
	v_and_b32_e32 v5, 0xffff0000, v81
	v_pk_fma_f32 v[2:3], v[2:3], s[8:9], 1.0 op_sel_hi:[1,0,0]
	v_pk_mul_f32 v[6:7], v[4:5], v[4:5]
	v_pk_mul_f32 v[2:3], v[2:3], v[0:1]
	v_pk_fma_f32 v[6:7], v[6:7], s[8:9], 1.0 op_sel_hi:[1,0,0]
	v_pk_mul_f32 v[2:3], v[2:3], s[34:35] op_sel_hi:[1,0]
	v_pk_mul_f32 v[6:7], v[6:7], v[4:5]
	v_exp_f32_e32 v2, v2
	v_exp_f32_e32 v3, v3
	v_pk_mul_f32 v[6:7], v[6:7], s[34:35] op_sel_hi:[1,0]
	v_cndmask_b32_e64 v10, 0, 1, s[12:13]
	v_exp_f32_e32 v6, v6
	v_exp_f32_e32 v7, v7
	v_pk_add_f32 v[2:3], v[2:3], 1.0 op_sel_hi:[1,0]
	v_cmp_ne_u32_e64 s[8:9], 1, v10
	v_rcp_f32_e32 v2, v2
	v_rcp_f32_e32 v3, v3
	v_pk_add_f32 v[6:7], v[6:7], 1.0 op_sel_hi:[1,0]
	v_pk_mul_f32 v[0:1], v[2:3], v[0:1]
	v_rcp_f32_e32 v6, v6
	v_rcp_f32_e32 v7, v7
	v_pk_add_f32 v[2:3], v[68:69], v[12:13] op_sel_hi:[0,1]
	v_pk_mul_f32 v[0:1], v[0:1], v[2:3]
	v_pk_mul_f32 v[2:3], v[6:7], v[4:5]
	v_pk_add_f32 v[4:5], v[68:69], v[14:15] op_sel_hi:[0,1]
	v_cvt_pk_bf16_f32 v134, v0, v1
	v_pk_mul_f32 v[2:3], v[2:3], v[4:5]
	s_nop 0
	v_cvt_pk_bf16_f32 v135, v2, v3
	s_nop 1
	v_permlane32_swap_b32_e32 v132, v134
	v_permlane32_swap_b32_e32 v133, v135
	global_store_dwordx4 v[136:137], v[132:135], off offset:1248
	v_mov_b32_e32 v0, 0x60
	v_bitop3_b32 v0, v124, s37, v0 bitop3:0xde
	v_lshlrev_b32_e32 v0, 9, v0
	v_mov_b32_e32 v1, v123
	v_lshl_add_u64 v[8:9], v[90:91], 0, v[0:1]
	global_load_dwordx4 v[0:3], v[8:9], off offset:16
	global_load_dwordx4 v[4:7], v[8:9], off
	global_load_dwordx4 v[112:115], v[8:9], off offset:80
	global_load_dwordx4 v[116:119], v[8:9], off offset:64
	global_load_dwordx4 v[104:107], v[8:9], off offset:144
	global_load_dwordx4 v[108:111], v[8:9], off offset:128
	global_load_dwordx4 v[96:99], v[8:9], off offset:208
	global_load_dwordx4 v[100:103], v[8:9], off offset:192
	global_load_dwordx4 v[88:91], v[8:9], off offset:272
	global_load_dwordx4 v[92:95], v[8:9], off offset:256
	global_load_dwordx4 v[80:83], v[8:9], off offset:336
	global_load_dwordx4 v[84:87], v[8:9], off offset:320
	s_cbranch_vccnz .LBB0_412
	global_load_dwordx4 v[76:79], v[8:9], off offset:384
	global_load_dwordx4 v[72:75], v[8:9], off offset:400

.LBB0_418:
	s_waitcnt vmcnt(15)
	v_lshlrev_b32_e32 v66, 16, v112
	v_and_b32_e32 v67, 0xffff0000, v112
	v_pk_mul_f32 v[70:71], v[66:67], v[66:67]
	s_mov_b32 s8, 0x3d372713
	v_lshlrev_b32_e32 v72, 16, v113
	v_and_b32_e32 v73, 0xffff0000, v113
	v_lshlrev_b64 v[64:65], 11, v[110:111]
	v_pk_fma_f32 v[70:71], v[70:71], s[8:9], 1.0 op_sel_hi:[1,0,0]
	v_pk_mul_f32 v[74:75], v[72:73], v[72:73]
	v_lshl_add_u64 v[64:65], s[10:11], 0, v[64:65]
	v_pk_mul_f32 v[70:71], v[70:71], v[66:67]
	s_mov_b32 s10, 0xc0135761
	v_pk_fma_f32 v[74:75], v[74:75], s[8:9], 1.0 op_sel_hi:[1,0,0]
	v_pk_mul_f32 v[70:71], v[70:71], s[10:11] op_sel_hi:[1,0]
	v_pk_mul_f32 v[74:75], v[74:75], v[72:73]
	v_exp_f32_e32 v70, v70
	v_exp_f32_e32 v71, v71
	v_pk_mul_f32 v[74:75], v[74:75], s[10:11] op_sel_hi:[1,0]
	v_pk_add_f32 v[48:49], v[68:69], v[48:49] op_sel_hi:[0,1]
	v_exp_f32_e32 v74, v74
	v_exp_f32_e32 v75, v75
	v_pk_add_f32 v[70:71], v[70:71], 1.0 op_sel_hi:[1,0]
	v_lshl_add_u64 v[64:65], v[64:65], 0, s[16:17]
	v_rcp_f32_e32 v70, v70
	v_rcp_f32_e32 v71, v71
	v_pk_add_f32 v[74:75], v[74:75], 1.0 op_sel_hi:[1,0]
	v_mov_b32_e32 v123, 0
	v_rcp_f32_e32 v74, v74
	v_rcp_f32_e32 v75, v75
	v_pk_mul_f32 v[66:67], v[70:71], v[66:67]
	v_pk_add_f32 v[50:51], v[68:69], v[50:51] op_sel_hi:[0,1]
	v_pk_mul_f32 v[48:49], v[66:67], v[48:49]
	v_pk_mul_f32 v[66:67], v[74:75], v[72:73]
	v_lshl_add_u64 v[64:65], v[64:65], 0, v[122:123]
	v_bfe_u32 v138, v224, 5, 1
	v_lshlrev_b32_e32 v138, 3, v138
	v_mov_b32_e32 v139, 0
	v_lshl_add_u64 v[136:137], v[64:65], 0, v[138:139]
	v_pk_mul_f32 v[50:51], v[66:67], v[50:51]
	v_cvt_pk_bf16_f32 v128, v48, v49
	s_waitcnt vmcnt(14)
	v_lshlrev_b32_e32 v66, 16, v109
	v_cvt_pk_bf16_f32 v129, v50, v51
	v_lshlrev_b32_e32 v48, 16, v108
	v_and_b32_e32 v49, 0xffff0000, v108
	v_pk_mul_f32 v[50:51], v[48:49], v[48:49]
	v_and_b32_e32 v67, 0xffff0000, v109
	v_pk_fma_f32 v[50:51], v[50:51], s[8:9], 1.0 op_sel_hi:[1,0,0]
	v_pk_mul_f32 v[70:71], v[66:67], v[66:67]
	v_pk_mul_f32 v[50:51], v[50:51], v[48:49]
	v_pk_fma_f32 v[70:71], v[70:71], s[8:9], 1.0 op_sel_hi:[1,0,0]
	v_pk_mul_f32 v[50:51], v[50:51], s[10:11] op_sel_hi:[1,0]
	v_pk_mul_f32 v[70:71], v[70:71], v[66:67]
	v_exp_f32_e32 v50, v50
	v_exp_f32_e32 v51, v51
	v_pk_mul_f32 v[70:71], v[70:71], s[10:11] op_sel_hi:[1,0]
	v_pk_add_f32 v[32:33], v[68:69], v[32:33] op_sel_hi:[0,1]
	v_exp_f32_e32 v70, v70
	v_exp_f32_e32 v71, v71
	v_pk_add_f32 v[50:51], v[50:51], 1.0 op_sel_hi:[1,0]
	v_pk_add_f32 v[34:35], v[68:69], v[34:35] op_sel_hi:[0,1]
	v_rcp_f32_e32 v50, v50
	v_rcp_f32_e32 v51, v51
	v_pk_add_f32 v[70:71], v[70:71], 1.0 op_sel_hi:[1,0]
	v_pk_add_f32 v[16:17], v[68:69], v[16:17] op_sel_hi:[0,1]
	v_rcp_f32_e32 v70, v70
	v_rcp_f32_e32 v71, v71
	v_pk_mul_f32 v[48:49], v[50:51], v[48:49]
	v_pk_add_f32 v[50:51], v[68:69], v[52:53] op_sel_hi:[0,1]
	v_pk_mul_f32 v[48:49], v[48:49], v[50:51]
	v_pk_mul_f32 v[50:51], v[70:71], v[66:67]
	v_pk_add_f32 v[52:53], v[68:69], v[54:55] op_sel_hi:[0,1]
	v_pk_mul_f32 v[50:51], v[50:51], v[52:53]
	v_cvt_pk_bf16_f32 v130, v48, v49
	s_waitcnt vmcnt(13)
	v_lshlrev_b32_e32 v52, 16, v107
	v_cvt_pk_bf16_f32 v131, v50, v51
	s_nop 1
	v_permlane32_swap_b32_e32 v128, v130
	v_permlane32_swap_b32_e32 v129, v131
	global_store_dwordx4 v[136:137], v[128:131], off offset:1024
	v_lshlrev_b32_e32 v48, 16, v106
	v_and_b32_e32 v49, 0xffff0000, v106
	v_pk_mul_f32 v[50:51], v[48:49], v[48:49]
	v_and_b32_e32 v53, 0xffff0000, v107
	v_pk_fma_f32 v[50:51], v[50:51], s[8:9], 1.0 op_sel_hi:[1,0,0]
	v_pk_mul_f32 v[54:55], v[52:53], v[52:53]
	v_pk_mul_f32 v[50:51], v[50:51], v[48:49]
	v_pk_fma_f32 v[54:55], v[54:55], s[8:9], 1.0 op_sel_hi:[1,0,0]
	v_pk_mul_f32 v[50:51], v[50:51], s[10:11] op_sel_hi:[1,0]
	v_pk_mul_f32 v[54:55], v[54:55], v[52:53]
	v_exp_f32_e32 v50, v50
	v_exp_f32_e32 v51, v51
	v_pk_mul_f32 v[54:55], v[54:55], s[10:11] op_sel_hi:[1,0]
	v_pk_add_f32 v[18:19], v[68:69], v[18:19] op_sel_hi:[0,1]
	v_exp_f32_e32 v54, v54
	v_exp_f32_e32 v55, v55
	v_pk_add_f32 v[50:51], v[50:51], 1.0 op_sel_hi:[1,0]
	v_pk_add_f32 v[0:1], v[68:69], v[0:1] op_sel_hi:[0,1]
	v_rcp_f32_e32 v50, v50
	v_rcp_f32_e32 v51, v51
	v_pk_add_f32 v[54:55], v[54:55], 1.0 op_sel_hi:[1,0]
	v_pk_add_f32 v[2:3], v[68:69], v[2:3] op_sel_hi:[0,1]
	v_rcp_f32_e32 v54, v54
	v_rcp_f32_e32 v55, v55
	v_pk_mul_f32 v[48:49], v[50:51], v[48:49]
	v_pk_add_f32 v[50:51], v[68:69], v[56:57] op_sel_hi:[0,1]
	v_pk_mul_f32 v[48:49], v[48:49], v[50:51]
	v_pk_mul_f32 v[50:51], v[54:55], v[52:53]
	v_pk_add_f32 v[52:53], v[68:69], v[58:59] op_sel_hi:[0,1]
	v_pk_mul_f32 v[50:51], v[50:51], v[52:53]
	v_cvt_pk_bf16_f32 v132, v48, v49
	s_waitcnt vmcnt(13)
	v_lshlrev_b32_e32 v52, 16, v105
	v_cvt_pk_bf16_f32 v133, v50, v51
	v_lshlrev_b32_e32 v48, 16, v104
	v_and_b32_e32 v49, 0xffff0000, v104
	v_pk_mul_f32 v[50:51], v[48:49], v[48:49]
	v_and_b32_e32 v53, 0xffff0000, v105
	v_pk_fma_f32 v[50:51], v[50:51], s[8:9], 1.0 op_sel_hi:[1,0,0]
	v_pk_mul_f32 v[54:55], v[52:53], v[52:53]
	v_pk_mul_f32 v[50:51], v[50:51], v[48:49]
	v_pk_fma_f32 v[54:55], v[54:55], s[8:9], 1.0 op_sel_hi:[1,0,0]
	v_pk_mul_f32 v[50:51], v[50:51], s[10:11] op_sel_hi:[1,0]
	v_pk_mul_f32 v[54:55], v[54:55], v[52:53]
	v_exp_f32_e32 v50, v50
	v_exp_f32_e32 v51, v51
	v_pk_mul_f32 v[54:55], v[54:55], s[10:11] op_sel_hi:[1,0]
	v_pk_add_f32 v[50:51], v[50:51], 1.0 op_sel_hi:[1,0]
	v_exp_f32_e32 v54, v54
	v_exp_f32_e32 v55, v55
	v_rcp_f32_e32 v50, v50
	v_rcp_f32_e32 v51, v51
	v_pk_add_f32 v[54:55], v[54:55], 1.0 op_sel_hi:[1,0]
	s_nop 0
	v_rcp_f32_e32 v54, v54
	v_rcp_f32_e32 v55, v55
	v_pk_mul_f32 v[48:49], v[50:51], v[48:49]
	v_pk_add_f32 v[50:51], v[68:69], v[60:61] op_sel_hi:[0,1]
	v_pk_mul_f32 v[48:49], v[48:49], v[50:51]
	v_pk_mul_f32 v[50:51], v[54:55], v[52:53]
	v_pk_add_f32 v[52:53], v[68:69], v[62:63] op_sel_hi:[0,1]
	v_pk_mul_f32 v[50:51], v[50:51], v[52:53]
	v_cvt_pk_bf16_f32 v134, v48, v49
	s_waitcnt vmcnt(12)
	v_lshlrev_b32_e32 v52, 16, v103
	v_cvt_pk_bf16_f32 v135, v50, v51
	s_nop 1
	v_permlane32_swap_b32_e32 v132, v134
	v_permlane32_swap_b32_e32 v133, v135
	global_store_dwordx4 v[136:137], v[132:135], off offset:1056
	v_lshlrev_b32_e32 v48, 16, v102
	v_and_b32_e32 v49, 0xffff0000, v102
	v_pk_mul_f32 v[50:51], v[48:49], v[48:49]
	v_and_b32_e32 v53, 0xffff0000, v103
	v_pk_fma_f32 v[50:51], v[50:51], s[8:9], 1.0 op_sel_hi:[1,0,0]
	v_pk_mul_f32 v[54:55], v[52:53], v[52:53]
	v_pk_mul_f32 v[50:51], v[50:51], v[48:49]
	v_pk_fma_f32 v[54:55], v[54:55], s[8:9], 1.0 op_sel_hi:[1,0,0]
	v_pk_mul_f32 v[50:51], v[50:51], s[10:11] op_sel_hi:[1,0]
	v_pk_mul_f32 v[54:55], v[54:55], v[52:53]
	v_exp_f32_e32 v50, v50
	v_exp_f32_e32 v51, v51
	v_pk_mul_f32 v[54:55], v[54:55], s[10:11] op_sel_hi:[1,0]
	v_pk_add_f32 v[50:51], v[50:51], 1.0 op_sel_hi:[1,0]
	v_exp_f32_e32 v54, v54
	v_exp_f32_e32 v55, v55
	v_rcp_f32_e32 v50, v50
	v_rcp_f32_e32 v51, v51
	v_pk_add_f32 v[54:55], v[54:55], 1.0 op_sel_hi:[1,0]
	s_nop 0
	v_rcp_f32_e32 v54, v54
	v_rcp_f32_e32 v55, v55
	v_pk_mul_f32 v[48:49], v[50:51], v[48:49]
	s_nop 0
	v_pk_mul_f32 v[32:33], v[48:49], v[32:33]
	v_pk_mul_f32 v[48:49], v[54:55], v[52:53]
	v_cvt_pk_bf16_f32 v128, v32, v33
	s_nop 0
	v_pk_mul_f32 v[34:35], v[48:49], v[34:35]
	s_waitcnt vmcnt(12)
	v_lshlrev_b32_e32 v48, 16, v101
	v_cvt_pk_bf16_f32 v129, v34, v35
	v_lshlrev_b32_e32 v32, 16, v100
	v_and_b32_e32 v33, 0xffff0000, v100
	v_pk_mul_f32 v[34:35], v[32:33], v[32:33]
	v_and_b32_e32 v49, 0xffff0000, v101
	v_pk_fma_f32 v[34:35], v[34:35], s[8:9], 1.0 op_sel_hi:[1,0,0]
	v_pk_mul_f32 v[50:51], v[48:49], v[48:49]
	v_pk_mul_f32 v[34:35], v[34:35], v[32:33]
	v_pk_fma_f32 v[50:51], v[50:51], s[8:9], 1.0 op_sel_hi:[1,0,0]
	v_pk_mul_f32 v[34:35], v[34:35], s[10:11] op_sel_hi:[1,0]
	v_pk_mul_f32 v[50:51], v[50:51], v[48:49]
	v_exp_f32_e32 v34, v34
	v_exp_f32_e32 v35, v35
	v_pk_mul_f32 v[50:51], v[50:51], s[10:11] op_sel_hi:[1,0]
	v_pk_add_f32 v[34:35], v[34:35], 1.0 op_sel_hi:[1,0]
	v_exp_f32_e32 v50, v50
	v_exp_f32_e32 v51, v51
	v_rcp_f32_e32 v34, v34
	v_rcp_f32_e32 v35, v35
	v_pk_add_f32 v[50:51], v[50:51], 1.0 op_sel_hi:[1,0]
	s_nop 0
	v_rcp_f32_e32 v50, v50
	v_rcp_f32_e32 v51, v51
	v_pk_mul_f32 v[32:33], v[34:35], v[32:33]
	v_pk_add_f32 v[34:35], v[68:69], v[36:37] op_sel_hi:[0,1]
	v_pk_mul_f32 v[32:33], v[32:33], v[34:35]
	v_pk_mul_f32 v[34:35], v[50:51], v[48:49]
	v_pk_add_f32 v[36:37], v[68:69], v[38:39] op_sel_hi:[0,1]
	v_pk_mul_f32 v[34:35], v[34:35], v[36:37]
	v_cvt_pk_bf16_f32 v130, v32, v33
	s_waitcnt vmcnt(11)
	v_lshlrev_b32_e32 v36, 16, v99
	v_cvt_pk_bf16_f32 v131, v34, v35
	s_nop 1
	v_permlane32_swap_b32_e32 v128, v130
	v_permlane32_swap_b32_e32 v129, v131
	global_store_dwordx4 v[136:137], v[128:131], off offset:1088
	v_lshlrev_b32_e32 v32, 16, v98
	v_and_b32_e32 v33, 0xffff0000, v98
	v_pk_mul_f32 v[34:35], v[32:33], v[32:33]
	v_and_b32_e32 v37, 0xffff0000, v99
	v_pk_fma_f32 v[34:35], v[34:35], s[8:9], 1.0 op_sel_hi:[1,0,0]
	v_pk_mul_f32 v[38:39], v[36:37], v[36:37]
	v_pk_mul_f32 v[34:35], v[34:35], v[32:33]
	v_pk_fma_f32 v[38:39], v[38:39], s[8:9], 1.0 op_sel_hi:[1,0,0]
	v_pk_mul_f32 v[34:35], v[34:35], s[10:11] op_sel_hi:[1,0]
	v_pk_mul_f32 v[38:39], v[38:39], v[36:37]
	v_exp_f32_e32 v34, v34
	v_exp_f32_e32 v35, v35
	v_pk_mul_f32 v[38:39], v[38:39], s[10:11] op_sel_hi:[1,0]
	v_pk_add_f32 v[34:35], v[34:35], 1.0 op_sel_hi:[1,0]
	v_exp_f32_e32 v38, v38
	v_exp_f32_e32 v39, v39
	v_rcp_f32_e32 v34, v34
	v_rcp_f32_e32 v35, v35
	v_pk_add_f32 v[38:39], v[38:39], 1.0 op_sel_hi:[1,0]
	s_nop 0
	v_rcp_f32_e32 v38, v38
	v_rcp_f32_e32 v39, v39
	v_pk_mul_f32 v[32:33], v[34:35], v[32:33]
	v_pk_add_f32 v[34:35], v[68:69], v[40:41] op_sel_hi:[0,1]
	v_pk_mul_f32 v[32:33], v[32:33], v[34:35]
	v_pk_mul_f32 v[34:35], v[38:39], v[36:37]
	v_pk_add_f32 v[36:37], v[68:69], v[42:43] op_sel_hi:[0,1]
	v_pk_mul_f32 v[34:35], v[34:35], v[36:37]
	v_cvt_pk_bf16_f32 v132, v32, v33
	s_waitcnt vmcnt(11)
	v_lshlrev_b32_e32 v36, 16, v97
	v_cvt_pk_bf16_f32 v133, v34, v35
	v_lshlrev_b32_e32 v32, 16, v96
	v_and_b32_e32 v33, 0xffff0000, v96
	v_pk_mul_f32 v[34:35], v[32:33], v[32:33]
	v_and_b32_e32 v37, 0xffff0000, v97
	v_pk_fma_f32 v[34:35], v[34:35], s[8:9], 1.0 op_sel_hi:[1,0,0]
	v_pk_mul_f32 v[38:39], v[36:37], v[36:37]
	v_pk_mul_f32 v[34:35], v[34:35], v[32:33]
	v_pk_fma_f32 v[38:39], v[38:39], s[8:9], 1.0 op_sel_hi:[1,0,0]
	v_pk_mul_f32 v[34:35], v[34:35], s[10:11] op_sel_hi:[1,0]
	v_pk_mul_f32 v[38:39], v[38:39], v[36:37]
	v_exp_f32_e32 v34, v34
	v_exp_f32_e32 v35, v35
	v_pk_mul_f32 v[38:39], v[38:39], s[10:11] op_sel_hi:[1,0]
	v_pk_add_f32 v[34:35], v[34:35], 1.0 op_sel_hi:[1,0]
	v_exp_f32_e32 v38, v38
	v_exp_f32_e32 v39, v39
	v_rcp_f32_e32 v34, v34
	v_rcp_f32_e32 v35, v35
	v_pk_add_f32 v[38:39], v[38:39], 1.0 op_sel_hi:[1,0]
	s_nop 0
	v_rcp_f32_e32 v38, v38
	v_rcp_f32_e32 v39, v39
	v_pk_mul_f32 v[32:33], v[34:35], v[32:33]
	v_pk_add_f32 v[34:35], v[68:69], v[44:45] op_sel_hi:[0,1]
	v_pk_mul_f32 v[32:33], v[32:33], v[34:35]
	v_pk_mul_f32 v[34:35], v[38:39], v[36:37]
	v_pk_add_f32 v[36:37], v[68:69], v[46:47] op_sel_hi:[0,1]
	v_pk_mul_f32 v[34:35], v[34:35], v[36:37]
	v_cvt_pk_bf16_f32 v134, v32, v33
	s_waitcnt vmcnt(10)
	v_lshlrev_b32_e32 v36, 16, v95
	v_cvt_pk_bf16_f32 v135, v34, v35
	s_nop 1
	v_permlane32_swap_b32_e32 v132, v134
	v_permlane32_swap_b32_e32 v133, v135
	global_store_dwordx4 v[136:137], v[132:135], off offset:1120
	v_lshlrev_b32_e32 v32, 16, v94
	v_and_b32_e32 v33, 0xffff0000, v94
	v_pk_mul_f32 v[34:35], v[32:33], v[32:33]
	v_and_b32_e32 v37, 0xffff0000, v95
	v_pk_fma_f32 v[34:35], v[34:35], s[8:9], 1.0 op_sel_hi:[1,0,0]
	v_pk_mul_f32 v[38:39], v[36:37], v[36:37]
	v_pk_mul_f32 v[34:35], v[34:35], v[32:33]
	v_pk_fma_f32 v[38:39], v[38:39], s[8:9], 1.0 op_sel_hi:[1,0,0]
	v_pk_mul_f32 v[34:35], v[34:35], s[10:11] op_sel_hi:[1,0]
	v_pk_mul_f32 v[38:39], v[38:39], v[36:37]
	v_exp_f32_e32 v34, v34
	v_exp_f32_e32 v35, v35
	v_pk_mul_f32 v[38:39], v[38:39], s[10:11] op_sel_hi:[1,0]
	v_pk_add_f32 v[34:35], v[34:35], 1.0 op_sel_hi:[1,0]
	v_exp_f32_e32 v38, v38
	v_exp_f32_e32 v39, v39
	v_rcp_f32_e32 v34, v34
	v_rcp_f32_e32 v35, v35
	v_pk_add_f32 v[38:39], v[38:39], 1.0 op_sel_hi:[1,0]
	s_nop 0
	v_rcp_f32_e32 v38, v38
	v_rcp_f32_e32 v39, v39
	v_pk_mul_f32 v[32:33], v[34:35], v[32:33]
	s_nop 0
	v_pk_mul_f32 v[16:17], v[32:33], v[16:17]
	v_pk_mul_f32 v[32:33], v[38:39], v[36:37]
	v_cvt_pk_bf16_f32 v128, v16, v17
	s_nop 0
	v_pk_mul_f32 v[18:19], v[32:33], v[18:19]
	s_waitcnt vmcnt(10)
	v_lshlrev_b32_e32 v32, 16, v93
	v_cvt_pk_bf16_f32 v129, v18, v19
	v_lshlrev_b32_e32 v16, 16, v92
	v_and_b32_e32 v17, 0xffff0000, v92
	v_pk_mul_f32 v[18:19], v[16:17], v[16:17]
	v_and_b32_e32 v33, 0xffff0000, v93
	v_pk_fma_f32 v[18:19], v[18:19], s[8:9], 1.0 op_sel_hi:[1,0,0]
	v_pk_mul_f32 v[34:35], v[32:33], v[32:33]
	v_pk_mul_f32 v[18:19], v[18:19], v[16:17]
	v_pk_fma_f32 v[34:35], v[34:35], s[8:9], 1.0 op_sel_hi:[1,0,0]
	v_pk_mul_f32 v[18:19], v[18:19], s[10:11] op_sel_hi:[1,0]
	v_pk_mul_f32 v[34:35], v[34:35], v[32:33]
	v_exp_f32_e32 v18, v18
	v_exp_f32_e32 v19, v19
	v_pk_mul_f32 v[34:35], v[34:35], s[10:11] op_sel_hi:[1,0]
	v_pk_add_f32 v[18:19], v[18:19], 1.0 op_sel_hi:[1,0]
	v_exp_f32_e32 v34, v34
	v_exp_f32_e32 v35, v35
	v_rcp_f32_e32 v18, v18
	v_rcp_f32_e32 v19, v19
	v_pk_add_f32 v[34:35], v[34:35], 1.0 op_sel_hi:[1,0]
	s_nop 0
	v_rcp_f32_e32 v34, v34
	v_rcp_f32_e32 v35, v35
	v_pk_mul_f32 v[16:17], v[18:19], v[16:17]
	v_pk_add_f32 v[18:19], v[68:69], v[20:21] op_sel_hi:[0,1]
	v_pk_mul_f32 v[16:17], v[16:17], v[18:19]
	v_pk_mul_f32 v[18:19], v[34:35], v[32:33]
	v_pk_add_f32 v[20:21], v[68:69], v[22:23] op_sel_hi:[0,1]
	v_pk_mul_f32 v[18:19], v[18:19], v[20:21]
	v_cvt_pk_bf16_f32 v130, v16, v17
	s_waitcnt vmcnt(9)
	v_lshlrev_b32_e32 v20, 16, v91
	v_cvt_pk_bf16_f32 v131, v18, v19
	s_nop 1
	v_permlane32_swap_b32_e32 v128, v130
	v_permlane32_swap_b32_e32 v129, v131
	global_store_dwordx4 v[136:137], v[128:131], off offset:1152
	v_lshlrev_b32_e32 v16, 16, v90
	v_and_b32_e32 v17, 0xffff0000, v90
	v_pk_mul_f32 v[18:19], v[16:17], v[16:17]
	v_and_b32_e32 v21, 0xffff0000, v91
	v_pk_fma_f32 v[18:19], v[18:19], s[8:9], 1.0 op_sel_hi:[1,0,0]
	v_pk_mul_f32 v[22:23], v[20:21], v[20:21]
	v_pk_mul_f32 v[18:19], v[18:19], v[16:17]
	v_pk_fma_f32 v[22:23], v[22:23], s[8:9], 1.0 op_sel_hi:[1,0,0]
	v_pk_mul_f32 v[18:19], v[18:19], s[10:11] op_sel_hi:[1,0]
	v_pk_mul_f32 v[22:23], v[22:23], v[20:21]
	v_exp_f32_e32 v18, v18
	v_exp_f32_e32 v19, v19
	v_pk_mul_f32 v[22:23], v[22:23], s[10:11] op_sel_hi:[1,0]
	v_pk_add_f32 v[18:19], v[18:19], 1.0 op_sel_hi:[1,0]
	v_exp_f32_e32 v22, v22
	v_exp_f32_e32 v23, v23
	v_rcp_f32_e32 v18, v18
	v_rcp_f32_e32 v19, v19
	v_pk_add_f32 v[22:23], v[22:23], 1.0 op_sel_hi:[1,0]
	s_nop 0
	v_rcp_f32_e32 v22, v22
	v_rcp_f32_e32 v23, v23
	v_pk_mul_f32 v[16:17], v[18:19], v[16:17]
	v_pk_add_f32 v[18:19], v[68:69], v[24:25] op_sel_hi:[0,1]
	v_pk_mul_f32 v[16:17], v[16:17], v[18:19]
	v_pk_mul_f32 v[18:19], v[22:23], v[20:21]
	v_pk_add_f32 v[20:21], v[68:69], v[26:27] op_sel_hi:[0,1]
	v_pk_mul_f32 v[18:19], v[18:19], v[20:21]
	v_cvt_pk_bf16_f32 v132, v16, v17
	s_waitcnt vmcnt(9)
	v_lshlrev_b32_e32 v20, 16, v89
	v_cvt_pk_bf16_f32 v133, v18, v19
	v_lshlrev_b32_e32 v16, 16, v88
	v_and_b32_e32 v17, 0xffff0000, v88
	v_pk_mul_f32 v[18:19], v[16:17], v[16:17]
	v_and_b32_e32 v21, 0xffff0000, v89
	v_pk_fma_f32 v[18:19], v[18:19], s[8:9], 1.0 op_sel_hi:[1,0,0]
	v_pk_mul_f32 v[22:23], v[20:21], v[20:21]
	v_pk_mul_f32 v[18:19], v[18:19], v[16:17]
	v_pk_fma_f32 v[22:23], v[22:23], s[8:9], 1.0 op_sel_hi:[1,0,0]
	v_pk_mul_f32 v[18:19], v[18:19], s[10:11] op_sel_hi:[1,0]
	v_pk_mul_f32 v[22:23], v[22:23], v[20:21]
	v_exp_f32_e32 v18, v18
	v_exp_f32_e32 v19, v19
	v_pk_mul_f32 v[22:23], v[22:23], s[10:11] op_sel_hi:[1,0]
	v_pk_add_f32 v[18:19], v[18:19], 1.0 op_sel_hi:[1,0]
	v_exp_f32_e32 v22, v22
	v_exp_f32_e32 v23, v23
	v_rcp_f32_e32 v18, v18
	v_rcp_f32_e32 v19, v19
	v_pk_add_f32 v[22:23], v[22:23], 1.0 op_sel_hi:[1,0]
	s_nop 0
	v_rcp_f32_e32 v22, v22
	v_rcp_f32_e32 v23, v23
	v_pk_mul_f32 v[16:17], v[18:19], v[16:17]
	v_pk_add_f32 v[18:19], v[68:69], v[28:29] op_sel_hi:[0,1]
	v_pk_mul_f32 v[16:17], v[16:17], v[18:19]
	v_pk_mul_f32 v[18:19], v[22:23], v[20:21]
	v_pk_add_f32 v[20:21], v[68:69], v[30:31] op_sel_hi:[0,1]
	v_pk_mul_f32 v[18:19], v[18:19], v[20:21]
	v_cvt_pk_bf16_f32 v134, v16, v17
	s_waitcnt vmcnt(8)
	v_lshlrev_b32_e32 v20, 16, v87
	v_cvt_pk_bf16_f32 v135, v18, v19
	s_nop 1
	v_permlane32_swap_b32_e32 v132, v134
	v_permlane32_swap_b32_e32 v133, v135
	global_store_dwordx4 v[136:137], v[132:135], off offset:1184
	v_lshlrev_b32_e32 v16, 16, v86
	v_and_b32_e32 v17, 0xffff0000, v86
	v_pk_mul_f32 v[18:19], v[16:17], v[16:17]
	v_and_b32_e32 v21, 0xffff0000, v87
	v_pk_fma_f32 v[18:19], v[18:19], s[8:9], 1.0 op_sel_hi:[1,0,0]
	v_pk_mul_f32 v[22:23], v[20:21], v[20:21]
	v_pk_mul_f32 v[18:19], v[18:19], v[16:17]
	v_pk_fma_f32 v[22:23], v[22:23], s[8:9], 1.0 op_sel_hi:[1,0,0]
	v_pk_mul_f32 v[18:19], v[18:19], s[10:11] op_sel_hi:[1,0]
	v_pk_mul_f32 v[22:23], v[22:23], v[20:21]
	v_exp_f32_e32 v18, v18
	v_exp_f32_e32 v19, v19
	v_pk_mul_f32 v[22:23], v[22:23], s[10:11] op_sel_hi:[1,0]
	v_pk_add_f32 v[18:19], v[18:19], 1.0 op_sel_hi:[1,0]
	v_exp_f32_e32 v22, v22
	v_exp_f32_e32 v23, v23
	v_rcp_f32_e32 v18, v18
	v_rcp_f32_e32 v19, v19
	v_pk_add_f32 v[22:23], v[22:23], 1.0 op_sel_hi:[1,0]
	s_nop 0
	v_rcp_f32_e32 v22, v22
	v_rcp_f32_e32 v23, v23
	v_pk_mul_f32 v[16:17], v[18:19], v[16:17]
	s_nop 0
	v_pk_mul_f32 v[0:1], v[16:17], v[0:1]
	v_pk_mul_f32 v[16:17], v[22:23], v[20:21]
	v_cvt_pk_bf16_f32 v128, v0, v1
	s_nop 0
	v_pk_mul_f32 v[2:3], v[16:17], v[2:3]
	s_waitcnt vmcnt(8)
	v_lshlrev_b32_e32 v16, 16, v85
	v_cvt_pk_bf16_f32 v129, v2, v3
	v_lshlrev_b32_e32 v0, 16, v84
	v_and_b32_e32 v1, 0xffff0000, v84
	v_pk_mul_f32 v[2:3], v[0:1], v[0:1]
	v_and_b32_e32 v17, 0xffff0000, v85
	v_pk_fma_f32 v[2:3], v[2:3], s[8:9], 1.0 op_sel_hi:[1,0,0]
	v_pk_mul_f32 v[18:19], v[16:17], v[16:17]
	v_pk_mul_f32 v[2:3], v[2:3], v[0:1]
	v_pk_fma_f32 v[18:19], v[18:19], s[8:9], 1.0 op_sel_hi:[1,0,0]
	v_pk_mul_f32 v[2:3], v[2:3], s[10:11] op_sel_hi:[1,0]
	v_pk_mul_f32 v[18:19], v[18:19], v[16:17]
	v_exp_f32_e32 v2, v2
	v_exp_f32_e32 v3, v3
	v_pk_mul_f32 v[18:19], v[18:19], s[10:11] op_sel_hi:[1,0]
	v_pk_add_f32 v[2:3], v[2:3], 1.0 op_sel_hi:[1,0]
	v_exp_f32_e32 v18, v18
	v_exp_f32_e32 v19, v19
	v_rcp_f32_e32 v2, v2
	v_rcp_f32_e32 v3, v3
	v_pk_add_f32 v[18:19], v[18:19], 1.0 op_sel_hi:[1,0]
	s_nop 0
	v_rcp_f32_e32 v18, v18
	v_rcp_f32_e32 v19, v19
	v_pk_mul_f32 v[0:1], v[2:3], v[0:1]
	v_pk_add_f32 v[2:3], v[68:69], v[4:5] op_sel_hi:[0,1]
	v_pk_mul_f32 v[0:1], v[0:1], v[2:3]
	v_pk_mul_f32 v[2:3], v[18:19], v[16:17]
	v_pk_add_f32 v[4:5], v[68:69], v[6:7] op_sel_hi:[0,1]
	v_pk_mul_f32 v[2:3], v[2:3], v[4:5]
	v_cvt_pk_bf16_f32 v130, v0, v1
	s_waitcnt vmcnt(7)
	v_lshlrev_b32_e32 v4, 16, v83
	v_cvt_pk_bf16_f32 v131, v2, v3
	s_nop 1
	v_permlane32_swap_b32_e32 v128, v130
	v_permlane32_swap_b32_e32 v129, v131
	global_store_dwordx4 v[136:137], v[128:131], off offset:1216
	v_lshlrev_b32_e32 v0, 16, v82
	v_and_b32_e32 v1, 0xffff0000, v82
	v_pk_mul_f32 v[2:3], v[0:1], v[0:1]
	v_and_b32_e32 v5, 0xffff0000, v83
	v_pk_fma_f32 v[2:3], v[2:3], s[8:9], 1.0 op_sel_hi:[1,0,0]
	v_pk_mul_f32 v[6:7], v[4:5], v[4:5]
	v_pk_mul_f32 v[2:3], v[2:3], v[0:1]
	v_pk_fma_f32 v[6:7], v[6:7], s[8:9], 1.0 op_sel_hi:[1,0,0]
	v_pk_mul_f32 v[2:3], v[2:3], s[10:11] op_sel_hi:[1,0]
	v_pk_mul_f32 v[6:7], v[6:7], v[4:5]
	v_exp_f32_e32 v2, v2
	v_exp_f32_e32 v3, v3
	v_pk_mul_f32 v[6:7], v[6:7], s[10:11] op_sel_hi:[1,0]
	v_pk_add_f32 v[2:3], v[2:3], 1.0 op_sel_hi:[1,0]
	v_exp_f32_e32 v6, v6
	v_exp_f32_e32 v7, v7
	v_rcp_f32_e32 v2, v2
	v_rcp_f32_e32 v3, v3
	v_pk_add_f32 v[6:7], v[6:7], 1.0 op_sel_hi:[1,0]
	s_nop 0
	v_rcp_f32_e32 v6, v6
	v_rcp_f32_e32 v7, v7
	v_pk_mul_f32 v[0:1], v[2:3], v[0:1]
	v_pk_add_f32 v[2:3], v[68:69], v[8:9] op_sel_hi:[0,1]
	v_pk_mul_f32 v[0:1], v[0:1], v[2:3]
	v_pk_mul_f32 v[2:3], v[6:7], v[4:5]
	v_pk_add_f32 v[4:5], v[68:69], v[10:11] op_sel_hi:[0,1]
	v_pk_mul_f32 v[2:3], v[2:3], v[4:5]
	v_cvt_pk_bf16_f32 v132, v0, v1
	s_waitcnt vmcnt(7)
	v_lshlrev_b32_e32 v4, 16, v81
	v_cvt_pk_bf16_f32 v133, v2, v3
	v_lshlrev_b32_e32 v0, 16, v80
	v_and_b32_e32 v1, 0xffff0000, v80
	v_pk_mul_f32 v[2:3], v[0:1], v[0:1]
	v_and_b32_e32 v5, 0xffff0000, v81
	v_pk_fma_f32 v[2:3], v[2:3], s[8:9], 1.0 op_sel_hi:[1,0,0]
	v_pk_mul_f32 v[6:7], v[4:5], v[4:5]
	v_pk_mul_f32 v[2:3], v[2:3], v[0:1]
	v_pk_fma_f32 v[6:7], v[6:7], s[8:9], 1.0 op_sel_hi:[1,0,0]
	v_pk_mul_f32 v[2:3], v[2:3], s[10:11] op_sel_hi:[1,0]
	v_pk_mul_f32 v[6:7], v[6:7], v[4:5]
	v_exp_f32_e32 v2, v2
	v_exp_f32_e32 v3, v3
	v_pk_mul_f32 v[6:7], v[6:7], s[10:11] op_sel_hi:[1,0]
	v_pk_add_f32 v[2:3], v[2:3], 1.0 op_sel_hi:[1,0]
	v_exp_f32_e32 v6, v6
	v_exp_f32_e32 v7, v7
	v_rcp_f32_e32 v2, v2
	v_rcp_f32_e32 v3, v3
	v_pk_add_f32 v[6:7], v[6:7], 1.0 op_sel_hi:[1,0]
	s_nop 0
	v_rcp_f32_e32 v6, v6
	v_rcp_f32_e32 v7, v7
	v_pk_mul_f32 v[0:1], v[2:3], v[0:1]
	v_pk_add_f32 v[2:3], v[68:69], v[12:13] op_sel_hi:[0,1]
	v_pk_mul_f32 v[0:1], v[0:1], v[2:3]
	v_pk_mul_f32 v[2:3], v[6:7], v[4:5]
	v_pk_add_f32 v[4:5], v[68:69], v[14:15] op_sel_hi:[0,1]
	v_pk_mul_f32 v[2:3], v[2:3], v[4:5]
	v_cvt_pk_bf16_f32 v134, v0, v1
	s_nop 0
	v_cvt_pk_bf16_f32 v135, v2, v3
	s_nop 1
	v_permlane32_swap_b32_e32 v132, v134
	v_permlane32_swap_b32_e32 v133, v135
	global_store_dwordx4 v[136:137], v[132:135], off offset:1248
	s_barrier

.LBB0_1272:
	s_or_b64 exec, exec, s[10:11]
	v_mov_b32_e32 v108, v224
	s_load_dwordx4 s[12:15], s[38:39], 0x40
	s_and_b32 s16, s64, 3
	s_lshl_b32 s16, s16, 9
	v_lshlrev_b32_e32 v0, 3, v224
	v_add_u32_e32 v0, s16, v0
	v_lshlrev_b32_e32 v1, 4, v224
	v_add_u32_e32 v1, 0x22800, v1
	v_cmp_gt_u32_e32 vcc, 64, v224
	s_and_saveexec_b64 s[18:19], vcc
	s_waitcnt lgkmcnt(0)
	global_load_dwordx2 v[2:3], v0, s[12:13] offset:2048
	global_load_dwordx2 v[4:5], v0, s[14:15] offset:2048
	s_waitcnt vmcnt(0)
	ds_write_b128 v1, v[2:5]
	s_waitcnt lgkmcnt(0)
	s_or_b64 exec, exec, s[18:19]
	s_waitcnt vmcnt(0)
	s_barrier
	s_load_dwordx8 s[12:19], s[38:39], 0x40
	v_mov_b32_e32 v255, 0x22800
	s_movk_i32 s10, 0x80
	v_readfirstlane_b32 s11, v108
	s_ashr_i32 s45, s11, 7
	s_cmp_eq_u32 s45, 2
	s_cselect_b32 s10, s10, 0x100
	s_cmp_lg_u32 s45, 1
	s_cselect_b32 s10, s10, 0
	s_cmpk_gt_u32 s11, 0x7f
	s_cselect_b32 s10, s10, 0xffffff80
	s_add_i32 s10, s10, s64
	s_mov_b32 s39, 0
	s_lshr_b32 s38, s10, 2
	v_and_b32_e32 v109, 0x7f, v108
	s_lshl_b64 s[40:41], s[38:39], 7
	v_or_b32_e32 v2, s40, v109
	s_movk_i32 s10, 0x1400
	v_mov_b64_e32 v[0:1], s[20:21]
	v_mad_u64_u32 v[0:1], s[22:23], v2, s10, v[0:1]
	s_lshl_b32 s10, s64, 7
	v_mov_b32_e32 v2, 0x1400
	s_and_b32 s43, s10, 0x180
	v_mad_u32_u24 v1, s41, v2, v1
	s_lshl_b32 s38, s43, 1
	v_lshl_add_u64 v[4:5], v[0:1], 0, s[38:39]
	s_movk_i32 s10, 0x1000
	v_add_co_u32_e32 v0, vcc, s10, v4
	s_mov_b32 s42, 0x3d372713
	s_nop 0
	v_addc_co_u32_e32 v1, vcc, 0, v5, vcc
	global_load_dwordx4 v[0:3], v[0:1], off
	s_mov_b32 s10, 0xc0135761
	s_mov_b64 s[22:23], 0x1000
	v_lshl_add_u64 v[4:5], v[4:5], 0, s[22:23]
	global_load_dwordx4 v[172:175], v[4:5], off offset:16
	global_load_dwordx4 v[176:179], v[4:5], off offset:32
	global_load_dwordx4 v[180:183], v[4:5], off offset:48
	global_load_dwordx4 v[184:187], v[4:5], off offset:64
	global_load_dwordx4 v[188:191], v[4:5], off offset:80
	global_load_dwordx4 v[192:195], v[4:5], off offset:96
	global_load_dwordx4 v[196:199], v[4:5], off offset:112
	global_load_dwordx4 v[200:203], v[4:5], off offset:128
	global_load_dwordx4 v[204:207], v[4:5], off offset:144
	global_load_dwordx4 v[208:211], v[4:5], off offset:160
	global_load_dwordx4 v[212:215], v[4:5], off offset:176
	global_load_dwordx4 v[216:219], v[4:5], off offset:192
	global_load_dwordx4 v[220:223], v[4:5], off offset:208
	global_load_dwordx4 v[228:231], v[4:5], off offset:224
	global_load_dwordx4 v[232:235], v[4:5], off offset:240
	s_lshl_b32 s22, s43, 2
	s_brev_b32 s44, 60
	s_waitcnt vmcnt(15)
	v_lshlrev_b32_e32 v6, 16, v0
	v_and_b32_e32 v7, 0xffff0000, v0
	v_lshlrev_b32_e32 v0, 16, v1
	v_and_b32_e32 v1, 0xffff0000, v1
	v_lshlrev_b32_e32 v8, 16, v2
	v_and_b32_e32 v9, 0xffff0000, v2
	v_lshlrev_b32_e32 v2, 16, v3
	v_and_b32_e32 v3, 0xffff0000, v3
	v_pk_mul_f32 v[10:11], v[6:7], v[6:7]
	v_pk_mul_f32 v[12:13], v[0:1], v[0:1]
	v_pk_mul_f32 v[14:15], v[8:9], v[8:9]
	v_pk_mul_f32 v[16:17], v[2:3], v[2:3]
	v_pk_fma_f32 v[10:11], v[10:11], s[42:43], 1.0 op_sel_hi:[1,0,0]
	v_pk_fma_f32 v[12:13], v[12:13], s[42:43], 1.0 op_sel_hi:[1,0,0]
	v_pk_fma_f32 v[14:15], v[14:15], s[42:43], 1.0 op_sel_hi:[1,0,0]
	v_pk_fma_f32 v[16:17], v[16:17], s[42:43], 1.0 op_sel_hi:[1,0,0]
	v_pk_mul_f32 v[10:11], v[10:11], v[6:7]
	v_pk_mul_f32 v[12:13], v[12:13], v[0:1]
	v_pk_mul_f32 v[14:15], v[14:15], v[8:9]
	v_pk_mul_f32 v[16:17], v[16:17], v[2:3]
	v_pk_mul_f32 v[10:11], v[10:11], s[10:11] op_sel_hi:[1,0]
	v_pk_mul_f32 v[12:13], v[12:13], s[10:11] op_sel_hi:[1,0]
	v_pk_mul_f32 v[14:15], v[14:15], s[10:11] op_sel_hi:[1,0]
	v_pk_mul_f32 v[16:17], v[16:17], s[10:11] op_sel_hi:[1,0]
	v_exp_f32_e32 v10, v10
	v_exp_f32_e32 v11, v11
	v_exp_f32_e32 v12, v12
	v_exp_f32_e32 v13, v13
	v_exp_f32_e32 v14, v14
	v_exp_f32_e32 v15, v15
	v_exp_f32_e32 v16, v16
	v_exp_f32_e32 v17, v17
	v_pk_add_f32 v[10:11], v[10:11], 1.0 op_sel_hi:[1,0]
	v_pk_add_f32 v[12:13], v[12:13], 1.0 op_sel_hi:[1,0]
	v_pk_add_f32 v[18:19], v[14:15], 1.0 op_sel_hi:[1,0]
	v_pk_add_f32 v[16:17], v[16:17], 1.0 op_sel_hi:[1,0]
	v_rcp_f32_e32 v14, v10
	v_rcp_f32_e32 v15, v11
	v_rcp_f32_e32 v10, v12
	v_rcp_f32_e32 v11, v13
	v_rcp_f32_e32 v12, v18
	v_rcp_f32_e32 v13, v19
	v_rcp_f32_e32 v18, v16
	v_rcp_f32_e32 v19, v17
	v_pk_mul_f32 v[16:17], v[14:15], v[6:7]
	v_pk_mul_f32 v[10:11], v[10:11], v[0:1]
	v_pk_mul_f32 v[8:9], v[12:13], v[8:9]
	v_pk_mul_f32 v[12:13], v[18:19], v[2:3]
	v_cvt_pk_bf16_f32 v114, v16, v17
	v_cvt_pk_bf16_f32 v112, v10, v11
	v_cvt_pk_bf16_f32 v111, v8, v9
	v_pk_fma_f32 v[6:7], v[14:15], v[6:7], v[16:17] op_sel_hi:[1,1,0]
	v_cvt_pk_bf16_f32 v110, v12, v13
	v_pk_mul_f32 v[14:15], v[16:17], v[16:17]
	v_pk_mul_f32 v[16:17], v[10:11], v[10:11]
	v_mov_b32_e32 v165, v10
	v_mov_b32_e32 v164, v14
	v_mov_b32_e32 v10, v15
	v_mov_b32_e32 v6, v16
	v_mov_b32_e32 v167, v8
	v_pk_add_f32 v[10:11], v[164:165], v[10:11]
	v_pk_mul_f32 v[162:163], v[12:13], v[12:13]
	v_mov_b32_e32 v169, v12
	v_mov_b32_e32 v168, v162
	v_mov_b32_e32 v12, v163
	v_pk_add_f32 v[12:13], v[168:169], v[12:13]
	s_waitcnt vmcnt(14)
	v_mov_b32_e32 v0, v172
	v_mov_b32_e32 v1, v173
	v_mov_b32_e32 v2, v174
	v_mov_b32_e32 v3, v175
	v_lshlrev_b32_e32 v18, 16, v0
	v_and_b32_e32 v19, 0xffff0000, v0
	v_lshlrev_b32_e32 v0, 16, v1
	v_and_b32_e32 v1, 0xffff0000, v1
	v_lshlrev_b32_e32 v24, 16, v2
	v_and_b32_e32 v25, 0xffff0000, v2
	v_lshlrev_b32_e32 v2, 16, v3
	v_and_b32_e32 v3, 0xffff0000, v3
	v_pk_mul_f32 v[20:21], v[18:19], v[18:19]
	v_pk_mul_f32 v[22:23], v[0:1], v[0:1]
	v_pk_mul_f32 v[26:27], v[24:25], v[24:25]
	v_pk_mul_f32 v[28:29], v[2:3], v[2:3]
	v_pk_fma_f32 v[20:21], v[20:21], s[42:43], 1.0 op_sel_hi:[1,0,0]
	v_pk_fma_f32 v[22:23], v[22:23], s[42:43], 1.0 op_sel_hi:[1,0,0]
	v_pk_fma_f32 v[26:27], v[26:27], s[42:43], 1.0 op_sel_hi:[1,0,0]
	v_pk_fma_f32 v[28:29], v[28:29], s[42:43], 1.0 op_sel_hi:[1,0,0]
	v_pk_mul_f32 v[20:21], v[20:21], v[18:19]
	v_pk_mul_f32 v[22:23], v[22:23], v[0:1]
	v_pk_mul_f32 v[26:27], v[26:27], v[24:25]
	v_pk_mul_f32 v[28:29], v[28:29], v[2:3]
	v_pk_mul_f32 v[20:21], v[20:21], s[10:11] op_sel_hi:[1,0]
	v_pk_mul_f32 v[22:23], v[22:23], s[10:11] op_sel_hi:[1,0]
	v_pk_mul_f32 v[26:27], v[26:27], s[10:11] op_sel_hi:[1,0]
	v_pk_mul_f32 v[28:29], v[28:29], s[10:11] op_sel_hi:[1,0]
	v_exp_f32_e32 v20, v20
	v_exp_f32_e32 v21, v21
	v_exp_f32_e32 v22, v22
	v_exp_f32_e32 v23, v23
	v_exp_f32_e32 v26, v26
	v_exp_f32_e32 v27, v27
	v_exp_f32_e32 v28, v28
	v_exp_f32_e32 v29, v29
	v_pk_add_f32 v[20:21], v[20:21], 1.0 op_sel_hi:[1,0]
	v_pk_add_f32 v[22:23], v[22:23], 1.0 op_sel_hi:[1,0]
	v_pk_add_f32 v[26:27], v[26:27], 1.0 op_sel_hi:[1,0]
	v_pk_add_f32 v[28:29], v[28:29], 1.0 op_sel_hi:[1,0]
	v_rcp_f32_e32 v20, v20
	v_rcp_f32_e32 v21, v21
	v_rcp_f32_e32 v30, v22
	v_rcp_f32_e32 v31, v23
	v_rcp_f32_e32 v26, v26
	v_rcp_f32_e32 v27, v27
	v_rcp_f32_e32 v28, v28
	v_rcp_f32_e32 v29, v29
	v_pk_mul_f32 v[22:23], v[20:21], v[18:19]
	v_pk_mul_f32 v[20:21], v[30:31], v[0:1]
	v_pk_mul_f32 v[18:19], v[26:27], v[24:25]
	v_pk_mul_f32 v[24:25], v[28:29], v[2:3]
	v_cvt_pk_bf16_f32 v117, v22, v23
	v_cvt_pk_bf16_f32 v116, v20, v21
	v_cvt_pk_bf16_f32 v115, v18, v19
	v_mov_b32_e32 v163, v18
	v_cvt_pk_bf16_f32 v113, v24, v25
	v_pk_mul_f32 v[14:15], v[24:25], v[24:25]
	v_mov_b32_e32 v165, v24
	v_mov_b32_e32 v164, v14
	v_mov_b32_e32 v24, v15
	v_pk_add_f32 v[14:15], v[164:165], v[24:25]
	s_waitcnt vmcnt(13)
	v_mov_b32_e32 v0, v176
	v_mov_b32_e32 v1, v177
	v_mov_b32_e32 v2, v178
	v_mov_b32_e32 v3, v179
	v_lshlrev_b32_e32 v26, 16, v0
	v_and_b32_e32 v27, 0xffff0000, v0
	v_lshlrev_b32_e32 v0, 16, v1
	v_and_b32_e32 v1, 0xffff0000, v1
	v_lshlrev_b32_e32 v32, 16, v2
	v_and_b32_e32 v33, 0xffff0000, v2
	v_lshlrev_b32_e32 v2, 16, v3
	v_and_b32_e32 v3, 0xffff0000, v3
	v_pk_mul_f32 v[28:29], v[26:27], v[26:27]
	v_pk_mul_f32 v[30:31], v[0:1], v[0:1]
	v_pk_mul_f32 v[34:35], v[32:33], v[32:33]
	v_pk_mul_f32 v[36:37], v[2:3], v[2:3]
	v_pk_fma_f32 v[28:29], v[28:29], s[42:43], 1.0 op_sel_hi:[1,0,0]
	v_pk_fma_f32 v[30:31], v[30:31], s[42:43], 1.0 op_sel_hi:[1,0,0]
	v_pk_fma_f32 v[34:35], v[34:35], s[42:43], 1.0 op_sel_hi:[1,0,0]
	v_pk_fma_f32 v[36:37], v[36:37], s[42:43], 1.0 op_sel_hi:[1,0,0]
	v_pk_mul_f32 v[28:29], v[28:29], v[26:27]
	v_pk_mul_f32 v[30:31], v[30:31], v[0:1]
	v_pk_mul_f32 v[34:35], v[34:35], v[32:33]
	v_pk_mul_f32 v[36:37], v[36:37], v[2:3]
	v_pk_mul_f32 v[28:29], v[28:29], s[10:11] op_sel_hi:[1,0]
	v_pk_mul_f32 v[30:31], v[30:31], s[10:11] op_sel_hi:[1,0]
	v_pk_mul_f32 v[34:35], v[34:35], s[10:11] op_sel_hi:[1,0]
	v_pk_mul_f32 v[36:37], v[36:37], s[10:11] op_sel_hi:[1,0]
	v_exp_f32_e32 v28, v28
	v_exp_f32_e32 v29, v29
	v_exp_f32_e32 v30, v30
	v_exp_f32_e32 v31, v31
	v_exp_f32_e32 v34, v34
	v_exp_f32_e32 v35, v35
	v_exp_f32_e32 v36, v36
	v_exp_f32_e32 v37, v37
	v_pk_add_f32 v[28:29], v[28:29], 1.0 op_sel_hi:[1,0]
	v_pk_add_f32 v[30:31], v[30:31], 1.0 op_sel_hi:[1,0]
	v_pk_add_f32 v[34:35], v[34:35], 1.0 op_sel_hi:[1,0]
	v_pk_add_f32 v[36:37], v[36:37], 1.0 op_sel_hi:[1,0]
	v_rcp_f32_e32 v28, v28
	v_rcp_f32_e32 v29, v29
	v_rcp_f32_e32 v38, v30
	v_rcp_f32_e32 v39, v31
	v_rcp_f32_e32 v34, v34
	v_rcp_f32_e32 v35, v35
	v_rcp_f32_e32 v36, v36
	v_rcp_f32_e32 v37, v37
	v_pk_mul_f32 v[30:31], v[28:29], v[26:27]
	v_pk_mul_f32 v[28:29], v[38:39], v[0:1]
	v_pk_mul_f32 v[26:27], v[34:35], v[32:33]
	v_pk_mul_f32 v[32:33], v[36:37], v[2:3]
	v_cvt_pk_bf16_f32 v122, v30, v31
	v_cvt_pk_bf16_f32 v120, v28, v29
	v_cvt_pk_bf16_f32 v119, v26, v27
	s_nop 0
	v_cvt_pk_bf16_f32 v118, v32, v33
	s_waitcnt vmcnt(12)
	v_mov_b32_e32 v0, v180
	v_mov_b32_e32 v1, v181
	v_mov_b32_e32 v2, v182
	v_mov_b32_e32 v3, v183
	v_lshlrev_b32_e32 v34, 16, v0
	v_and_b32_e32 v35, 0xffff0000, v0
	v_lshlrev_b32_e32 v0, 16, v1
	v_and_b32_e32 v1, 0xffff0000, v1
	v_lshlrev_b32_e32 v40, 16, v2
	v_and_b32_e32 v41, 0xffff0000, v2
	v_lshlrev_b32_e32 v2, 16, v3
	v_and_b32_e32 v3, 0xffff0000, v3
	v_pk_mul_f32 v[36:37], v[34:35], v[34:35]
	v_pk_mul_f32 v[38:39], v[0:1], v[0:1]
	v_pk_mul_f32 v[42:43], v[40:41], v[40:41]
	v_pk_mul_f32 v[44:45], v[2:3], v[2:3]
	v_pk_fma_f32 v[36:37], v[36:37], s[42:43], 1.0 op_sel_hi:[1,0,0]
	v_pk_fma_f32 v[38:39], v[38:39], s[42:43], 1.0 op_sel_hi:[1,0,0]
	v_pk_fma_f32 v[42:43], v[42:43], s[42:43], 1.0 op_sel_hi:[1,0,0]
	v_pk_fma_f32 v[44:45], v[44:45], s[42:43], 1.0 op_sel_hi:[1,0,0]
	v_pk_mul_f32 v[36:37], v[36:37], v[34:35]
	v_pk_mul_f32 v[38:39], v[38:39], v[0:1]
	v_pk_mul_f32 v[42:43], v[42:43], v[40:41]
	v_pk_mul_f32 v[44:45], v[44:45], v[2:3]
	v_pk_mul_f32 v[36:37], v[36:37], s[10:11] op_sel_hi:[1,0]
	v_pk_mul_f32 v[38:39], v[38:39], s[10:11] op_sel_hi:[1,0]
	v_pk_mul_f32 v[42:43], v[42:43], s[10:11] op_sel_hi:[1,0]
	v_pk_mul_f32 v[44:45], v[44:45], s[10:11] op_sel_hi:[1,0]
	v_exp_f32_e32 v36, v36
	v_exp_f32_e32 v37, v37
	v_exp_f32_e32 v38, v38
	v_exp_f32_e32 v39, v39
	v_exp_f32_e32 v42, v42
	v_exp_f32_e32 v43, v43
	v_exp_f32_e32 v44, v44
	v_exp_f32_e32 v45, v45
	v_pk_add_f32 v[36:37], v[36:37], 1.0 op_sel_hi:[1,0]
	v_pk_add_f32 v[38:39], v[38:39], 1.0 op_sel_hi:[1,0]
	v_pk_add_f32 v[42:43], v[42:43], 1.0 op_sel_hi:[1,0]
	v_pk_add_f32 v[44:45], v[44:45], 1.0 op_sel_hi:[1,0]
	v_rcp_f32_e32 v36, v36
	v_rcp_f32_e32 v37, v37
	v_rcp_f32_e32 v46, v38
	v_rcp_f32_e32 v47, v39
	v_rcp_f32_e32 v42, v42
	v_rcp_f32_e32 v43, v43
	v_rcp_f32_e32 v44, v44
	v_rcp_f32_e32 v45, v45
	v_pk_mul_f32 v[38:39], v[36:37], v[34:35]
	v_pk_mul_f32 v[36:37], v[46:47], v[0:1]
	v_pk_mul_f32 v[34:35], v[42:43], v[40:41]
	v_pk_mul_f32 v[40:41], v[44:45], v[2:3]
	v_cvt_pk_bf16_f32 v126, v38, v39
	v_cvt_pk_bf16_f32 v124, v36, v37
	v_cvt_pk_bf16_f32 v123, v34, v35
	v_pk_mul_f32 v[24:25], v[36:37], v[36:37]
	v_cvt_pk_bf16_f32 v121, v40, v41
	s_waitcnt vmcnt(11)
	v_mov_b32_e32 v0, v184
	v_mov_b32_e32 v1, v185
	v_mov_b32_e32 v2, v186
	v_mov_b32_e32 v3, v187
	v_lshlrev_b32_e32 v42, 16, v0
	v_and_b32_e32 v43, 0xffff0000, v0
	v_lshlrev_b32_e32 v0, 16, v1
	v_and_b32_e32 v1, 0xffff0000, v1
	v_lshlrev_b32_e32 v48, 16, v2
	v_and_b32_e32 v49, 0xffff0000, v2
	v_lshlrev_b32_e32 v2, 16, v3
	v_and_b32_e32 v3, 0xffff0000, v3
	v_pk_mul_f32 v[44:45], v[42:43], v[42:43]
	v_pk_mul_f32 v[46:47], v[0:1], v[0:1]
	v_pk_mul_f32 v[50:51], v[48:49], v[48:49]
	v_pk_mul_f32 v[52:53], v[2:3], v[2:3]
	v_pk_fma_f32 v[44:45], v[44:45], s[42:43], 1.0 op_sel_hi:[1,0,0]
	v_pk_fma_f32 v[46:47], v[46:47], s[42:43], 1.0 op_sel_hi:[1,0,0]
	v_pk_fma_f32 v[50:51], v[50:51], s[42:43], 1.0 op_sel_hi:[1,0,0]
	v_pk_fma_f32 v[52:53], v[52:53], s[42:43], 1.0 op_sel_hi:[1,0,0]
	v_pk_mul_f32 v[44:45], v[44:45], v[42:43]
	v_pk_mul_f32 v[46:47], v[46:47], v[0:1]
	v_pk_mul_f32 v[50:51], v[50:51], v[48:49]
	v_pk_mul_f32 v[52:53], v[52:53], v[2:3]
	v_pk_mul_f32 v[44:45], v[44:45], s[10:11] op_sel_hi:[1,0]
	v_pk_mul_f32 v[46:47], v[46:47], s[10:11] op_sel_hi:[1,0]
	v_pk_mul_f32 v[50:51], v[50:51], s[10:11] op_sel_hi:[1,0]
	v_pk_mul_f32 v[52:53], v[52:53], s[10:11] op_sel_hi:[1,0]
	v_exp_f32_e32 v44, v44
	v_exp_f32_e32 v45, v45
	v_exp_f32_e32 v46, v46
	v_exp_f32_e32 v47, v47
	v_exp_f32_e32 v50, v50
	v_exp_f32_e32 v51, v51
	v_exp_f32_e32 v52, v52
	v_exp_f32_e32 v53, v53
	v_pk_add_f32 v[44:45], v[44:45], 1.0 op_sel_hi:[1,0]
	v_pk_add_f32 v[46:47], v[46:47], 1.0 op_sel_hi:[1,0]
	v_pk_add_f32 v[50:51], v[50:51], 1.0 op_sel_hi:[1,0]
	v_pk_add_f32 v[52:53], v[52:53], 1.0 op_sel_hi:[1,0]
	v_rcp_f32_e32 v44, v44
	v_rcp_f32_e32 v45, v45
	v_rcp_f32_e32 v54, v46
	v_rcp_f32_e32 v55, v47
	v_rcp_f32_e32 v50, v50
	v_rcp_f32_e32 v51, v51
	v_rcp_f32_e32 v52, v52
	v_rcp_f32_e32 v53, v53
	v_pk_mul_f32 v[46:47], v[44:45], v[42:43]
	v_pk_mul_f32 v[44:45], v[54:55], v[0:1]
	v_pk_mul_f32 v[42:43], v[50:51], v[48:49]
	v_pk_mul_f32 v[48:49], v[52:53], v[2:3]
	v_cvt_pk_bf16_f32 v129, v46, v47
	v_cvt_pk_bf16_f32 v128, v44, v45
	v_cvt_pk_bf16_f32 v127, v42, v43
	s_nop 0
	v_cvt_pk_bf16_f32 v125, v48, v49
	s_waitcnt vmcnt(10)
	v_mov_b32_e32 v0, v188
	v_mov_b32_e32 v1, v189
	v_mov_b32_e32 v2, v190
	v_mov_b32_e32 v3, v191
	v_lshlrev_b32_e32 v50, 16, v0
	v_and_b32_e32 v51, 0xffff0000, v0
	v_lshlrev_b32_e32 v0, 16, v1
	v_and_b32_e32 v1, 0xffff0000, v1
	v_lshlrev_b32_e32 v56, 16, v2
	v_and_b32_e32 v57, 0xffff0000, v2
	v_lshlrev_b32_e32 v2, 16, v3
	v_and_b32_e32 v3, 0xffff0000, v3
	v_pk_mul_f32 v[52:53], v[50:51], v[50:51]
	v_pk_mul_f32 v[54:55], v[0:1], v[0:1]
	v_pk_mul_f32 v[58:59], v[56:57], v[56:57]
	v_pk_mul_f32 v[60:61], v[2:3], v[2:3]
	v_pk_fma_f32 v[52:53], v[52:53], s[42:43], 1.0 op_sel_hi:[1,0,0]
	v_pk_fma_f32 v[54:55], v[54:55], s[42:43], 1.0 op_sel_hi:[1,0,0]
	v_pk_fma_f32 v[58:59], v[58:59], s[42:43], 1.0 op_sel_hi:[1,0,0]
	v_pk_fma_f32 v[60:61], v[60:61], s[42:43], 1.0 op_sel_hi:[1,0,0]
	v_pk_mul_f32 v[52:53], v[52:53], v[50:51]
	v_pk_mul_f32 v[54:55], v[54:55], v[0:1]
	v_pk_mul_f32 v[58:59], v[58:59], v[56:57]
	v_pk_mul_f32 v[60:61], v[60:61], v[2:3]
	v_pk_mul_f32 v[52:53], v[52:53], s[10:11] op_sel_hi:[1,0]
	v_pk_mul_f32 v[54:55], v[54:55], s[10:11] op_sel_hi:[1,0]
	v_pk_mul_f32 v[58:59], v[58:59], s[10:11] op_sel_hi:[1,0]
	v_pk_mul_f32 v[60:61], v[60:61], s[10:11] op_sel_hi:[1,0]
	v_exp_f32_e32 v52, v52
	v_exp_f32_e32 v53, v53
	v_exp_f32_e32 v54, v54
	v_exp_f32_e32 v55, v55
	v_exp_f32_e32 v58, v58
	v_exp_f32_e32 v59, v59
	v_exp_f32_e32 v60, v60
	v_exp_f32_e32 v61, v61
	v_pk_add_f32 v[52:53], v[52:53], 1.0 op_sel_hi:[1,0]
	v_pk_add_f32 v[54:55], v[54:55], 1.0 op_sel_hi:[1,0]
	v_pk_add_f32 v[58:59], v[58:59], 1.0 op_sel_hi:[1,0]
	v_pk_add_f32 v[60:61], v[60:61], 1.0 op_sel_hi:[1,0]
	v_rcp_f32_e32 v52, v52
	v_rcp_f32_e32 v53, v53
	v_rcp_f32_e32 v62, v54
	v_rcp_f32_e32 v63, v55
	v_rcp_f32_e32 v58, v58
	v_rcp_f32_e32 v59, v59
	v_rcp_f32_e32 v60, v60
	v_rcp_f32_e32 v61, v61
	v_pk_mul_f32 v[54:55], v[52:53], v[50:51]
	v_pk_mul_f32 v[52:53], v[62:63], v[0:1]
	v_pk_mul_f32 v[50:51], v[58:59], v[56:57]
	v_pk_mul_f32 v[56:57], v[60:61], v[2:3]
	v_cvt_pk_bf16_f32 v134, v54, v55
	v_cvt_pk_bf16_f32 v132, v52, v53
	v_cvt_pk_bf16_f32 v131, v50, v51
	s_nop 0
	v_cvt_pk_bf16_f32 v130, v56, v57
	s_waitcnt vmcnt(9)
	v_mov_b32_e32 v0, v192
	v_mov_b32_e32 v1, v193
	v_mov_b32_e32 v2, v194
	v_mov_b32_e32 v3, v195
	v_lshlrev_b32_e32 v58, 16, v0
	v_and_b32_e32 v59, 0xffff0000, v0
	v_lshlrev_b32_e32 v0, 16, v1
	v_and_b32_e32 v1, 0xffff0000, v1
	v_lshlrev_b32_e32 v64, 16, v2
	v_and_b32_e32 v65, 0xffff0000, v2
	v_lshlrev_b32_e32 v2, 16, v3
	v_and_b32_e32 v3, 0xffff0000, v3
	v_pk_mul_f32 v[60:61], v[58:59], v[58:59]
	v_pk_mul_f32 v[62:63], v[0:1], v[0:1]
	v_pk_mul_f32 v[66:67], v[64:65], v[64:65]
	v_pk_mul_f32 v[68:69], v[2:3], v[2:3]
	v_pk_fma_f32 v[60:61], v[60:61], s[42:43], 1.0 op_sel_hi:[1,0,0]
	v_pk_fma_f32 v[62:63], v[62:63], s[42:43], 1.0 op_sel_hi:[1,0,0]
	v_pk_fma_f32 v[66:67], v[66:67], s[42:43], 1.0 op_sel_hi:[1,0,0]
	v_pk_fma_f32 v[68:69], v[68:69], s[42:43], 1.0 op_sel_hi:[1,0,0]
	v_pk_mul_f32 v[60:61], v[60:61], v[58:59]
	v_pk_mul_f32 v[62:63], v[62:63], v[0:1]
	v_pk_mul_f32 v[66:67], v[66:67], v[64:65]
	v_pk_mul_f32 v[68:69], v[68:69], v[2:3]
	v_pk_mul_f32 v[60:61], v[60:61], s[10:11] op_sel_hi:[1,0]
	v_pk_mul_f32 v[62:63], v[62:63], s[10:11] op_sel_hi:[1,0]
	v_pk_mul_f32 v[66:67], v[66:67], s[10:11] op_sel_hi:[1,0]
	v_pk_mul_f32 v[68:69], v[68:69], s[10:11] op_sel_hi:[1,0]
	v_exp_f32_e32 v60, v60
	v_exp_f32_e32 v61, v61
	v_exp_f32_e32 v62, v62
	v_exp_f32_e32 v63, v63
	v_exp_f32_e32 v66, v66
	v_exp_f32_e32 v67, v67
	v_exp_f32_e32 v68, v68
	v_exp_f32_e32 v69, v69
	v_pk_add_f32 v[60:61], v[60:61], 1.0 op_sel_hi:[1,0]
	v_pk_add_f32 v[62:63], v[62:63], 1.0 op_sel_hi:[1,0]
	v_pk_add_f32 v[66:67], v[66:67], 1.0 op_sel_hi:[1,0]
	v_pk_add_f32 v[68:69], v[68:69], 1.0 op_sel_hi:[1,0]
	v_rcp_f32_e32 v60, v60
	v_rcp_f32_e32 v61, v61
	v_rcp_f32_e32 v70, v62
	v_rcp_f32_e32 v71, v63
	v_rcp_f32_e32 v66, v66
	v_rcp_f32_e32 v67, v67
	v_rcp_f32_e32 v68, v68
	v_rcp_f32_e32 v69, v69
	v_pk_mul_f32 v[62:63], v[60:61], v[58:59]
	v_pk_mul_f32 v[60:61], v[70:71], v[0:1]
	v_pk_mul_f32 v[58:59], v[66:67], v[64:65]
	v_pk_mul_f32 v[64:65], v[68:69], v[2:3]
	v_cvt_pk_bf16_f32 v137, v62, v63
	v_cvt_pk_bf16_f32 v136, v60, v61
	v_cvt_pk_bf16_f32 v135, v58, v59
	s_nop 0
	v_cvt_pk_bf16_f32 v133, v64, v65
	s_waitcnt vmcnt(8)
	v_mov_b32_e32 v0, v196
	v_mov_b32_e32 v1, v197
	v_mov_b32_e32 v2, v198
	v_mov_b32_e32 v3, v199
	v_lshlrev_b32_e32 v66, 16, v0
	v_and_b32_e32 v67, 0xffff0000, v0
	v_lshlrev_b32_e32 v0, 16, v1
	v_and_b32_e32 v1, 0xffff0000, v1
	v_lshlrev_b32_e32 v72, 16, v2
	v_and_b32_e32 v73, 0xffff0000, v2
	v_lshlrev_b32_e32 v2, 16, v3
	v_and_b32_e32 v3, 0xffff0000, v3
	v_pk_mul_f32 v[68:69], v[66:67], v[66:67]
	v_pk_mul_f32 v[70:71], v[0:1], v[0:1]
	v_pk_mul_f32 v[74:75], v[72:73], v[72:73]
	v_pk_mul_f32 v[76:77], v[2:3], v[2:3]
	v_pk_fma_f32 v[68:69], v[68:69], s[42:43], 1.0 op_sel_hi:[1,0,0]
	v_pk_fma_f32 v[70:71], v[70:71], s[42:43], 1.0 op_sel_hi:[1,0,0]
	v_pk_fma_f32 v[74:75], v[74:75], s[42:43], 1.0 op_sel_hi:[1,0,0]
	v_pk_fma_f32 v[76:77], v[76:77], s[42:43], 1.0 op_sel_hi:[1,0,0]
	v_pk_mul_f32 v[68:69], v[68:69], v[66:67]
	v_pk_mul_f32 v[70:71], v[70:71], v[0:1]
	v_pk_mul_f32 v[74:75], v[74:75], v[72:73]
	v_pk_mul_f32 v[76:77], v[76:77], v[2:3]
	v_pk_mul_f32 v[68:69], v[68:69], s[10:11] op_sel_hi:[1,0]
	v_pk_mul_f32 v[70:71], v[70:71], s[10:11] op_sel_hi:[1,0]
	v_pk_mul_f32 v[74:75], v[74:75], s[10:11] op_sel_hi:[1,0]
	v_pk_mul_f32 v[76:77], v[76:77], s[10:11] op_sel_hi:[1,0]
	v_exp_f32_e32 v68, v68
	v_exp_f32_e32 v69, v69
	v_exp_f32_e32 v70, v70
	v_exp_f32_e32 v71, v71
	v_exp_f32_e32 v74, v74
	v_exp_f32_e32 v75, v75
	v_exp_f32_e32 v76, v76
	v_exp_f32_e32 v77, v77
	v_pk_add_f32 v[68:69], v[68:69], 1.0 op_sel_hi:[1,0]
	v_pk_add_f32 v[70:71], v[70:71], 1.0 op_sel_hi:[1,0]
	v_pk_add_f32 v[74:75], v[74:75], 1.0 op_sel_hi:[1,0]
	v_pk_add_f32 v[76:77], v[76:77], 1.0 op_sel_hi:[1,0]
	v_rcp_f32_e32 v68, v68
	v_rcp_f32_e32 v69, v69
	v_rcp_f32_e32 v78, v70
	v_rcp_f32_e32 v79, v71
	v_rcp_f32_e32 v74, v74
	v_rcp_f32_e32 v75, v75
	v_rcp_f32_e32 v76, v76
	v_rcp_f32_e32 v77, v77
	v_pk_mul_f32 v[70:71], v[68:69], v[66:67]
	v_pk_mul_f32 v[68:69], v[78:79], v[0:1]
	v_pk_mul_f32 v[66:67], v[74:75], v[72:73]
	v_pk_mul_f32 v[72:73], v[76:77], v[2:3]
	v_cvt_pk_bf16_f32 v142, v70, v71
	v_cvt_pk_bf16_f32 v140, v68, v69
	v_cvt_pk_bf16_f32 v139, v66, v67
	s_nop 0
	v_cvt_pk_bf16_f32 v138, v72, v73
	s_waitcnt vmcnt(7)
	v_mov_b32_e32 v0, v200
	v_mov_b32_e32 v1, v201
	v_mov_b32_e32 v2, v202
	v_mov_b32_e32 v3, v203
	v_lshlrev_b32_e32 v74, 16, v0
	v_and_b32_e32 v75, 0xffff0000, v0
	v_lshlrev_b32_e32 v0, 16, v1
	v_and_b32_e32 v1, 0xffff0000, v1
	v_lshlrev_b32_e32 v80, 16, v2
	v_and_b32_e32 v81, 0xffff0000, v2
	v_lshlrev_b32_e32 v2, 16, v3
	v_and_b32_e32 v3, 0xffff0000, v3
	v_pk_mul_f32 v[76:77], v[74:75], v[74:75]
	v_pk_mul_f32 v[78:79], v[0:1], v[0:1]
	v_pk_mul_f32 v[82:83], v[80:81], v[80:81]
	v_pk_mul_f32 v[84:85], v[2:3], v[2:3]
	v_pk_fma_f32 v[76:77], v[76:77], s[42:43], 1.0 op_sel_hi:[1,0,0]
	v_pk_fma_f32 v[78:79], v[78:79], s[42:43], 1.0 op_sel_hi:[1,0,0]
	v_pk_fma_f32 v[82:83], v[82:83], s[42:43], 1.0 op_sel_hi:[1,0,0]
	v_pk_fma_f32 v[84:85], v[84:85], s[42:43], 1.0 op_sel_hi:[1,0,0]
	v_pk_mul_f32 v[76:77], v[76:77], v[74:75]
	v_pk_mul_f32 v[78:79], v[78:79], v[0:1]
	v_pk_mul_f32 v[82:83], v[82:83], v[80:81]
	v_pk_mul_f32 v[84:85], v[84:85], v[2:3]
	v_pk_mul_f32 v[76:77], v[76:77], s[10:11] op_sel_hi:[1,0]
	v_pk_mul_f32 v[78:79], v[78:79], s[10:11] op_sel_hi:[1,0]
	v_pk_mul_f32 v[82:83], v[82:83], s[10:11] op_sel_hi:[1,0]
	v_pk_mul_f32 v[84:85], v[84:85], s[10:11] op_sel_hi:[1,0]
	v_exp_f32_e32 v76, v76
	v_exp_f32_e32 v77, v77
	v_exp_f32_e32 v78, v78
	v_exp_f32_e32 v79, v79
	v_exp_f32_e32 v82, v82
	v_exp_f32_e32 v83, v83
	v_exp_f32_e32 v84, v84
	v_exp_f32_e32 v85, v85
	v_pk_add_f32 v[76:77], v[76:77], 1.0 op_sel_hi:[1,0]
	v_pk_add_f32 v[78:79], v[78:79], 1.0 op_sel_hi:[1,0]
	v_pk_add_f32 v[82:83], v[82:83], 1.0 op_sel_hi:[1,0]
	v_pk_add_f32 v[84:85], v[84:85], 1.0 op_sel_hi:[1,0]
	v_rcp_f32_e32 v76, v76
	v_rcp_f32_e32 v77, v77
	v_rcp_f32_e32 v86, v78
	v_rcp_f32_e32 v87, v79
	v_rcp_f32_e32 v82, v82
	v_rcp_f32_e32 v83, v83
	v_rcp_f32_e32 v84, v84
	v_rcp_f32_e32 v85, v85
	v_pk_mul_f32 v[78:79], v[76:77], v[74:75]
	v_pk_mul_f32 v[76:77], v[86:87], v[0:1]
	v_pk_mul_f32 v[74:75], v[82:83], v[80:81]
	v_pk_mul_f32 v[80:81], v[84:85], v[2:3]
	v_cvt_pk_bf16_f32 v146, v78, v79
	v_cvt_pk_bf16_f32 v144, v76, v77
	v_cvt_pk_bf16_f32 v143, v74, v75
	s_nop 0
	v_cvt_pk_bf16_f32 v141, v80, v81
	s_waitcnt vmcnt(6)
	v_mov_b32_e32 v0, v204
	v_mov_b32_e32 v1, v205
	v_mov_b32_e32 v2, v206
	v_mov_b32_e32 v3, v207
	v_lshlrev_b32_e32 v82, 16, v0
	v_and_b32_e32 v83, 0xffff0000, v0
	v_lshlrev_b32_e32 v0, 16, v1
	v_and_b32_e32 v1, 0xffff0000, v1
	v_lshlrev_b32_e32 v84, 16, v2
	v_and_b32_e32 v85, 0xffff0000, v2
	v_lshlrev_b32_e32 v2, 16, v3
	v_and_b32_e32 v3, 0xffff0000, v3
	v_pk_mul_f32 v[86:87], v[82:83], v[82:83]
	v_pk_mul_f32 v[88:89], v[0:1], v[0:1]
	v_pk_mul_f32 v[90:91], v[84:85], v[84:85]
	v_pk_mul_f32 v[92:93], v[2:3], v[2:3]
	v_pk_fma_f32 v[86:87], v[86:87], s[42:43], 1.0 op_sel_hi:[1,0,0]
	v_pk_fma_f32 v[88:89], v[88:89], s[42:43], 1.0 op_sel_hi:[1,0,0]
	v_pk_fma_f32 v[90:91], v[90:91], s[42:43], 1.0 op_sel_hi:[1,0,0]
	v_pk_fma_f32 v[92:93], v[92:93], s[42:43], 1.0 op_sel_hi:[1,0,0]
	v_pk_mul_f32 v[86:87], v[86:87], v[82:83]
	v_pk_mul_f32 v[88:89], v[88:89], v[0:1]
	v_pk_mul_f32 v[90:91], v[90:91], v[84:85]
	v_pk_mul_f32 v[92:93], v[92:93], v[2:3]
	v_pk_mul_f32 v[86:87], v[86:87], s[10:11] op_sel_hi:[1,0]
	v_pk_mul_f32 v[88:89], v[88:89], s[10:11] op_sel_hi:[1,0]
	v_pk_mul_f32 v[90:91], v[90:91], s[10:11] op_sel_hi:[1,0]
	v_pk_mul_f32 v[92:93], v[92:93], s[10:11] op_sel_hi:[1,0]
	v_exp_f32_e32 v86, v86
	v_exp_f32_e32 v87, v87
	v_exp_f32_e32 v88, v88
	v_exp_f32_e32 v89, v89
	v_exp_f32_e32 v90, v90
	v_exp_f32_e32 v91, v91
	v_exp_f32_e32 v92, v92
	v_exp_f32_e32 v93, v93
	v_pk_add_f32 v[86:87], v[86:87], 1.0 op_sel_hi:[1,0]
	v_pk_add_f32 v[88:89], v[88:89], 1.0 op_sel_hi:[1,0]
	v_pk_add_f32 v[90:91], v[90:91], 1.0 op_sel_hi:[1,0]
	v_pk_add_f32 v[92:93], v[92:93], 1.0 op_sel_hi:[1,0]
	v_rcp_f32_e32 v86, v86
	v_rcp_f32_e32 v87, v87
	v_rcp_f32_e32 v88, v88
	v_rcp_f32_e32 v89, v89
	v_rcp_f32_e32 v94, v90
	v_rcp_f32_e32 v95, v91
	v_rcp_f32_e32 v92, v92
	v_rcp_f32_e32 v93, v93
	v_pk_mul_f32 v[90:91], v[86:87], v[82:83]
	v_pk_mul_f32 v[86:87], v[88:89], v[0:1]
	v_pk_mul_f32 v[84:85], v[94:95], v[84:85]
	v_pk_mul_f32 v[82:83], v[92:93], v[2:3]
	v_cvt_pk_bf16_f32 v149, v90, v91
	v_cvt_pk_bf16_f32 v148, v86, v87
	v_cvt_pk_bf16_f32 v147, v84, v85
	s_nop 0
	v_cvt_pk_bf16_f32 v145, v82, v83
	s_waitcnt vmcnt(5)
	v_mov_b32_e32 v0, v208
	v_mov_b32_e32 v1, v209
	v_mov_b32_e32 v2, v210
	v_mov_b32_e32 v3, v211
	v_lshlrev_b32_e32 v88, 16, v0
	v_and_b32_e32 v89, 0xffff0000, v0
	v_lshlrev_b32_e32 v0, 16, v1
	v_and_b32_e32 v1, 0xffff0000, v1
	v_lshlrev_b32_e32 v92, 16, v2
	v_and_b32_e32 v93, 0xffff0000, v2
	v_lshlrev_b32_e32 v2, 16, v3
	v_and_b32_e32 v3, 0xffff0000, v3
	v_pk_mul_f32 v[94:95], v[88:89], v[88:89]
	v_pk_mul_f32 v[96:97], v[0:1], v[0:1]
	v_pk_mul_f32 v[98:99], v[92:93], v[92:93]
	v_pk_mul_f32 v[100:101], v[2:3], v[2:3]
	v_pk_fma_f32 v[94:95], v[94:95], s[42:43], 1.0 op_sel_hi:[1,0,0]
	v_pk_fma_f32 v[96:97], v[96:97], s[42:43], 1.0 op_sel_hi:[1,0,0]
	v_pk_fma_f32 v[98:99], v[98:99], s[42:43], 1.0 op_sel_hi:[1,0,0]
	v_pk_fma_f32 v[100:101], v[100:101], s[42:43], 1.0 op_sel_hi:[1,0,0]
	v_pk_mul_f32 v[94:95], v[94:95], v[88:89]
	v_pk_mul_f32 v[96:97], v[96:97], v[0:1]
	v_pk_mul_f32 v[98:99], v[98:99], v[92:93]
	v_pk_mul_f32 v[100:101], v[100:101], v[2:3]
	v_pk_mul_f32 v[94:95], v[94:95], s[10:11] op_sel_hi:[1,0]
	v_pk_mul_f32 v[96:97], v[96:97], s[10:11] op_sel_hi:[1,0]
	v_pk_mul_f32 v[98:99], v[98:99], s[10:11] op_sel_hi:[1,0]
	v_pk_mul_f32 v[100:101], v[100:101], s[10:11] op_sel_hi:[1,0]
	v_exp_f32_e32 v94, v94
	v_exp_f32_e32 v95, v95
	v_exp_f32_e32 v96, v96
	v_exp_f32_e32 v97, v97
	v_exp_f32_e32 v98, v98
	v_exp_f32_e32 v99, v99
	v_exp_f32_e32 v100, v100
	v_exp_f32_e32 v101, v101
	v_pk_add_f32 v[94:95], v[94:95], 1.0 op_sel_hi:[1,0]
	v_pk_add_f32 v[96:97], v[96:97], 1.0 op_sel_hi:[1,0]
	v_pk_add_f32 v[98:99], v[98:99], 1.0 op_sel_hi:[1,0]
	v_pk_add_f32 v[100:101], v[100:101], 1.0 op_sel_hi:[1,0]
	v_rcp_f32_e32 v94, v94
	v_rcp_f32_e32 v95, v95
	v_rcp_f32_e32 v102, v96
	v_rcp_f32_e32 v103, v97
	v_rcp_f32_e32 v98, v98
	v_rcp_f32_e32 v99, v99
	v_rcp_f32_e32 v100, v100
	v_rcp_f32_e32 v101, v101
	v_pk_mul_f32 v[96:97], v[94:95], v[88:89]
	v_pk_mul_f32 v[94:95], v[102:103], v[0:1]
	v_pk_mul_f32 v[92:93], v[98:99], v[92:93]
	v_pk_mul_f32 v[98:99], v[100:101], v[2:3]
	v_cvt_pk_bf16_f32 v154, v96, v97
	v_cvt_pk_bf16_f32 v152, v94, v95
	v_cvt_pk_bf16_f32 v151, v92, v93
	v_mov_b32_e32 v89, 0
	v_cvt_pk_bf16_f32 v150, v98, v99
	v_mov_b32_e32 v88, v17
	v_pk_add_f32 v[6:7], v[6:7], v[88:89]
	v_mov_b32_e32 v17, v22
	v_pk_add_f32 v[6:7], v[10:11], v[6:7]
	v_pk_mul_f32 v[10:11], v[20:21], v[20:21]
	s_waitcnt vmcnt(4)
	v_mov_b32_e32 v0, v212
	v_mov_b32_e32 v1, v213
	v_mov_b32_e32 v2, v214
	v_mov_b32_e32 v3, v215
	v_lshlrev_b32_e32 v100, 16, v0
	v_and_b32_e32 v101, 0xffff0000, v0
	v_lshlrev_b32_e32 v0, 16, v1
	v_and_b32_e32 v1, 0xffff0000, v1
	v_lshlrev_b32_e32 v106, 16, v2
	v_and_b32_e32 v107, 0xffff0000, v2
	v_lshlrev_b32_e32 v2, 16, v3
	v_and_b32_e32 v3, 0xffff0000, v3
	v_pk_mul_f32 v[102:103], v[100:101], v[100:101]
	v_pk_mul_f32 v[104:105], v[0:1], v[0:1]
	v_pk_mul_f32 v[156:157], v[106:107], v[106:107]
	v_pk_mul_f32 v[158:159], v[2:3], v[2:3]
	v_pk_fma_f32 v[102:103], v[102:103], s[42:43], 1.0 op_sel_hi:[1,0,0]
	v_pk_fma_f32 v[104:105], v[104:105], s[42:43], 1.0 op_sel_hi:[1,0,0]
	v_pk_fma_f32 v[156:157], v[156:157], s[42:43], 1.0 op_sel_hi:[1,0,0]
	v_pk_fma_f32 v[158:159], v[158:159], s[42:43], 1.0 op_sel_hi:[1,0,0]
	v_pk_mul_f32 v[102:103], v[102:103], v[100:101]
	v_pk_mul_f32 v[104:105], v[104:105], v[0:1]
	v_pk_mul_f32 v[156:157], v[156:157], v[106:107]
	v_pk_mul_f32 v[158:159], v[158:159], v[2:3]
	v_pk_mul_f32 v[102:103], v[102:103], s[10:11] op_sel_hi:[1,0]
	v_pk_mul_f32 v[104:105], v[104:105], s[10:11] op_sel_hi:[1,0]
	v_pk_mul_f32 v[156:157], v[156:157], s[10:11] op_sel_hi:[1,0]
	v_pk_mul_f32 v[158:159], v[158:159], s[10:11] op_sel_hi:[1,0]
	v_exp_f32_e32 v102, v102
	v_exp_f32_e32 v103, v103
	v_exp_f32_e32 v104, v104
	v_exp_f32_e32 v105, v105
	v_exp_f32_e32 v156, v156
	v_exp_f32_e32 v157, v157
	v_exp_f32_e32 v158, v158
	v_exp_f32_e32 v159, v159
	v_pk_add_f32 v[102:103], v[102:103], 1.0 op_sel_hi:[1,0]
	v_pk_add_f32 v[104:105], v[104:105], 1.0 op_sel_hi:[1,0]
	v_pk_add_f32 v[156:157], v[156:157], 1.0 op_sel_hi:[1,0]
	v_pk_add_f32 v[158:159], v[158:159], 1.0 op_sel_hi:[1,0]
	v_rcp_f32_e32 v102, v102
	v_rcp_f32_e32 v103, v103
	v_rcp_f32_e32 v160, v104
	v_rcp_f32_e32 v161, v105
	v_rcp_f32_e32 v156, v156
	v_rcp_f32_e32 v157, v157
	v_rcp_f32_e32 v158, v158
	v_rcp_f32_e32 v159, v159
	v_pk_mul_f32 v[104:105], v[102:103], v[100:101]
	v_pk_mul_f32 v[102:103], v[160:161], v[0:1]
	v_pk_mul_f32 v[100:101], v[156:157], v[106:107]
	v_pk_mul_f32 v[106:107], v[158:159], v[2:3]
	v_cvt_pk_bf16_f32 v157, v104, v105
	v_cvt_pk_bf16_f32 v156, v102, v103
	v_cvt_pk_bf16_f32 v155, v100, v101
	v_pk_mul_f32 v[160:161], v[8:9], v[8:9]
	v_cvt_pk_bf16_f32 v153, v106, v107
	v_mov_b32_e32 v166, v160
	v_mov_b32_e32 v8, v161
	v_pk_add_f32 v[8:9], v[166:167], v[8:9]
	v_mov_b32_e32 v161, v20
	v_pk_add_f32 v[6:7], v[8:9], v[6:7]
	v_pk_mul_f32 v[8:9], v[22:23], v[22:23]
	v_pk_add_f32 v[6:7], v[12:13], v[6:7]
	v_mov_b32_e32 v16, v8
	v_mov_b32_e32 v22, v9
	v_pk_mul_f32 v[12:13], v[18:19], v[18:19]
	v_mov_b32_e32 v160, v10
	v_mov_b32_e32 v20, v11
	v_pk_add_f32 v[8:9], v[16:17], v[22:23]
	v_mov_b32_e32 v162, v12
	v_mov_b32_e32 v18, v13
	v_pk_add_f32 v[10:11], v[160:161], v[20:21]
	v_pk_add_f32 v[6:7], v[6:7], v[8:9]
	v_pk_add_f32 v[12:13], v[162:163], v[18:19]
	v_pk_add_f32 v[6:7], v[10:11], v[6:7]
	v_pk_mul_f32 v[8:9], v[30:31], v[30:31]
	v_pk_add_f32 v[6:7], v[12:13], v[6:7]
	v_mov_b32_e32 v11, v30
	v_pk_mul_f32 v[12:13], v[28:29], v[28:29]
	v_mov_b32_e32 v10, v8
	v_mov_b32_e32 v30, v9
	v_pk_add_f32 v[6:7], v[14:15], v[6:7]
	v_mov_b32_e32 v15, v28
	v_pk_mul_f32 v[16:17], v[26:27], v[26:27]
	v_mov_b32_e32 v14, v12
	v_mov_b32_e32 v28, v13
	v_pk_add_f32 v[8:9], v[10:11], v[30:31]
	v_pk_mul_f32 v[18:19], v[32:33], v[32:33]
	v_mov_b32_e32 v21, v26
	v_mov_b32_e32 v20, v16
	v_mov_b32_e32 v26, v17
	v_pk_add_f32 v[10:11], v[14:15], v[28:29]
	v_pk_add_f32 v[6:7], v[6:7], v[8:9]
	v_mov_b32_e32 v23, v32
	v_mov_b32_e32 v22, v18
	v_mov_b32_e32 v32, v19
	v_pk_add_f32 v[12:13], v[20:21], v[26:27]
	v_pk_add_f32 v[6:7], v[10:11], v[6:7]
	v_pk_add_f32 v[14:15], v[22:23], v[32:33]
	v_pk_add_f32 v[6:7], v[12:13], v[6:7]
	v_pk_mul_f32 v[16:17], v[38:39], v[38:39]
	v_pk_add_f32 v[14:15], v[14:15], v[6:7]
	v_mov_b32_e32 v31, v38
	v_mov_b32_e32 v30, v16
	v_mov_b32_e32 v38, v17
	v_pk_mul_f32 v[26:27], v[34:35], v[34:35]
	v_mov_b32_e32 v33, v36
	v_mov_b32_e32 v32, v24
	v_mov_b32_e32 v36, v25
	v_pk_add_f32 v[16:17], v[30:31], v[38:39]
	v_pk_mul_f32 v[28:29], v[40:41], v[40:41]
	v_mov_b32_e32 v161, v34
	v_mov_b32_e32 v160, v26
	v_mov_b32_e32 v34, v27
	v_pk_add_f32 v[24:25], v[32:33], v[36:37]
	v_pk_add_f32 v[14:15], v[14:15], v[16:17]
	v_mov_b32_e32 v163, v40
	v_mov_b32_e32 v162, v28
	v_mov_b32_e32 v40, v29
	v_pk_add_f32 v[26:27], v[160:161], v[34:35]
	v_pk_add_f32 v[14:15], v[24:25], v[14:15]
	v_pk_mul_f32 v[16:17], v[46:47], v[46:47]
	v_pk_add_f32 v[28:29], v[162:163], v[40:41]
	v_pk_add_f32 v[14:15], v[26:27], v[14:15]
	v_pk_mul_f32 v[24:25], v[44:45], v[44:45]
	v_mov_b32_e32 v31, v46
	v_mov_b32_e32 v30, v16
	v_mov_b32_e32 v46, v17
	v_pk_add_f32 v[14:15], v[28:29], v[14:15]
	v_pk_mul_f32 v[26:27], v[42:43], v[42:43]
	v_mov_b32_e32 v33, v44
	v_mov_b32_e32 v32, v24
	v_mov_b32_e32 v44, v25
	v_pk_add_f32 v[16:17], v[30:31], v[46:47]
	v_pk_mul_f32 v[28:29], v[48:49], v[48:49]
	s_waitcnt vmcnt(3)
	v_mov_b32_e32 v0, v216
	v_mov_b32_e32 v1, v217
	v_mov_b32_e32 v2, v218
	v_mov_b32_e32 v3, v219
	v_lshlrev_b32_e32 v6, 16, v0
	v_and_b32_e32 v7, 0xffff0000, v0
	v_lshlrev_b32_e32 v0, 16, v1
	v_and_b32_e32 v1, 0xffff0000, v1
	v_lshlrev_b32_e32 v10, 16, v2
	v_and_b32_e32 v11, 0xffff0000, v2
	v_lshlrev_b32_e32 v12, 16, v3
	v_and_b32_e32 v13, 0xffff0000, v3
	v_pk_mul_f32 v[2:3], v[6:7], v[6:7]
	v_pk_mul_f32 v[8:9], v[0:1], v[0:1]
	v_pk_mul_f32 v[18:19], v[10:11], v[10:11]
	v_pk_mul_f32 v[20:21], v[12:13], v[12:13]
	v_pk_fma_f32 v[2:3], v[2:3], s[42:43], 1.0 op_sel_hi:[1,0,0]
	v_pk_fma_f32 v[8:9], v[8:9], s[42:43], 1.0 op_sel_hi:[1,0,0]
	v_pk_fma_f32 v[18:19], v[18:19], s[42:43], 1.0 op_sel_hi:[1,0,0]
	v_pk_fma_f32 v[20:21], v[20:21], s[42:43], 1.0 op_sel_hi:[1,0,0]
	v_pk_mul_f32 v[2:3], v[2:3], v[6:7]
	v_pk_mul_f32 v[8:9], v[8:9], v[0:1]
	v_pk_mul_f32 v[18:19], v[18:19], v[10:11]
	v_pk_mul_f32 v[20:21], v[20:21], v[12:13]
	v_pk_mul_f32 v[2:3], v[2:3], s[10:11] op_sel_hi:[1,0]
	v_pk_mul_f32 v[8:9], v[8:9], s[10:11] op_sel_hi:[1,0]
	v_pk_mul_f32 v[18:19], v[18:19], s[10:11] op_sel_hi:[1,0]
	v_pk_mul_f32 v[20:21], v[20:21], s[10:11] op_sel_hi:[1,0]
	v_exp_f32_e32 v2, v2
	v_exp_f32_e32 v3, v3
	v_exp_f32_e32 v8, v8
	v_exp_f32_e32 v9, v9
	v_exp_f32_e32 v18, v18
	v_exp_f32_e32 v19, v19
	v_exp_f32_e32 v20, v20
	v_exp_f32_e32 v21, v21
	v_pk_add_f32 v[2:3], v[2:3], 1.0 op_sel_hi:[1,0]
	v_pk_add_f32 v[8:9], v[8:9], 1.0 op_sel_hi:[1,0]
	v_pk_add_f32 v[18:19], v[18:19], 1.0 op_sel_hi:[1,0]
	v_pk_add_f32 v[20:21], v[20:21], 1.0 op_sel_hi:[1,0]
	v_rcp_f32_e32 v2, v2
	v_rcp_f32_e32 v3, v3
	v_rcp_f32_e32 v22, v8
	v_rcp_f32_e32 v23, v9
	v_rcp_f32_e32 v18, v18
	v_rcp_f32_e32 v19, v19
	v_rcp_f32_e32 v20, v20
	v_rcp_f32_e32 v21, v21
	v_pk_mul_f32 v[8:9], v[2:3], v[6:7]
	v_pk_mul_f32 v[6:7], v[22:23], v[0:1]
	v_pk_mul_f32 v[2:3], v[18:19], v[10:11]
	v_pk_mul_f32 v[0:1], v[20:21], v[12:13]
	v_cvt_pk_bf16_f32 v22, v8, v9
	v_cvt_pk_bf16_f32 v20, v6, v7
	v_cvt_pk_bf16_f32 v19, v2, v3
	v_mov_b32_e32 v35, v42
	v_cvt_pk_bf16_f32 v18, v0, v1
	v_mov_b32_e32 v34, v26
	v_mov_b32_e32 v42, v27
	v_pk_add_f32 v[24:25], v[32:33], v[44:45]
	v_pk_add_f32 v[14:15], v[14:15], v[16:17]
	v_mov_b32_e32 v37, v48
	v_mov_b32_e32 v36, v28
	v_mov_b32_e32 v48, v29
	v_pk_add_f32 v[26:27], v[34:35], v[42:43]
	v_pk_add_f32 v[14:15], v[24:25], v[14:15]
	v_pk_mul_f32 v[16:17], v[54:55], v[54:55]
	v_pk_add_f32 v[28:29], v[36:37], v[48:49]
	v_pk_add_f32 v[14:15], v[26:27], v[14:15]
	v_mov_b32_e32 v25, v54
	v_pk_mul_f32 v[26:27], v[52:53], v[52:53]
	v_mov_b32_e32 v24, v16
	v_mov_b32_e32 v54, v17
	v_pk_add_f32 v[14:15], v[28:29], v[14:15]
	v_pk_mul_f32 v[28:29], v[50:51], v[50:51]
	v_mov_b32_e32 v33, v52
	v_mov_b32_e32 v32, v26
	v_mov_b32_e32 v52, v27
	v_pk_add_f32 v[16:17], v[24:25], v[54:55]
	v_pk_mul_f32 v[30:31], v[56:57], v[56:57]
	v_mov_b32_e32 v35, v50
	v_mov_b32_e32 v34, v28
	v_mov_b32_e32 v50, v29
	v_pk_add_f32 v[24:25], v[32:33], v[52:53]
	v_pk_add_f32 v[14:15], v[14:15], v[16:17]
	v_mov_b32_e32 v37, v56
	v_mov_b32_e32 v36, v30
	v_mov_b32_e32 v56, v31
	v_pk_add_f32 v[26:27], v[34:35], v[50:51]
	v_pk_add_f32 v[14:15], v[24:25], v[14:15]
	v_pk_add_f32 v[28:29], v[36:37], v[56:57]
	v_pk_add_f32 v[14:15], v[26:27], v[14:15]
	v_pk_mul_f32 v[16:17], v[60:61], v[60:61]
	v_pk_add_f32 v[32:33], v[28:29], v[14:15]
	v_pk_mul_f32 v[14:15], v[62:63], v[62:63]
	v_mov_b32_e32 v39, v62
	v_mov_b32_e32 v38, v14
	v_mov_b32_e32 v62, v15
	v_mov_b32_e32 v41, v60
	v_mov_b32_e32 v40, v16
	v_mov_b32_e32 v60, v17
	v_pk_mul_f32 v[34:35], v[58:59], v[58:59]
	v_pk_mul_f32 v[36:37], v[64:65], v[64:65]
	v_mov_b32_e32 v43, v58
	v_mov_b32_e32 v42, v34
	v_mov_b32_e32 v58, v35
	v_pk_add_f32 v[34:35], v[38:39], v[62:63]
	v_mov_b32_e32 v45, v64
	v_mov_b32_e32 v44, v36
	v_mov_b32_e32 v64, v37
	v_pk_add_f32 v[36:37], v[40:41], v[60:61]
	v_pk_add_f32 v[32:33], v[32:33], v[34:35]
	v_pk_add_f32 v[38:39], v[42:43], v[58:59]
	v_pk_add_f32 v[32:33], v[36:37], v[32:33]
	v_pk_add_f32 v[40:41], v[44:45], v[64:65]
	v_pk_add_f32 v[32:33], v[38:39], v[32:33]
	v_pk_mul_f32 v[34:35], v[70:71], v[70:71]
	v_pk_add_f32 v[32:33], v[40:41], v[32:33]
	v_pk_mul_f32 v[36:37], v[68:69], v[68:69]
	v_mov_b32_e32 v41, v70
	v_mov_b32_e32 v40, v34
	v_mov_b32_e32 v70, v35
	v_pk_mul_f32 v[38:39], v[66:67], v[66:67]
	v_mov_b32_e32 v43, v68
	v_mov_b32_e32 v42, v36
	v_mov_b32_e32 v68, v37
	v_pk_add_f32 v[34:35], v[40:41], v[70:71]
	v_mov_b32_e32 v45, v66
	v_mov_b32_e32 v44, v38
	v_mov_b32_e32 v66, v39
	v_pk_add_f32 v[36:37], v[42:43], v[68:69]
	v_pk_add_f32 v[32:33], v[32:33], v[34:35]
	v_mov_b32_e32 v49, v72
	v_pk_add_f32 v[38:39], v[44:45], v[66:67]
	v_pk_add_f32 v[32:33], v[36:37], v[32:33]
	v_pk_mul_f32 v[34:35], v[78:79], v[78:79]
	s_waitcnt vmcnt(2)
	v_mov_b32_e32 v10, v220
	v_mov_b32_e32 v11, v221
	v_mov_b32_e32 v12, v222
	v_mov_b32_e32 v13, v223
	v_lshlrev_b32_e32 v14, 16, v10
	v_and_b32_e32 v15, 0xffff0000, v10
	v_lshlrev_b32_e32 v10, 16, v11
	v_and_b32_e32 v11, 0xffff0000, v11
	v_lshlrev_b32_e32 v24, 16, v12
	v_and_b32_e32 v25, 0xffff0000, v12
	v_lshlrev_b32_e32 v26, 16, v13
	v_and_b32_e32 v27, 0xffff0000, v13
	v_pk_mul_f32 v[12:13], v[14:15], v[14:15]
	v_pk_mul_f32 v[16:17], v[10:11], v[10:11]
	v_pk_mul_f32 v[28:29], v[24:25], v[24:25]
	v_pk_mul_f32 v[30:31], v[26:27], v[26:27]
	v_pk_fma_f32 v[12:13], v[12:13], s[42:43], 1.0 op_sel_hi:[1,0,0]
	v_pk_fma_f32 v[16:17], v[16:17], s[42:43], 1.0 op_sel_hi:[1,0,0]
	v_pk_fma_f32 v[28:29], v[28:29], s[42:43], 1.0 op_sel_hi:[1,0,0]
	v_pk_fma_f32 v[30:31], v[30:31], s[42:43], 1.0 op_sel_hi:[1,0,0]
	v_pk_mul_f32 v[12:13], v[12:13], v[14:15]
	v_pk_mul_f32 v[16:17], v[16:17], v[10:11]
	v_pk_mul_f32 v[28:29], v[28:29], v[24:25]
	v_pk_mul_f32 v[30:31], v[30:31], v[26:27]
	v_pk_mul_f32 v[12:13], v[12:13], s[10:11] op_sel_hi:[1,0]
	v_pk_mul_f32 v[16:17], v[16:17], s[10:11] op_sel_hi:[1,0]
	v_pk_mul_f32 v[28:29], v[28:29], s[10:11] op_sel_hi:[1,0]
	v_pk_mul_f32 v[30:31], v[30:31], s[10:11] op_sel_hi:[1,0]
	v_exp_f32_e32 v12, v12
	v_exp_f32_e32 v13, v13
	v_exp_f32_e32 v16, v16
	v_exp_f32_e32 v17, v17
	v_exp_f32_e32 v28, v28
	v_exp_f32_e32 v29, v29
	v_exp_f32_e32 v30, v30
	v_exp_f32_e32 v31, v31
	v_pk_add_f32 v[12:13], v[12:13], 1.0 op_sel_hi:[1,0]
	v_pk_add_f32 v[16:17], v[16:17], 1.0 op_sel_hi:[1,0]
	v_pk_add_f32 v[28:29], v[28:29], 1.0 op_sel_hi:[1,0]
	v_pk_add_f32 v[30:31], v[30:31], 1.0 op_sel_hi:[1,0]
	v_rcp_f32_e32 v12, v12
	v_rcp_f32_e32 v13, v13
	v_rcp_f32_e32 v46, v16
	v_rcp_f32_e32 v47, v17
	v_rcp_f32_e32 v28, v28
	v_rcp_f32_e32 v29, v29
	v_rcp_f32_e32 v30, v30
	v_rcp_f32_e32 v31, v31
	v_pk_mul_f32 v[16:17], v[12:13], v[14:15]
	v_pk_mul_f32 v[14:15], v[46:47], v[10:11]
	v_pk_mul_f32 v[12:13], v[28:29], v[24:25]
	v_pk_mul_f32 v[10:11], v[30:31], v[26:27]
	v_cvt_pk_bf16_f32 v26, v16, v17
	v_cvt_pk_bf16_f32 v24, v14, v15
	v_cvt_pk_bf16_f32 v23, v12, v13
	v_pk_mul_f32 v[46:47], v[72:73], v[72:73]
	v_cvt_pk_bf16_f32 v21, v10, v11
	v_mov_b32_e32 v48, v46
	v_mov_b32_e32 v72, v47
	v_pk_add_f32 v[40:41], v[48:49], v[72:73]
	v_pk_add_f32 v[32:33], v[38:39], v[32:33]
	v_pk_mul_f32 v[36:37], v[76:77], v[76:77]
	v_mov_b32_e32 v43, v78
	v_mov_b32_e32 v42, v34
	v_mov_b32_e32 v78, v35
	v_pk_add_f32 v[32:33], v[40:41], v[32:33]
	v_pk_mul_f32 v[38:39], v[74:75], v[74:75]
	v_mov_b32_e32 v45, v76
	v_mov_b32_e32 v44, v36
	v_mov_b32_e32 v76, v37
	v_pk_add_f32 v[34:35], v[42:43], v[78:79]
	v_pk_mul_f32 v[40:41], v[80:81], v[80:81]
	v_mov_b32_e32 v47, v74
	v_mov_b32_e32 v46, v38
	v_mov_b32_e32 v74, v39
	v_pk_add_f32 v[36:37], v[44:45], v[76:77]
	v_pk_add_f32 v[32:33], v[32:33], v[34:35]
	v_mov_b32_e32 v49, v80
	v_mov_b32_e32 v48, v40
	v_mov_b32_e32 v80, v41
	v_pk_add_f32 v[38:39], v[46:47], v[74:75]
	v_pk_add_f32 v[32:33], v[36:37], v[32:33]
	v_pk_add_f32 v[40:41], v[48:49], v[80:81]
	v_pk_add_f32 v[32:33], v[38:39], v[32:33]
	v_pk_mul_f32 v[36:37], v[86:87], v[86:87]
	v_pk_add_f32 v[34:35], v[40:41], v[32:33]
	v_pk_mul_f32 v[32:33], v[90:91], v[90:91]
	v_pk_mul_f32 v[38:39], v[84:85], v[84:85]
	v_mov_b32_e32 v43, v90
	v_mov_b32_e32 v42, v32
	v_mov_b32_e32 v90, v33
	v_pk_mul_f32 v[40:41], v[82:83], v[82:83]
	v_mov_b32_e32 v45, v86
	v_mov_b32_e32 v47, v84
	v_mov_b32_e32 v44, v36
	v_mov_b32_e32 v86, v37
	v_mov_b32_e32 v46, v38
	v_mov_b32_e32 v84, v39
	v_pk_add_f32 v[36:37], v[42:43], v[90:91]
	v_mov_b32_e32 v49, v82
	v_mov_b32_e32 v48, v40
	v_mov_b32_e32 v82, v41
	v_pk_add_f32 v[38:39], v[44:45], v[86:87]
	v_pk_add_f32 v[40:41], v[46:47], v[84:85]
	v_pk_add_f32 v[34:35], v[34:35], v[36:37]
	v_pk_mul_f32 v[36:37], v[94:95], v[94:95]
	v_pk_add_f32 v[34:35], v[38:39], v[34:35]
	v_mov_b32_e32 v39, v96
	v_pk_add_f32 v[34:35], v[40:41], v[34:35]
	v_mov_b32_e32 v41, v94
	v_mov_b32_e32 v40, v36
	v_mov_b32_e32 v94, v37
	v_pk_mul_f32 v[54:55], v[98:99], v[98:99]
	v_pk_add_f32 v[36:37], v[40:41], v[94:95]
	v_mov_b32_e32 v57, v98
	v_mov_b32_e32 v56, v54
	v_mov_b32_e32 v98, v55
	v_pk_add_f32 v[40:41], v[56:57], v[98:99]
	v_mov_b32_e32 v55, v100
	v_mov_b32_e32 v57, v106
	v_mov_b32_e32 v158, s22
	v_pk_mul_f32 v[58:59], v[10:11], v[10:11]
	v_mov_b32_e32 v61, v12
	v_mov_b32_e32 v63, v10
	v_mov_b32_e32 v62, v58
	v_mov_b32_e32 v10, v59
	v_pk_add_f32 v[10:11], v[62:63], v[10:11]
	v_mov_b32_e32 v76, 0
	v_mov_b32_e32 v77, 0
	v_mov_b32_e32 v78, 0
	v_mov_b32_e32 v79, 0
	v_mov_b32_e32 v72, 0
	v_mov_b32_e32 v73, 0
	v_mov_b32_e32 v74, 0
	v_mov_b32_e32 v75, 0
	s_waitcnt vmcnt(1)
	v_mov_b32_e32 v28, v228
	v_mov_b32_e32 v29, v229
	v_mov_b32_e32 v30, v230
	v_mov_b32_e32 v31, v231
	v_lshlrev_b32_e32 v32, 16, v28
	v_and_b32_e32 v33, 0xffff0000, v28
	v_lshlrev_b32_e32 v28, 16, v29
	v_and_b32_e32 v29, 0xffff0000, v29
	v_lshlrev_b32_e32 v42, 16, v30
	v_and_b32_e32 v43, 0xffff0000, v30
	v_lshlrev_b32_e32 v30, 16, v31
	v_and_b32_e32 v31, 0xffff0000, v31
	v_pk_mul_f32 v[44:45], v[32:33], v[32:33]
	v_pk_mul_f32 v[46:47], v[28:29], v[28:29]
	v_pk_mul_f32 v[50:51], v[42:43], v[42:43]
	v_pk_mul_f32 v[52:53], v[30:31], v[30:31]
	v_pk_fma_f32 v[44:45], v[44:45], s[42:43], 1.0 op_sel_hi:[1,0,0]
	v_pk_fma_f32 v[46:47], v[46:47], s[42:43], 1.0 op_sel_hi:[1,0,0]
	v_pk_fma_f32 v[50:51], v[50:51], s[42:43], 1.0 op_sel_hi:[1,0,0]
	v_pk_fma_f32 v[52:53], v[52:53], s[42:43], 1.0 op_sel_hi:[1,0,0]
	v_pk_mul_f32 v[44:45], v[44:45], v[32:33]
	v_pk_mul_f32 v[46:47], v[46:47], v[28:29]
	v_pk_mul_f32 v[50:51], v[50:51], v[42:43]
	v_pk_mul_f32 v[52:53], v[52:53], v[30:31]
	v_pk_mul_f32 v[44:45], v[44:45], s[10:11] op_sel_hi:[1,0]
	v_pk_mul_f32 v[46:47], v[46:47], s[10:11] op_sel_hi:[1,0]
	v_pk_mul_f32 v[50:51], v[50:51], s[10:11] op_sel_hi:[1,0]
	v_pk_mul_f32 v[52:53], v[52:53], s[10:11] op_sel_hi:[1,0]
	v_exp_f32_e32 v44, v44
	v_exp_f32_e32 v45, v45
	v_exp_f32_e32 v46, v46
	v_exp_f32_e32 v47, v47
	v_exp_f32_e32 v50, v50
	v_exp_f32_e32 v51, v51
	v_exp_f32_e32 v52, v52
	v_exp_f32_e32 v53, v53
	v_pk_add_f32 v[44:45], v[44:45], 1.0 op_sel_hi:[1,0]
	v_pk_add_f32 v[46:47], v[46:47], 1.0 op_sel_hi:[1,0]
	v_pk_add_f32 v[50:51], v[50:51], 1.0 op_sel_hi:[1,0]
	v_pk_add_f32 v[52:53], v[52:53], 1.0 op_sel_hi:[1,0]
	v_rcp_f32_e32 v44, v44
	v_rcp_f32_e32 v45, v45
	v_rcp_f32_e32 v46, v46
	v_rcp_f32_e32 v47, v47
	v_rcp_f32_e32 v50, v50
	v_rcp_f32_e32 v51, v51
	v_rcp_f32_e32 v52, v52
	v_rcp_f32_e32 v53, v53
	v_pk_mul_f32 v[44:45], v[44:45], v[32:33]
	v_pk_mul_f32 v[46:47], v[46:47], v[28:29]
	v_pk_mul_f32 v[42:43], v[50:51], v[42:43]
	v_pk_mul_f32 v[50:51], v[52:53], v[30:31]
	v_cvt_pk_bf16_f32 v29, v44, v45
	v_cvt_pk_bf16_f32 v28, v46, v47
	v_cvt_pk_bf16_f32 v27, v42, v43
	v_mov_b32_e32 v53, v92
	v_cvt_pk_bf16_f32 v25, v50, v51
	v_pk_add_f32 v[4:5], v[48:49], v[82:83]
	v_pk_mul_f32 v[48:49], v[92:93], v[92:93]
	v_pk_add_f32 v[4:5], v[4:5], v[34:35]
	v_pk_mul_f32 v[34:35], v[96:97], v[96:97]
	v_mov_b32_e32 v52, v48
	v_mov_b32_e32 v38, v34
	v_mov_b32_e32 v96, v35
	v_pk_add_f32 v[34:35], v[38:39], v[96:97]
	v_mov_b32_e32 v92, v49
	v_pk_add_f32 v[4:5], v[4:5], v[34:35]
	v_pk_add_f32 v[38:39], v[52:53], v[92:93]
	v_pk_add_f32 v[4:5], v[36:37], v[4:5]
	v_pk_mul_f32 v[34:35], v[104:105], v[104:105]
	v_pk_add_f32 v[4:5], v[38:39], v[4:5]
	v_pk_mul_f32 v[36:37], v[102:103], v[102:103]
	v_mov_b32_e32 v49, v104
	v_mov_b32_e32 v48, v34
	v_mov_b32_e32 v104, v35
	v_pk_add_f32 v[4:5], v[40:41], v[4:5]
	v_pk_mul_f32 v[38:39], v[100:101], v[100:101]
	v_mov_b32_e32 v53, v102
	v_mov_b32_e32 v52, v36
	v_mov_b32_e32 v102, v37
	v_pk_add_f32 v[34:35], v[48:49], v[104:105]
	v_pk_mul_f32 v[40:41], v[106:107], v[106:107]
	v_mov_b32_e32 v54, v38
	v_mov_b32_e32 v100, v39
	v_pk_add_f32 v[36:37], v[52:53], v[102:103]
	v_pk_add_f32 v[4:5], v[4:5], v[34:35]
	v_mov_b32_e32 v56, v40
	v_mov_b32_e32 v106, v41
	v_pk_add_f32 v[38:39], v[54:55], v[100:101]
	v_pk_add_f32 v[4:5], v[36:37], v[4:5]
	v_pk_mul_f32 v[34:35], v[8:9], v[8:9]
	v_pk_add_f32 v[40:41], v[56:57], v[106:107]
	v_pk_add_f32 v[4:5], v[38:39], v[4:5]
	v_pk_mul_f32 v[36:37], v[6:7], v[6:7]
	v_mov_b32_e32 v49, v8
	v_mov_b32_e32 v48, v34
	v_mov_b32_e32 v8, v35
	v_pk_add_f32 v[4:5], v[40:41], v[4:5]
	v_pk_mul_f32 v[38:39], v[2:3], v[2:3]
	v_mov_b32_e32 v53, v6
	v_mov_b32_e32 v52, v36
	v_mov_b32_e32 v6, v37
	v_pk_add_f32 v[8:9], v[48:49], v[8:9]
	v_pk_mul_f32 v[40:41], v[0:1], v[0:1]
	v_mov_b32_e32 v55, v2
	v_mov_b32_e32 v54, v38
	v_mov_b32_e32 v2, v39
	v_pk_add_f32 v[6:7], v[52:53], v[6:7]
	v_pk_add_f32 v[4:5], v[4:5], v[8:9]
	v_mov_b32_e32 v57, v0
	v_mov_b32_e32 v56, v40
	v_mov_b32_e32 v0, v41
	v_pk_add_f32 v[2:3], v[54:55], v[2:3]
	v_pk_add_f32 v[4:5], v[6:7], v[4:5]
	v_pk_add_f32 v[0:1], v[56:57], v[0:1]
	v_pk_add_f32 v[2:3], v[2:3], v[4:5]
	v_pk_mul_f32 v[8:9], v[16:17], v[16:17]
	v_pk_add_f32 v[0:1], v[0:1], v[2:3]
	v_mov_b32_e32 v35, v16
	v_pk_mul_f32 v[52:53], v[14:15], v[14:15]
	v_mov_b32_e32 v34, v8
	v_mov_b32_e32 v16, v9
	v_mov_b32_e32 v55, v14
	v_pk_mul_f32 v[56:57], v[12:13], v[12:13]
	v_mov_b32_e32 v54, v52
	v_mov_b32_e32 v14, v53
	v_pk_add_f32 v[8:9], v[34:35], v[16:17]
	v_mov_b32_e32 v60, v56
	v_mov_b32_e32 v12, v57
	v_pk_add_f32 v[14:15], v[54:55], v[14:15]
	v_pk_add_f32 v[0:1], v[0:1], v[8:9]
	v_pk_add_f32 v[12:13], v[60:61], v[12:13]
	v_pk_add_f32 v[0:1], v[14:15], v[0:1]
	v_pk_mul_f32 v[8:9], v[44:45], v[44:45]
	v_pk_add_f32 v[0:1], v[12:13], v[0:1]
	v_mov_b32_e32 v17, v44
	s_waitcnt vmcnt(0)
	v_mov_b32_e32 v30, v232
	v_mov_b32_e32 v31, v233
	v_mov_b32_e32 v32, v234
	v_mov_b32_e32 v33, v235
	v_lshlrev_b32_e32 v2, 16, v30
	v_and_b32_e32 v3, 0xffff0000, v30
	v_lshlrev_b32_e32 v4, 16, v31
	v_and_b32_e32 v5, 0xffff0000, v31
	v_lshlrev_b32_e32 v6, 16, v32
	v_and_b32_e32 v7, 0xffff0000, v32
	v_lshlrev_b32_e32 v30, 16, v33
	v_and_b32_e32 v31, 0xffff0000, v33
	v_pk_mul_f32 v[32:33], v[2:3], v[2:3]
	v_pk_mul_f32 v[36:37], v[4:5], v[4:5]
	v_pk_mul_f32 v[38:39], v[6:7], v[6:7]
	v_pk_mul_f32 v[40:41], v[30:31], v[30:31]
	v_pk_fma_f32 v[32:33], v[32:33], s[42:43], 1.0 op_sel_hi:[1,0,0]
	v_pk_fma_f32 v[36:37], v[36:37], s[42:43], 1.0 op_sel_hi:[1,0,0]
	v_pk_fma_f32 v[38:39], v[38:39], s[42:43], 1.0 op_sel_hi:[1,0,0]
	v_pk_fma_f32 v[40:41], v[40:41], s[42:43], 1.0 op_sel_hi:[1,0,0]
	v_pk_mul_f32 v[32:33], v[32:33], v[2:3]
	v_pk_mul_f32 v[36:37], v[36:37], v[4:5]
	v_pk_mul_f32 v[38:39], v[38:39], v[6:7]
	v_pk_mul_f32 v[40:41], v[40:41], v[30:31]
	v_pk_mul_f32 v[32:33], v[32:33], s[10:11] op_sel_hi:[1,0]
	v_pk_mul_f32 v[36:37], v[36:37], s[10:11] op_sel_hi:[1,0]
	v_pk_mul_f32 v[38:39], v[38:39], s[10:11] op_sel_hi:[1,0]
	v_pk_mul_f32 v[40:41], v[40:41], s[10:11] op_sel_hi:[1,0]
	v_exp_f32_e32 v32, v32
	v_exp_f32_e32 v33, v33
	v_exp_f32_e32 v36, v36
	v_exp_f32_e32 v37, v37
	v_exp_f32_e32 v38, v38
	v_exp_f32_e32 v39, v39
	v_exp_f32_e32 v40, v40
	v_exp_f32_e32 v41, v41
	v_pk_add_f32 v[32:33], v[32:33], 1.0 op_sel_hi:[1,0]
	v_pk_add_f32 v[36:37], v[36:37], 1.0 op_sel_hi:[1,0]
	v_pk_add_f32 v[38:39], v[38:39], 1.0 op_sel_hi:[1,0]
	v_pk_add_f32 v[40:41], v[40:41], 1.0 op_sel_hi:[1,0]
	v_rcp_f32_e32 v32, v32
	v_rcp_f32_e32 v33, v33
	v_rcp_f32_e32 v36, v36
	v_rcp_f32_e32 v37, v37
	v_rcp_f32_e32 v38, v38
	v_rcp_f32_e32 v39, v39
	v_rcp_f32_e32 v40, v40
	v_rcp_f32_e32 v41, v41
	v_pk_mul_f32 v[32:33], v[32:33], v[2:3]
	v_pk_mul_f32 v[36:37], v[36:37], v[4:5]
	v_pk_mul_f32 v[38:39], v[38:39], v[6:7]
	v_pk_mul_f32 v[30:31], v[40:41], v[30:31]
	v_cvt_pk_bf16_f32 v6, v32, v33
	v_cvt_pk_bf16_f32 v5, v36, v37
	v_cvt_pk_bf16_f32 v4, v38, v39
	v_pk_add_f32 v[0:1], v[10:11], v[0:1]
	v_cvt_pk_bf16_f32 v3, v30, v31
	s_waitcnt lgkmcnt(0)
	ds_read_b128 v[172:175], v255 offset:0
	ds_read_b128 v[176:179], v255 offset:16
	ds_read_b128 v[180:183], v255 offset:32
	ds_read_b128 v[184:187], v255 offset:48
	ds_read_b128 v[188:191], v255 offset:64
	ds_read_b128 v[192:195], v255 offset:80
	ds_read_b128 v[196:199], v255 offset:96
	ds_read_b128 v[200:203], v255 offset:112
	ds_read_b128 v[204:207], v255 offset:128
	ds_read_b128 v[208:211], v255 offset:144
	ds_read_b128 v[212:215], v255 offset:160
	ds_read_b128 v[216:219], v255 offset:176
	ds_read_b128 v[220:223], v255 offset:192
	ds_read_b128 v[228:231], v255 offset:208
	ds_read_b128 v[232:235], v255 offset:224
	ds_read_b128 v[236:239], v255 offset:240
	v_pk_mul_f32 v[10:11], v[46:47], v[46:47]
	v_mov_b32_e32 v16, v8
	v_mov_b32_e32 v44, v9
	v_pk_mul_f32 v[12:13], v[42:43], v[42:43]
	v_mov_b32_e32 v35, v46
	v_mov_b32_e32 v34, v10
	v_mov_b32_e32 v46, v11
	v_pk_add_f32 v[8:9], v[16:17], v[44:45]
	v_pk_mul_f32 v[14:15], v[50:51], v[50:51]
	v_mov_b32_e32 v53, v42
	v_mov_b32_e32 v52, v12
	v_mov_b32_e32 v42, v13
	v_pk_add_f32 v[10:11], v[34:35], v[46:47]
	v_pk_add_f32 v[0:1], v[0:1], v[8:9]
	v_mov_b32_e32 v55, v50
	v_mov_b32_e32 v54, v14
	v_mov_b32_e32 v50, v15
	v_pk_add_f32 v[12:13], v[52:53], v[42:43]
	v_pk_add_f32 v[0:1], v[10:11], v[0:1]
	v_pk_mul_f32 v[8:9], v[32:33], v[32:33]
	v_pk_add_f32 v[14:15], v[54:55], v[50:51]
	v_pk_add_f32 v[0:1], v[12:13], v[0:1]
	v_pk_mul_f32 v[10:11], v[36:37], v[36:37]
	v_mov_b32_e32 v17, v32
	v_mov_b32_e32 v16, v8
	v_mov_b32_e32 v32, v9
	v_pk_add_f32 v[0:1], v[14:15], v[0:1]
	v_pk_mul_f32 v[12:13], v[38:39], v[38:39]
	v_mov_b32_e32 v35, v36
	v_mov_b32_e32 v34, v10
	v_mov_b32_e32 v36, v11
	v_pk_add_f32 v[8:9], v[16:17], v[32:33]
	v_pk_mul_f32 v[14:15], v[30:31], v[30:31]
	v_mov_b32_e32 v43, v38
	v_mov_b32_e32 v42, v12
	v_mov_b32_e32 v38, v13
	v_pk_add_f32 v[10:11], v[34:35], v[36:37]
	v_pk_add_f32 v[0:1], v[0:1], v[8:9]
	v_mov_b32_e32 v45, v30
	v_mov_b32_e32 v44, v14
	v_mov_b32_e32 v30, v15
	v_pk_add_f32 v[12:13], v[42:43], v[38:39]
	v_pk_add_f32 v[0:1], v[10:11], v[0:1]
	v_pk_add_f32 v[14:15], v[44:45], v[30:31]
	v_pk_add_f32 v[0:1], v[12:13], v[0:1]
	v_lshlrev_b32_e32 v8, 16, v114
	v_pk_add_f32 v[0:1], v[14:15], v[0:1]
	v_and_b32_e32 v9, 0xffff0000, v114
	v_pk_mul_f32 v[0:1], v[0:1], s[44:45] op_sel_hi:[1,0]
	v_lshlrev_b32_e32 v12, 16, v112
	v_fma_f32 v2, -v1, v1, v0
	v_max_f32_e32 v2, 0, v2
	v_add_f32_e32 v2, 0x3727c5ac, v2
	v_rsq_f32_e32 v2, v2
	v_pk_add_f32 v[8:9], v[8:9], v[0:1] op_sel:[0,1] neg_lo:[0,1] neg_hi:[0,1]
	v_and_b32_e32 v13, 0xffff0000, v112
	s_mul_i32 s45, s45, 0x8a00
	v_pk_mul_f32 v[8:9], v[8:9], v[2:3] op_sel_hi:[1,0]
	v_pk_add_f32 v[12:13], v[12:13], v[0:1] op_sel:[0,1] neg_lo:[0,1] neg_hi:[0,1]
	s_add_i32 s26, s45, 0
	v_pk_mul_f32 v[12:13], v[12:13], v[2:3] op_sel_hi:[1,0]
	v_lshl_add_u32 v7, v109, 1, s26
	s_bfe_u32 s10, s11, 0x10006
	v_and_b32_e32 v15, 0xffff0000, v3
	s_and_b32 s11, 64, s11
	s_cmp_eq_u32 s10, 0
	s_waitcnt lgkmcnt(15)
	v_pk_fma_f32 v[8:9], v[172:173], v[8:9], v[174:175]
	s_nop 0
	v_cvt_pk_bf16_f32 v14, v8, v9
	ds_write_b16 v7, v14
	ds_write_b16_d16_hi v7, v14 offset:272
	s_waitcnt lgkmcnt(15)
	v_pk_fma_f32 v[8:9], v[176:177], v[12:13], v[178:179]
	s_nop 0
	v_cvt_pk_bf16_f32 v14, v8, v9
	v_lshlrev_b32_e32 v12, 16, v111
	v_and_b32_e32 v13, 0xffff0000, v111
	v_pk_add_f32 v[12:13], v[12:13], v[0:1] op_sel:[0,1] neg_lo:[0,1] neg_hi:[0,1]
	ds_write_b16 v7, v14 offset:544
	ds_write_b16_d16_hi v7, v14 offset:816
	v_pk_mul_f32 v[12:13], v[12:13], v[2:3] op_sel_hi:[1,0]
	s_waitcnt lgkmcnt(15)
	v_pk_fma_f32 v[8:9], v[180:181], v[12:13], v[182:183]
	s_nop 0
	v_cvt_pk_bf16_f32 v14, v8, v9
	v_lshlrev_b32_e32 v12, 16, v110
	v_and_b32_e32 v13, 0xffff0000, v110
	v_pk_add_f32 v[12:13], v[12:13], v[0:1] op_sel:[0,1] neg_lo:[0,1] neg_hi:[0,1]
	ds_write_b16 v7, v14 offset:1088
	ds_write_b16_d16_hi v7, v14 offset:1360
	v_pk_mul_f32 v[12:13], v[12:13], v[2:3] op_sel_hi:[1,0]
	s_waitcnt lgkmcnt(15)
	v_pk_fma_f32 v[8:9], v[184:185], v[12:13], v[186:187]
	s_nop 0
	v_cvt_pk_bf16_f32 v14, v8, v9
	v_lshlrev_b32_e32 v12, 16, v117
	v_and_b32_e32 v13, 0xffff0000, v117
	v_pk_add_f32 v[12:13], v[12:13], v[0:1] op_sel:[0,1] neg_lo:[0,1] neg_hi:[0,1]
	ds_write_b16 v7, v14 offset:1632
	ds_write_b16_d16_hi v7, v14 offset:1904
	v_pk_mul_f32 v[12:13], v[12:13], v[2:3] op_sel_hi:[1,0]
	s_waitcnt lgkmcnt(15)
	v_pk_fma_f32 v[8:9], v[188:189], v[12:13], v[190:191]
	s_nop 0
	v_cvt_pk_bf16_f32 v14, v8, v9
	v_lshlrev_b32_e32 v12, 16, v116
	v_and_b32_e32 v13, 0xffff0000, v116
	v_pk_add_f32 v[12:13], v[12:13], v[0:1] op_sel:[0,1] neg_lo:[0,1] neg_hi:[0,1]
	ds_write_b16 v7, v14 offset:2176
	ds_write_b16_d16_hi v7, v14 offset:2448
	v_pk_mul_f32 v[12:13], v[12:13], v[2:3] op_sel_hi:[1,0]
	s_waitcnt lgkmcnt(15)
	v_pk_fma_f32 v[8:9], v[12:13], v[192:193], v[194:195]
	s_nop 0
	v_cvt_pk_bf16_f32 v14, v8, v9
	v_lshlrev_b32_e32 v12, 16, v115
	v_and_b32_e32 v13, 0xffff0000, v115
	v_pk_add_f32 v[12:13], v[12:13], v[0:1] op_sel:[0,1] neg_lo:[0,1] neg_hi:[0,1]
	ds_write_b16 v7, v14 offset:2720
	ds_write_b16_d16_hi v7, v14 offset:2992
	v_pk_mul_f32 v[12:13], v[12:13], v[2:3] op_sel_hi:[1,0]
	v_bfe_u32 v115, v108, 5, 1
	v_lshlrev_b32_e32 v88, 5, v115
	s_waitcnt lgkmcnt(15)
	v_pk_fma_f32 v[8:9], v[12:13], v[196:197], v[198:199]
	s_nop 0
	v_cvt_pk_bf16_f32 v14, v8, v9
	v_lshlrev_b32_e32 v12, 16, v113
	v_and_b32_e32 v13, 0xffff0000, v113
	v_pk_add_f32 v[12:13], v[12:13], v[0:1] op_sel:[0,1] neg_lo:[0,1] neg_hi:[0,1]
	ds_write_b16 v7, v14 offset:3264
	ds_write_b16_d16_hi v7, v14 offset:3536
	v_pk_mul_f32 v[12:13], v[12:13], v[2:3] op_sel_hi:[1,0]
	s_waitcnt lgkmcnt(15)
	v_pk_fma_f32 v[8:9], v[12:13], v[200:201], v[202:203]
	s_nop 0
	v_cvt_pk_bf16_f32 v14, v8, v9
	ds_read_b128 v[172:175], v255 offset:256
	ds_read_b128 v[176:179], v255 offset:272
	ds_read_b128 v[180:183], v255 offset:288
	ds_read_b128 v[184:187], v255 offset:304
	ds_read_b128 v[188:191], v255 offset:320
	ds_read_b128 v[192:195], v255 offset:336
	ds_read_b128 v[196:199], v255 offset:352
	ds_read_b128 v[200:203], v255 offset:368
	v_lshlrev_b32_e32 v12, 16, v122
	v_and_b32_e32 v13, 0xffff0000, v122
	v_pk_add_f32 v[12:13], v[12:13], v[0:1] op_sel:[0,1] neg_lo:[0,1] neg_hi:[0,1]
	ds_write_b16 v7, v14 offset:3808
	ds_write_b16_d16_hi v7, v14 offset:4080
	v_pk_mul_f32 v[12:13], v[12:13], v[2:3] op_sel_hi:[1,0]
	s_waitcnt lgkmcnt(15)
	v_pk_fma_f32 v[8:9], v[12:13], v[204:205], v[206:207]
	s_nop 0
	v_cvt_pk_bf16_f32 v14, v8, v9
	v_lshlrev_b32_e32 v12, 16, v120
	v_and_b32_e32 v13, 0xffff0000, v120
	v_pk_add_f32 v[12:13], v[12:13], v[0:1] op_sel:[0,1] neg_lo:[0,1] neg_hi:[0,1]
	ds_write_b16 v7, v14 offset:4352
	ds_write_b16_d16_hi v7, v14 offset:4624
	v_pk_mul_f32 v[12:13], v[12:13], v[2:3] op_sel_hi:[1,0]
	s_waitcnt lgkmcnt(15)
	v_pk_fma_f32 v[8:9], v[12:13], v[208:209], v[210:211]
	s_nop 0
	v_cvt_pk_bf16_f32 v14, v8, v9
	v_lshlrev_b32_e32 v12, 16, v119
	v_and_b32_e32 v13, 0xffff0000, v119
	v_pk_add_f32 v[12:13], v[12:13], v[0:1] op_sel:[0,1] neg_lo:[0,1] neg_hi:[0,1]
	ds_write_b16 v7, v14 offset:4896
	ds_write_b16_d16_hi v7, v14 offset:5168
	v_pk_mul_f32 v[12:13], v[12:13], v[2:3] op_sel_hi:[1,0]
	s_waitcnt lgkmcnt(15)
	v_pk_fma_f32 v[8:9], v[12:13], v[212:213], v[214:215]
	s_nop 0
	v_cvt_pk_bf16_f32 v14, v8, v9
	v_lshlrev_b32_e32 v12, 16, v118
	v_and_b32_e32 v13, 0xffff0000, v118
	v_pk_add_f32 v[12:13], v[12:13], v[0:1] op_sel:[0,1] neg_lo:[0,1] neg_hi:[0,1]
	ds_write_b16 v7, v14 offset:5440
	ds_write_b16_d16_hi v7, v14 offset:5712
	v_pk_mul_f32 v[12:13], v[12:13], v[2:3] op_sel_hi:[1,0]
	v_and_b32_e32 v118, 31, v108
	s_waitcnt lgkmcnt(15)
	v_pk_fma_f32 v[8:9], v[12:13], v[216:217], v[218:219]
	s_nop 0
	v_cvt_pk_bf16_f32 v14, v8, v9
	v_lshlrev_b32_e32 v12, 16, v126
	v_and_b32_e32 v13, 0xffff0000, v126
	v_pk_add_f32 v[12:13], v[12:13], v[0:1] op_sel:[0,1] neg_lo:[0,1] neg_hi:[0,1]
	ds_write_b16 v7, v14 offset:5984
	ds_write_b16_d16_hi v7, v14 offset:6256
	v_pk_mul_f32 v[12:13], v[12:13], v[2:3] op_sel_hi:[1,0]
	s_waitcnt lgkmcnt(15)
	v_pk_fma_f32 v[8:9], v[12:13], v[220:221], v[222:223]
	s_nop 0
	v_cvt_pk_bf16_f32 v14, v8, v9
	v_lshlrev_b32_e32 v12, 16, v124
	v_and_b32_e32 v13, 0xffff0000, v124
	v_pk_add_f32 v[12:13], v[12:13], v[0:1] op_sel:[0,1] neg_lo:[0,1] neg_hi:[0,1]
	ds_write_b16 v7, v14 offset:6528
	ds_write_b16_d16_hi v7, v14 offset:6800
	v_pk_mul_f32 v[12:13], v[12:13], v[2:3] op_sel_hi:[1,0]
	v_lshl_or_b32 v124, s10, 5, v118
	s_waitcnt lgkmcnt(15)
	v_pk_fma_f32 v[8:9], v[12:13], v[228:229], v[230:231]
	s_nop 0
	v_cvt_pk_bf16_f32 v14, v8, v9
	v_lshlrev_b32_e32 v12, 16, v123
	v_and_b32_e32 v13, 0xffff0000, v123
	v_pk_add_f32 v[12:13], v[12:13], v[0:1] op_sel:[0,1] neg_lo:[0,1] neg_hi:[0,1]
	ds_write_b16 v7, v14 offset:7072
	ds_write_b16_d16_hi v7, v14 offset:7344
	v_pk_mul_f32 v[12:13], v[12:13], v[2:3] op_sel_hi:[1,0]
	s_waitcnt lgkmcnt(15)
	v_pk_fma_f32 v[8:9], v[12:13], v[232:233], v[234:235]
	s_nop 0
	v_cvt_pk_bf16_f32 v14, v8, v9
	v_lshlrev_b32_e32 v12, 16, v121
	v_and_b32_e32 v13, 0xffff0000, v121
	v_pk_add_f32 v[12:13], v[12:13], v[0:1] op_sel:[0,1] neg_lo:[0,1] neg_hi:[0,1]
	ds_write_b16 v7, v14 offset:7616
	ds_write_b16_d16_hi v7, v14 offset:7888
	v_pk_mul_f32 v[12:13], v[12:13], v[2:3] op_sel_hi:[1,0]
	s_waitcnt lgkmcnt(15)
	v_pk_fma_f32 v[8:9], v[12:13], v[236:237], v[238:239]
	s_nop 0
	v_cvt_pk_bf16_f32 v14, v8, v9
	ds_read_b128 v[204:207], v255 offset:384
	ds_read_b128 v[208:211], v255 offset:400
	ds_read_b128 v[212:215], v255 offset:416
	ds_read_b128 v[216:219], v255 offset:432
	ds_read_b128 v[220:223], v255 offset:448
	ds_read_b128 v[228:231], v255 offset:464
	ds_read_b128 v[232:235], v255 offset:480
	ds_read_b128 v[236:239], v255 offset:496
	v_lshlrev_b32_e32 v12, 16, v129
	v_and_b32_e32 v13, 0xffff0000, v129
	v_pk_add_f32 v[12:13], v[12:13], v[0:1] op_sel:[0,1] neg_lo:[0,1] neg_hi:[0,1]
	ds_write_b16 v7, v14 offset:8160
	ds_write_b16_d16_hi v7, v14 offset:8432
	v_pk_mul_f32 v[12:13], v[12:13], v[2:3] op_sel_hi:[1,0]
	s_waitcnt lgkmcnt(15)
	v_pk_fma_f32 v[8:9], v[12:13], v[172:173], v[174:175]
	s_nop 0
	v_cvt_pk_bf16_f32 v14, v8, v9
	v_lshlrev_b32_e32 v12, 16, v128
	v_and_b32_e32 v13, 0xffff0000, v128
	v_pk_add_f32 v[12:13], v[12:13], v[0:1] op_sel:[0,1] neg_lo:[0,1] neg_hi:[0,1]
	ds_write_b16 v7, v14 offset:8704
	ds_write_b16_d16_hi v7, v14 offset:8976
	v_pk_mul_f32 v[12:13], v[12:13], v[2:3] op_sel_hi:[1,0]
	s_waitcnt lgkmcnt(15)
	v_pk_fma_f32 v[8:9], v[12:13], v[176:177], v[178:179]
	s_nop 0
	v_cvt_pk_bf16_f32 v14, v8, v9
	v_lshlrev_b32_e32 v12, 16, v127
	v_and_b32_e32 v13, 0xffff0000, v127
	v_pk_add_f32 v[12:13], v[12:13], v[0:1] op_sel:[0,1] neg_lo:[0,1] neg_hi:[0,1]
	ds_write_b16 v7, v14 offset:9248
	ds_write_b16_d16_hi v7, v14 offset:9520
	v_pk_mul_f32 v[12:13], v[12:13], v[2:3] op_sel_hi:[1,0]
	s_waitcnt lgkmcnt(15)
	v_pk_fma_f32 v[8:9], v[12:13], v[180:181], v[182:183]
	s_nop 0
	v_cvt_pk_bf16_f32 v14, v8, v9
	v_lshlrev_b32_e32 v12, 16, v125
	v_and_b32_e32 v13, 0xffff0000, v125
	v_pk_add_f32 v[12:13], v[12:13], v[0:1] op_sel:[0,1] neg_lo:[0,1] neg_hi:[0,1]
	ds_write_b16 v7, v14 offset:9792
	ds_write_b16_d16_hi v7, v14 offset:10064
	v_pk_mul_f32 v[12:13], v[12:13], v[2:3] op_sel_hi:[1,0]
	s_waitcnt lgkmcnt(15)
	v_pk_fma_f32 v[8:9], v[12:13], v[184:185], v[186:187]
	s_nop 0
	v_cvt_pk_bf16_f32 v14, v8, v9
	v_lshlrev_b32_e32 v12, 16, v134
	v_and_b32_e32 v13, 0xffff0000, v134
	v_pk_add_f32 v[12:13], v[12:13], v[0:1] op_sel:[0,1] neg_lo:[0,1] neg_hi:[0,1]
	ds_write_b16 v7, v14 offset:10336
	ds_write_b16_d16_hi v7, v14 offset:10608
	v_pk_mul_f32 v[12:13], v[12:13], v[2:3] op_sel_hi:[1,0]
	s_waitcnt lgkmcnt(15)
	v_pk_fma_f32 v[8:9], v[12:13], v[188:189], v[190:191]
	s_nop 0
	v_cvt_pk_bf16_f32 v14, v8, v9
	v_lshlrev_b32_e32 v12, 16, v132
	v_and_b32_e32 v13, 0xffff0000, v132
	v_pk_add_f32 v[12:13], v[12:13], v[0:1] op_sel:[0,1] neg_lo:[0,1] neg_hi:[0,1]
	ds_write_b16 v7, v14 offset:10880
	ds_write_b16_d16_hi v7, v14 offset:11152
	v_pk_mul_f32 v[12:13], v[12:13], v[2:3] op_sel_hi:[1,0]
	s_waitcnt lgkmcnt(15)
	v_pk_fma_f32 v[8:9], v[12:13], v[192:193], v[194:195]
	s_nop 0
	v_cvt_pk_bf16_f32 v14, v8, v9
	v_lshlrev_b32_e32 v12, 16, v131
	v_and_b32_e32 v13, 0xffff0000, v131
	v_pk_add_f32 v[12:13], v[12:13], v[0:1] op_sel:[0,1] neg_lo:[0,1] neg_hi:[0,1]
	ds_write_b16 v7, v14 offset:11424
	ds_write_b16_d16_hi v7, v14 offset:11696
	v_pk_mul_f32 v[12:13], v[12:13], v[2:3] op_sel_hi:[1,0]
	s_waitcnt lgkmcnt(15)
	v_pk_fma_f32 v[8:9], v[12:13], v[196:197], v[198:199]
	s_nop 0
	v_cvt_pk_bf16_f32 v14, v8, v9
	v_lshlrev_b32_e32 v12, 16, v130
	v_and_b32_e32 v13, 0xffff0000, v130
	v_pk_add_f32 v[12:13], v[12:13], v[0:1] op_sel:[0,1] neg_lo:[0,1] neg_hi:[0,1]
	ds_write_b16 v7, v14 offset:11968
	ds_write_b16_d16_hi v7, v14 offset:12240
	v_pk_mul_f32 v[12:13], v[12:13], v[2:3] op_sel_hi:[1,0]
	s_waitcnt lgkmcnt(15)
	v_pk_fma_f32 v[8:9], v[12:13], v[200:201], v[202:203]
	s_nop 0
	v_cvt_pk_bf16_f32 v14, v8, v9
	ds_read_b128 v[172:175], v255 offset:512
	ds_read_b128 v[176:179], v255 offset:528
	ds_read_b128 v[180:183], v255 offset:544
	ds_read_b128 v[184:187], v255 offset:560
	ds_read_b128 v[188:191], v255 offset:576
	ds_read_b128 v[192:195], v255 offset:592
	ds_read_b128 v[196:199], v255 offset:608
	ds_read_b128 v[200:203], v255 offset:624
	v_lshlrev_b32_e32 v12, 16, v137
	v_and_b32_e32 v13, 0xffff0000, v137
	v_pk_add_f32 v[12:13], v[12:13], v[0:1] op_sel:[0,1] neg_lo:[0,1] neg_hi:[0,1]
	ds_write_b16 v7, v14 offset:12512
	ds_write_b16_d16_hi v7, v14 offset:12784
	v_pk_mul_f32 v[12:13], v[12:13], v[2:3] op_sel_hi:[1,0]
	s_waitcnt lgkmcnt(15)
	v_pk_fma_f32 v[8:9], v[12:13], v[204:205], v[206:207]
	s_nop 0
	v_cvt_pk_bf16_f32 v14, v8, v9
	v_lshlrev_b32_e32 v12, 16, v136
	v_and_b32_e32 v13, 0xffff0000, v136
	v_pk_add_f32 v[12:13], v[12:13], v[0:1] op_sel:[0,1] neg_lo:[0,1] neg_hi:[0,1]
	ds_write_b16 v7, v14 offset:13056
	ds_write_b16_d16_hi v7, v14 offset:13328
	v_pk_mul_f32 v[12:13], v[12:13], v[2:3] op_sel_hi:[1,0]
	s_waitcnt lgkmcnt(15)
	v_pk_fma_f32 v[8:9], v[12:13], v[208:209], v[210:211]
	s_nop 0
	v_cvt_pk_bf16_f32 v14, v8, v9
	v_lshlrev_b32_e32 v12, 16, v135
	v_and_b32_e32 v13, 0xffff0000, v135
	v_pk_add_f32 v[12:13], v[12:13], v[0:1] op_sel:[0,1] neg_lo:[0,1] neg_hi:[0,1]
	ds_write_b16 v7, v14 offset:13600
	ds_write_b16_d16_hi v7, v14 offset:13872
	v_pk_mul_f32 v[12:13], v[12:13], v[2:3] op_sel_hi:[1,0]
	s_waitcnt lgkmcnt(15)
	v_pk_fma_f32 v[8:9], v[12:13], v[212:213], v[214:215]
	s_nop 0
	v_cvt_pk_bf16_f32 v14, v8, v9
	v_lshlrev_b32_e32 v12, 16, v133
	v_and_b32_e32 v13, 0xffff0000, v133
	v_pk_add_f32 v[12:13], v[12:13], v[0:1] op_sel:[0,1] neg_lo:[0,1] neg_hi:[0,1]
	ds_write_b16 v7, v14 offset:14144
	ds_write_b16_d16_hi v7, v14 offset:14416
	v_pk_mul_f32 v[12:13], v[12:13], v[2:3] op_sel_hi:[1,0]
	s_waitcnt lgkmcnt(15)
	v_pk_fma_f32 v[8:9], v[12:13], v[216:217], v[218:219]
	s_nop 0
	v_cvt_pk_bf16_f32 v14, v8, v9
	v_lshlrev_b32_e32 v12, 16, v142
	v_and_b32_e32 v13, 0xffff0000, v142
	v_pk_add_f32 v[12:13], v[12:13], v[0:1] op_sel:[0,1] neg_lo:[0,1] neg_hi:[0,1]
	ds_write_b16 v7, v14 offset:14688
	ds_write_b16_d16_hi v7, v14 offset:14960
	v_pk_mul_f32 v[12:13], v[12:13], v[2:3] op_sel_hi:[1,0]
	s_waitcnt lgkmcnt(15)
	v_pk_fma_f32 v[8:9], v[12:13], v[220:221], v[222:223]
	s_nop 0
	v_cvt_pk_bf16_f32 v14, v8, v9
	v_lshlrev_b32_e32 v12, 16, v140
	v_and_b32_e32 v13, 0xffff0000, v140
	v_pk_add_f32 v[12:13], v[12:13], v[0:1] op_sel:[0,1] neg_lo:[0,1] neg_hi:[0,1]
	ds_write_b16 v7, v14 offset:15232
	ds_write_b16_d16_hi v7, v14 offset:15504
	v_pk_mul_f32 v[12:13], v[12:13], v[2:3] op_sel_hi:[1,0]
	s_waitcnt lgkmcnt(15)
	v_pk_fma_f32 v[8:9], v[12:13], v[228:229], v[230:231]
	s_nop 0
	v_cvt_pk_bf16_f32 v14, v8, v9
	v_lshlrev_b32_e32 v12, 16, v139
	v_and_b32_e32 v13, 0xffff0000, v139
	v_pk_add_f32 v[12:13], v[12:13], v[0:1] op_sel:[0,1] neg_lo:[0,1] neg_hi:[0,1]
	ds_write_b16 v7, v14 offset:15776
	ds_write_b16_d16_hi v7, v14 offset:16048
	v_pk_mul_f32 v[12:13], v[12:13], v[2:3] op_sel_hi:[1,0]
	s_waitcnt lgkmcnt(15)
	v_pk_fma_f32 v[8:9], v[12:13], v[232:233], v[234:235]
	s_nop 0
	v_cvt_pk_bf16_f32 v14, v8, v9
	v_lshlrev_b32_e32 v12, 16, v138
	v_and_b32_e32 v13, 0xffff0000, v138
	v_pk_add_f32 v[12:13], v[12:13], v[0:1] op_sel:[0,1] neg_lo:[0,1] neg_hi:[0,1]
	ds_write_b16 v7, v14 offset:16320
	ds_write_b16_d16_hi v7, v14 offset:16592
	v_pk_mul_f32 v[12:13], v[12:13], v[2:3] op_sel_hi:[1,0]
	s_waitcnt lgkmcnt(15)
	v_pk_fma_f32 v[8:9], v[12:13], v[236:237], v[238:239]
	s_nop 0
	v_cvt_pk_bf16_f32 v14, v8, v9
	ds_read_b128 v[204:207], v255 offset:640
	ds_read_b128 v[208:211], v255 offset:656
	ds_read_b128 v[212:215], v255 offset:672
	ds_read_b128 v[216:219], v255 offset:688
	ds_read_b128 v[220:223], v255 offset:704
	ds_read_b128 v[228:231], v255 offset:720
	ds_read_b128 v[232:235], v255 offset:736
	ds_read_b128 v[236:239], v255 offset:752
	v_lshlrev_b32_e32 v12, 16, v146
	v_and_b32_e32 v13, 0xffff0000, v146
	v_pk_add_f32 v[12:13], v[12:13], v[0:1] op_sel:[0,1] neg_lo:[0,1] neg_hi:[0,1]
	ds_write_b16 v7, v14 offset:16864
	ds_write_b16_d16_hi v7, v14 offset:17136
	v_pk_mul_f32 v[12:13], v[12:13], v[2:3] op_sel_hi:[1,0]
	s_waitcnt lgkmcnt(15)
	v_pk_fma_f32 v[8:9], v[12:13], v[172:173], v[174:175]
	s_nop 0
	v_cvt_pk_bf16_f32 v14, v8, v9
	v_lshlrev_b32_e32 v12, 16, v144
	v_and_b32_e32 v13, 0xffff0000, v144
	v_pk_add_f32 v[12:13], v[12:13], v[0:1] op_sel:[0,1] neg_lo:[0,1] neg_hi:[0,1]
	ds_write_b16 v7, v14 offset:17408
	ds_write_b16_d16_hi v7, v14 offset:17680
	v_pk_mul_f32 v[12:13], v[12:13], v[2:3] op_sel_hi:[1,0]
	s_waitcnt lgkmcnt(15)
	v_pk_fma_f32 v[8:9], v[12:13], v[176:177], v[178:179]
	s_nop 0
	v_cvt_pk_bf16_f32 v14, v8, v9
	v_lshlrev_b32_e32 v12, 16, v143
	v_and_b32_e32 v13, 0xffff0000, v143
	v_pk_add_f32 v[12:13], v[12:13], v[0:1] op_sel:[0,1] neg_lo:[0,1] neg_hi:[0,1]
	ds_write_b16 v7, v14 offset:17952
	ds_write_b16_d16_hi v7, v14 offset:18224
	v_pk_mul_f32 v[12:13], v[12:13], v[2:3] op_sel_hi:[1,0]
	s_waitcnt lgkmcnt(15)
	v_pk_fma_f32 v[8:9], v[12:13], v[180:181], v[182:183]
	s_nop 0
	v_cvt_pk_bf16_f32 v14, v8, v9
	v_lshlrev_b32_e32 v12, 16, v141
	v_and_b32_e32 v13, 0xffff0000, v141
	v_pk_add_f32 v[12:13], v[12:13], v[0:1] op_sel:[0,1] neg_lo:[0,1] neg_hi:[0,1]
	ds_write_b16 v7, v14 offset:18496
	ds_write_b16_d16_hi v7, v14 offset:18768
	v_pk_mul_f32 v[12:13], v[12:13], v[2:3] op_sel_hi:[1,0]
	s_waitcnt lgkmcnt(15)
	v_pk_fma_f32 v[8:9], v[12:13], v[184:185], v[186:187]
	s_nop 0
	v_cvt_pk_bf16_f32 v14, v8, v9
	v_lshlrev_b32_e32 v12, 16, v149
	v_and_b32_e32 v13, 0xffff0000, v149
	v_pk_add_f32 v[12:13], v[12:13], v[0:1] op_sel:[0,1] neg_lo:[0,1] neg_hi:[0,1]
	ds_write_b16 v7, v14 offset:19040
	ds_write_b16_d16_hi v7, v14 offset:19312
	v_pk_mul_f32 v[12:13], v[12:13], v[2:3] op_sel_hi:[1,0]
	s_waitcnt lgkmcnt(15)
	v_pk_fma_f32 v[8:9], v[12:13], v[188:189], v[190:191]
	s_nop 0
	v_cvt_pk_bf16_f32 v14, v8, v9
	v_lshlrev_b32_e32 v12, 16, v148
	v_and_b32_e32 v13, 0xffff0000, v148
	v_pk_add_f32 v[12:13], v[12:13], v[0:1] op_sel:[0,1] neg_lo:[0,1] neg_hi:[0,1]
	ds_write_b16 v7, v14 offset:19584
	ds_write_b16_d16_hi v7, v14 offset:19856
	v_pk_mul_f32 v[12:13], v[12:13], v[2:3] op_sel_hi:[1,0]
	s_waitcnt lgkmcnt(15)
	v_pk_fma_f32 v[8:9], v[12:13], v[192:193], v[194:195]
	s_nop 0
	v_cvt_pk_bf16_f32 v14, v8, v9
	v_lshlrev_b32_e32 v12, 16, v147
	v_and_b32_e32 v13, 0xffff0000, v147
	v_pk_add_f32 v[12:13], v[12:13], v[0:1] op_sel:[0,1] neg_lo:[0,1] neg_hi:[0,1]
	ds_write_b16 v7, v14 offset:20128
	ds_write_b16_d16_hi v7, v14 offset:20400
	v_pk_mul_f32 v[12:13], v[12:13], v[2:3] op_sel_hi:[1,0]
	s_waitcnt lgkmcnt(15)
	v_pk_fma_f32 v[8:9], v[12:13], v[196:197], v[198:199]
	s_nop 0
	v_cvt_pk_bf16_f32 v14, v8, v9
	v_lshlrev_b32_e32 v12, 16, v145
	v_and_b32_e32 v13, 0xffff0000, v145
	v_pk_add_f32 v[12:13], v[12:13], v[0:1] op_sel:[0,1] neg_lo:[0,1] neg_hi:[0,1]
	ds_write_b16 v7, v14 offset:20672
	ds_write_b16_d16_hi v7, v14 offset:20944
	v_pk_mul_f32 v[12:13], v[12:13], v[2:3] op_sel_hi:[1,0]
	s_waitcnt lgkmcnt(15)
	v_pk_fma_f32 v[8:9], v[12:13], v[200:201], v[202:203]
	s_nop 0
	v_cvt_pk_bf16_f32 v14, v8, v9
	ds_read_b128 v[172:175], v255 offset:768
	ds_read_b128 v[176:179], v255 offset:784
	ds_read_b128 v[180:183], v255 offset:800
	ds_read_b128 v[184:187], v255 offset:816
	ds_read_b128 v[188:191], v255 offset:832
	ds_read_b128 v[192:195], v255 offset:848
	ds_read_b128 v[196:199], v255 offset:864
	ds_read_b128 v[200:203], v255 offset:880
	v_lshlrev_b32_e32 v12, 16, v154
	v_and_b32_e32 v13, 0xffff0000, v154
	v_pk_add_f32 v[12:13], v[12:13], v[0:1] op_sel:[0,1] neg_lo:[0,1] neg_hi:[0,1]
	ds_write_b16 v7, v14 offset:21216
	ds_write_b16_d16_hi v7, v14 offset:21488
	v_pk_mul_f32 v[12:13], v[12:13], v[2:3] op_sel_hi:[1,0]
	s_waitcnt lgkmcnt(15)
	v_pk_fma_f32 v[8:9], v[12:13], v[204:205], v[206:207]
	s_nop 0
	v_cvt_pk_bf16_f32 v14, v8, v9
	v_lshlrev_b32_e32 v12, 16, v152
	v_and_b32_e32 v13, 0xffff0000, v152
	v_pk_add_f32 v[12:13], v[12:13], v[0:1] op_sel:[0,1] neg_lo:[0,1] neg_hi:[0,1]
	ds_write_b16 v7, v14 offset:21760
	ds_write_b16_d16_hi v7, v14 offset:22032
	v_pk_mul_f32 v[12:13], v[12:13], v[2:3] op_sel_hi:[1,0]
	s_waitcnt lgkmcnt(15)
	v_pk_fma_f32 v[8:9], v[12:13], v[208:209], v[210:211]
	s_nop 0
	v_cvt_pk_bf16_f32 v14, v8, v9
	v_lshlrev_b32_e32 v12, 16, v151
	v_and_b32_e32 v13, 0xffff0000, v151
	v_pk_add_f32 v[12:13], v[12:13], v[0:1] op_sel:[0,1] neg_lo:[0,1] neg_hi:[0,1]
	ds_write_b16 v7, v14 offset:22304
	ds_write_b16_d16_hi v7, v14 offset:22576
	v_pk_mul_f32 v[12:13], v[12:13], v[2:3] op_sel_hi:[1,0]
	s_waitcnt lgkmcnt(15)
	v_pk_fma_f32 v[8:9], v[12:13], v[212:213], v[214:215]
	s_nop 0
	v_cvt_pk_bf16_f32 v14, v8, v9
	v_lshlrev_b32_e32 v12, 16, v150
	v_and_b32_e32 v13, 0xffff0000, v150
	v_pk_add_f32 v[12:13], v[12:13], v[0:1] op_sel:[0,1] neg_lo:[0,1] neg_hi:[0,1]
	ds_write_b16 v7, v14 offset:22848
	ds_write_b16_d16_hi v7, v14 offset:23120
	v_pk_mul_f32 v[12:13], v[12:13], v[2:3] op_sel_hi:[1,0]
	s_waitcnt lgkmcnt(15)
	v_pk_fma_f32 v[8:9], v[12:13], v[216:217], v[218:219]
	s_nop 0
	v_cvt_pk_bf16_f32 v14, v8, v9
	v_lshlrev_b32_e32 v12, 16, v157
	v_and_b32_e32 v13, 0xffff0000, v157
	v_pk_add_f32 v[12:13], v[12:13], v[0:1] op_sel:[0,1] neg_lo:[0,1] neg_hi:[0,1]
	ds_write_b16 v7, v14 offset:23392
	ds_write_b16_d16_hi v7, v14 offset:23664
	v_pk_mul_f32 v[12:13], v[12:13], v[2:3] op_sel_hi:[1,0]
	s_waitcnt lgkmcnt(15)
	v_pk_fma_f32 v[8:9], v[12:13], v[220:221], v[222:223]
	s_nop 0
	v_cvt_pk_bf16_f32 v14, v8, v9
	v_lshlrev_b32_e32 v12, 16, v156
	v_and_b32_e32 v13, 0xffff0000, v156
	v_pk_add_f32 v[12:13], v[12:13], v[0:1] op_sel:[0,1] neg_lo:[0,1] neg_hi:[0,1]
	ds_write_b16 v7, v14 offset:23936
	ds_write_b16_d16_hi v7, v14 offset:24208
	v_pk_mul_f32 v[12:13], v[12:13], v[2:3] op_sel_hi:[1,0]
	s_waitcnt lgkmcnt(15)
	v_pk_fma_f32 v[8:9], v[12:13], v[228:229], v[230:231]
	s_nop 0
	v_cvt_pk_bf16_f32 v14, v8, v9
	v_lshlrev_b32_e32 v12, 16, v155
	v_and_b32_e32 v13, 0xffff0000, v155
	v_pk_add_f32 v[12:13], v[12:13], v[0:1] op_sel:[0,1] neg_lo:[0,1] neg_hi:[0,1]
	ds_write_b16 v7, v14 offset:24480
	ds_write_b16_d16_hi v7, v14 offset:24752
	v_pk_mul_f32 v[12:13], v[12:13], v[2:3] op_sel_hi:[1,0]
	s_waitcnt lgkmcnt(15)
	v_pk_fma_f32 v[8:9], v[12:13], v[232:233], v[234:235]
	s_nop 0
	v_cvt_pk_bf16_f32 v14, v8, v9
	v_lshlrev_b32_e32 v12, 16, v153
	v_and_b32_e32 v13, 0xffff0000, v153
	v_pk_add_f32 v[12:13], v[12:13], v[0:1] op_sel:[0,1] neg_lo:[0,1] neg_hi:[0,1]
	ds_write_b16 v7, v14 offset:25024
	ds_write_b16_d16_hi v7, v14 offset:25296
	v_pk_mul_f32 v[12:13], v[12:13], v[2:3] op_sel_hi:[1,0]
	s_waitcnt lgkmcnt(15)
	v_pk_fma_f32 v[8:9], v[12:13], v[236:237], v[238:239]
	s_nop 0
	v_cvt_pk_bf16_f32 v14, v8, v9
	ds_read_b128 v[204:207], v255 offset:896
	ds_read_b128 v[208:211], v255 offset:912
	ds_read_b128 v[212:215], v255 offset:928
	ds_read_b128 v[216:219], v255 offset:944
	ds_read_b128 v[220:223], v255 offset:960
	ds_read_b128 v[228:231], v255 offset:976
	ds_read_b128 v[232:235], v255 offset:992
	ds_read_b128 v[236:239], v255 offset:1008
	v_lshlrev_b32_e32 v12, 16, v22
	v_and_b32_e32 v13, 0xffff0000, v22
	v_pk_add_f32 v[12:13], v[12:13], v[0:1] op_sel:[0,1] neg_lo:[0,1] neg_hi:[0,1]
	ds_write_b16 v7, v14 offset:25568
	ds_write_b16_d16_hi v7, v14 offset:25840
	v_pk_mul_f32 v[12:13], v[12:13], v[2:3] op_sel_hi:[1,0]
	s_waitcnt lgkmcnt(15)
	v_pk_fma_f32 v[8:9], v[12:13], v[172:173], v[174:175]
	s_nop 0
	v_cvt_pk_bf16_f32 v14, v8, v9
	v_lshlrev_b32_e32 v12, 16, v20
	v_and_b32_e32 v13, 0xffff0000, v20
	v_pk_add_f32 v[12:13], v[12:13], v[0:1] op_sel:[0,1] neg_lo:[0,1] neg_hi:[0,1]
	ds_write_b16 v7, v14 offset:26112
	ds_write_b16_d16_hi v7, v14 offset:26384
	v_pk_mul_f32 v[12:13], v[12:13], v[2:3] op_sel_hi:[1,0]
	s_waitcnt lgkmcnt(15)
	v_pk_fma_f32 v[8:9], v[12:13], v[176:177], v[178:179]
	s_nop 0
	v_cvt_pk_bf16_f32 v14, v8, v9
	v_lshlrev_b32_e32 v12, 16, v19
	v_and_b32_e32 v13, 0xffff0000, v19
	v_pk_add_f32 v[12:13], v[12:13], v[0:1] op_sel:[0,1] neg_lo:[0,1] neg_hi:[0,1]
	ds_write_b16 v7, v14 offset:26656
	ds_write_b16_d16_hi v7, v14 offset:26928
	v_pk_mul_f32 v[12:13], v[12:13], v[2:3] op_sel_hi:[1,0]
	s_waitcnt lgkmcnt(15)
	v_pk_fma_f32 v[8:9], v[12:13], v[180:181], v[182:183]
	s_nop 0
	v_cvt_pk_bf16_f32 v14, v8, v9
	v_lshlrev_b32_e32 v12, 16, v18
	v_and_b32_e32 v13, 0xffff0000, v18
	v_pk_add_f32 v[12:13], v[12:13], v[0:1] op_sel:[0,1] neg_lo:[0,1] neg_hi:[0,1]
	ds_write_b16 v7, v14 offset:27200
	ds_write_b16_d16_hi v7, v14 offset:27472
	v_pk_mul_f32 v[12:13], v[12:13], v[2:3] op_sel_hi:[1,0]
	s_waitcnt lgkmcnt(15)
	v_pk_fma_f32 v[8:9], v[12:13], v[184:185], v[186:187]
	s_nop 0
	v_cvt_pk_bf16_f32 v14, v8, v9
	v_lshlrev_b32_e32 v12, 16, v26
	v_and_b32_e32 v13, 0xffff0000, v26
	v_pk_add_f32 v[12:13], v[12:13], v[0:1] op_sel:[0,1] neg_lo:[0,1] neg_hi:[0,1]
	ds_write_b16 v7, v14 offset:27744
	ds_write_b16_d16_hi v7, v14 offset:28016
	v_pk_mul_f32 v[12:13], v[12:13], v[2:3] op_sel_hi:[1,0]
	s_waitcnt lgkmcnt(15)
	v_pk_fma_f32 v[8:9], v[12:13], v[188:189], v[190:191]
	s_nop 0
	v_cvt_pk_bf16_f32 v14, v8, v9
	v_lshlrev_b32_e32 v12, 16, v24
	v_and_b32_e32 v13, 0xffff0000, v24
	v_pk_add_f32 v[12:13], v[12:13], v[0:1] op_sel:[0,1] neg_lo:[0,1] neg_hi:[0,1]
	ds_write_b16 v7, v14 offset:28288
	ds_write_b16_d16_hi v7, v14 offset:28560
	v_pk_mul_f32 v[12:13], v[12:13], v[2:3] op_sel_hi:[1,0]
	s_waitcnt lgkmcnt(15)
	v_pk_fma_f32 v[8:9], v[12:13], v[192:193], v[194:195]
	s_nop 0
	v_cvt_pk_bf16_f32 v14, v8, v9
	v_lshlrev_b32_e32 v12, 16, v23
	v_and_b32_e32 v13, 0xffff0000, v23
	v_pk_add_f32 v[12:13], v[12:13], v[0:1] op_sel:[0,1] neg_lo:[0,1] neg_hi:[0,1]
	ds_write_b16 v7, v14 offset:28832
	ds_write_b16_d16_hi v7, v14 offset:29104
	v_pk_mul_f32 v[12:13], v[12:13], v[2:3] op_sel_hi:[1,0]
	s_waitcnt lgkmcnt(15)
	v_pk_fma_f32 v[8:9], v[12:13], v[196:197], v[198:199]
	s_nop 0
	v_cvt_pk_bf16_f32 v14, v8, v9
	v_lshlrev_b32_e32 v12, 16, v21
	v_and_b32_e32 v13, 0xffff0000, v21
	v_pk_add_f32 v[12:13], v[12:13], v[0:1] op_sel:[0,1] neg_lo:[0,1] neg_hi:[0,1]
	ds_write_b16 v7, v14 offset:29376
	ds_write_b16_d16_hi v7, v14 offset:29648
	v_pk_mul_f32 v[12:13], v[12:13], v[2:3] op_sel_hi:[1,0]
	s_waitcnt lgkmcnt(15)
	v_pk_fma_f32 v[8:9], v[12:13], v[200:201], v[202:203]
	s_nop 0
	v_cvt_pk_bf16_f32 v14, v8, v9
	v_lshlrev_b32_e32 v12, 16, v29
	v_and_b32_e32 v13, 0xffff0000, v29
	v_pk_add_f32 v[12:13], v[12:13], v[0:1] op_sel:[0,1] neg_lo:[0,1] neg_hi:[0,1]
	ds_write_b16 v7, v14 offset:29920
	ds_write_b16_d16_hi v7, v14 offset:30192
	v_pk_mul_f32 v[12:13], v[12:13], v[2:3] op_sel_hi:[1,0]
	s_waitcnt lgkmcnt(15)
	v_pk_fma_f32 v[8:9], v[12:13], v[204:205], v[206:207]
	s_nop 0
	v_cvt_pk_bf16_f32 v14, v8, v9
	v_lshlrev_b32_e32 v12, 16, v28
	v_and_b32_e32 v13, 0xffff0000, v28
	v_pk_add_f32 v[12:13], v[12:13], v[0:1] op_sel:[0,1] neg_lo:[0,1] neg_hi:[0,1]
	ds_write_b16 v7, v14 offset:30464
	ds_write_b16_d16_hi v7, v14 offset:30736
	v_pk_mul_f32 v[12:13], v[12:13], v[2:3] op_sel_hi:[1,0]
	s_waitcnt lgkmcnt(15)
	v_pk_fma_f32 v[8:9], v[12:13], v[208:209], v[210:211]
	s_nop 0
	v_cvt_pk_bf16_f32 v14, v8, v9
	v_lshlrev_b32_e32 v12, 16, v27
	v_and_b32_e32 v13, 0xffff0000, v27
	v_pk_add_f32 v[12:13], v[12:13], v[0:1] op_sel:[0,1] neg_lo:[0,1] neg_hi:[0,1]
	ds_write_b16 v7, v14 offset:31008
	ds_write_b16_d16_hi v7, v14 offset:31280
	v_pk_mul_f32 v[12:13], v[12:13], v[2:3] op_sel_hi:[1,0]
	s_waitcnt lgkmcnt(15)
	v_pk_fma_f32 v[8:9], v[12:13], v[212:213], v[214:215]
	s_nop 0
	v_cvt_pk_bf16_f32 v14, v8, v9
	v_lshlrev_b32_e32 v12, 16, v25
	v_and_b32_e32 v13, 0xffff0000, v25
	v_pk_add_f32 v[12:13], v[12:13], v[0:1] op_sel:[0,1] neg_lo:[0,1] neg_hi:[0,1]
	ds_write_b16 v7, v14 offset:31552
	ds_write_b16_d16_hi v7, v14 offset:31824
	v_pk_mul_f32 v[12:13], v[12:13], v[2:3] op_sel_hi:[1,0]
	s_waitcnt lgkmcnt(15)
	v_pk_fma_f32 v[8:9], v[12:13], v[216:217], v[218:219]
	s_nop 0
	v_cvt_pk_bf16_f32 v14, v8, v9
	v_lshlrev_b32_e32 v12, 16, v6
	v_and_b32_e32 v13, 0xffff0000, v6
	v_pk_add_f32 v[12:13], v[12:13], v[0:1] op_sel:[0,1] neg_lo:[0,1] neg_hi:[0,1]
	ds_write_b16 v7, v14 offset:32096
	ds_write_b16_d16_hi v7, v14 offset:32368
	v_pk_mul_f32 v[12:13], v[12:13], v[2:3] op_sel_hi:[1,0]
	v_lshlrev_b32_e32 v14, 16, v3
	s_waitcnt lgkmcnt(15)
	v_pk_fma_f32 v[8:9], v[12:13], v[220:221], v[222:223]
	s_nop 0
	v_cvt_pk_bf16_f32 v6, v8, v9
	v_lshlrev_b32_e32 v12, 16, v5
	v_and_b32_e32 v13, 0xffff0000, v5
	v_pk_add_f32 v[12:13], v[12:13], v[0:1] op_sel:[0,1] neg_lo:[0,1] neg_hi:[0,1]
	ds_write_b16 v7, v6 offset:32640
	ds_write_b16_d16_hi v7, v6 offset:32912
	v_pk_mul_f32 v[12:13], v[12:13], v[2:3] op_sel_hi:[1,0]
	s_waitcnt lgkmcnt(15)
	v_pk_fma_f32 v[8:9], v[12:13], v[228:229], v[230:231]
	s_nop 0
	v_cvt_pk_bf16_f32 v6, v8, v9
	v_lshlrev_b32_e32 v12, 16, v4
	v_and_b32_e32 v13, 0xffff0000, v4
	v_pk_add_f32 v[4:5], v[12:13], v[0:1] op_sel:[0,1] neg_lo:[0,1] neg_hi:[0,1]
	ds_write_b16 v7, v6 offset:33184
	ds_write_b16_d16_hi v7, v6 offset:33456
	v_pk_mul_f32 v[4:5], v[4:5], v[2:3] op_sel_hi:[1,0]
	v_pk_add_f32 v[0:1], v[14:15], v[0:1] op_sel:[0,1] neg_lo:[0,1] neg_hi:[0,1]
	s_waitcnt lgkmcnt(15)
	v_pk_fma_f32 v[4:5], v[4:5], v[232:233], v[234:235]
	s_nop 0
	v_cvt_pk_bf16_f32 v6, v4, v5
	s_mov_b64 s[12:13], 0x40000
	v_or_b32_e32 v10, s43, v124
	v_lshl_add_u64 v[8:9], s[16:17], 0, v[88:89]
	v_pk_mul_f32 v[0:1], v[0:1], v[2:3] op_sel_hi:[1,0]
	v_lshlrev_b32_e32 v88, 9, v10
	v_lshl_add_u64 v[90:91], v[8:9], 0, s[12:13]
	v_lshl_add_u64 v[8:9], v[90:91], 0, v[88:89]
	ds_write_b16 v7, v6 offset:33728
	ds_write_b16_d16_hi v7, v6 offset:34000
	s_cselect_b64 s[14:15], -1, 0
	s_cmp_lg_u32 s11, 0
	s_cselect_b64 s[12:13], -1, 0
	s_and_b64 vcc, exec, s[14:15]
	s_waitcnt lgkmcnt(15)
	v_pk_fma_f32 v[0:1], v[0:1], v[236:237], v[238:239]
	s_nop 0
	v_cvt_pk_bf16_f32 v0, v0, v1
	ds_write_b16 v7, v0 offset:34272
	ds_write_b16_d16_hi v7, v0 offset:34544
	s_waitcnt lgkmcnt(0)
	s_barrier
	global_load_dwordx4 v[0:3], v[8:9], off offset:16
	global_load_dwordx4 v[4:7], v[8:9], off
	global_load_dwordx4 v[80:83], v[8:9], off offset:80
	global_load_dwordx4 v[84:87], v[8:9], off offset:64
	s_cbranch_vccnz .LBB0_1274
	global_load_dwordx4 v[76:79], v[8:9], off offset:128
	global_load_dwordx4 v[72:75], v[8:9], off offset:144

.LBB0_1280:
	s_waitcnt vmcnt(15)
	v_lshlrev_b32_e32 v66, 16, v116
	v_and_b32_e32 v67, 0xffff0000, v116
	v_pk_mul_f32 v[70:71], v[66:67], v[66:67]
	s_mov_b32 s10, 0x3d372713
	v_lshlrev_b32_e32 v72, 16, v117
	v_and_b32_e32 v73, 0xffff0000, v117
	v_pk_fma_f32 v[70:71], v[70:71], s[10:11], 1.0 op_sel_hi:[1,0,0]
	v_pk_mul_f32 v[74:75], v[72:73], v[72:73]
	v_pk_mul_f32 v[70:71], v[70:71], v[66:67]
	s_mov_b32 s16, 0xc0135761
	v_pk_fma_f32 v[74:75], v[74:75], s[10:11], 1.0 op_sel_hi:[1,0,0]
	v_pk_mul_f32 v[70:71], v[70:71], s[16:17] op_sel_hi:[1,0]
	v_pk_mul_f32 v[74:75], v[74:75], v[72:73]
	v_exp_f32_e32 v70, v70
	v_exp_f32_e32 v71, v71
	v_pk_mul_f32 v[74:75], v[74:75], s[16:17] op_sel_hi:[1,0]
	s_add_u32 s12, s36, 0xa000000
	v_exp_f32_e32 v74, v74
	v_exp_f32_e32 v75, v75
	v_pk_add_f32 v[70:71], v[70:71], 1.0 op_sel_hi:[1,0]
	s_addc_u32 s13, s37, 0
	v_rcp_f32_e32 v70, v70
	v_rcp_f32_e32 v71, v71
	v_pk_add_f32 v[74:75], v[74:75], 1.0 op_sel_hi:[1,0]
	v_lshlrev_b64 v[64:65], 11, v[114:115]
	v_rcp_f32_e32 v74, v74
	v_rcp_f32_e32 v75, v75
	v_lshl_add_u64 v[64:65], s[12:13], 0, v[64:65]
	v_pk_mul_f32 v[66:67], v[70:71], v[66:67]
	v_pk_add_f32 v[48:49], v[68:69], v[48:49] op_sel_hi:[0,1]
	v_lshl_add_u64 v[64:65], v[64:65], 0, s[38:39]
	v_lshlrev_b32_e32 v122, 1, v88
	v_mov_b32_e32 v123, 0
	v_pk_mul_f32 v[48:49], v[66:67], v[48:49]
	v_pk_mul_f32 v[66:67], v[74:75], v[72:73]
	v_pk_add_f32 v[50:51], v[68:69], v[50:51] op_sel_hi:[0,1]
	v_lshl_add_u64 v[64:65], v[64:65], 0, v[122:123]
	v_bfe_u32 v138, v224, 5, 1
	v_lshlrev_b32_e32 v138, 3, v138
	v_mov_b32_e32 v139, 0
	v_lshl_add_u64 v[136:137], v[64:65], 0, v[138:139]
	v_pk_mul_f32 v[50:51], v[66:67], v[50:51]
	v_cvt_pk_bf16_f32 v128, v48, v49
	s_waitcnt vmcnt(14)
	v_lshlrev_b32_e32 v66, 16, v113
	v_cvt_pk_bf16_f32 v129, v50, v51
	v_lshlrev_b32_e32 v48, 16, v112
	v_and_b32_e32 v49, 0xffff0000, v112
	v_pk_mul_f32 v[50:51], v[48:49], v[48:49]
	v_and_b32_e32 v67, 0xffff0000, v113
	v_pk_fma_f32 v[50:51], v[50:51], s[10:11], 1.0 op_sel_hi:[1,0,0]
	v_pk_mul_f32 v[70:71], v[66:67], v[66:67]
	v_pk_mul_f32 v[50:51], v[50:51], v[48:49]
	v_pk_fma_f32 v[70:71], v[70:71], s[10:11], 1.0 op_sel_hi:[1,0,0]
	v_pk_mul_f32 v[50:51], v[50:51], s[16:17] op_sel_hi:[1,0]
	v_pk_mul_f32 v[70:71], v[70:71], v[66:67]
	v_exp_f32_e32 v50, v50
	v_exp_f32_e32 v51, v51
	v_pk_mul_f32 v[70:71], v[70:71], s[16:17] op_sel_hi:[1,0]
	v_pk_add_f32 v[32:33], v[68:69], v[32:33] op_sel_hi:[0,1]
	v_exp_f32_e32 v70, v70
	v_exp_f32_e32 v71, v71
	v_pk_add_f32 v[50:51], v[50:51], 1.0 op_sel_hi:[1,0]
	v_pk_add_f32 v[34:35], v[68:69], v[34:35] op_sel_hi:[0,1]
	v_rcp_f32_e32 v50, v50
	v_rcp_f32_e32 v51, v51
	v_pk_add_f32 v[70:71], v[70:71], 1.0 op_sel_hi:[1,0]
	v_pk_add_f32 v[16:17], v[68:69], v[16:17] op_sel_hi:[0,1]
	v_rcp_f32_e32 v70, v70
	v_rcp_f32_e32 v71, v71
	v_pk_mul_f32 v[48:49], v[50:51], v[48:49]
	v_pk_add_f32 v[50:51], v[68:69], v[52:53] op_sel_hi:[0,1]
	v_pk_mul_f32 v[48:49], v[48:49], v[50:51]
	v_pk_mul_f32 v[50:51], v[70:71], v[66:67]
	v_pk_add_f32 v[52:53], v[68:69], v[54:55] op_sel_hi:[0,1]
	v_pk_mul_f32 v[50:51], v[50:51], v[52:53]
	v_cvt_pk_bf16_f32 v130, v48, v49
	s_waitcnt vmcnt(13)
	v_lshlrev_b32_e32 v52, 16, v111
	v_cvt_pk_bf16_f32 v131, v50, v51
	s_nop 1
	v_permlane32_swap_b32_e32 v128, v130
	v_permlane32_swap_b32_e32 v129, v131
	global_store_dwordx4 v[136:137], v[128:131], off offset:1024
	v_lshlrev_b32_e32 v48, 16, v110
	v_and_b32_e32 v49, 0xffff0000, v110
	v_pk_mul_f32 v[50:51], v[48:49], v[48:49]
	v_and_b32_e32 v53, 0xffff0000, v111
	v_pk_fma_f32 v[50:51], v[50:51], s[10:11], 1.0 op_sel_hi:[1,0,0]
	v_pk_mul_f32 v[54:55], v[52:53], v[52:53]
	v_pk_mul_f32 v[50:51], v[50:51], v[48:49]
	v_pk_fma_f32 v[54:55], v[54:55], s[10:11], 1.0 op_sel_hi:[1,0,0]
	v_pk_mul_f32 v[50:51], v[50:51], s[16:17] op_sel_hi:[1,0]
	v_pk_mul_f32 v[54:55], v[54:55], v[52:53]
	v_exp_f32_e32 v50, v50
	v_exp_f32_e32 v51, v51
	v_pk_mul_f32 v[54:55], v[54:55], s[16:17] op_sel_hi:[1,0]
	v_pk_add_f32 v[18:19], v[68:69], v[18:19] op_sel_hi:[0,1]
	v_exp_f32_e32 v54, v54
	v_exp_f32_e32 v55, v55
	v_pk_add_f32 v[50:51], v[50:51], 1.0 op_sel_hi:[1,0]
	v_pk_add_f32 v[0:1], v[68:69], v[0:1] op_sel_hi:[0,1]
	v_rcp_f32_e32 v50, v50
	v_rcp_f32_e32 v51, v51
	v_pk_add_f32 v[54:55], v[54:55], 1.0 op_sel_hi:[1,0]
	v_pk_add_f32 v[2:3], v[68:69], v[2:3] op_sel_hi:[0,1]
	v_rcp_f32_e32 v54, v54
	v_rcp_f32_e32 v55, v55
	v_pk_mul_f32 v[48:49], v[50:51], v[48:49]
	v_pk_add_f32 v[50:51], v[68:69], v[56:57] op_sel_hi:[0,1]
	v_pk_mul_f32 v[48:49], v[48:49], v[50:51]
	v_pk_mul_f32 v[50:51], v[54:55], v[52:53]
	v_pk_add_f32 v[52:53], v[68:69], v[58:59] op_sel_hi:[0,1]
	v_pk_mul_f32 v[50:51], v[50:51], v[52:53]
	v_cvt_pk_bf16_f32 v132, v48, v49
	s_waitcnt vmcnt(13)
	v_lshlrev_b32_e32 v52, 16, v109
	v_cvt_pk_bf16_f32 v133, v50, v51
	v_lshlrev_b32_e32 v48, 16, v108
	v_and_b32_e32 v49, 0xffff0000, v108
	v_pk_mul_f32 v[50:51], v[48:49], v[48:49]
	v_and_b32_e32 v53, 0xffff0000, v109
	v_pk_fma_f32 v[50:51], v[50:51], s[10:11], 1.0 op_sel_hi:[1,0,0]
	v_pk_mul_f32 v[54:55], v[52:53], v[52:53]
	v_pk_mul_f32 v[50:51], v[50:51], v[48:49]
	v_pk_fma_f32 v[54:55], v[54:55], s[10:11], 1.0 op_sel_hi:[1,0,0]
	v_pk_mul_f32 v[50:51], v[50:51], s[16:17] op_sel_hi:[1,0]
	v_pk_mul_f32 v[54:55], v[54:55], v[52:53]
	v_exp_f32_e32 v50, v50
	v_exp_f32_e32 v51, v51
	v_pk_mul_f32 v[54:55], v[54:55], s[16:17] op_sel_hi:[1,0]
	s_andn2_b64 vcc, exec, s[14:15]
	v_exp_f32_e32 v54, v54
	v_exp_f32_e32 v55, v55
	v_pk_add_f32 v[50:51], v[50:51], 1.0 op_sel_hi:[1,0]
	v_mov_b32_e32 v76, 0
	v_rcp_f32_e32 v50, v50
	v_rcp_f32_e32 v51, v51
	v_pk_add_f32 v[54:55], v[54:55], 1.0 op_sel_hi:[1,0]
	v_mov_b32_e32 v77, 0
	v_rcp_f32_e32 v54, v54
	v_rcp_f32_e32 v55, v55
	v_pk_mul_f32 v[48:49], v[50:51], v[48:49]
	v_pk_add_f32 v[50:51], v[68:69], v[60:61] op_sel_hi:[0,1]
	v_pk_mul_f32 v[48:49], v[48:49], v[50:51]
	v_pk_mul_f32 v[50:51], v[54:55], v[52:53]
	v_pk_add_f32 v[52:53], v[68:69], v[62:63] op_sel_hi:[0,1]
	v_pk_mul_f32 v[50:51], v[50:51], v[52:53]
	v_cvt_pk_bf16_f32 v134, v48, v49
	s_waitcnt vmcnt(12)
	v_lshlrev_b32_e32 v52, 16, v107
	v_cvt_pk_bf16_f32 v135, v50, v51
	s_nop 1
	v_permlane32_swap_b32_e32 v132, v134
	v_permlane32_swap_b32_e32 v133, v135
	global_store_dwordx4 v[136:137], v[132:135], off offset:1056
	v_lshlrev_b32_e32 v48, 16, v106
	v_and_b32_e32 v49, 0xffff0000, v106
	v_pk_mul_f32 v[50:51], v[48:49], v[48:49]
	v_and_b32_e32 v53, 0xffff0000, v107
	v_pk_fma_f32 v[50:51], v[50:51], s[10:11], 1.0 op_sel_hi:[1,0,0]
	v_pk_mul_f32 v[54:55], v[52:53], v[52:53]
	v_pk_mul_f32 v[50:51], v[50:51], v[48:49]
	v_pk_fma_f32 v[54:55], v[54:55], s[10:11], 1.0 op_sel_hi:[1,0,0]
	v_pk_mul_f32 v[50:51], v[50:51], s[16:17] op_sel_hi:[1,0]
	v_pk_mul_f32 v[54:55], v[54:55], v[52:53]
	v_exp_f32_e32 v50, v50
	v_exp_f32_e32 v51, v51
	v_pk_mul_f32 v[54:55], v[54:55], s[16:17] op_sel_hi:[1,0]
	v_mov_b32_e32 v78, 0
	v_exp_f32_e32 v54, v54
	v_exp_f32_e32 v55, v55
	v_pk_add_f32 v[50:51], v[50:51], 1.0 op_sel_hi:[1,0]
	v_mov_b32_e32 v79, 0
	v_rcp_f32_e32 v50, v50
	v_rcp_f32_e32 v51, v51
	v_pk_add_f32 v[54:55], v[54:55], 1.0 op_sel_hi:[1,0]
	v_mov_b32_e32 v72, 0
	v_rcp_f32_e32 v54, v54
	v_rcp_f32_e32 v55, v55
	v_pk_mul_f32 v[48:49], v[50:51], v[48:49]
	v_mov_b32_e32 v73, 0
	v_pk_mul_f32 v[32:33], v[48:49], v[32:33]
	v_pk_mul_f32 v[48:49], v[54:55], v[52:53]
	v_cvt_pk_bf16_f32 v128, v32, v33
	v_mov_b32_e32 v74, 0
	v_pk_mul_f32 v[34:35], v[48:49], v[34:35]
	s_waitcnt vmcnt(12)
	v_lshlrev_b32_e32 v48, 16, v105
	v_cvt_pk_bf16_f32 v129, v34, v35
	v_lshlrev_b32_e32 v32, 16, v104
	v_and_b32_e32 v33, 0xffff0000, v104
	v_pk_mul_f32 v[34:35], v[32:33], v[32:33]
	v_and_b32_e32 v49, 0xffff0000, v105
	v_pk_fma_f32 v[34:35], v[34:35], s[10:11], 1.0 op_sel_hi:[1,0,0]
	v_pk_mul_f32 v[50:51], v[48:49], v[48:49]
	v_pk_mul_f32 v[34:35], v[34:35], v[32:33]
	v_pk_fma_f32 v[50:51], v[50:51], s[10:11], 1.0 op_sel_hi:[1,0,0]
	v_pk_mul_f32 v[34:35], v[34:35], s[16:17] op_sel_hi:[1,0]
	v_pk_mul_f32 v[50:51], v[50:51], v[48:49]
	v_exp_f32_e32 v34, v34
	v_exp_f32_e32 v35, v35
	v_pk_mul_f32 v[50:51], v[50:51], s[16:17] op_sel_hi:[1,0]
	v_mov_b32_e32 v75, 0
	v_exp_f32_e32 v50, v50
	v_exp_f32_e32 v51, v51
	v_pk_add_f32 v[34:35], v[34:35], 1.0 op_sel_hi:[1,0]
	v_pk_add_f32 v[50:51], v[50:51], 1.0 op_sel_hi:[1,0]
	v_rcp_f32_e32 v34, v34
	v_rcp_f32_e32 v35, v35
	v_rcp_f32_e32 v50, v50
	v_rcp_f32_e32 v51, v51
	v_pk_mul_f32 v[32:33], v[34:35], v[32:33]
	v_pk_add_f32 v[34:35], v[68:69], v[36:37] op_sel_hi:[0,1]
	v_pk_mul_f32 v[32:33], v[32:33], v[34:35]
	v_pk_mul_f32 v[34:35], v[50:51], v[48:49]
	v_pk_add_f32 v[36:37], v[68:69], v[38:39] op_sel_hi:[0,1]
	v_pk_mul_f32 v[34:35], v[34:35], v[36:37]
	v_cvt_pk_bf16_f32 v130, v32, v33
	s_waitcnt vmcnt(11)
	v_lshlrev_b32_e32 v36, 16, v103
	v_cvt_pk_bf16_f32 v131, v34, v35
	s_nop 1
	v_permlane32_swap_b32_e32 v128, v130
	v_permlane32_swap_b32_e32 v129, v131
	global_store_dwordx4 v[136:137], v[128:131], off offset:1088
	v_lshlrev_b32_e32 v32, 16, v102
	v_and_b32_e32 v33, 0xffff0000, v102
	v_pk_mul_f32 v[34:35], v[32:33], v[32:33]
	v_and_b32_e32 v37, 0xffff0000, v103
	v_pk_fma_f32 v[34:35], v[34:35], s[10:11], 1.0 op_sel_hi:[1,0,0]
	v_pk_mul_f32 v[38:39], v[36:37], v[36:37]
	v_pk_mul_f32 v[34:35], v[34:35], v[32:33]
	v_pk_fma_f32 v[38:39], v[38:39], s[10:11], 1.0 op_sel_hi:[1,0,0]
	v_pk_mul_f32 v[34:35], v[34:35], s[16:17] op_sel_hi:[1,0]
	v_pk_mul_f32 v[38:39], v[38:39], v[36:37]
	v_exp_f32_e32 v34, v34
	v_exp_f32_e32 v35, v35
	v_pk_mul_f32 v[38:39], v[38:39], s[16:17] op_sel_hi:[1,0]
	v_pk_add_f32 v[34:35], v[34:35], 1.0 op_sel_hi:[1,0]
	v_exp_f32_e32 v38, v38
	v_exp_f32_e32 v39, v39
	v_rcp_f32_e32 v34, v34
	v_rcp_f32_e32 v35, v35
	v_pk_add_f32 v[38:39], v[38:39], 1.0 op_sel_hi:[1,0]
	s_nop 0
	v_rcp_f32_e32 v38, v38
	v_rcp_f32_e32 v39, v39
	v_pk_mul_f32 v[32:33], v[34:35], v[32:33]
	v_pk_add_f32 v[34:35], v[68:69], v[40:41] op_sel_hi:[0,1]
	v_pk_mul_f32 v[32:33], v[32:33], v[34:35]
	v_pk_mul_f32 v[34:35], v[38:39], v[36:37]
	v_pk_add_f32 v[36:37], v[68:69], v[42:43] op_sel_hi:[0,1]
	v_pk_mul_f32 v[34:35], v[34:35], v[36:37]
	v_cvt_pk_bf16_f32 v132, v32, v33
	s_waitcnt vmcnt(11)
	v_lshlrev_b32_e32 v36, 16, v101
	v_cvt_pk_bf16_f32 v133, v34, v35
	v_lshlrev_b32_e32 v32, 16, v100
	v_and_b32_e32 v33, 0xffff0000, v100
	v_pk_mul_f32 v[34:35], v[32:33], v[32:33]
	v_and_b32_e32 v37, 0xffff0000, v101
	v_pk_fma_f32 v[34:35], v[34:35], s[10:11], 1.0 op_sel_hi:[1,0,0]
	v_pk_mul_f32 v[38:39], v[36:37], v[36:37]
	v_pk_mul_f32 v[34:35], v[34:35], v[32:33]
	v_pk_fma_f32 v[38:39], v[38:39], s[10:11], 1.0 op_sel_hi:[1,0,0]
	v_pk_mul_f32 v[34:35], v[34:35], s[16:17] op_sel_hi:[1,0]
	v_pk_mul_f32 v[38:39], v[38:39], v[36:37]
	v_exp_f32_e32 v34, v34
	v_exp_f32_e32 v35, v35
	v_pk_mul_f32 v[38:39], v[38:39], s[16:17] op_sel_hi:[1,0]
	v_pk_add_f32 v[34:35], v[34:35], 1.0 op_sel_hi:[1,0]
	v_exp_f32_e32 v38, v38
	v_exp_f32_e32 v39, v39
	v_rcp_f32_e32 v34, v34
	v_rcp_f32_e32 v35, v35
	v_pk_add_f32 v[38:39], v[38:39], 1.0 op_sel_hi:[1,0]
	s_nop 0
	v_rcp_f32_e32 v38, v38
	v_rcp_f32_e32 v39, v39
	v_pk_mul_f32 v[32:33], v[34:35], v[32:33]
	v_pk_add_f32 v[34:35], v[68:69], v[44:45] op_sel_hi:[0,1]
	v_pk_mul_f32 v[32:33], v[32:33], v[34:35]
	v_pk_mul_f32 v[34:35], v[38:39], v[36:37]
	v_pk_add_f32 v[36:37], v[68:69], v[46:47] op_sel_hi:[0,1]
	v_pk_mul_f32 v[34:35], v[34:35], v[36:37]
	v_cvt_pk_bf16_f32 v134, v32, v33
	s_waitcnt vmcnt(10)
	v_lshlrev_b32_e32 v36, 16, v99
	v_cvt_pk_bf16_f32 v135, v34, v35
	s_nop 1
	v_permlane32_swap_b32_e32 v132, v134
	v_permlane32_swap_b32_e32 v133, v135
	global_store_dwordx4 v[136:137], v[132:135], off offset:1120
	v_lshlrev_b32_e32 v32, 16, v98
	v_and_b32_e32 v33, 0xffff0000, v98
	v_pk_mul_f32 v[34:35], v[32:33], v[32:33]
	v_and_b32_e32 v37, 0xffff0000, v99
	v_pk_fma_f32 v[34:35], v[34:35], s[10:11], 1.0 op_sel_hi:[1,0,0]
	v_pk_mul_f32 v[38:39], v[36:37], v[36:37]
	v_pk_mul_f32 v[34:35], v[34:35], v[32:33]
	v_pk_fma_f32 v[38:39], v[38:39], s[10:11], 1.0 op_sel_hi:[1,0,0]
	v_pk_mul_f32 v[34:35], v[34:35], s[16:17] op_sel_hi:[1,0]
	v_pk_mul_f32 v[38:39], v[38:39], v[36:37]
	v_exp_f32_e32 v34, v34
	v_exp_f32_e32 v35, v35
	v_pk_mul_f32 v[38:39], v[38:39], s[16:17] op_sel_hi:[1,0]
	v_pk_add_f32 v[34:35], v[34:35], 1.0 op_sel_hi:[1,0]
	v_exp_f32_e32 v38, v38
	v_exp_f32_e32 v39, v39
	v_rcp_f32_e32 v34, v34
	v_rcp_f32_e32 v35, v35
	v_pk_add_f32 v[38:39], v[38:39], 1.0 op_sel_hi:[1,0]
	s_nop 0
	v_rcp_f32_e32 v38, v38
	v_rcp_f32_e32 v39, v39
	v_pk_mul_f32 v[32:33], v[34:35], v[32:33]
	s_nop 0
	v_pk_mul_f32 v[16:17], v[32:33], v[16:17]
	v_pk_mul_f32 v[32:33], v[38:39], v[36:37]
	v_cvt_pk_bf16_f32 v128, v16, v17
	s_nop 0
	v_pk_mul_f32 v[18:19], v[32:33], v[18:19]
	s_waitcnt vmcnt(10)
	v_lshlrev_b32_e32 v32, 16, v97
	v_cvt_pk_bf16_f32 v129, v18, v19
	v_lshlrev_b32_e32 v16, 16, v96
	v_and_b32_e32 v17, 0xffff0000, v96
	v_pk_mul_f32 v[18:19], v[16:17], v[16:17]
	v_and_b32_e32 v33, 0xffff0000, v97
	v_pk_fma_f32 v[18:19], v[18:19], s[10:11], 1.0 op_sel_hi:[1,0,0]
	v_pk_mul_f32 v[34:35], v[32:33], v[32:33]
	v_pk_mul_f32 v[18:19], v[18:19], v[16:17]
	v_pk_fma_f32 v[34:35], v[34:35], s[10:11], 1.0 op_sel_hi:[1,0,0]
	v_pk_mul_f32 v[18:19], v[18:19], s[16:17] op_sel_hi:[1,0]
	v_pk_mul_f32 v[34:35], v[34:35], v[32:33]
	v_exp_f32_e32 v18, v18
	v_exp_f32_e32 v19, v19
	v_pk_mul_f32 v[34:35], v[34:35], s[16:17] op_sel_hi:[1,0]
	v_pk_add_f32 v[18:19], v[18:19], 1.0 op_sel_hi:[1,0]
	v_exp_f32_e32 v34, v34
	v_exp_f32_e32 v35, v35
	v_rcp_f32_e32 v18, v18
	v_rcp_f32_e32 v19, v19
	v_pk_add_f32 v[34:35], v[34:35], 1.0 op_sel_hi:[1,0]
	s_nop 0
	v_rcp_f32_e32 v34, v34
	v_rcp_f32_e32 v35, v35
	v_pk_mul_f32 v[16:17], v[18:19], v[16:17]
	v_pk_add_f32 v[18:19], v[68:69], v[20:21] op_sel_hi:[0,1]
	v_pk_mul_f32 v[16:17], v[16:17], v[18:19]
	v_pk_mul_f32 v[18:19], v[34:35], v[32:33]
	v_pk_add_f32 v[20:21], v[68:69], v[22:23] op_sel_hi:[0,1]
	v_pk_mul_f32 v[18:19], v[18:19], v[20:21]
	v_cvt_pk_bf16_f32 v130, v16, v17
	s_waitcnt vmcnt(9)
	v_lshlrev_b32_e32 v20, 16, v95
	v_cvt_pk_bf16_f32 v131, v18, v19
	s_nop 1
	v_permlane32_swap_b32_e32 v128, v130
	v_permlane32_swap_b32_e32 v129, v131
	global_store_dwordx4 v[136:137], v[128:131], off offset:1152
	v_lshlrev_b32_e32 v16, 16, v94
	v_and_b32_e32 v17, 0xffff0000, v94
	v_pk_mul_f32 v[18:19], v[16:17], v[16:17]
	v_and_b32_e32 v21, 0xffff0000, v95
	v_pk_fma_f32 v[18:19], v[18:19], s[10:11], 1.0 op_sel_hi:[1,0,0]
	v_pk_mul_f32 v[22:23], v[20:21], v[20:21]
	v_pk_mul_f32 v[18:19], v[18:19], v[16:17]
	v_pk_fma_f32 v[22:23], v[22:23], s[10:11], 1.0 op_sel_hi:[1,0,0]
	v_pk_mul_f32 v[18:19], v[18:19], s[16:17] op_sel_hi:[1,0]
	v_pk_mul_f32 v[22:23], v[22:23], v[20:21]
	v_exp_f32_e32 v18, v18
	v_exp_f32_e32 v19, v19
	v_pk_mul_f32 v[22:23], v[22:23], s[16:17] op_sel_hi:[1,0]
	v_pk_add_f32 v[18:19], v[18:19], 1.0 op_sel_hi:[1,0]
	v_exp_f32_e32 v22, v22
	v_exp_f32_e32 v23, v23
	v_rcp_f32_e32 v18, v18
	v_rcp_f32_e32 v19, v19
	v_pk_add_f32 v[22:23], v[22:23], 1.0 op_sel_hi:[1,0]
	s_nop 0
	v_rcp_f32_e32 v22, v22
	v_rcp_f32_e32 v23, v23
	v_pk_mul_f32 v[16:17], v[18:19], v[16:17]
	v_pk_add_f32 v[18:19], v[68:69], v[24:25] op_sel_hi:[0,1]
	v_pk_mul_f32 v[16:17], v[16:17], v[18:19]
	v_pk_mul_f32 v[18:19], v[22:23], v[20:21]
	v_pk_add_f32 v[20:21], v[68:69], v[26:27] op_sel_hi:[0,1]
	v_pk_mul_f32 v[18:19], v[18:19], v[20:21]
	v_cvt_pk_bf16_f32 v132, v16, v17
	s_waitcnt vmcnt(9)
	v_lshlrev_b32_e32 v20, 16, v93
	v_cvt_pk_bf16_f32 v133, v18, v19
	v_lshlrev_b32_e32 v16, 16, v92
	v_and_b32_e32 v17, 0xffff0000, v92
	v_pk_mul_f32 v[18:19], v[16:17], v[16:17]
	v_and_b32_e32 v21, 0xffff0000, v93
	v_pk_fma_f32 v[18:19], v[18:19], s[10:11], 1.0 op_sel_hi:[1,0,0]
	v_pk_mul_f32 v[22:23], v[20:21], v[20:21]
	v_pk_mul_f32 v[18:19], v[18:19], v[16:17]
	v_pk_fma_f32 v[22:23], v[22:23], s[10:11], 1.0 op_sel_hi:[1,0,0]
	v_pk_mul_f32 v[18:19], v[18:19], s[16:17] op_sel_hi:[1,0]
	v_pk_mul_f32 v[22:23], v[22:23], v[20:21]
	v_exp_f32_e32 v18, v18
	v_exp_f32_e32 v19, v19
	v_pk_mul_f32 v[22:23], v[22:23], s[16:17] op_sel_hi:[1,0]
	v_pk_add_f32 v[18:19], v[18:19], 1.0 op_sel_hi:[1,0]
	v_exp_f32_e32 v22, v22
	v_exp_f32_e32 v23, v23
	v_rcp_f32_e32 v18, v18
	v_rcp_f32_e32 v19, v19
	v_pk_add_f32 v[22:23], v[22:23], 1.0 op_sel_hi:[1,0]
	s_nop 0
	v_rcp_f32_e32 v22, v22
	v_rcp_f32_e32 v23, v23
	v_pk_mul_f32 v[16:17], v[18:19], v[16:17]
	v_pk_add_f32 v[18:19], v[68:69], v[28:29] op_sel_hi:[0,1]
	v_pk_mul_f32 v[16:17], v[16:17], v[18:19]
	v_pk_mul_f32 v[18:19], v[22:23], v[20:21]
	v_pk_add_f32 v[20:21], v[68:69], v[30:31] op_sel_hi:[0,1]
	v_pk_mul_f32 v[18:19], v[18:19], v[20:21]
	v_cvt_pk_bf16_f32 v134, v16, v17
	s_waitcnt vmcnt(8)
	v_lshlrev_b32_e32 v20, 16, v87
	v_cvt_pk_bf16_f32 v135, v18, v19
	s_nop 1
	v_permlane32_swap_b32_e32 v132, v134
	v_permlane32_swap_b32_e32 v133, v135
	global_store_dwordx4 v[136:137], v[132:135], off offset:1184
	v_lshlrev_b32_e32 v16, 16, v86
	v_and_b32_e32 v17, 0xffff0000, v86
	v_pk_mul_f32 v[18:19], v[16:17], v[16:17]
	v_and_b32_e32 v21, 0xffff0000, v87
	v_pk_fma_f32 v[18:19], v[18:19], s[10:11], 1.0 op_sel_hi:[1,0,0]
	v_pk_mul_f32 v[22:23], v[20:21], v[20:21]
	v_pk_mul_f32 v[18:19], v[18:19], v[16:17]
	v_pk_fma_f32 v[22:23], v[22:23], s[10:11], 1.0 op_sel_hi:[1,0,0]
	v_pk_mul_f32 v[18:19], v[18:19], s[16:17] op_sel_hi:[1,0]
	v_pk_mul_f32 v[22:23], v[22:23], v[20:21]
	v_exp_f32_e32 v18, v18
	v_exp_f32_e32 v19, v19
	v_pk_mul_f32 v[22:23], v[22:23], s[16:17] op_sel_hi:[1,0]
	v_pk_add_f32 v[18:19], v[18:19], 1.0 op_sel_hi:[1,0]
	v_exp_f32_e32 v22, v22
	v_exp_f32_e32 v23, v23
	v_rcp_f32_e32 v18, v18
	v_rcp_f32_e32 v19, v19
	v_pk_add_f32 v[22:23], v[22:23], 1.0 op_sel_hi:[1,0]
	s_nop 0
	v_rcp_f32_e32 v22, v22
	v_rcp_f32_e32 v23, v23
	v_pk_mul_f32 v[16:17], v[18:19], v[16:17]
	s_nop 0
	v_pk_mul_f32 v[0:1], v[16:17], v[0:1]
	v_pk_mul_f32 v[16:17], v[22:23], v[20:21]
	v_cvt_pk_bf16_f32 v128, v0, v1
	s_nop 0
	v_pk_mul_f32 v[2:3], v[16:17], v[2:3]
	s_waitcnt vmcnt(8)
	v_lshlrev_b32_e32 v16, 16, v85
	v_cvt_pk_bf16_f32 v129, v2, v3
	v_lshlrev_b32_e32 v0, 16, v84
	v_and_b32_e32 v1, 0xffff0000, v84
	v_pk_mul_f32 v[2:3], v[0:1], v[0:1]
	v_and_b32_e32 v17, 0xffff0000, v85
	v_pk_fma_f32 v[2:3], v[2:3], s[10:11], 1.0 op_sel_hi:[1,0,0]
	v_pk_mul_f32 v[18:19], v[16:17], v[16:17]
	v_pk_mul_f32 v[2:3], v[2:3], v[0:1]
	v_pk_fma_f32 v[18:19], v[18:19], s[10:11], 1.0 op_sel_hi:[1,0,0]
	v_pk_mul_f32 v[2:3], v[2:3], s[16:17] op_sel_hi:[1,0]
	v_pk_mul_f32 v[18:19], v[18:19], v[16:17]
	v_exp_f32_e32 v2, v2
	v_exp_f32_e32 v3, v3
	v_pk_mul_f32 v[18:19], v[18:19], s[16:17] op_sel_hi:[1,0]
	v_pk_add_f32 v[2:3], v[2:3], 1.0 op_sel_hi:[1,0]
	v_exp_f32_e32 v18, v18
	v_exp_f32_e32 v19, v19
	v_rcp_f32_e32 v2, v2
	v_rcp_f32_e32 v3, v3
	v_pk_add_f32 v[18:19], v[18:19], 1.0 op_sel_hi:[1,0]
	s_nop 0
	v_rcp_f32_e32 v18, v18
	v_rcp_f32_e32 v19, v19
	v_pk_mul_f32 v[0:1], v[2:3], v[0:1]
	v_pk_add_f32 v[2:3], v[68:69], v[4:5] op_sel_hi:[0,1]
	v_pk_mul_f32 v[0:1], v[0:1], v[2:3]
	v_pk_mul_f32 v[2:3], v[18:19], v[16:17]
	v_pk_add_f32 v[4:5], v[68:69], v[6:7] op_sel_hi:[0,1]
	v_pk_mul_f32 v[2:3], v[2:3], v[4:5]
	v_cvt_pk_bf16_f32 v130, v0, v1
	s_waitcnt vmcnt(7)
	v_lshlrev_b32_e32 v4, 16, v83
	v_cvt_pk_bf16_f32 v131, v2, v3
	s_nop 1
	v_permlane32_swap_b32_e32 v128, v130
	v_permlane32_swap_b32_e32 v129, v131
	global_store_dwordx4 v[136:137], v[128:131], off offset:1216
	v_lshlrev_b32_e32 v0, 16, v82
	v_and_b32_e32 v1, 0xffff0000, v82
	v_pk_mul_f32 v[2:3], v[0:1], v[0:1]
	v_and_b32_e32 v5, 0xffff0000, v83
	v_pk_fma_f32 v[2:3], v[2:3], s[10:11], 1.0 op_sel_hi:[1,0,0]
	v_pk_mul_f32 v[6:7], v[4:5], v[4:5]
	v_pk_mul_f32 v[2:3], v[2:3], v[0:1]
	v_pk_fma_f32 v[6:7], v[6:7], s[10:11], 1.0 op_sel_hi:[1,0,0]
	v_pk_mul_f32 v[2:3], v[2:3], s[16:17] op_sel_hi:[1,0]
	v_pk_mul_f32 v[6:7], v[6:7], v[4:5]
	v_exp_f32_e32 v2, v2
	v_exp_f32_e32 v3, v3
	v_pk_mul_f32 v[6:7], v[6:7], s[16:17] op_sel_hi:[1,0]
	v_pk_add_f32 v[2:3], v[2:3], 1.0 op_sel_hi:[1,0]
	v_exp_f32_e32 v6, v6
	v_exp_f32_e32 v7, v7
	v_rcp_f32_e32 v2, v2
	v_rcp_f32_e32 v3, v3
	v_pk_add_f32 v[6:7], v[6:7], 1.0 op_sel_hi:[1,0]
	s_nop 0
	v_rcp_f32_e32 v6, v6
	v_rcp_f32_e32 v7, v7
	v_pk_mul_f32 v[0:1], v[2:3], v[0:1]
	v_pk_add_f32 v[2:3], v[68:69], v[8:9] op_sel_hi:[0,1]
	v_pk_mul_f32 v[0:1], v[0:1], v[2:3]
	v_pk_mul_f32 v[2:3], v[6:7], v[4:5]
	v_pk_add_f32 v[4:5], v[68:69], v[10:11] op_sel_hi:[0,1]
	v_pk_mul_f32 v[2:3], v[2:3], v[4:5]
	v_cvt_pk_bf16_f32 v132, v0, v1
	s_waitcnt vmcnt(7)
	v_lshlrev_b32_e32 v4, 16, v81
	v_cvt_pk_bf16_f32 v133, v2, v3
	v_lshlrev_b32_e32 v0, 16, v80
	v_and_b32_e32 v1, 0xffff0000, v80
	v_pk_mul_f32 v[2:3], v[0:1], v[0:1]
	v_and_b32_e32 v5, 0xffff0000, v81
	v_pk_fma_f32 v[2:3], v[2:3], s[10:11], 1.0 op_sel_hi:[1,0,0]
	v_pk_mul_f32 v[6:7], v[4:5], v[4:5]
	v_pk_mul_f32 v[2:3], v[2:3], v[0:1]
	v_pk_fma_f32 v[6:7], v[6:7], s[10:11], 1.0 op_sel_hi:[1,0,0]
	v_pk_mul_f32 v[2:3], v[2:3], s[16:17] op_sel_hi:[1,0]
	v_pk_mul_f32 v[6:7], v[6:7], v[4:5]
	v_exp_f32_e32 v2, v2
	v_exp_f32_e32 v3, v3
	v_pk_mul_f32 v[6:7], v[6:7], s[16:17] op_sel_hi:[1,0]
	v_cndmask_b32_e64 v10, 0, 1, s[14:15]
	v_exp_f32_e32 v6, v6
	v_exp_f32_e32 v7, v7
	v_pk_add_f32 v[2:3], v[2:3], 1.0 op_sel_hi:[1,0]
	v_cmp_ne_u32_e64 s[10:11], 1, v10
	v_rcp_f32_e32 v2, v2
	v_rcp_f32_e32 v3, v3
	v_pk_add_f32 v[6:7], v[6:7], 1.0 op_sel_hi:[1,0]
	v_pk_mul_f32 v[0:1], v[2:3], v[0:1]
	v_rcp_f32_e32 v6, v6
	v_rcp_f32_e32 v7, v7
	v_pk_add_f32 v[2:3], v[68:69], v[12:13] op_sel_hi:[0,1]
	v_pk_mul_f32 v[0:1], v[0:1], v[2:3]
	v_pk_mul_f32 v[2:3], v[6:7], v[4:5]
	v_pk_add_f32 v[4:5], v[68:69], v[14:15] op_sel_hi:[0,1]
	v_cvt_pk_bf16_f32 v134, v0, v1
	v_pk_mul_f32 v[2:3], v[2:3], v[4:5]
	s_nop 0
	v_cvt_pk_bf16_f32 v135, v2, v3
	s_nop 1
	v_permlane32_swap_b32_e32 v132, v134
	v_permlane32_swap_b32_e32 v133, v135
	global_store_dwordx4 v[136:137], v[132:135], off offset:1248
	v_mov_b32_e32 v0, 0x60
	v_bitop3_b32 v0, v124, s43, v0 bitop3:0xde
	v_lshlrev_b32_e32 v0, 9, v0
	v_mov_b32_e32 v1, v123
	v_lshl_add_u64 v[8:9], v[90:91], 0, v[0:1]
	global_load_dwordx4 v[0:3], v[8:9], off offset:16
	global_load_dwordx4 v[4:7], v[8:9], off
	global_load_dwordx4 v[112:115], v[8:9], off offset:80
	global_load_dwordx4 v[116:119], v[8:9], off offset:64
	global_load_dwordx4 v[104:107], v[8:9], off offset:144
	global_load_dwordx4 v[108:111], v[8:9], off offset:128
	global_load_dwordx4 v[96:99], v[8:9], off offset:208
	global_load_dwordx4 v[100:103], v[8:9], off offset:192
	global_load_dwordx4 v[88:91], v[8:9], off offset:272
	global_load_dwordx4 v[92:95], v[8:9], off offset:256
	global_load_dwordx4 v[80:83], v[8:9], off offset:336
	global_load_dwordx4 v[84:87], v[8:9], off offset:320
	s_cbranch_vccnz .LBB0_1282
	global_load_dwordx4 v[76:79], v[8:9], off offset:384
	global_load_dwordx4 v[72:75], v[8:9], off offset:400

.LBB0_1288:
	s_waitcnt vmcnt(15)
	v_lshlrev_b32_e32 v66, 16, v112
	v_and_b32_e32 v67, 0xffff0000, v112
	v_pk_mul_f32 v[70:71], v[66:67], v[66:67]
	s_mov_b32 s10, 0x3d372713
	v_lshlrev_b32_e32 v72, 16, v113
	v_and_b32_e32 v73, 0xffff0000, v113
	v_lshlrev_b64 v[64:65], 11, v[110:111]
	v_pk_fma_f32 v[70:71], v[70:71], s[10:11], 1.0 op_sel_hi:[1,0,0]
	v_pk_mul_f32 v[74:75], v[72:73], v[72:73]
	v_lshl_add_u64 v[64:65], s[12:13], 0, v[64:65]
	v_pk_mul_f32 v[70:71], v[70:71], v[66:67]
	s_mov_b32 s12, 0xc0135761
	v_pk_fma_f32 v[74:75], v[74:75], s[10:11], 1.0 op_sel_hi:[1,0,0]
	v_pk_mul_f32 v[70:71], v[70:71], s[12:13] op_sel_hi:[1,0]
	v_pk_mul_f32 v[74:75], v[74:75], v[72:73]
	v_exp_f32_e32 v70, v70
	v_exp_f32_e32 v71, v71
	v_pk_mul_f32 v[74:75], v[74:75], s[12:13] op_sel_hi:[1,0]
	v_pk_add_f32 v[48:49], v[68:69], v[48:49] op_sel_hi:[0,1]
	v_exp_f32_e32 v74, v74
	v_exp_f32_e32 v75, v75
	v_pk_add_f32 v[70:71], v[70:71], 1.0 op_sel_hi:[1,0]
	v_lshl_add_u64 v[64:65], v[64:65], 0, s[38:39]
	v_rcp_f32_e32 v70, v70
	v_rcp_f32_e32 v71, v71
	v_pk_add_f32 v[74:75], v[74:75], 1.0 op_sel_hi:[1,0]
	v_mov_b32_e32 v123, 0
	v_rcp_f32_e32 v74, v74
	v_rcp_f32_e32 v75, v75
	v_pk_mul_f32 v[66:67], v[70:71], v[66:67]
	v_pk_add_f32 v[50:51], v[68:69], v[50:51] op_sel_hi:[0,1]
	v_pk_mul_f32 v[48:49], v[66:67], v[48:49]
	v_pk_mul_f32 v[66:67], v[74:75], v[72:73]
	v_lshl_add_u64 v[64:65], v[64:65], 0, v[122:123]
	v_bfe_u32 v138, v224, 5, 1
	v_lshlrev_b32_e32 v138, 3, v138
	v_mov_b32_e32 v139, 0
	v_lshl_add_u64 v[136:137], v[64:65], 0, v[138:139]
	v_pk_mul_f32 v[50:51], v[66:67], v[50:51]
	v_cvt_pk_bf16_f32 v128, v48, v49
	s_waitcnt vmcnt(14)
	v_lshlrev_b32_e32 v66, 16, v109
	v_cvt_pk_bf16_f32 v129, v50, v51
	v_lshlrev_b32_e32 v48, 16, v108
	v_and_b32_e32 v49, 0xffff0000, v108
	v_pk_mul_f32 v[50:51], v[48:49], v[48:49]
	v_and_b32_e32 v67, 0xffff0000, v109
	v_pk_fma_f32 v[50:51], v[50:51], s[10:11], 1.0 op_sel_hi:[1,0,0]
	v_pk_mul_f32 v[70:71], v[66:67], v[66:67]
	v_pk_mul_f32 v[50:51], v[50:51], v[48:49]
	v_pk_fma_f32 v[70:71], v[70:71], s[10:11], 1.0 op_sel_hi:[1,0,0]
	v_pk_mul_f32 v[50:51], v[50:51], s[12:13] op_sel_hi:[1,0]
	v_pk_mul_f32 v[70:71], v[70:71], v[66:67]
	v_exp_f32_e32 v50, v50
	v_exp_f32_e32 v51, v51
	v_pk_mul_f32 v[70:71], v[70:71], s[12:13] op_sel_hi:[1,0]
	v_pk_add_f32 v[32:33], v[68:69], v[32:33] op_sel_hi:[0,1]
	v_exp_f32_e32 v70, v70
	v_exp_f32_e32 v71, v71
	v_pk_add_f32 v[50:51], v[50:51], 1.0 op_sel_hi:[1,0]
	v_pk_add_f32 v[34:35], v[68:69], v[34:35] op_sel_hi:[0,1]
	v_rcp_f32_e32 v50, v50
	v_rcp_f32_e32 v51, v51
	v_pk_add_f32 v[70:71], v[70:71], 1.0 op_sel_hi:[1,0]
	v_pk_add_f32 v[16:17], v[68:69], v[16:17] op_sel_hi:[0,1]
	v_rcp_f32_e32 v70, v70
	v_rcp_f32_e32 v71, v71
	v_pk_mul_f32 v[48:49], v[50:51], v[48:49]
	v_pk_add_f32 v[50:51], v[68:69], v[52:53] op_sel_hi:[0,1]
	v_pk_mul_f32 v[48:49], v[48:49], v[50:51]
	v_pk_mul_f32 v[50:51], v[70:71], v[66:67]
	v_pk_add_f32 v[52:53], v[68:69], v[54:55] op_sel_hi:[0,1]
	v_pk_mul_f32 v[50:51], v[50:51], v[52:53]
	v_cvt_pk_bf16_f32 v130, v48, v49
	s_waitcnt vmcnt(13)
	v_lshlrev_b32_e32 v52, 16, v107
	v_cvt_pk_bf16_f32 v131, v50, v51
	s_nop 1
	v_permlane32_swap_b32_e32 v128, v130
	v_permlane32_swap_b32_e32 v129, v131
	global_store_dwordx4 v[136:137], v[128:131], off offset:1024
	v_lshlrev_b32_e32 v48, 16, v106
	v_and_b32_e32 v49, 0xffff0000, v106
	v_pk_mul_f32 v[50:51], v[48:49], v[48:49]
	v_and_b32_e32 v53, 0xffff0000, v107
	v_pk_fma_f32 v[50:51], v[50:51], s[10:11], 1.0 op_sel_hi:[1,0,0]
	v_pk_mul_f32 v[54:55], v[52:53], v[52:53]
	v_pk_mul_f32 v[50:51], v[50:51], v[48:49]
	v_pk_fma_f32 v[54:55], v[54:55], s[10:11], 1.0 op_sel_hi:[1,0,0]
	v_pk_mul_f32 v[50:51], v[50:51], s[12:13] op_sel_hi:[1,0]
	v_pk_mul_f32 v[54:55], v[54:55], v[52:53]
	v_exp_f32_e32 v50, v50
	v_exp_f32_e32 v51, v51
	v_pk_mul_f32 v[54:55], v[54:55], s[12:13] op_sel_hi:[1,0]
	v_pk_add_f32 v[18:19], v[68:69], v[18:19] op_sel_hi:[0,1]
	v_exp_f32_e32 v54, v54
	v_exp_f32_e32 v55, v55
	v_pk_add_f32 v[50:51], v[50:51], 1.0 op_sel_hi:[1,0]
	v_pk_add_f32 v[0:1], v[68:69], v[0:1] op_sel_hi:[0,1]
	v_rcp_f32_e32 v50, v50
	v_rcp_f32_e32 v51, v51
	v_pk_add_f32 v[54:55], v[54:55], 1.0 op_sel_hi:[1,0]
	v_pk_add_f32 v[2:3], v[68:69], v[2:3] op_sel_hi:[0,1]
	v_rcp_f32_e32 v54, v54
	v_rcp_f32_e32 v55, v55
	v_pk_mul_f32 v[48:49], v[50:51], v[48:49]
	v_pk_add_f32 v[50:51], v[68:69], v[56:57] op_sel_hi:[0,1]
	v_pk_mul_f32 v[48:49], v[48:49], v[50:51]
	v_pk_mul_f32 v[50:51], v[54:55], v[52:53]
	v_pk_add_f32 v[52:53], v[68:69], v[58:59] op_sel_hi:[0,1]
	v_pk_mul_f32 v[50:51], v[50:51], v[52:53]
	v_cvt_pk_bf16_f32 v132, v48, v49
	s_waitcnt vmcnt(13)
	v_lshlrev_b32_e32 v52, 16, v105
	v_cvt_pk_bf16_f32 v133, v50, v51
	v_lshlrev_b32_e32 v48, 16, v104
	v_and_b32_e32 v49, 0xffff0000, v104
	v_pk_mul_f32 v[50:51], v[48:49], v[48:49]
	v_and_b32_e32 v53, 0xffff0000, v105
	v_pk_fma_f32 v[50:51], v[50:51], s[10:11], 1.0 op_sel_hi:[1,0,0]
	v_pk_mul_f32 v[54:55], v[52:53], v[52:53]
	v_pk_mul_f32 v[50:51], v[50:51], v[48:49]
	v_pk_fma_f32 v[54:55], v[54:55], s[10:11], 1.0 op_sel_hi:[1,0,0]
	v_pk_mul_f32 v[50:51], v[50:51], s[12:13] op_sel_hi:[1,0]
	v_pk_mul_f32 v[54:55], v[54:55], v[52:53]
	v_exp_f32_e32 v50, v50
	v_exp_f32_e32 v51, v51
	v_pk_mul_f32 v[54:55], v[54:55], s[12:13] op_sel_hi:[1,0]
	v_pk_add_f32 v[50:51], v[50:51], 1.0 op_sel_hi:[1,0]
	v_exp_f32_e32 v54, v54
	v_exp_f32_e32 v55, v55
	v_rcp_f32_e32 v50, v50
	v_rcp_f32_e32 v51, v51
	v_pk_add_f32 v[54:55], v[54:55], 1.0 op_sel_hi:[1,0]
	s_nop 0
	v_rcp_f32_e32 v54, v54
	v_rcp_f32_e32 v55, v55
	v_pk_mul_f32 v[48:49], v[50:51], v[48:49]
	v_pk_add_f32 v[50:51], v[68:69], v[60:61] op_sel_hi:[0,1]
	v_pk_mul_f32 v[48:49], v[48:49], v[50:51]
	v_pk_mul_f32 v[50:51], v[54:55], v[52:53]
	v_pk_add_f32 v[52:53], v[68:69], v[62:63] op_sel_hi:[0,1]
	v_pk_mul_f32 v[50:51], v[50:51], v[52:53]
	v_cvt_pk_bf16_f32 v134, v48, v49
	s_waitcnt vmcnt(12)
	v_lshlrev_b32_e32 v52, 16, v103
	v_cvt_pk_bf16_f32 v135, v50, v51
	s_nop 1
	v_permlane32_swap_b32_e32 v132, v134
	v_permlane32_swap_b32_e32 v133, v135
	global_store_dwordx4 v[136:137], v[132:135], off offset:1056
	v_lshlrev_b32_e32 v48, 16, v102
	v_and_b32_e32 v49, 0xffff0000, v102
	v_pk_mul_f32 v[50:51], v[48:49], v[48:49]
	v_and_b32_e32 v53, 0xffff0000, v103
	v_pk_fma_f32 v[50:51], v[50:51], s[10:11], 1.0 op_sel_hi:[1,0,0]
	v_pk_mul_f32 v[54:55], v[52:53], v[52:53]
	v_pk_mul_f32 v[50:51], v[50:51], v[48:49]
	v_pk_fma_f32 v[54:55], v[54:55], s[10:11], 1.0 op_sel_hi:[1,0,0]
	v_pk_mul_f32 v[50:51], v[50:51], s[12:13] op_sel_hi:[1,0]
	v_pk_mul_f32 v[54:55], v[54:55], v[52:53]
	v_exp_f32_e32 v50, v50
	v_exp_f32_e32 v51, v51
	v_pk_mul_f32 v[54:55], v[54:55], s[12:13] op_sel_hi:[1,0]
	v_pk_add_f32 v[50:51], v[50:51], 1.0 op_sel_hi:[1,0]
	v_exp_f32_e32 v54, v54
	v_exp_f32_e32 v55, v55
	v_rcp_f32_e32 v50, v50
	v_rcp_f32_e32 v51, v51
	v_pk_add_f32 v[54:55], v[54:55], 1.0 op_sel_hi:[1,0]
	s_nop 0
	v_rcp_f32_e32 v54, v54
	v_rcp_f32_e32 v55, v55
	v_pk_mul_f32 v[48:49], v[50:51], v[48:49]
	s_nop 0
	v_pk_mul_f32 v[32:33], v[48:49], v[32:33]
	v_pk_mul_f32 v[48:49], v[54:55], v[52:53]
	v_cvt_pk_bf16_f32 v128, v32, v33
	s_nop 0
	v_pk_mul_f32 v[34:35], v[48:49], v[34:35]
	s_waitcnt vmcnt(12)
	v_lshlrev_b32_e32 v48, 16, v101
	v_cvt_pk_bf16_f32 v129, v34, v35
	v_lshlrev_b32_e32 v32, 16, v100
	v_and_b32_e32 v33, 0xffff0000, v100
	v_pk_mul_f32 v[34:35], v[32:33], v[32:33]
	v_and_b32_e32 v49, 0xffff0000, v101
	v_pk_fma_f32 v[34:35], v[34:35], s[10:11], 1.0 op_sel_hi:[1,0,0]
	v_pk_mul_f32 v[50:51], v[48:49], v[48:49]
	v_pk_mul_f32 v[34:35], v[34:35], v[32:33]
	v_pk_fma_f32 v[50:51], v[50:51], s[10:11], 1.0 op_sel_hi:[1,0,0]
	v_pk_mul_f32 v[34:35], v[34:35], s[12:13] op_sel_hi:[1,0]
	v_pk_mul_f32 v[50:51], v[50:51], v[48:49]
	v_exp_f32_e32 v34, v34
	v_exp_f32_e32 v35, v35
	v_pk_mul_f32 v[50:51], v[50:51], s[12:13] op_sel_hi:[1,0]
	v_pk_add_f32 v[34:35], v[34:35], 1.0 op_sel_hi:[1,0]
	v_exp_f32_e32 v50, v50
	v_exp_f32_e32 v51, v51
	v_rcp_f32_e32 v34, v34
	v_rcp_f32_e32 v35, v35
	v_pk_add_f32 v[50:51], v[50:51], 1.0 op_sel_hi:[1,0]
	s_nop 0
	v_rcp_f32_e32 v50, v50
	v_rcp_f32_e32 v51, v51
	v_pk_mul_f32 v[32:33], v[34:35], v[32:33]
	v_pk_add_f32 v[34:35], v[68:69], v[36:37] op_sel_hi:[0,1]
	v_pk_mul_f32 v[32:33], v[32:33], v[34:35]
	v_pk_mul_f32 v[34:35], v[50:51], v[48:49]
	v_pk_add_f32 v[36:37], v[68:69], v[38:39] op_sel_hi:[0,1]
	v_pk_mul_f32 v[34:35], v[34:35], v[36:37]
	v_cvt_pk_bf16_f32 v130, v32, v33
	s_waitcnt vmcnt(11)
	v_lshlrev_b32_e32 v36, 16, v99
	v_cvt_pk_bf16_f32 v131, v34, v35
	s_nop 1
	v_permlane32_swap_b32_e32 v128, v130
	v_permlane32_swap_b32_e32 v129, v131
	global_store_dwordx4 v[136:137], v[128:131], off offset:1088
	v_lshlrev_b32_e32 v32, 16, v98
	v_and_b32_e32 v33, 0xffff0000, v98
	v_pk_mul_f32 v[34:35], v[32:33], v[32:33]
	v_and_b32_e32 v37, 0xffff0000, v99
	v_pk_fma_f32 v[34:35], v[34:35], s[10:11], 1.0 op_sel_hi:[1,0,0]
	v_pk_mul_f32 v[38:39], v[36:37], v[36:37]
	v_pk_mul_f32 v[34:35], v[34:35], v[32:33]
	v_pk_fma_f32 v[38:39], v[38:39], s[10:11], 1.0 op_sel_hi:[1,0,0]
	v_pk_mul_f32 v[34:35], v[34:35], s[12:13] op_sel_hi:[1,0]
	v_pk_mul_f32 v[38:39], v[38:39], v[36:37]
	v_exp_f32_e32 v34, v34
	v_exp_f32_e32 v35, v35
	v_pk_mul_f32 v[38:39], v[38:39], s[12:13] op_sel_hi:[1,0]
	v_pk_add_f32 v[34:35], v[34:35], 1.0 op_sel_hi:[1,0]
	v_exp_f32_e32 v38, v38
	v_exp_f32_e32 v39, v39
	v_rcp_f32_e32 v34, v34
	v_rcp_f32_e32 v35, v35
	v_pk_add_f32 v[38:39], v[38:39], 1.0 op_sel_hi:[1,0]
	s_nop 0
	v_rcp_f32_e32 v38, v38
	v_rcp_f32_e32 v39, v39
	v_pk_mul_f32 v[32:33], v[34:35], v[32:33]
	v_pk_add_f32 v[34:35], v[68:69], v[40:41] op_sel_hi:[0,1]
	v_pk_mul_f32 v[32:33], v[32:33], v[34:35]
	v_pk_mul_f32 v[34:35], v[38:39], v[36:37]
	v_pk_add_f32 v[36:37], v[68:69], v[42:43] op_sel_hi:[0,1]
	v_pk_mul_f32 v[34:35], v[34:35], v[36:37]
	v_cvt_pk_bf16_f32 v132, v32, v33
	s_waitcnt vmcnt(11)
	v_lshlrev_b32_e32 v36, 16, v97
	v_cvt_pk_bf16_f32 v133, v34, v35
	v_lshlrev_b32_e32 v32, 16, v96
	v_and_b32_e32 v33, 0xffff0000, v96
	v_pk_mul_f32 v[34:35], v[32:33], v[32:33]
	v_and_b32_e32 v37, 0xffff0000, v97
	v_pk_fma_f32 v[34:35], v[34:35], s[10:11], 1.0 op_sel_hi:[1,0,0]
	v_pk_mul_f32 v[38:39], v[36:37], v[36:37]
	v_pk_mul_f32 v[34:35], v[34:35], v[32:33]
	v_pk_fma_f32 v[38:39], v[38:39], s[10:11], 1.0 op_sel_hi:[1,0,0]
	v_pk_mul_f32 v[34:35], v[34:35], s[12:13] op_sel_hi:[1,0]
	v_pk_mul_f32 v[38:39], v[38:39], v[36:37]
	v_exp_f32_e32 v34, v34
	v_exp_f32_e32 v35, v35
	v_pk_mul_f32 v[38:39], v[38:39], s[12:13] op_sel_hi:[1,0]
	v_pk_add_f32 v[34:35], v[34:35], 1.0 op_sel_hi:[1,0]
	v_exp_f32_e32 v38, v38
	v_exp_f32_e32 v39, v39
	v_rcp_f32_e32 v34, v34
	v_rcp_f32_e32 v35, v35
	v_pk_add_f32 v[38:39], v[38:39], 1.0 op_sel_hi:[1,0]
	s_nop 0
	v_rcp_f32_e32 v38, v38
	v_rcp_f32_e32 v39, v39
	v_pk_mul_f32 v[32:33], v[34:35], v[32:33]
	v_pk_add_f32 v[34:35], v[68:69], v[44:45] op_sel_hi:[0,1]
	v_pk_mul_f32 v[32:33], v[32:33], v[34:35]
	v_pk_mul_f32 v[34:35], v[38:39], v[36:37]
	v_pk_add_f32 v[36:37], v[68:69], v[46:47] op_sel_hi:[0,1]
	v_pk_mul_f32 v[34:35], v[34:35], v[36:37]
	v_cvt_pk_bf16_f32 v134, v32, v33
	s_waitcnt vmcnt(10)
	v_lshlrev_b32_e32 v36, 16, v95
	v_cvt_pk_bf16_f32 v135, v34, v35
	s_nop 1
	v_permlane32_swap_b32_e32 v132, v134
	v_permlane32_swap_b32_e32 v133, v135
	global_store_dwordx4 v[136:137], v[132:135], off offset:1120
	v_lshlrev_b32_e32 v32, 16, v94
	v_and_b32_e32 v33, 0xffff0000, v94
	v_pk_mul_f32 v[34:35], v[32:33], v[32:33]
	v_and_b32_e32 v37, 0xffff0000, v95
	v_pk_fma_f32 v[34:35], v[34:35], s[10:11], 1.0 op_sel_hi:[1,0,0]
	v_pk_mul_f32 v[38:39], v[36:37], v[36:37]
	v_pk_mul_f32 v[34:35], v[34:35], v[32:33]
	v_pk_fma_f32 v[38:39], v[38:39], s[10:11], 1.0 op_sel_hi:[1,0,0]
	v_pk_mul_f32 v[34:35], v[34:35], s[12:13] op_sel_hi:[1,0]
	v_pk_mul_f32 v[38:39], v[38:39], v[36:37]
	v_exp_f32_e32 v34, v34
	v_exp_f32_e32 v35, v35
	v_pk_mul_f32 v[38:39], v[38:39], s[12:13] op_sel_hi:[1,0]
	v_pk_add_f32 v[34:35], v[34:35], 1.0 op_sel_hi:[1,0]
	v_exp_f32_e32 v38, v38
	v_exp_f32_e32 v39, v39
	v_rcp_f32_e32 v34, v34
	v_rcp_f32_e32 v35, v35
	v_pk_add_f32 v[38:39], v[38:39], 1.0 op_sel_hi:[1,0]
	s_nop 0
	v_rcp_f32_e32 v38, v38
	v_rcp_f32_e32 v39, v39
	v_pk_mul_f32 v[32:33], v[34:35], v[32:33]
	s_nop 0
	v_pk_mul_f32 v[16:17], v[32:33], v[16:17]
	v_pk_mul_f32 v[32:33], v[38:39], v[36:37]
	v_cvt_pk_bf16_f32 v128, v16, v17
	s_nop 0
	v_pk_mul_f32 v[18:19], v[32:33], v[18:19]
	s_waitcnt vmcnt(10)
	v_lshlrev_b32_e32 v32, 16, v93
	v_cvt_pk_bf16_f32 v129, v18, v19
	v_lshlrev_b32_e32 v16, 16, v92
	v_and_b32_e32 v17, 0xffff0000, v92
	v_pk_mul_f32 v[18:19], v[16:17], v[16:17]
	v_and_b32_e32 v33, 0xffff0000, v93
	v_pk_fma_f32 v[18:19], v[18:19], s[10:11], 1.0 op_sel_hi:[1,0,0]
	v_pk_mul_f32 v[34:35], v[32:33], v[32:33]
	v_pk_mul_f32 v[18:19], v[18:19], v[16:17]
	v_pk_fma_f32 v[34:35], v[34:35], s[10:11], 1.0 op_sel_hi:[1,0,0]
	v_pk_mul_f32 v[18:19], v[18:19], s[12:13] op_sel_hi:[1,0]
	v_pk_mul_f32 v[34:35], v[34:35], v[32:33]
	v_exp_f32_e32 v18, v18
	v_exp_f32_e32 v19, v19
	v_pk_mul_f32 v[34:35], v[34:35], s[12:13] op_sel_hi:[1,0]
	v_pk_add_f32 v[18:19], v[18:19], 1.0 op_sel_hi:[1,0]
	v_exp_f32_e32 v34, v34
	v_exp_f32_e32 v35, v35
	v_rcp_f32_e32 v18, v18
	v_rcp_f32_e32 v19, v19
	v_pk_add_f32 v[34:35], v[34:35], 1.0 op_sel_hi:[1,0]
	s_nop 0
	v_rcp_f32_e32 v34, v34
	v_rcp_f32_e32 v35, v35
	v_pk_mul_f32 v[16:17], v[18:19], v[16:17]
	v_pk_add_f32 v[18:19], v[68:69], v[20:21] op_sel_hi:[0,1]
	v_pk_mul_f32 v[16:17], v[16:17], v[18:19]
	v_pk_mul_f32 v[18:19], v[34:35], v[32:33]
	v_pk_add_f32 v[20:21], v[68:69], v[22:23] op_sel_hi:[0,1]
	v_pk_mul_f32 v[18:19], v[18:19], v[20:21]
	v_cvt_pk_bf16_f32 v130, v16, v17
	s_waitcnt vmcnt(9)
	v_lshlrev_b32_e32 v20, 16, v91
	v_cvt_pk_bf16_f32 v131, v18, v19
	s_nop 1
	v_permlane32_swap_b32_e32 v128, v130
	v_permlane32_swap_b32_e32 v129, v131
	global_store_dwordx4 v[136:137], v[128:131], off offset:1152
	v_lshlrev_b32_e32 v16, 16, v90
	v_and_b32_e32 v17, 0xffff0000, v90
	v_pk_mul_f32 v[18:19], v[16:17], v[16:17]
	v_and_b32_e32 v21, 0xffff0000, v91
	v_pk_fma_f32 v[18:19], v[18:19], s[10:11], 1.0 op_sel_hi:[1,0,0]
	v_pk_mul_f32 v[22:23], v[20:21], v[20:21]
	v_pk_mul_f32 v[18:19], v[18:19], v[16:17]
	v_pk_fma_f32 v[22:23], v[22:23], s[10:11], 1.0 op_sel_hi:[1,0,0]
	v_pk_mul_f32 v[18:19], v[18:19], s[12:13] op_sel_hi:[1,0]
	v_pk_mul_f32 v[22:23], v[22:23], v[20:21]
	v_exp_f32_e32 v18, v18
	v_exp_f32_e32 v19, v19
	v_pk_mul_f32 v[22:23], v[22:23], s[12:13] op_sel_hi:[1,0]
	v_pk_add_f32 v[18:19], v[18:19], 1.0 op_sel_hi:[1,0]
	v_exp_f32_e32 v22, v22
	v_exp_f32_e32 v23, v23
	v_rcp_f32_e32 v18, v18
	v_rcp_f32_e32 v19, v19
	v_pk_add_f32 v[22:23], v[22:23], 1.0 op_sel_hi:[1,0]
	s_nop 0
	v_rcp_f32_e32 v22, v22
	v_rcp_f32_e32 v23, v23
	v_pk_mul_f32 v[16:17], v[18:19], v[16:17]
	v_pk_add_f32 v[18:19], v[68:69], v[24:25] op_sel_hi:[0,1]
	v_pk_mul_f32 v[16:17], v[16:17], v[18:19]
	v_pk_mul_f32 v[18:19], v[22:23], v[20:21]
	v_pk_add_f32 v[20:21], v[68:69], v[26:27] op_sel_hi:[0,1]
	v_pk_mul_f32 v[18:19], v[18:19], v[20:21]
	v_cvt_pk_bf16_f32 v132, v16, v17
	s_waitcnt vmcnt(9)
	v_lshlrev_b32_e32 v20, 16, v89
	v_cvt_pk_bf16_f32 v133, v18, v19
	v_lshlrev_b32_e32 v16, 16, v88
	v_and_b32_e32 v17, 0xffff0000, v88
	v_pk_mul_f32 v[18:19], v[16:17], v[16:17]
	v_and_b32_e32 v21, 0xffff0000, v89
	v_pk_fma_f32 v[18:19], v[18:19], s[10:11], 1.0 op_sel_hi:[1,0,0]
	v_pk_mul_f32 v[22:23], v[20:21], v[20:21]
	v_pk_mul_f32 v[18:19], v[18:19], v[16:17]
	v_pk_fma_f32 v[22:23], v[22:23], s[10:11], 1.0 op_sel_hi:[1,0,0]
	v_pk_mul_f32 v[18:19], v[18:19], s[12:13] op_sel_hi:[1,0]
	v_pk_mul_f32 v[22:23], v[22:23], v[20:21]
	v_exp_f32_e32 v18, v18
	v_exp_f32_e32 v19, v19
	v_pk_mul_f32 v[22:23], v[22:23], s[12:13] op_sel_hi:[1,0]
	v_pk_add_f32 v[18:19], v[18:19], 1.0 op_sel_hi:[1,0]
	v_exp_f32_e32 v22, v22
	v_exp_f32_e32 v23, v23
	v_rcp_f32_e32 v18, v18
	v_rcp_f32_e32 v19, v19
	v_pk_add_f32 v[22:23], v[22:23], 1.0 op_sel_hi:[1,0]
	s_nop 0
	v_rcp_f32_e32 v22, v22
	v_rcp_f32_e32 v23, v23
	v_pk_mul_f32 v[16:17], v[18:19], v[16:17]
	v_pk_add_f32 v[18:19], v[68:69], v[28:29] op_sel_hi:[0,1]
	v_pk_mul_f32 v[16:17], v[16:17], v[18:19]
	v_pk_mul_f32 v[18:19], v[22:23], v[20:21]
	v_pk_add_f32 v[20:21], v[68:69], v[30:31] op_sel_hi:[0,1]
	v_pk_mul_f32 v[18:19], v[18:19], v[20:21]
	v_cvt_pk_bf16_f32 v134, v16, v17
	s_waitcnt vmcnt(8)
	v_lshlrev_b32_e32 v20, 16, v87
	v_cvt_pk_bf16_f32 v135, v18, v19
	s_nop 1
	v_permlane32_swap_b32_e32 v132, v134
	v_permlane32_swap_b32_e32 v133, v135
	global_store_dwordx4 v[136:137], v[132:135], off offset:1184
	v_lshlrev_b32_e32 v16, 16, v86
	v_and_b32_e32 v17, 0xffff0000, v86
	v_pk_mul_f32 v[18:19], v[16:17], v[16:17]
	v_and_b32_e32 v21, 0xffff0000, v87
	v_pk_fma_f32 v[18:19], v[18:19], s[10:11], 1.0 op_sel_hi:[1,0,0]
	v_pk_mul_f32 v[22:23], v[20:21], v[20:21]
	v_pk_mul_f32 v[18:19], v[18:19], v[16:17]
	v_pk_fma_f32 v[22:23], v[22:23], s[10:11], 1.0 op_sel_hi:[1,0,0]
	v_pk_mul_f32 v[18:19], v[18:19], s[12:13] op_sel_hi:[1,0]
	v_pk_mul_f32 v[22:23], v[22:23], v[20:21]
	v_exp_f32_e32 v18, v18
	v_exp_f32_e32 v19, v19
	v_pk_mul_f32 v[22:23], v[22:23], s[12:13] op_sel_hi:[1,0]
	v_pk_add_f32 v[18:19], v[18:19], 1.0 op_sel_hi:[1,0]
	v_exp_f32_e32 v22, v22
	v_exp_f32_e32 v23, v23
	v_rcp_f32_e32 v18, v18
	v_rcp_f32_e32 v19, v19
	v_pk_add_f32 v[22:23], v[22:23], 1.0 op_sel_hi:[1,0]
	s_nop 0
	v_rcp_f32_e32 v22, v22
	v_rcp_f32_e32 v23, v23
	v_pk_mul_f32 v[16:17], v[18:19], v[16:17]
	s_nop 0
	v_pk_mul_f32 v[0:1], v[16:17], v[0:1]
	v_pk_mul_f32 v[16:17], v[22:23], v[20:21]
	v_cvt_pk_bf16_f32 v128, v0, v1
	s_nop 0
	v_pk_mul_f32 v[2:3], v[16:17], v[2:3]
	s_waitcnt vmcnt(8)
	v_lshlrev_b32_e32 v16, 16, v85
	v_cvt_pk_bf16_f32 v129, v2, v3
	v_lshlrev_b32_e32 v0, 16, v84
	v_and_b32_e32 v1, 0xffff0000, v84
	v_pk_mul_f32 v[2:3], v[0:1], v[0:1]
	v_and_b32_e32 v17, 0xffff0000, v85
	v_pk_fma_f32 v[2:3], v[2:3], s[10:11], 1.0 op_sel_hi:[1,0,0]
	v_pk_mul_f32 v[18:19], v[16:17], v[16:17]
	v_pk_mul_f32 v[2:3], v[2:3], v[0:1]
	v_pk_fma_f32 v[18:19], v[18:19], s[10:11], 1.0 op_sel_hi:[1,0,0]
	v_pk_mul_f32 v[2:3], v[2:3], s[12:13] op_sel_hi:[1,0]
	v_pk_mul_f32 v[18:19], v[18:19], v[16:17]
	v_exp_f32_e32 v2, v2
	v_exp_f32_e32 v3, v3
	v_pk_mul_f32 v[18:19], v[18:19], s[12:13] op_sel_hi:[1,0]
	v_pk_add_f32 v[2:3], v[2:3], 1.0 op_sel_hi:[1,0]
	v_exp_f32_e32 v18, v18
	v_exp_f32_e32 v19, v19
	v_rcp_f32_e32 v2, v2
	v_rcp_f32_e32 v3, v3
	v_pk_add_f32 v[18:19], v[18:19], 1.0 op_sel_hi:[1,0]
	s_nop 0
	v_rcp_f32_e32 v18, v18
	v_rcp_f32_e32 v19, v19
	v_pk_mul_f32 v[0:1], v[2:3], v[0:1]
	v_pk_add_f32 v[2:3], v[68:69], v[4:5] op_sel_hi:[0,1]
	v_pk_mul_f32 v[0:1], v[0:1], v[2:3]
	v_pk_mul_f32 v[2:3], v[18:19], v[16:17]
	v_pk_add_f32 v[4:5], v[68:69], v[6:7] op_sel_hi:[0,1]
	v_pk_mul_f32 v[2:3], v[2:3], v[4:5]
	v_cvt_pk_bf16_f32 v130, v0, v1
	s_waitcnt vmcnt(7)
	v_lshlrev_b32_e32 v4, 16, v83
	v_cvt_pk_bf16_f32 v131, v2, v3
	s_nop 1
	v_permlane32_swap_b32_e32 v128, v130
	v_permlane32_swap_b32_e32 v129, v131
	global_store_dwordx4 v[136:137], v[128:131], off offset:1216
	v_lshlrev_b32_e32 v0, 16, v82
	v_and_b32_e32 v1, 0xffff0000, v82
	v_pk_mul_f32 v[2:3], v[0:1], v[0:1]
	v_and_b32_e32 v5, 0xffff0000, v83
	v_pk_fma_f32 v[2:3], v[2:3], s[10:11], 1.0 op_sel_hi:[1,0,0]
	v_pk_mul_f32 v[6:7], v[4:5], v[4:5]
	v_pk_mul_f32 v[2:3], v[2:3], v[0:1]
	v_pk_fma_f32 v[6:7], v[6:7], s[10:11], 1.0 op_sel_hi:[1,0,0]
	v_pk_mul_f32 v[2:3], v[2:3], s[12:13] op_sel_hi:[1,0]
	v_pk_mul_f32 v[6:7], v[6:7], v[4:5]
	v_exp_f32_e32 v2, v2
	v_exp_f32_e32 v3, v3
	v_pk_mul_f32 v[6:7], v[6:7], s[12:13] op_sel_hi:[1,0]
	v_pk_add_f32 v[2:3], v[2:3], 1.0 op_sel_hi:[1,0]
	v_exp_f32_e32 v6, v6
	v_exp_f32_e32 v7, v7
	v_rcp_f32_e32 v2, v2
	v_rcp_f32_e32 v3, v3
	v_pk_add_f32 v[6:7], v[6:7], 1.0 op_sel_hi:[1,0]
	s_nop 0
	v_rcp_f32_e32 v6, v6
	v_rcp_f32_e32 v7, v7
	v_pk_mul_f32 v[0:1], v[2:3], v[0:1]
	v_pk_add_f32 v[2:3], v[68:69], v[8:9] op_sel_hi:[0,1]
	v_pk_mul_f32 v[0:1], v[0:1], v[2:3]
	v_pk_mul_f32 v[2:3], v[6:7], v[4:5]
	v_pk_add_f32 v[4:5], v[68:69], v[10:11] op_sel_hi:[0,1]
	v_pk_mul_f32 v[2:3], v[2:3], v[4:5]
	v_cvt_pk_bf16_f32 v132, v0, v1
	s_waitcnt vmcnt(7)
	v_lshlrev_b32_e32 v4, 16, v81
	v_cvt_pk_bf16_f32 v133, v2, v3
	v_lshlrev_b32_e32 v0, 16, v80
	v_and_b32_e32 v1, 0xffff0000, v80
	v_pk_mul_f32 v[2:3], v[0:1], v[0:1]
	v_and_b32_e32 v5, 0xffff0000, v81
	v_pk_fma_f32 v[2:3], v[2:3], s[10:11], 1.0 op_sel_hi:[1,0,0]
	v_pk_mul_f32 v[6:7], v[4:5], v[4:5]
	v_pk_mul_f32 v[2:3], v[2:3], v[0:1]
	v_pk_fma_f32 v[6:7], v[6:7], s[10:11], 1.0 op_sel_hi:[1,0,0]
	v_pk_mul_f32 v[2:3], v[2:3], s[12:13] op_sel_hi:[1,0]
	v_pk_mul_f32 v[6:7], v[6:7], v[4:5]
	v_exp_f32_e32 v2, v2
	v_exp_f32_e32 v3, v3
	v_pk_mul_f32 v[6:7], v[6:7], s[12:13] op_sel_hi:[1,0]
	v_pk_add_f32 v[2:3], v[2:3], 1.0 op_sel_hi:[1,0]
	v_exp_f32_e32 v6, v6
	v_exp_f32_e32 v7, v7
	v_rcp_f32_e32 v2, v2
	v_rcp_f32_e32 v3, v3
	v_pk_add_f32 v[6:7], v[6:7], 1.0 op_sel_hi:[1,0]
	s_nop 0
	v_rcp_f32_e32 v6, v6
	v_rcp_f32_e32 v7, v7
	v_pk_mul_f32 v[0:1], v[2:3], v[0:1]
	v_pk_add_f32 v[2:3], v[68:69], v[12:13] op_sel_hi:[0,1]
	v_pk_mul_f32 v[0:1], v[0:1], v[2:3]
	v_pk_mul_f32 v[2:3], v[6:7], v[4:5]
	v_pk_add_f32 v[4:5], v[68:69], v[14:15] op_sel_hi:[0,1]
	v_pk_mul_f32 v[2:3], v[2:3], v[4:5]
	v_cvt_pk_bf16_f32 v134, v0, v1
	s_nop 0
	v_cvt_pk_bf16_f32 v135, v2, v3
	s_nop 1
	v_permlane32_swap_b32_e32 v132, v134
	v_permlane32_swap_b32_e32 v133, v135
	global_store_dwordx4 v[136:137], v[132:135], off offset:1248
	s_barrier
